# v6 + in-loop LDS-DMA pieces whose address is not reused converted to SGPR-base form (8 v_lshl_add_u64 removed per K-loop iteration); includes P5 mid/epilogue batching, chain write-through stores witho
# baseline (speedup 1.0000x reference)
.LBB0_402:
	ds_read_b128 v[130:133], v167
	ds_read_b128 v[134:137], v167 offset:1024
	ds_read_b128 v[138:141], v167 offset:2048
	ds_read_b128 v[178:181], v167 offset:3072
	ds_read_b128 v[182:185], v168
	ds_read_b128 v[188:191], v168 offset:1024
	ds_read_b128 v[192:195], v168 offset:2048
	ds_read_b128 v[196:199], v168 offset:3072
	s_add_u32 s41, s60, 0xfff00080
	s_addc_u32 s62, s61, -1
	s_cmp_eq_u32 s39, 60
	s_cselect_b32 s65, s43, s62
	s_cselect_b32 s64, s42, s41
	s_cselect_b32 s63, s45, s10
	s_cselect_b32 s62, s44, s9
	s_add_i32 m0, s47, 0xc000
	ds_read_b128 v[200:203], v169
	ds_read_b128 v[204:207], v169 offset:1024
	ds_read_b128 v[208:211], v169 offset:2048
	ds_read_b128 v[212:215], v169 offset:3072
	ds_read_b128 v[216:219], v169 offset:4096
	ds_read_b128 v[220:223], v169 offset:5120
	ds_read_b128 v[224:227], v169 offset:6144
	ds_read_b128 v[228:231], v169 offset:7168
	global_load_lds_dwordx4 v158, s[60:61]
	s_add_i32 m0, s47, 0xe000
	s_nop 0
	global_load_lds_dwordx4 v156, s[60:61]
	s_waitcnt vmcnt(8)
	s_waitcnt lgkmcnt(0)
	s_barrier
	s_setprio 1
	s_waitcnt lgkmcnt(0)
	v_mfma_f32_16x16x32_bf16 v[126:129], v[130:133], v[200:203], v[126:129]
	v_mfma_f32_16x16x32_bf16 v[122:125], v[138:141], v[200:203], v[122:125]
	v_mfma_f32_16x16x32_bf16 v[110:113], v[130:133], v[208:211], v[110:113]
	v_mfma_f32_16x16x32_bf16 v[106:109], v[138:141], v[208:211], v[106:109]
	v_mfma_f32_16x16x32_bf16 v[94:97], v[130:133], v[216:219], v[94:97]
	v_mfma_f32_16x16x32_bf16 v[90:93], v[138:141], v[216:219], v[90:93]
	v_mfma_f32_16x16x32_bf16 v[78:81], v[130:133], v[224:227], v[78:81]
	v_mfma_f32_16x16x32_bf16 v[74:77], v[138:141], v[224:227], v[74:77]
	v_mfma_f32_16x16x32_bf16 v[126:129], v[134:137], v[204:207], v[126:129]
	v_mfma_f32_16x16x32_bf16 v[122:125], v[178:181], v[204:207], v[122:125]
	v_mfma_f32_16x16x32_bf16 v[110:113], v[134:137], v[212:215], v[110:113]
	v_mfma_f32_16x16x32_bf16 v[106:109], v[178:181], v[212:215], v[106:109]
	v_mfma_f32_16x16x32_bf16 v[94:97], v[134:137], v[220:223], v[94:97]
	v_mfma_f32_16x16x32_bf16 v[90:93], v[178:181], v[220:223], v[90:93]
	v_mfma_f32_16x16x32_bf16 v[78:81], v[134:137], v[228:231], v[78:81]
	v_mfma_f32_16x16x32_bf16 v[74:77], v[178:181], v[228:231], v[74:77]
	s_setprio 0
	s_setprio 1
	v_mfma_f32_16x16x32_bf16 v[118:121], v[182:185], v[200:203], v[118:121]
	v_mfma_f32_16x16x32_bf16 v[114:117], v[192:195], v[200:203], v[114:117]
	v_mfma_f32_16x16x32_bf16 v[102:105], v[182:185], v[208:211], v[102:105]
	v_mfma_f32_16x16x32_bf16 v[98:101], v[192:195], v[208:211], v[98:101]
	v_mfma_f32_16x16x32_bf16 v[86:89], v[182:185], v[216:219], v[86:89]
	v_mfma_f32_16x16x32_bf16 v[82:85], v[192:195], v[216:219], v[82:85]
	v_mfma_f32_16x16x32_bf16 v[70:73], v[182:185], v[224:227], v[70:73]
	v_mfma_f32_16x16x32_bf16 v[66:69], v[192:195], v[224:227], v[66:69]
	v_mfma_f32_16x16x32_bf16 v[118:121], v[188:191], v[204:207], v[118:121]
	v_mfma_f32_16x16x32_bf16 v[114:117], v[196:199], v[204:207], v[114:117]
	v_mfma_f32_16x16x32_bf16 v[102:105], v[188:191], v[212:215], v[102:105]
	v_mfma_f32_16x16x32_bf16 v[98:101], v[196:199], v[212:215], v[98:101]
	v_mfma_f32_16x16x32_bf16 v[86:89], v[188:191], v[220:223], v[86:89]
	v_mfma_f32_16x16x32_bf16 v[82:85], v[196:199], v[220:223], v[82:85]
	v_mfma_f32_16x16x32_bf16 v[70:73], v[188:191], v[228:231], v[70:73]
	v_mfma_f32_16x16x32_bf16 v[66:69], v[196:199], v[228:231], v[66:69]
	s_setprio 0
	s_barrier
	s_add_i32 s41, s83, s70
	v_lshl_add_u64 v[164:165], s[62:63], 0, v[144:145]
	s_mov_b32 m0, s41
	ds_read_b128 v[200:203], v169 offset:16384
	ds_read_b128 v[204:207], v169 offset:17408
	ds_read_b128 v[208:211], v169 offset:18432
	ds_read_b128 v[212:215], v169 offset:19456
	ds_read_b128 v[216:219], v169 offset:20480
	ds_read_b128 v[220:223], v169 offset:21504
	ds_read_b128 v[224:227], v169 offset:22528
	ds_read_b128 v[228:231], v169 offset:23552
	global_load_lds_dwordx4 v[164:165], off
	s_add_i32 m0, s41, 0x2000
	s_add_u32 vcc_lo, s62, 0x100000
	v_lshl_add_u64 v[232:233], s[62:63], 0, v[148:149]
	s_addc_u32 vcc_hi, s63, 0
	s_add_i32 s41, s84, s70
	global_load_lds_dwordx4 v[232:233], off
	s_mov_b32 m0, s41
	v_lshl_add_u64 v[236:237], s[64:65], 0, v[146:147]
	global_load_lds_dwordx4 v144, vcc
	s_add_i32 m0, s41, 0x2000
	s_nop 0
	global_load_lds_dwordx4 v148, vcc
	v_lshl_add_u64 v[234:235], s[64:65], 0, v[142:143]
	s_mov_b32 m0, s47
	s_nop 0
	global_load_lds_dwordx4 v[234:235], off
	s_mov_b32 m0, s71
	s_nop 0
	global_load_lds_dwordx4 v[236:237], off
	s_waitcnt vmcnt(8)
	s_waitcnt lgkmcnt(0)
	s_barrier
	s_setprio 1
	s_waitcnt lgkmcnt(0)
	v_mfma_f32_16x16x32_bf16 v[62:65], v[130:133], v[200:203], v[62:65]
	v_mfma_f32_16x16x32_bf16 v[58:61], v[138:141], v[200:203], v[58:61]
	v_mfma_f32_16x16x32_bf16 v[46:49], v[130:133], v[208:211], v[46:49]
	v_mfma_f32_16x16x32_bf16 v[42:45], v[138:141], v[208:211], v[42:45]
	v_mfma_f32_16x16x32_bf16 v[30:33], v[130:133], v[216:219], v[30:33]
	v_mfma_f32_16x16x32_bf16 v[26:29], v[138:141], v[216:219], v[26:29]
	v_mfma_f32_16x16x32_bf16 v[14:17], v[130:133], v[224:227], v[14:17]
	v_mfma_f32_16x16x32_bf16 v[10:13], v[138:141], v[224:227], v[10:13]
	v_mfma_f32_16x16x32_bf16 v[62:65], v[134:137], v[204:207], v[62:65]
	v_mfma_f32_16x16x32_bf16 v[58:61], v[178:181], v[204:207], v[58:61]
	v_mfma_f32_16x16x32_bf16 v[46:49], v[134:137], v[212:215], v[46:49]
	v_mfma_f32_16x16x32_bf16 v[42:45], v[178:181], v[212:215], v[42:45]
	v_mfma_f32_16x16x32_bf16 v[30:33], v[134:137], v[220:223], v[30:33]
	v_mfma_f32_16x16x32_bf16 v[26:29], v[178:181], v[220:223], v[26:29]
	v_mfma_f32_16x16x32_bf16 v[14:17], v[134:137], v[228:231], v[14:17]
	v_mfma_f32_16x16x32_bf16 v[10:13], v[178:181], v[228:231], v[10:13]
	s_setprio 0
	s_setprio 1
	v_mfma_f32_16x16x32_bf16 v[54:57], v[182:185], v[200:203], v[54:57]
	v_mfma_f32_16x16x32_bf16 v[50:53], v[192:195], v[200:203], v[50:53]
	v_mfma_f32_16x16x32_bf16 v[38:41], v[182:185], v[208:211], v[38:41]
	v_mfma_f32_16x16x32_bf16 v[34:37], v[192:195], v[208:211], v[34:37]
	v_mfma_f32_16x16x32_bf16 v[22:25], v[182:185], v[216:219], v[22:25]
	v_mfma_f32_16x16x32_bf16 v[18:21], v[192:195], v[216:219], v[18:21]
	v_mfma_f32_16x16x32_bf16 v[6:9], v[182:185], v[224:227], v[6:9]
	v_mfma_f32_16x16x32_bf16 v[2:5], v[192:195], v[224:227], v[2:5]
	v_mfma_f32_16x16x32_bf16 v[54:57], v[188:191], v[204:207], v[54:57]
	v_mfma_f32_16x16x32_bf16 v[50:53], v[196:199], v[204:207], v[50:53]
	v_mfma_f32_16x16x32_bf16 v[38:41], v[188:191], v[212:215], v[38:41]
	v_mfma_f32_16x16x32_bf16 v[34:37], v[196:199], v[212:215], v[34:37]
	v_mfma_f32_16x16x32_bf16 v[22:25], v[188:191], v[220:223], v[22:25]
	v_mfma_f32_16x16x32_bf16 v[18:21], v[196:199], v[220:223], v[18:21]
	v_mfma_f32_16x16x32_bf16 v[6:9], v[188:191], v[228:231], v[6:9]
	v_mfma_f32_16x16x32_bf16 v[2:5], v[196:199], v[228:231], v[2:5]
	s_setprio 0
	s_barrier
	s_add_i32 s41, 0, 0x18000
	v_add_u32_e32 v150, s41, v153
	s_add_i32 s90, 0, 0x1c000
	ds_read_b128 v[130:133], v150
	ds_read_b128 v[134:137], v150 offset:1024
	ds_read_b128 v[138:141], v150 offset:2048
	ds_read_b128 v[178:181], v150 offset:3072
	v_add_u32_e32 v150, s90, v153
	ds_read_b128 v[182:185], v150
	ds_read_b128 v[188:191], v150 offset:1024
	ds_read_b128 v[192:195], v150 offset:2048
	ds_read_b128 v[196:199], v150 offset:3072
	s_add_u32 s64, s64, 0x100000
	s_addc_u32 s65, s65, 0
	s_mov_b32 m0, s72
	ds_read_b128 v[200:203], v169 offset:32768
	ds_read_b128 v[204:207], v169 offset:33792
	ds_read_b128 v[208:211], v169 offset:34816
	ds_read_b128 v[212:215], v169 offset:35840
	ds_read_b128 v[216:219], v169 offset:36864
	ds_read_b128 v[220:223], v169 offset:37888
	ds_read_b128 v[224:227], v169 offset:38912
	ds_read_b128 v[228:231], v169 offset:39936
	global_load_lds_dwordx4 v142, s[64:65]
	s_mov_b32 m0, s73
	s_nop 0
	global_load_lds_dwordx4 v146, s[64:65]
	s_waitcnt vmcnt(8)
	s_waitcnt lgkmcnt(0)
	s_barrier
	s_setprio 1
	s_waitcnt lgkmcnt(0)
	v_mfma_f32_16x16x32_bf16 v[126:129], v[130:133], v[200:203], v[126:129]
	v_mfma_f32_16x16x32_bf16 v[122:125], v[138:141], v[200:203], v[122:125]
	v_mfma_f32_16x16x32_bf16 v[110:113], v[130:133], v[208:211], v[110:113]
	v_mfma_f32_16x16x32_bf16 v[106:109], v[138:141], v[208:211], v[106:109]
	v_mfma_f32_16x16x32_bf16 v[94:97], v[130:133], v[216:219], v[94:97]
	v_mfma_f32_16x16x32_bf16 v[90:93], v[138:141], v[216:219], v[90:93]
	v_mfma_f32_16x16x32_bf16 v[78:81], v[130:133], v[224:227], v[78:81]
	v_mfma_f32_16x16x32_bf16 v[74:77], v[138:141], v[224:227], v[74:77]
	v_mfma_f32_16x16x32_bf16 v[126:129], v[134:137], v[204:207], v[126:129]
	v_mfma_f32_16x16x32_bf16 v[122:125], v[178:181], v[204:207], v[122:125]
	v_mfma_f32_16x16x32_bf16 v[110:113], v[134:137], v[212:215], v[110:113]
	v_mfma_f32_16x16x32_bf16 v[106:109], v[178:181], v[212:215], v[106:109]
	v_mfma_f32_16x16x32_bf16 v[94:97], v[134:137], v[220:223], v[94:97]
	v_mfma_f32_16x16x32_bf16 v[90:93], v[178:181], v[220:223], v[90:93]
	v_mfma_f32_16x16x32_bf16 v[78:81], v[134:137], v[228:231], v[78:81]
	v_mfma_f32_16x16x32_bf16 v[74:77], v[178:181], v[228:231], v[74:77]
	s_setprio 0
	s_setprio 1
	v_mfma_f32_16x16x32_bf16 v[118:121], v[182:185], v[200:203], v[118:121]
	v_mfma_f32_16x16x32_bf16 v[114:117], v[192:195], v[200:203], v[114:117]
	v_mfma_f32_16x16x32_bf16 v[102:105], v[182:185], v[208:211], v[102:105]
	v_mfma_f32_16x16x32_bf16 v[98:101], v[192:195], v[208:211], v[98:101]
	v_mfma_f32_16x16x32_bf16 v[86:89], v[182:185], v[216:219], v[86:89]
	v_mfma_f32_16x16x32_bf16 v[82:85], v[192:195], v[216:219], v[82:85]
	v_mfma_f32_16x16x32_bf16 v[70:73], v[182:185], v[224:227], v[70:73]
	v_mfma_f32_16x16x32_bf16 v[66:69], v[192:195], v[224:227], v[66:69]
	v_mfma_f32_16x16x32_bf16 v[118:121], v[188:191], v[204:207], v[118:121]
	v_mfma_f32_16x16x32_bf16 v[114:117], v[196:199], v[204:207], v[114:117]
	v_mfma_f32_16x16x32_bf16 v[102:105], v[188:191], v[212:215], v[102:105]
	v_mfma_f32_16x16x32_bf16 v[98:101], v[196:199], v[212:215], v[98:101]
	v_mfma_f32_16x16x32_bf16 v[86:89], v[188:191], v[220:223], v[86:89]
	v_mfma_f32_16x16x32_bf16 v[82:85], v[196:199], v[220:223], v[82:85]
	v_mfma_f32_16x16x32_bf16 v[70:73], v[188:191], v[228:231], v[70:73]
	v_mfma_f32_16x16x32_bf16 v[66:69], v[196:199], v[228:231], v[66:69]
	s_setprio 0
	s_barrier
	s_add_i32 s41, s41, s70
	v_lshl_add_u64 v[164:165], v[164:165], 0, s[26:27]
	s_mov_b32 m0, s41
	ds_read_b128 v[200:203], v169 offset:49152
	ds_read_b128 v[204:207], v169 offset:50176
	ds_read_b128 v[208:211], v169 offset:51200
	ds_read_b128 v[212:215], v169 offset:52224
	ds_read_b128 v[216:219], v169 offset:53248
	ds_read_b128 v[220:223], v169 offset:54272
	ds_read_b128 v[224:227], v169 offset:55296
	ds_read_b128 v[228:231], v169 offset:56320
	global_load_lds_dwordx4 v[164:165], off
	s_add_i32 m0, s41, 0x2000
	s_add_u32 s62, s62, 0x100080
	v_lshl_add_u64 v[164:165], v[232:233], 0, s[26:27]
	s_addc_u32 s63, s63, 0
	s_add_i32 s41, s90, s70
	global_load_lds_dwordx4 v[164:165], off
	s_mov_b32 m0, s41
	s_nop 0
	global_load_lds_dwordx4 v144, s[62:63]
	s_add_i32 m0, s41, 0x2000
	s_nop 0
	global_load_lds_dwordx4 v148, s[62:63]
	v_lshl_add_u64 v[164:165], v[234:235], 0, s[26:27]
	s_mov_b32 m0, s77
	s_nop 0
	global_load_lds_dwordx4 v[164:165], off
	v_lshl_add_u64 v[164:165], v[236:237], 0, s[26:27]
	s_mov_b32 m0, s78
	s_nop 0
	global_load_lds_dwordx4 v[164:165], off
	s_waitcnt vmcnt(8)
	s_waitcnt lgkmcnt(0)
	s_barrier
	s_setprio 1
	s_waitcnt lgkmcnt(0)
	v_mfma_f32_16x16x32_bf16 v[62:65], v[130:133], v[200:203], v[62:65]
	v_mfma_f32_16x16x32_bf16 v[58:61], v[138:141], v[200:203], v[58:61]
	v_mfma_f32_16x16x32_bf16 v[46:49], v[130:133], v[208:211], v[46:49]
	v_mfma_f32_16x16x32_bf16 v[42:45], v[138:141], v[208:211], v[42:45]
	v_mfma_f32_16x16x32_bf16 v[30:33], v[130:133], v[216:219], v[30:33]
	v_mfma_f32_16x16x32_bf16 v[26:29], v[138:141], v[216:219], v[26:29]
	v_mfma_f32_16x16x32_bf16 v[14:17], v[130:133], v[224:227], v[14:17]
	v_mfma_f32_16x16x32_bf16 v[10:13], v[138:141], v[224:227], v[10:13]
	v_mfma_f32_16x16x32_bf16 v[62:65], v[134:137], v[204:207], v[62:65]
	v_mfma_f32_16x16x32_bf16 v[58:61], v[178:181], v[204:207], v[58:61]
	v_mfma_f32_16x16x32_bf16 v[46:49], v[134:137], v[212:215], v[46:49]
	v_mfma_f32_16x16x32_bf16 v[42:45], v[178:181], v[212:215], v[42:45]
	v_mfma_f32_16x16x32_bf16 v[30:33], v[134:137], v[220:223], v[30:33]
	v_mfma_f32_16x16x32_bf16 v[26:29], v[178:181], v[220:223], v[26:29]
	v_mfma_f32_16x16x32_bf16 v[14:17], v[134:137], v[228:231], v[14:17]
	v_mfma_f32_16x16x32_bf16 v[10:13], v[178:181], v[228:231], v[10:13]
	s_setprio 0
	s_setprio 1
	v_mfma_f32_16x16x32_bf16 v[54:57], v[182:185], v[200:203], v[54:57]
	v_mfma_f32_16x16x32_bf16 v[50:53], v[192:195], v[200:203], v[50:53]
	v_mfma_f32_16x16x32_bf16 v[38:41], v[182:185], v[208:211], v[38:41]
	v_mfma_f32_16x16x32_bf16 v[34:37], v[192:195], v[208:211], v[34:37]
	v_mfma_f32_16x16x32_bf16 v[22:25], v[182:185], v[216:219], v[22:25]
	v_mfma_f32_16x16x32_bf16 v[18:21], v[192:195], v[216:219], v[18:21]
	v_mfma_f32_16x16x32_bf16 v[6:9], v[182:185], v[224:227], v[6:9]
	v_mfma_f32_16x16x32_bf16 v[2:5], v[192:195], v[224:227], v[2:5]
	v_mfma_f32_16x16x32_bf16 v[54:57], v[188:191], v[204:207], v[54:57]
	v_mfma_f32_16x16x32_bf16 v[50:53], v[196:199], v[204:207], v[50:53]
	v_mfma_f32_16x16x32_bf16 v[38:41], v[188:191], v[212:215], v[38:41]
	v_mfma_f32_16x16x32_bf16 v[34:37], v[196:199], v[212:215], v[34:37]
	v_mfma_f32_16x16x32_bf16 v[22:25], v[188:191], v[220:223], v[22:25]
	v_mfma_f32_16x16x32_bf16 v[18:21], v[196:199], v[220:223], v[18:21]
	v_mfma_f32_16x16x32_bf16 v[6:9], v[188:191], v[228:231], v[6:9]
	v_mfma_f32_16x16x32_bf16 v[2:5], v[196:199], v[228:231], v[2:5]
	s_setprio 0
	s_barrier
	s_add_i32 s39, s39, 2
	s_add_u32 s9, s9, 0x100
	s_addc_u32 s10, s10, 0
	s_add_u32 s60, s60, 0x100
	s_addc_u32 s61, s61, 0
	s_cmp_gt_u32 s39, 61
	s_cbranch_scc0 .LBB0_402
	s_and_b64 vcc, exec, s[28:29]
	s_cbranch_vccz .LBB0_405
	s_barrier

.LBB0_697:
	s_waitcnt lgkmcnt(0)
	ds_read_b128 v[2:5], v188
	ds_read_b128 v[6:9], v188 offset:1024
	s_waitcnt vmcnt(0)
	ds_read_b128 v[138:141], v188 offset:2048
	ds_read_b128 v[142:145], v188 offset:3072
	ds_read_b128 v[146:149], v189
	ds_read_b128 v[150:153], v189 offset:1024
	ds_read_b128 v[172:175], v189 offset:2048
	ds_read_b128 v[176:179], v189 offset:3072
	s_add_u32 s38, s36, 0xfff80080
	s_addc_u32 s39, s37, -1
	s_cmp_eq_u32 s72, 28
	s_cselect_b32 s41, s29, s39
	s_cselect_b32 s40, s68, s38
	s_cselect_b32 s39, s27, s71
	s_cselect_b32 s38, s69, s70
	s_add_i32 m0, s9, 0xc000
	ds_read_b128 v[192:195], v190
	ds_read_b128 v[196:199], v190 offset:1024
	ds_read_b128 v[200:203], v190 offset:2048
	ds_read_b128 v[204:207], v190 offset:3072
	ds_read_b128 v[208:211], v190 offset:4096
	ds_read_b128 v[212:215], v190 offset:5120
	ds_read_b128 v[216:219], v190 offset:6144
	ds_read_b128 v[220:223], v190 offset:7168
	global_load_lds_dwordx4 v166, s[36:37]
	s_add_i32 m0, s9, 0xe000
	s_nop 0
	global_load_lds_dwordx4 v164, s[36:37]
	s_waitcnt vmcnt(8)
	s_waitcnt lgkmcnt(0)
	s_barrier
	s_setprio 1
	s_waitcnt lgkmcnt(0)
	v_mfma_i32_16x16x64_i8 v[134:137], v[2:5], v[192:195], v[134:137]
	v_mfma_i32_16x16x64_i8 v[130:133], v[138:141], v[192:195], v[130:133]
	v_mfma_i32_16x16x64_i8 v[118:121], v[2:5], v[200:203], v[118:121]
	v_mfma_i32_16x16x64_i8 v[114:117], v[138:141], v[200:203], v[114:117]
	v_mfma_i32_16x16x64_i8 v[102:105], v[2:5], v[208:211], v[102:105]
	v_mfma_i32_16x16x64_i8 v[98:101], v[138:141], v[208:211], v[98:101]
	v_mfma_i32_16x16x64_i8 v[86:89], v[2:5], v[216:219], v[86:89]
	v_mfma_i32_16x16x64_i8 v[82:85], v[138:141], v[216:219], v[82:85]
	v_mfma_i32_16x16x64_i8 v[134:137], v[6:9], v[196:199], v[134:137]
	v_mfma_i32_16x16x64_i8 v[130:133], v[142:145], v[196:199], v[130:133]
	v_mfma_i32_16x16x64_i8 v[118:121], v[6:9], v[204:207], v[118:121]
	v_mfma_i32_16x16x64_i8 v[114:117], v[142:145], v[204:207], v[114:117]
	v_mfma_i32_16x16x64_i8 v[102:105], v[6:9], v[212:215], v[102:105]
	v_mfma_i32_16x16x64_i8 v[98:101], v[142:145], v[212:215], v[98:101]
	v_mfma_i32_16x16x64_i8 v[86:89], v[6:9], v[220:223], v[86:89]
	v_mfma_i32_16x16x64_i8 v[82:85], v[142:145], v[220:223], v[82:85]
	s_setprio 0
	s_setprio 1
	v_mfma_i32_16x16x64_i8 v[126:129], v[146:149], v[192:195], v[126:129]
	v_mfma_i32_16x16x64_i8 v[122:125], v[172:175], v[192:195], v[122:125]
	v_mfma_i32_16x16x64_i8 v[110:113], v[146:149], v[200:203], v[110:113]
	v_mfma_i32_16x16x64_i8 v[106:109], v[172:175], v[200:203], v[106:109]
	v_mfma_i32_16x16x64_i8 v[94:97], v[146:149], v[208:211], v[94:97]
	v_mfma_i32_16x16x64_i8 v[90:93], v[172:175], v[208:211], v[90:93]
	v_mfma_i32_16x16x64_i8 v[78:81], v[146:149], v[216:219], v[78:81]
	v_mfma_i32_16x16x64_i8 v[74:77], v[172:175], v[216:219], v[74:77]
	v_mfma_i32_16x16x64_i8 v[126:129], v[150:153], v[196:199], v[126:129]
	v_mfma_i32_16x16x64_i8 v[122:125], v[176:179], v[196:199], v[122:125]
	v_mfma_i32_16x16x64_i8 v[110:113], v[150:153], v[204:207], v[110:113]
	v_mfma_i32_16x16x64_i8 v[106:109], v[176:179], v[204:207], v[106:109]
	v_mfma_i32_16x16x64_i8 v[94:97], v[150:153], v[212:215], v[94:97]
	v_mfma_i32_16x16x64_i8 v[90:93], v[176:179], v[212:215], v[90:93]
	v_mfma_i32_16x16x64_i8 v[78:81], v[150:153], v[220:223], v[78:81]
	v_mfma_i32_16x16x64_i8 v[74:77], v[176:179], v[220:223], v[74:77]
	s_setprio 0
	s_barrier
	s_add_i32 s73, s65, s44
	v_lshl_add_u64 v[180:181], s[38:39], 0, v[158:159]
	s_mov_b32 m0, s73
	ds_read_b128 v[192:195], v190 offset:16384
	ds_read_b128 v[196:199], v190 offset:17408
	ds_read_b128 v[200:203], v190 offset:18432
	ds_read_b128 v[204:207], v190 offset:19456
	ds_read_b128 v[208:211], v190 offset:20480
	ds_read_b128 v[212:215], v190 offset:21504
	ds_read_b128 v[216:219], v190 offset:22528
	ds_read_b128 v[220:223], v190 offset:23552
	global_load_lds_dwordx4 v[180:181], off
	s_add_i32 m0, s73, 0x2000
	s_add_u32 s76, s38, 0x80000
	v_lshl_add_u64 v[224:225], s[38:39], 0, v[154:155]
	s_addc_u32 s77, s39, 0
	s_add_i32 s73, s66, s44
	global_load_lds_dwordx4 v[224:225], off
	s_mov_b32 m0, s73
	v_lshl_add_u64 v[228:229], s[40:41], 0, v[156:157]
	global_load_lds_dwordx4 v158, s[76:77]
	s_add_i32 m0, s73, 0x2000
	s_nop 0
	global_load_lds_dwordx4 v154, s[76:77]
	v_lshl_add_u64 v[226:227], s[40:41], 0, v[160:161]
	s_mov_b32 m0, s9
	s_nop 0
	global_load_lds_dwordx4 v[226:227], off
	s_mov_b32 m0, s47
	s_nop 0
	global_load_lds_dwordx4 v[228:229], off
	s_waitcnt vmcnt(8)
	s_waitcnt lgkmcnt(0)
	s_barrier
	s_setprio 1
	s_waitcnt lgkmcnt(0)
	v_mfma_i32_16x16x64_i8 v[70:73], v[2:5], v[192:195], v[70:73]
	v_mfma_i32_16x16x64_i8 v[66:69], v[138:141], v[192:195], v[66:69]
	v_mfma_i32_16x16x64_i8 v[54:57], v[2:5], v[200:203], v[54:57]
	v_mfma_i32_16x16x64_i8 v[50:53], v[138:141], v[200:203], v[50:53]
	v_mfma_i32_16x16x64_i8 v[38:41], v[2:5], v[208:211], v[38:41]
	v_mfma_i32_16x16x64_i8 v[34:37], v[138:141], v[208:211], v[34:37]
	v_mfma_i32_16x16x64_i8 v[2:5], v[2:5], v[216:219], v[22:25]
	v_mfma_i32_16x16x64_i8 v[70:73], v[6:9], v[196:199], v[70:73]
	v_mfma_i32_16x16x64_i8 v[66:69], v[142:145], v[196:199], v[66:69]
	v_mfma_i32_16x16x64_i8 v[54:57], v[6:9], v[204:207], v[54:57]
	v_mfma_i32_16x16x64_i8 v[50:53], v[142:145], v[204:207], v[50:53]
	v_mfma_i32_16x16x64_i8 v[38:41], v[6:9], v[212:215], v[38:41]
	v_mfma_i32_16x16x64_i8 v[34:37], v[142:145], v[212:215], v[34:37]
	v_mfma_i32_16x16x64_i8 v[2:5], v[6:9], v[220:223], v[2:5]
	v_mfma_i32_16x16x64_i8 v[6:9], v[138:141], v[216:219], v[18:21]
	v_mfma_i32_16x16x64_i8 v[6:9], v[142:145], v[220:223], v[6:9]
	s_setprio 0
	s_setprio 1
	v_mfma_i32_16x16x64_i8 v[18:21], v[146:149], v[192:195], v[62:65]
	v_mfma_i32_16x16x64_i8 v[62:65], v[150:153], v[196:199], v[18:21]
	v_mfma_i32_16x16x64_i8 v[18:21], v[172:175], v[192:195], v[58:61]
	v_mfma_i32_16x16x64_i8 v[58:61], v[176:179], v[196:199], v[18:21]
	v_mfma_i32_16x16x64_i8 v[18:21], v[146:149], v[200:203], v[46:49]
	v_mfma_i32_16x16x64_i8 v[46:49], v[150:153], v[204:207], v[18:21]
	v_mfma_i32_16x16x64_i8 v[18:21], v[172:175], v[200:203], v[42:45]
	v_mfma_i32_16x16x64_i8 v[42:45], v[176:179], v[204:207], v[18:21]
	v_mfma_i32_16x16x64_i8 v[18:21], v[146:149], v[208:211], v[30:33]
	v_mfma_i32_16x16x64_i8 v[30:33], v[150:153], v[212:215], v[18:21]
	v_mfma_i32_16x16x64_i8 v[18:21], v[172:175], v[208:211], v[26:29]
	v_mfma_i32_16x16x64_i8 v[14:17], v[146:149], v[216:219], v[14:17]
	v_mfma_i32_16x16x64_i8 v[10:13], v[172:175], v[216:219], v[10:13]
	v_mfma_i32_16x16x64_i8 v[26:29], v[176:179], v[212:215], v[18:21]
	v_mfma_i32_16x16x64_i8 v[14:17], v[150:153], v[220:223], v[14:17]
	v_mfma_i32_16x16x64_i8 v[10:13], v[176:179], v[220:223], v[10:13]
	s_setprio 0
	s_barrier
	s_add_i32 s73, 0, 0x18000
	s_add_i32 s75, 0, 0x1c000
	v_add_u32_e32 v142, s73, v182
	v_add_u32_e32 v162, s75, v182
	ds_read_b128 v[18:21], v142
	ds_read_b128 v[22:25], v142 offset:1024
	ds_read_b128 v[138:141], v142 offset:2048
	ds_read_b128 v[142:145], v142 offset:3072
	ds_read_b128 v[146:149], v162
	ds_read_b128 v[150:153], v162 offset:1024
	ds_read_b128 v[172:175], v162 offset:2048
	ds_read_b128 v[176:179], v162 offset:3072
	s_add_u32 s40, s40, 0x80000
	s_addc_u32 s41, s41, 0
	s_mov_b32 m0, s49
	ds_read_b128 v[192:195], v190 offset:32768
	ds_read_b128 v[196:199], v190 offset:33792
	ds_read_b128 v[200:203], v190 offset:34816
	ds_read_b128 v[204:207], v190 offset:35840
	ds_read_b128 v[208:211], v190 offset:36864
	ds_read_b128 v[212:215], v190 offset:37888
	ds_read_b128 v[216:219], v190 offset:38912
	ds_read_b128 v[220:223], v190 offset:39936
	global_load_lds_dwordx4 v160, s[40:41]
	s_mov_b32 m0, s60
	s_nop 0
	global_load_lds_dwordx4 v156, s[40:41]
	s_waitcnt vmcnt(8)
	s_waitcnt lgkmcnt(0)
	s_barrier
	s_setprio 1
	s_waitcnt lgkmcnt(0)
	v_mfma_i32_16x16x64_i8 v[134:137], v[18:21], v[192:195], v[134:137]
	v_mfma_i32_16x16x64_i8 v[130:133], v[138:141], v[192:195], v[130:133]
	v_mfma_i32_16x16x64_i8 v[118:121], v[18:21], v[200:203], v[118:121]
	v_mfma_i32_16x16x64_i8 v[114:117], v[138:141], v[200:203], v[114:117]
	v_mfma_i32_16x16x64_i8 v[102:105], v[18:21], v[208:211], v[102:105]
	v_mfma_i32_16x16x64_i8 v[98:101], v[138:141], v[208:211], v[98:101]
	v_mfma_i32_16x16x64_i8 v[86:89], v[18:21], v[216:219], v[86:89]
	v_mfma_i32_16x16x64_i8 v[82:85], v[138:141], v[216:219], v[82:85]
	v_mfma_i32_16x16x64_i8 v[134:137], v[22:25], v[196:199], v[134:137]
	v_mfma_i32_16x16x64_i8 v[130:133], v[142:145], v[196:199], v[130:133]
	v_mfma_i32_16x16x64_i8 v[118:121], v[22:25], v[204:207], v[118:121]
	v_mfma_i32_16x16x64_i8 v[114:117], v[142:145], v[204:207], v[114:117]
	v_mfma_i32_16x16x64_i8 v[102:105], v[22:25], v[212:215], v[102:105]
	v_mfma_i32_16x16x64_i8 v[98:101], v[142:145], v[212:215], v[98:101]
	v_mfma_i32_16x16x64_i8 v[86:89], v[22:25], v[220:223], v[86:89]
	v_mfma_i32_16x16x64_i8 v[82:85], v[142:145], v[220:223], v[82:85]
	s_setprio 0
	s_setprio 1
	v_mfma_i32_16x16x64_i8 v[126:129], v[146:149], v[192:195], v[126:129]
	v_mfma_i32_16x16x64_i8 v[122:125], v[172:175], v[192:195], v[122:125]
	v_mfma_i32_16x16x64_i8 v[110:113], v[146:149], v[200:203], v[110:113]
	v_mfma_i32_16x16x64_i8 v[106:109], v[172:175], v[200:203], v[106:109]
	v_mfma_i32_16x16x64_i8 v[94:97], v[146:149], v[208:211], v[94:97]
	v_mfma_i32_16x16x64_i8 v[90:93], v[172:175], v[208:211], v[90:93]
	v_mfma_i32_16x16x64_i8 v[78:81], v[146:149], v[216:219], v[78:81]
	v_mfma_i32_16x16x64_i8 v[74:77], v[172:175], v[216:219], v[74:77]
	v_mfma_i32_16x16x64_i8 v[126:129], v[150:153], v[196:199], v[126:129]
	v_mfma_i32_16x16x64_i8 v[122:125], v[176:179], v[196:199], v[122:125]
	v_mfma_i32_16x16x64_i8 v[110:113], v[150:153], v[204:207], v[110:113]
	v_mfma_i32_16x16x64_i8 v[106:109], v[176:179], v[204:207], v[106:109]
	v_mfma_i32_16x16x64_i8 v[94:97], v[150:153], v[212:215], v[94:97]
	v_mfma_i32_16x16x64_i8 v[90:93], v[176:179], v[212:215], v[90:93]
	v_mfma_i32_16x16x64_i8 v[78:81], v[150:153], v[220:223], v[78:81]
	v_mfma_i32_16x16x64_i8 v[74:77], v[176:179], v[220:223], v[74:77]
	s_setprio 0
	s_barrier
	s_add_i32 s40, s73, s44
	v_lshl_add_u64 v[180:181], v[180:181], 0, s[20:21]
	s_mov_b32 m0, s40
	ds_read_b128 v[192:195], v190 offset:49152
	ds_read_b128 v[196:199], v190 offset:50176
	ds_read_b128 v[200:203], v190 offset:51200
	ds_read_b128 v[204:207], v190 offset:52224
	ds_read_b128 v[208:211], v190 offset:53248
	ds_read_b128 v[212:215], v190 offset:54272
	ds_read_b128 v[216:219], v190 offset:55296
	ds_read_b128 v[220:223], v190 offset:56320
	global_load_lds_dwordx4 v[180:181], off
	s_add_i32 m0, s40, 0x2000
	s_add_u32 s38, s38, 0x80080
	v_lshl_add_u64 v[180:181], v[224:225], 0, s[20:21]
	s_addc_u32 s39, s39, 0
	s_add_i32 s40, s75, s44
	global_load_lds_dwordx4 v[180:181], off
	s_mov_b32 m0, s40
	s_nop 0
	global_load_lds_dwordx4 v158, s[38:39]
	s_add_i32 m0, s40, 0x2000
	s_nop 0
	global_load_lds_dwordx4 v154, s[38:39]
	v_lshl_add_u64 v[180:181], v[226:227], 0, s[20:21]
	s_mov_b32 m0, s62
	s_nop 0
	global_load_lds_dwordx4 v[180:181], off
	v_lshl_add_u64 v[180:181], v[228:229], 0, s[20:21]
	s_mov_b32 m0, s63
	s_nop 0
	global_load_lds_dwordx4 v[180:181], off
	s_waitcnt vmcnt(8)
	s_waitcnt lgkmcnt(0)
	s_barrier
	s_setprio 1
	s_waitcnt lgkmcnt(0)
	v_mfma_i32_16x16x64_i8 v[70:73], v[18:21], v[192:195], v[70:73]
	v_mfma_i32_16x16x64_i8 v[54:57], v[18:21], v[200:203], v[54:57]
	v_mfma_i32_16x16x64_i8 v[38:41], v[18:21], v[208:211], v[38:41]
	v_mfma_i32_16x16x64_i8 v[2:5], v[18:21], v[216:219], v[2:5]
	v_mfma_i32_16x16x64_i8 v[70:73], v[22:25], v[196:199], v[70:73]
	v_mfma_i32_16x16x64_i8 v[66:69], v[138:141], v[192:195], v[66:69]
	v_mfma_i32_16x16x64_i8 v[54:57], v[22:25], v[204:207], v[54:57]
	v_mfma_i32_16x16x64_i8 v[50:53], v[138:141], v[200:203], v[50:53]
	v_mfma_i32_16x16x64_i8 v[38:41], v[22:25], v[212:215], v[38:41]
	v_mfma_i32_16x16x64_i8 v[34:37], v[138:141], v[208:211], v[34:37]
	v_mfma_i32_16x16x64_i8 v[22:25], v[22:25], v[220:223], v[2:5]
	v_mfma_i32_16x16x64_i8 v[2:5], v[138:141], v[216:219], v[6:9]
	v_mfma_i32_16x16x64_i8 v[66:69], v[142:145], v[196:199], v[66:69]
	v_mfma_i32_16x16x64_i8 v[50:53], v[142:145], v[204:207], v[50:53]
	v_mfma_i32_16x16x64_i8 v[34:37], v[142:145], v[212:215], v[34:37]
	v_mfma_i32_16x16x64_i8 v[18:21], v[142:145], v[220:223], v[2:5]
	s_setprio 0
	s_setprio 1
	v_mfma_i32_16x16x64_i8 v[2:5], v[146:149], v[192:195], v[62:65]
	v_mfma_i32_16x16x64_i8 v[62:65], v[150:153], v[196:199], v[2:5]
	v_mfma_i32_16x16x64_i8 v[2:5], v[172:175], v[192:195], v[58:61]
	v_mfma_i32_16x16x64_i8 v[58:61], v[176:179], v[196:199], v[2:5]
	v_mfma_i32_16x16x64_i8 v[2:5], v[146:149], v[200:203], v[46:49]
	v_mfma_i32_16x16x64_i8 v[46:49], v[150:153], v[204:207], v[2:5]
	v_mfma_i32_16x16x64_i8 v[2:5], v[172:175], v[200:203], v[42:45]
	v_mfma_i32_16x16x64_i8 v[42:45], v[176:179], v[204:207], v[2:5]
	v_mfma_i32_16x16x64_i8 v[2:5], v[146:149], v[208:211], v[30:33]
	v_mfma_i32_16x16x64_i8 v[30:33], v[150:153], v[212:215], v[2:5]
	v_mfma_i32_16x16x64_i8 v[2:5], v[172:175], v[208:211], v[26:29]
	v_mfma_i32_16x16x64_i8 v[26:29], v[176:179], v[212:215], v[2:5]
	v_mfma_i32_16x16x64_i8 v[2:5], v[146:149], v[216:219], v[14:17]
	v_mfma_i32_16x16x64_i8 v[14:17], v[150:153], v[220:223], v[2:5]
	v_mfma_i32_16x16x64_i8 v[2:5], v[172:175], v[216:219], v[10:13]
	v_mfma_i32_16x16x64_i8 v[10:13], v[176:179], v[220:223], v[2:5]
	s_setprio 0
	s_barrier
	s_add_i32 s72, s72, 2
	s_add_u32 s70, s70, 0x100
	s_addc_u32 s71, s71, 0
	s_add_u32 s36, s36, 0x100
	s_addc_u32 s37, s37, 0
	s_cmp_gt_u32 s72, 29
	s_cbranch_scc0 .LBB0_697
	s_and_b64 vcc, exec, s[22:23]
	s_cbranch_vccz .LBB0_700
	s_barrier

.LBB0_790:
	ds_read_b128 v[164:167], v1
	ds_read_b128 v[168:171], v1 offset:1024
	ds_read_b128 v[172:175], v1 offset:2048
	ds_read_b128 v[176:179], v1 offset:3072
	ds_read_b128 v[180:183], v143
	ds_read_b128 v[188:191], v143 offset:1024
	ds_read_b128 v[192:195], v143 offset:2048
	ds_read_b128 v[196:199], v143 offset:3072
	s_add_u32 s26, s24, 0xfff00080
	s_addc_u32 s27, s25, -1
	s_cmp_eq_u32 s77, 12
	s_cselect_b32 s29, s21, s27
	s_cselect_b32 s28, s20, s26
	s_cselect_b32 s27, s9, s76
	s_cselect_b32 s26, s8, s75
	s_mov_b32 m0, s61
	ds_read_b128 v[200:203], v141
	ds_read_b128 v[204:207], v141 offset:1024
	ds_read_b128 v[208:211], v141 offset:2048
	ds_read_b128 v[212:215], v141 offset:3072
	ds_read_b128 v[216:219], v141 offset:4096
	ds_read_b128 v[220:223], v141 offset:5120
	ds_read_b128 v[224:227], v141 offset:6144
	ds_read_b128 v[228:231], v141 offset:7168
	global_load_lds_dwordx4 v158, s[24:25]
	s_mov_b32 m0, s62
	s_nop 0
	global_load_lds_dwordx4 v156, s[24:25]
	s_waitcnt vmcnt(8)
	s_waitcnt lgkmcnt(0)
	s_barrier
	s_setprio 1
	s_waitcnt lgkmcnt(0)
	v_mfma_f32_16x16x32_bf16 v[126:129], v[164:167], v[200:203], v[126:129]
	v_mfma_f32_16x16x32_bf16 v[122:125], v[172:175], v[200:203], v[122:125]
	v_mfma_f32_16x16x32_bf16 v[118:121], v[164:167], v[208:211], v[118:121]
	v_mfma_f32_16x16x32_bf16 v[110:113], v[172:175], v[208:211], v[110:113]
	v_mfma_f32_16x16x32_bf16 v[102:105], v[164:167], v[216:219], v[102:105]
	v_mfma_f32_16x16x32_bf16 v[94:97], v[172:175], v[216:219], v[94:97]
	v_mfma_f32_16x16x32_bf16 v[86:89], v[164:167], v[224:227], v[86:89]
	v_mfma_f32_16x16x32_bf16 v[78:81], v[172:175], v[224:227], v[78:81]
	v_mfma_f32_16x16x32_bf16 v[126:129], v[168:171], v[204:207], v[126:129]
	v_mfma_f32_16x16x32_bf16 v[122:125], v[176:179], v[204:207], v[122:125]
	v_mfma_f32_16x16x32_bf16 v[118:121], v[168:171], v[212:215], v[118:121]
	v_mfma_f32_16x16x32_bf16 v[110:113], v[176:179], v[212:215], v[110:113]
	v_mfma_f32_16x16x32_bf16 v[102:105], v[168:171], v[220:223], v[102:105]
	v_mfma_f32_16x16x32_bf16 v[94:97], v[176:179], v[220:223], v[94:97]
	v_mfma_f32_16x16x32_bf16 v[86:89], v[168:171], v[228:231], v[86:89]
	v_mfma_f32_16x16x32_bf16 v[78:81], v[176:179], v[228:231], v[78:81]
	s_setprio 0
	s_setprio 1
	v_mfma_f32_16x16x32_bf16 v[114:117], v[180:183], v[200:203], v[114:117]
	v_mfma_f32_16x16x32_bf16 v[106:109], v[192:195], v[200:203], v[106:109]
	v_mfma_f32_16x16x32_bf16 v[98:101], v[180:183], v[208:211], v[98:101]
	v_mfma_f32_16x16x32_bf16 v[90:93], v[192:195], v[208:211], v[90:93]
	v_mfma_f32_16x16x32_bf16 v[82:85], v[180:183], v[216:219], v[82:85]
	v_mfma_f32_16x16x32_bf16 v[74:77], v[192:195], v[216:219], v[74:77]
	v_mfma_f32_16x16x32_bf16 v[70:73], v[180:183], v[224:227], v[70:73]
	v_mfma_f32_16x16x32_bf16 v[66:69], v[192:195], v[224:227], v[66:69]
	v_mfma_f32_16x16x32_bf16 v[114:117], v[188:191], v[204:207], v[114:117]
	v_mfma_f32_16x16x32_bf16 v[106:109], v[196:199], v[204:207], v[106:109]
	v_mfma_f32_16x16x32_bf16 v[98:101], v[188:191], v[212:215], v[98:101]
	v_mfma_f32_16x16x32_bf16 v[90:93], v[196:199], v[212:215], v[90:93]
	v_mfma_f32_16x16x32_bf16 v[82:85], v[188:191], v[220:223], v[82:85]
	v_mfma_f32_16x16x32_bf16 v[74:77], v[196:199], v[220:223], v[74:77]
	v_mfma_f32_16x16x32_bf16 v[70:73], v[188:191], v[228:231], v[70:73]
	v_mfma_f32_16x16x32_bf16 v[66:69], v[196:199], v[228:231], v[66:69]
	s_setprio 0
	s_barrier
	s_mov_b32 m0, s63
	v_lshl_add_u64 v[184:185], s[26:27], 0, v[134:135]
	s_add_u32 s78, s26, 0x100000
	ds_read_b128 v[200:203], v141 offset:16384
	ds_read_b128 v[204:207], v141 offset:17408
	ds_read_b128 v[208:211], v141 offset:18432
	ds_read_b128 v[212:215], v141 offset:19456
	ds_read_b128 v[216:219], v141 offset:20480
	ds_read_b128 v[220:223], v141 offset:21504
	ds_read_b128 v[224:227], v141 offset:22528
	ds_read_b128 v[228:231], v141 offset:23552
	global_load_lds_dwordx4 v[184:185], off
	v_lshl_add_u64 v[232:233], s[26:27], 0, v[130:131]
	s_mov_b32 m0, s64
	s_addc_u32 s79, s27, 0
	global_load_lds_dwordx4 v[232:233], off
	s_mov_b32 m0, s65
	v_lshl_add_u64 v[236:237], s[28:29], 0, v[132:133]
	global_load_lds_dwordx4 v134, s[78:79]
	s_mov_b32 m0, s66
	s_nop 0
	global_load_lds_dwordx4 v130, s[78:79]
	v_lshl_add_u64 v[234:235], s[28:29], 0, v[136:137]
	s_mov_b32 m0, s39
	s_nop 0
	global_load_lds_dwordx4 v[234:235], off
	s_mov_b32 m0, s40
	s_nop 0
	global_load_lds_dwordx4 v[236:237], off
	s_waitcnt vmcnt(8)
	s_waitcnt lgkmcnt(0)
	s_barrier
	s_setprio 1
	s_waitcnt lgkmcnt(0)
	v_mfma_f32_16x16x32_bf16 v[62:65], v[164:167], v[200:203], v[62:65]
	v_mfma_f32_16x16x32_bf16 v[58:61], v[172:175], v[200:203], v[58:61]
	v_mfma_f32_16x16x32_bf16 v[54:57], v[164:167], v[208:211], v[54:57]
	v_mfma_f32_16x16x32_bf16 v[46:49], v[172:175], v[208:211], v[46:49]
	v_mfma_f32_16x16x32_bf16 v[38:41], v[164:167], v[216:219], v[38:41]
	v_mfma_f32_16x16x32_bf16 v[30:33], v[172:175], v[216:219], v[30:33]
	v_mfma_f32_16x16x32_bf16 v[22:25], v[164:167], v[224:227], v[22:25]
	v_mfma_f32_16x16x32_bf16 v[14:17], v[172:175], v[224:227], v[14:17]
	v_mfma_f32_16x16x32_bf16 v[62:65], v[168:171], v[204:207], v[62:65]
	v_mfma_f32_16x16x32_bf16 v[58:61], v[176:179], v[204:207], v[58:61]
	v_mfma_f32_16x16x32_bf16 v[54:57], v[168:171], v[212:215], v[54:57]
	v_mfma_f32_16x16x32_bf16 v[46:49], v[176:179], v[212:215], v[46:49]
	v_mfma_f32_16x16x32_bf16 v[38:41], v[168:171], v[220:223], v[38:41]
	v_mfma_f32_16x16x32_bf16 v[30:33], v[176:179], v[220:223], v[30:33]
	v_mfma_f32_16x16x32_bf16 v[22:25], v[168:171], v[228:231], v[22:25]
	v_mfma_f32_16x16x32_bf16 v[14:17], v[176:179], v[228:231], v[14:17]
	s_setprio 0
	s_setprio 1
	v_mfma_f32_16x16x32_bf16 v[50:53], v[180:183], v[200:203], v[50:53]
	v_mfma_f32_16x16x32_bf16 v[42:45], v[192:195], v[200:203], v[42:45]
	v_mfma_f32_16x16x32_bf16 v[34:37], v[180:183], v[208:211], v[34:37]
	v_mfma_f32_16x16x32_bf16 v[26:29], v[192:195], v[208:211], v[26:29]
	v_mfma_f32_16x16x32_bf16 v[18:21], v[180:183], v[216:219], v[18:21]
	v_mfma_f32_16x16x32_bf16 v[10:13], v[192:195], v[216:219], v[10:13]
	v_mfma_f32_16x16x32_bf16 v[6:9], v[180:183], v[224:227], v[6:9]
	v_mfma_f32_16x16x32_bf16 v[2:5], v[192:195], v[224:227], v[2:5]
	v_mfma_f32_16x16x32_bf16 v[50:53], v[188:191], v[204:207], v[50:53]
	v_mfma_f32_16x16x32_bf16 v[42:45], v[196:199], v[204:207], v[42:45]
	v_mfma_f32_16x16x32_bf16 v[34:37], v[188:191], v[212:215], v[34:37]
	v_mfma_f32_16x16x32_bf16 v[26:29], v[196:199], v[212:215], v[26:29]
	v_mfma_f32_16x16x32_bf16 v[18:21], v[188:191], v[220:223], v[18:21]
	v_mfma_f32_16x16x32_bf16 v[10:13], v[196:199], v[220:223], v[10:13]
	v_mfma_f32_16x16x32_bf16 v[6:9], v[188:191], v[228:231], v[6:9]
	v_mfma_f32_16x16x32_bf16 v[2:5], v[196:199], v[228:231], v[2:5]
	s_setprio 0
	s_barrier
	ds_read_b128 v[164:167], v145
	ds_read_b128 v[168:171], v145 offset:1024
	ds_read_b128 v[172:175], v145 offset:2048
	ds_read_b128 v[176:179], v145 offset:3072
	ds_read_b128 v[180:183], v147
	ds_read_b128 v[188:191], v147 offset:1024
	ds_read_b128 v[192:195], v147 offset:2048
	ds_read_b128 v[196:199], v147 offset:3072
	s_add_u32 s28, s28, 0x100000
	s_addc_u32 s29, s29, 0
	s_mov_b32 m0, s41
	ds_read_b128 v[200:203], v141 offset:32768
	ds_read_b128 v[204:207], v141 offset:33792
	ds_read_b128 v[208:211], v141 offset:34816
	ds_read_b128 v[212:215], v141 offset:35840
	ds_read_b128 v[216:219], v141 offset:36864
	ds_read_b128 v[220:223], v141 offset:37888
	ds_read_b128 v[224:227], v141 offset:38912
	ds_read_b128 v[228:231], v141 offset:39936
	global_load_lds_dwordx4 v136, s[28:29]
	s_mov_b32 m0, s42
	s_nop 0
	global_load_lds_dwordx4 v132, s[28:29]
	s_waitcnt vmcnt(8)
	s_waitcnt lgkmcnt(0)
	s_barrier
	s_setprio 1
	s_waitcnt lgkmcnt(0)
	v_mfma_f32_16x16x32_bf16 v[126:129], v[164:167], v[200:203], v[126:129]
	v_mfma_f32_16x16x32_bf16 v[122:125], v[172:175], v[200:203], v[122:125]
	v_mfma_f32_16x16x32_bf16 v[118:121], v[164:167], v[208:211], v[118:121]
	v_mfma_f32_16x16x32_bf16 v[110:113], v[172:175], v[208:211], v[110:113]
	v_mfma_f32_16x16x32_bf16 v[102:105], v[164:167], v[216:219], v[102:105]
	v_mfma_f32_16x16x32_bf16 v[94:97], v[172:175], v[216:219], v[94:97]
	v_mfma_f32_16x16x32_bf16 v[86:89], v[164:167], v[224:227], v[86:89]
	v_mfma_f32_16x16x32_bf16 v[78:81], v[172:175], v[224:227], v[78:81]
	v_mfma_f32_16x16x32_bf16 v[126:129], v[168:171], v[204:207], v[126:129]
	v_mfma_f32_16x16x32_bf16 v[122:125], v[176:179], v[204:207], v[122:125]
	v_mfma_f32_16x16x32_bf16 v[118:121], v[168:171], v[212:215], v[118:121]
	v_mfma_f32_16x16x32_bf16 v[110:113], v[176:179], v[212:215], v[110:113]
	v_mfma_f32_16x16x32_bf16 v[102:105], v[168:171], v[220:223], v[102:105]
	v_mfma_f32_16x16x32_bf16 v[94:97], v[176:179], v[220:223], v[94:97]
	v_mfma_f32_16x16x32_bf16 v[86:89], v[168:171], v[228:231], v[86:89]
	v_mfma_f32_16x16x32_bf16 v[78:81], v[176:179], v[228:231], v[78:81]
	s_setprio 0
	s_setprio 1
	v_mfma_f32_16x16x32_bf16 v[114:117], v[180:183], v[200:203], v[114:117]
	v_mfma_f32_16x16x32_bf16 v[106:109], v[192:195], v[200:203], v[106:109]
	v_mfma_f32_16x16x32_bf16 v[98:101], v[180:183], v[208:211], v[98:101]
	v_mfma_f32_16x16x32_bf16 v[90:93], v[192:195], v[208:211], v[90:93]
	v_mfma_f32_16x16x32_bf16 v[82:85], v[180:183], v[216:219], v[82:85]
	v_mfma_f32_16x16x32_bf16 v[74:77], v[192:195], v[216:219], v[74:77]
	v_mfma_f32_16x16x32_bf16 v[70:73], v[180:183], v[224:227], v[70:73]
	v_mfma_f32_16x16x32_bf16 v[66:69], v[192:195], v[224:227], v[66:69]
	v_mfma_f32_16x16x32_bf16 v[114:117], v[188:191], v[204:207], v[114:117]
	v_mfma_f32_16x16x32_bf16 v[106:109], v[196:199], v[204:207], v[106:109]
	v_mfma_f32_16x16x32_bf16 v[98:101], v[188:191], v[212:215], v[98:101]
	v_mfma_f32_16x16x32_bf16 v[90:93], v[196:199], v[212:215], v[90:93]
	v_mfma_f32_16x16x32_bf16 v[82:85], v[188:191], v[220:223], v[82:85]
	v_mfma_f32_16x16x32_bf16 v[74:77], v[196:199], v[220:223], v[74:77]
	v_mfma_f32_16x16x32_bf16 v[70:73], v[188:191], v[228:231], v[70:73]
	v_mfma_f32_16x16x32_bf16 v[66:69], v[196:199], v[228:231], v[66:69]
	s_setprio 0
	s_barrier
	s_mov_b32 m0, s67
	v_lshl_add_u64 v[184:185], v[184:185], 0, s[12:13]
	s_add_u32 s26, s26, 0x100080
	ds_read_b128 v[200:203], v141 offset:49152
	ds_read_b128 v[204:207], v141 offset:50176
	ds_read_b128 v[208:211], v141 offset:51200
	ds_read_b128 v[212:215], v141 offset:52224
	ds_read_b128 v[216:219], v141 offset:53248
	ds_read_b128 v[220:223], v141 offset:54272
	ds_read_b128 v[224:227], v141 offset:55296
	ds_read_b128 v[228:231], v141 offset:56320
	global_load_lds_dwordx4 v[184:185], off
	v_lshl_add_u64 v[184:185], v[232:233], 0, s[12:13]
	s_mov_b32 m0, s68
	s_addc_u32 s27, s27, 0
	global_load_lds_dwordx4 v[184:185], off
	s_mov_b32 m0, s69
	s_nop 0
	global_load_lds_dwordx4 v134, s[26:27]
	s_add_i32 m0, s69, 0x2000
	s_nop 0
	global_load_lds_dwordx4 v130, s[26:27]
	v_lshl_add_u64 v[184:185], v[234:235], 0, s[12:13]
	s_mov_b32 m0, s49
	s_nop 0
	global_load_lds_dwordx4 v[184:185], off
	v_lshl_add_u64 v[184:185], v[236:237], 0, s[12:13]
	s_mov_b32 m0, s56
	s_nop 0
	global_load_lds_dwordx4 v[184:185], off
	s_waitcnt vmcnt(8)
	s_waitcnt lgkmcnt(0)
	s_barrier
	s_setprio 1
	s_waitcnt lgkmcnt(0)
	v_mfma_f32_16x16x32_bf16 v[62:65], v[164:167], v[200:203], v[62:65]
	v_mfma_f32_16x16x32_bf16 v[58:61], v[172:175], v[200:203], v[58:61]
	v_mfma_f32_16x16x32_bf16 v[54:57], v[164:167], v[208:211], v[54:57]
	v_mfma_f32_16x16x32_bf16 v[46:49], v[172:175], v[208:211], v[46:49]
	v_mfma_f32_16x16x32_bf16 v[38:41], v[164:167], v[216:219], v[38:41]
	v_mfma_f32_16x16x32_bf16 v[30:33], v[172:175], v[216:219], v[30:33]
	v_mfma_f32_16x16x32_bf16 v[22:25], v[164:167], v[224:227], v[22:25]
	v_mfma_f32_16x16x32_bf16 v[14:17], v[172:175], v[224:227], v[14:17]
	v_mfma_f32_16x16x32_bf16 v[62:65], v[168:171], v[204:207], v[62:65]
	v_mfma_f32_16x16x32_bf16 v[58:61], v[176:179], v[204:207], v[58:61]
	v_mfma_f32_16x16x32_bf16 v[54:57], v[168:171], v[212:215], v[54:57]
	v_mfma_f32_16x16x32_bf16 v[46:49], v[176:179], v[212:215], v[46:49]
	v_mfma_f32_16x16x32_bf16 v[38:41], v[168:171], v[220:223], v[38:41]
	v_mfma_f32_16x16x32_bf16 v[30:33], v[176:179], v[220:223], v[30:33]
	v_mfma_f32_16x16x32_bf16 v[22:25], v[168:171], v[228:231], v[22:25]
	v_mfma_f32_16x16x32_bf16 v[14:17], v[176:179], v[228:231], v[14:17]
	s_setprio 0
	s_setprio 1
	v_mfma_f32_16x16x32_bf16 v[50:53], v[180:183], v[200:203], v[50:53]
	v_mfma_f32_16x16x32_bf16 v[42:45], v[192:195], v[200:203], v[42:45]
	v_mfma_f32_16x16x32_bf16 v[34:37], v[180:183], v[208:211], v[34:37]
	v_mfma_f32_16x16x32_bf16 v[26:29], v[192:195], v[208:211], v[26:29]
	v_mfma_f32_16x16x32_bf16 v[18:21], v[180:183], v[216:219], v[18:21]
	v_mfma_f32_16x16x32_bf16 v[10:13], v[192:195], v[216:219], v[10:13]
	v_mfma_f32_16x16x32_bf16 v[6:9], v[180:183], v[224:227], v[6:9]
	v_mfma_f32_16x16x32_bf16 v[2:5], v[192:195], v[224:227], v[2:5]
	v_mfma_f32_16x16x32_bf16 v[50:53], v[188:191], v[204:207], v[50:53]
	v_mfma_f32_16x16x32_bf16 v[42:45], v[196:199], v[204:207], v[42:45]
	v_mfma_f32_16x16x32_bf16 v[34:37], v[188:191], v[212:215], v[34:37]
	v_mfma_f32_16x16x32_bf16 v[26:29], v[196:199], v[212:215], v[26:29]
	v_mfma_f32_16x16x32_bf16 v[18:21], v[188:191], v[220:223], v[18:21]
	v_mfma_f32_16x16x32_bf16 v[10:13], v[196:199], v[220:223], v[10:13]
	v_mfma_f32_16x16x32_bf16 v[6:9], v[188:191], v[228:231], v[6:9]
	v_mfma_f32_16x16x32_bf16 v[2:5], v[196:199], v[228:231], v[2:5]
	s_setprio 0
	s_barrier
	s_add_i32 s77, s77, 2
	s_add_u32 s75, s75, 0x100
	s_addc_u32 s76, s76, 0
	s_add_u32 s24, s24, 0x100
	s_addc_u32 s25, s25, 0
	s_cmp_gt_u32 s77, 13
	s_cbranch_scc0 .LBB0_790
	s_and_b64 vcc, exec, s[18:19]
	s_cbranch_vccz .LBB0_793
	s_barrier

.LBB0_1198:
	v_add_u32_e32 v3, s61, v186
	ds_read_b128 v[134:137], v3
	ds_read_b128 v[138:141], v3 offset:1024
	ds_read_b128 v[142:145], v3 offset:2048
	ds_read_b128 v[146:149], v3 offset:3072
	v_add_u32_e32 v3, s62, v186
	s_add_u32 s30, s28, s8
	ds_read_b128 v[150:153], v3
	ds_read_b128 v[154:157], v3 offset:1024
	ds_read_b128 v[158:161], v3 offset:2048
	ds_read_b128 v[190:193], v3 offset:3072
	s_addc_u32 s31, s29, s9
	s_add_u32 s30, s30, 0x100
	s_addc_u32 s31, s31, 0
	s_add_u32 s71, s68, s8
	s_addc_u32 s72, s69, s9
	s_cmpk_eq_i32 s8, 0x1f00
	s_cselect_b32 s35, s25, s31
	s_cselect_b32 s34, s24, s30
	s_cselect_b32 s31, s65, s72
	s_cselect_b32 s30, s66, s71
	v_lshl_add_u64 v[4:5], v[182:183], 0, s[8:9]
	s_add_i32 m0, s40, 0xc000
	ds_read_b128 v[194:197], v189
	ds_read_b128 v[198:201], v189 offset:1024
	ds_read_b128 v[202:205], v189 offset:2048
	ds_read_b128 v[206:209], v189 offset:3072
	ds_read_b128 v[210:213], v189 offset:4096
	ds_read_b128 v[214:217], v189 offset:5120
	ds_read_b128 v[218:221], v189 offset:6144
	ds_read_b128 v[222:225], v189 offset:7168
	global_load_lds_dwordx4 v[4:5], off
	v_lshl_add_u64 v[4:5], v[180:181], 0, s[8:9]
	s_add_i32 m0, s40, 0xe000
	s_nop 0
	global_load_lds_dwordx4 v[4:5], off
	s_waitcnt vmcnt(8)
	s_waitcnt lgkmcnt(0)
	s_barrier
	s_setprio 1
	s_waitcnt lgkmcnt(0)
	v_mfma_f32_16x16x32_bf16 v[130:133], v[134:137], v[194:197], v[130:133]
	v_mfma_f32_16x16x32_bf16 v[126:129], v[142:145], v[194:197], v[126:129]
	v_mfma_f32_16x16x32_bf16 v[114:117], v[134:137], v[202:205], v[114:117]
	v_mfma_f32_16x16x32_bf16 v[110:113], v[142:145], v[202:205], v[110:113]
	v_mfma_f32_16x16x32_bf16 v[98:101], v[134:137], v[210:213], v[98:101]
	v_mfma_f32_16x16x32_bf16 v[94:97], v[142:145], v[210:213], v[94:97]
	v_mfma_f32_16x16x32_bf16 v[82:85], v[134:137], v[218:221], v[82:85]
	v_mfma_f32_16x16x32_bf16 v[78:81], v[142:145], v[218:221], v[78:81]
	v_mfma_f32_16x16x32_bf16 v[130:133], v[138:141], v[198:201], v[130:133]
	v_mfma_f32_16x16x32_bf16 v[126:129], v[146:149], v[198:201], v[126:129]
	v_mfma_f32_16x16x32_bf16 v[114:117], v[138:141], v[206:209], v[114:117]
	v_mfma_f32_16x16x32_bf16 v[110:113], v[146:149], v[206:209], v[110:113]
	v_mfma_f32_16x16x32_bf16 v[98:101], v[138:141], v[214:217], v[98:101]
	v_mfma_f32_16x16x32_bf16 v[94:97], v[146:149], v[214:217], v[94:97]
	v_mfma_f32_16x16x32_bf16 v[82:85], v[138:141], v[222:225], v[82:85]
	v_mfma_f32_16x16x32_bf16 v[78:81], v[146:149], v[222:225], v[78:81]
	s_setprio 0
	s_setprio 1
	v_mfma_f32_16x16x32_bf16 v[122:125], v[150:153], v[194:197], v[122:125]
	v_mfma_f32_16x16x32_bf16 v[118:121], v[158:161], v[194:197], v[118:121]
	v_mfma_f32_16x16x32_bf16 v[106:109], v[150:153], v[202:205], v[106:109]
	v_mfma_f32_16x16x32_bf16 v[102:105], v[158:161], v[202:205], v[102:105]
	v_mfma_f32_16x16x32_bf16 v[90:93], v[150:153], v[210:213], v[90:93]
	v_mfma_f32_16x16x32_bf16 v[86:89], v[158:161], v[210:213], v[86:89]
	v_mfma_f32_16x16x32_bf16 v[74:77], v[150:153], v[218:221], v[74:77]
	v_mfma_f32_16x16x32_bf16 v[70:73], v[158:161], v[218:221], v[70:73]
	v_mfma_f32_16x16x32_bf16 v[122:125], v[154:157], v[198:201], v[122:125]
	v_mfma_f32_16x16x32_bf16 v[118:121], v[190:193], v[198:201], v[118:121]
	v_mfma_f32_16x16x32_bf16 v[106:109], v[154:157], v[206:209], v[106:109]
	v_mfma_f32_16x16x32_bf16 v[102:105], v[190:193], v[206:209], v[102:105]
	v_mfma_f32_16x16x32_bf16 v[90:93], v[154:157], v[214:217], v[90:93]
	v_mfma_f32_16x16x32_bf16 v[86:89], v[190:193], v[214:217], v[86:89]
	v_mfma_f32_16x16x32_bf16 v[74:77], v[154:157], v[222:225], v[74:77]
	v_mfma_f32_16x16x32_bf16 v[70:73], v[190:193], v[222:225], v[70:73]
	s_setprio 0
	s_barrier
	s_add_i32 s71, s61, s39
	v_lshl_add_u64 v[162:163], s[30:31], 0, v[166:167]
	s_mov_b32 m0, s71
	ds_read_b128 v[194:197], v189 offset:16384
	ds_read_b128 v[198:201], v189 offset:17408
	ds_read_b128 v[202:205], v189 offset:18432
	ds_read_b128 v[206:209], v189 offset:19456
	ds_read_b128 v[210:213], v189 offset:20480
	ds_read_b128 v[214:217], v189 offset:21504
	ds_read_b128 v[218:221], v189 offset:22528
	ds_read_b128 v[222:225], v189 offset:23552
	global_load_lds_dwordx4 v[162:163], off
	s_add_i32 m0, s71, 0x2000
	s_add_u32 s72, s30, 0x100000
	v_lshl_add_u64 v[184:185], s[30:31], 0, v[170:171]
	s_addc_u32 s73, s31, 0
	s_add_i32 s71, s62, s39
	global_load_lds_dwordx4 v[184:185], off
	s_mov_b32 m0, s71
	v_lshl_add_u64 v[226:227], s[34:35], 0, v[164:165]
	global_load_lds_dwordx4 v166, s[72:73]
	s_add_i32 m0, s71, 0x2000
	v_lshl_add_u64 v[228:229], s[34:35], 0, v[168:169]
	global_load_lds_dwordx4 v170, s[72:73]
	s_mov_b32 m0, s40
	s_nop 0
	global_load_lds_dwordx4 v[226:227], off
	s_mov_b32 m0, s41
	s_nop 0
	global_load_lds_dwordx4 v[228:229], off
	s_waitcnt vmcnt(8)
	s_waitcnt lgkmcnt(0)
	s_barrier
	s_setprio 1
	s_waitcnt lgkmcnt(0)
	v_mfma_f32_16x16x32_bf16 v[66:69], v[134:137], v[194:197], v[66:69]
	v_mfma_f32_16x16x32_bf16 v[62:65], v[142:145], v[194:197], v[62:65]
	v_mfma_f32_16x16x32_bf16 v[50:53], v[134:137], v[202:205], v[50:53]
	v_mfma_f32_16x16x32_bf16 v[46:49], v[142:145], v[202:205], v[46:49]
	v_mfma_f32_16x16x32_bf16 v[34:37], v[134:137], v[210:213], v[34:37]
	v_mfma_f32_16x16x32_bf16 v[30:33], v[142:145], v[210:213], v[30:33]
	v_mfma_f32_16x16x32_bf16 v[18:21], v[134:137], v[218:221], v[18:21]
	v_mfma_f32_16x16x32_bf16 v[14:17], v[142:145], v[218:221], v[14:17]
	v_mfma_f32_16x16x32_bf16 v[66:69], v[138:141], v[198:201], v[66:69]
	v_mfma_f32_16x16x32_bf16 v[62:65], v[146:149], v[198:201], v[62:65]
	v_mfma_f32_16x16x32_bf16 v[50:53], v[138:141], v[206:209], v[50:53]
	v_mfma_f32_16x16x32_bf16 v[46:49], v[146:149], v[206:209], v[46:49]
	v_mfma_f32_16x16x32_bf16 v[34:37], v[138:141], v[214:217], v[34:37]
	v_mfma_f32_16x16x32_bf16 v[30:33], v[146:149], v[214:217], v[30:33]
	v_mfma_f32_16x16x32_bf16 v[18:21], v[138:141], v[222:225], v[18:21]
	v_mfma_f32_16x16x32_bf16 v[14:17], v[146:149], v[222:225], v[14:17]
	s_setprio 0
	s_setprio 1
	v_mfma_f32_16x16x32_bf16 v[58:61], v[150:153], v[194:197], v[58:61]
	v_mfma_f32_16x16x32_bf16 v[54:57], v[158:161], v[194:197], v[54:57]
	v_mfma_f32_16x16x32_bf16 v[42:45], v[150:153], v[202:205], v[42:45]
	v_mfma_f32_16x16x32_bf16 v[38:41], v[158:161], v[202:205], v[38:41]
	v_mfma_f32_16x16x32_bf16 v[26:29], v[150:153], v[210:213], v[26:29]
	v_mfma_f32_16x16x32_bf16 v[22:25], v[158:161], v[210:213], v[22:25]
	v_mfma_f32_16x16x32_bf16 v[10:13], v[150:153], v[218:221], v[10:13]
	v_mfma_f32_16x16x32_bf16 v[4:7], v[158:161], v[218:221], v[6:9]
	v_mfma_f32_16x16x32_bf16 v[58:61], v[154:157], v[198:201], v[58:61]
	v_mfma_f32_16x16x32_bf16 v[54:57], v[190:193], v[198:201], v[54:57]
	v_mfma_f32_16x16x32_bf16 v[42:45], v[154:157], v[206:209], v[42:45]
	v_mfma_f32_16x16x32_bf16 v[38:41], v[190:193], v[206:209], v[38:41]
	v_mfma_f32_16x16x32_bf16 v[26:29], v[154:157], v[214:217], v[26:29]
	v_mfma_f32_16x16x32_bf16 v[22:25], v[190:193], v[214:217], v[22:25]
	v_mfma_f32_16x16x32_bf16 v[10:13], v[154:157], v[222:225], v[10:13]
	v_mfma_f32_16x16x32_bf16 v[4:7], v[190:193], v[222:225], v[4:7]
	s_setprio 0
	s_barrier
	s_add_i32 s71, 0, 0x18000
	v_add_u32_e32 v3, s71, v186
	s_add_i32 s72, 0, 0x1c000
	ds_read_b128 v[134:137], v3
	ds_read_b128 v[138:141], v3 offset:1024
	ds_read_b128 v[142:145], v3 offset:2048
	ds_read_b128 v[146:149], v3 offset:3072
	v_add_u32_e32 v3, s72, v186
	ds_read_b128 v[150:153], v3
	ds_read_b128 v[154:157], v3 offset:1024
	ds_read_b128 v[158:161], v3 offset:2048
	ds_read_b128 v[190:193], v3 offset:3072
	s_add_u32 s34, s34, 0x480000
	s_addc_u32 s35, s35, 0
	s_mov_b32 m0, s42
	ds_read_b128 v[194:197], v189 offset:32768
	ds_read_b128 v[198:201], v189 offset:33792
	ds_read_b128 v[202:205], v189 offset:34816
	ds_read_b128 v[206:209], v189 offset:35840
	ds_read_b128 v[210:213], v189 offset:36864
	ds_read_b128 v[214:217], v189 offset:37888
	ds_read_b128 v[218:221], v189 offset:38912
	ds_read_b128 v[222:225], v189 offset:39936
	global_load_lds_dwordx4 v164, s[34:35]
	s_mov_b32 m0, s43
	s_nop 0
	global_load_lds_dwordx4 v168, s[34:35]
	s_waitcnt vmcnt(8)
	s_waitcnt lgkmcnt(0)
	s_barrier
	s_setprio 1
	s_waitcnt lgkmcnt(0)
	v_mfma_f32_16x16x32_bf16 v[130:133], v[134:137], v[194:197], v[130:133]
	v_mfma_f32_16x16x32_bf16 v[126:129], v[142:145], v[194:197], v[126:129]
	v_mfma_f32_16x16x32_bf16 v[114:117], v[134:137], v[202:205], v[114:117]
	v_mfma_f32_16x16x32_bf16 v[110:113], v[142:145], v[202:205], v[110:113]
	v_mfma_f32_16x16x32_bf16 v[98:101], v[134:137], v[210:213], v[98:101]
	v_mfma_f32_16x16x32_bf16 v[94:97], v[142:145], v[210:213], v[94:97]
	v_mfma_f32_16x16x32_bf16 v[82:85], v[134:137], v[218:221], v[82:85]
	v_mfma_f32_16x16x32_bf16 v[78:81], v[142:145], v[218:221], v[78:81]
	v_mfma_f32_16x16x32_bf16 v[130:133], v[138:141], v[198:201], v[130:133]
	v_mfma_f32_16x16x32_bf16 v[126:129], v[146:149], v[198:201], v[126:129]
	v_mfma_f32_16x16x32_bf16 v[114:117], v[138:141], v[206:209], v[114:117]
	v_mfma_f32_16x16x32_bf16 v[110:113], v[146:149], v[206:209], v[110:113]
	v_mfma_f32_16x16x32_bf16 v[98:101], v[138:141], v[214:217], v[98:101]
	v_mfma_f32_16x16x32_bf16 v[94:97], v[146:149], v[214:217], v[94:97]
	v_mfma_f32_16x16x32_bf16 v[82:85], v[138:141], v[222:225], v[82:85]
	v_mfma_f32_16x16x32_bf16 v[78:81], v[146:149], v[222:225], v[78:81]
	s_setprio 0
	s_setprio 1
	v_mfma_f32_16x16x32_bf16 v[122:125], v[150:153], v[194:197], v[122:125]
	v_mfma_f32_16x16x32_bf16 v[118:121], v[158:161], v[194:197], v[118:121]
	v_mfma_f32_16x16x32_bf16 v[106:109], v[150:153], v[202:205], v[106:109]
	v_mfma_f32_16x16x32_bf16 v[102:105], v[158:161], v[202:205], v[102:105]
	v_mfma_f32_16x16x32_bf16 v[90:93], v[150:153], v[210:213], v[90:93]
	v_mfma_f32_16x16x32_bf16 v[86:89], v[158:161], v[210:213], v[86:89]
	v_mfma_f32_16x16x32_bf16 v[74:77], v[150:153], v[218:221], v[74:77]
	v_mfma_f32_16x16x32_bf16 v[70:73], v[158:161], v[218:221], v[70:73]
	v_mfma_f32_16x16x32_bf16 v[122:125], v[154:157], v[198:201], v[122:125]
	v_mfma_f32_16x16x32_bf16 v[118:121], v[190:193], v[198:201], v[118:121]
	v_mfma_f32_16x16x32_bf16 v[106:109], v[154:157], v[206:209], v[106:109]
	v_mfma_f32_16x16x32_bf16 v[102:105], v[190:193], v[206:209], v[102:105]
	v_mfma_f32_16x16x32_bf16 v[90:93], v[154:157], v[214:217], v[90:93]
	v_mfma_f32_16x16x32_bf16 v[86:89], v[190:193], v[214:217], v[86:89]
	v_mfma_f32_16x16x32_bf16 v[74:77], v[154:157], v[222:225], v[74:77]
	v_mfma_f32_16x16x32_bf16 v[70:73], v[190:193], v[222:225], v[70:73]
	s_setprio 0
	s_barrier
	s_add_i32 s34, s71, s39
	v_lshl_add_u64 v[8:9], v[162:163], 0, s[18:19]
	s_mov_b32 m0, s34
	ds_read_b128 v[194:197], v189 offset:49152
	ds_read_b128 v[198:201], v189 offset:50176
	ds_read_b128 v[202:205], v189 offset:51200
	ds_read_b128 v[206:209], v189 offset:52224
	ds_read_b128 v[210:213], v189 offset:53248
	ds_read_b128 v[214:217], v189 offset:54272
	ds_read_b128 v[218:221], v189 offset:55296
	ds_read_b128 v[222:225], v189 offset:56320
	global_load_lds_dwordx4 v[8:9], off
	s_add_i32 m0, s34, 0x2000
	s_add_u32 s30, s30, 0x100080
	v_lshl_add_u64 v[8:9], v[184:185], 0, s[18:19]
	s_addc_u32 s31, s31, 0
	s_add_i32 s34, s72, s39
	global_load_lds_dwordx4 v[8:9], off
	s_mov_b32 m0, s34
	s_nop 0
	global_load_lds_dwordx4 v166, s[30:31]
	s_add_i32 m0, s34, 0x2000
	s_nop 0
	global_load_lds_dwordx4 v170, s[30:31]
	v_lshl_add_u64 v[8:9], v[226:227], 0, s[18:19]
	s_mov_b32 m0, s47
	s_nop 0
	global_load_lds_dwordx4 v[8:9], off
	v_lshl_add_u64 v[8:9], v[228:229], 0, s[18:19]
	s_mov_b32 m0, s49
	s_nop 0
	global_load_lds_dwordx4 v[8:9], off
	s_waitcnt vmcnt(8)
	s_waitcnt lgkmcnt(0)
	s_barrier
	s_setprio 1
	s_waitcnt lgkmcnt(0)
	v_mfma_f32_16x16x32_bf16 v[66:69], v[134:137], v[194:197], v[66:69]
	v_mfma_f32_16x16x32_bf16 v[62:65], v[142:145], v[194:197], v[62:65]
	v_mfma_f32_16x16x32_bf16 v[50:53], v[134:137], v[202:205], v[50:53]
	v_mfma_f32_16x16x32_bf16 v[46:49], v[142:145], v[202:205], v[46:49]
	v_mfma_f32_16x16x32_bf16 v[34:37], v[134:137], v[210:213], v[34:37]
	v_mfma_f32_16x16x32_bf16 v[30:33], v[142:145], v[210:213], v[30:33]
	v_mfma_f32_16x16x32_bf16 v[18:21], v[134:137], v[218:221], v[18:21]
	v_mfma_f32_16x16x32_bf16 v[14:17], v[142:145], v[218:221], v[14:17]
	v_mfma_f32_16x16x32_bf16 v[66:69], v[138:141], v[198:201], v[66:69]
	v_mfma_f32_16x16x32_bf16 v[62:65], v[146:149], v[198:201], v[62:65]
	v_mfma_f32_16x16x32_bf16 v[50:53], v[138:141], v[206:209], v[50:53]
	v_mfma_f32_16x16x32_bf16 v[46:49], v[146:149], v[206:209], v[46:49]
	v_mfma_f32_16x16x32_bf16 v[34:37], v[138:141], v[214:217], v[34:37]
	v_mfma_f32_16x16x32_bf16 v[30:33], v[146:149], v[214:217], v[30:33]
	v_mfma_f32_16x16x32_bf16 v[18:21], v[138:141], v[222:225], v[18:21]
	v_mfma_f32_16x16x32_bf16 v[14:17], v[146:149], v[222:225], v[14:17]
	s_setprio 0
	s_setprio 1
	v_mfma_f32_16x16x32_bf16 v[58:61], v[150:153], v[194:197], v[58:61]
	v_mfma_f32_16x16x32_bf16 v[54:57], v[158:161], v[194:197], v[54:57]
	v_mfma_f32_16x16x32_bf16 v[42:45], v[150:153], v[202:205], v[42:45]
	v_mfma_f32_16x16x32_bf16 v[38:41], v[158:161], v[202:205], v[38:41]
	v_mfma_f32_16x16x32_bf16 v[26:29], v[150:153], v[210:213], v[26:29]
	v_mfma_f32_16x16x32_bf16 v[22:25], v[158:161], v[210:213], v[22:25]
	v_mfma_f32_16x16x32_bf16 v[8:11], v[150:153], v[218:221], v[10:13]
	v_mfma_f32_16x16x32_bf16 v[4:7], v[158:161], v[218:221], v[4:7]
	v_mfma_f32_16x16x32_bf16 v[58:61], v[154:157], v[198:201], v[58:61]
	v_mfma_f32_16x16x32_bf16 v[54:57], v[190:193], v[198:201], v[54:57]
	v_mfma_f32_16x16x32_bf16 v[42:45], v[154:157], v[206:209], v[42:45]
	v_mfma_f32_16x16x32_bf16 v[38:41], v[190:193], v[206:209], v[38:41]
	v_mfma_f32_16x16x32_bf16 v[26:29], v[154:157], v[214:217], v[26:29]
	v_mfma_f32_16x16x32_bf16 v[22:25], v[190:193], v[214:217], v[22:25]
	v_mfma_f32_16x16x32_bf16 v[10:13], v[154:157], v[222:225], v[8:11]
	v_mfma_f32_16x16x32_bf16 v[6:9], v[190:193], v[222:225], v[4:7]
	s_setprio 0
	s_barrier
	s_add_i32 s70, s70, 2
	s_add_u32 s8, s8, 0x100
	s_addc_u32 s9, s9, 0
	s_cmp_gt_u32 s70, 61
	s_cbranch_scc1 .LBB0_1201
.LBB0_1199:
	s_cmpk_lg_i32 s8, 0x1000
	s_cbranch_scc1 .LBB0_1198
	v_and_b32_e32 v245, 15, v187
	v_or_b32_e32 v245, s45, v245
	v_add_u32_e32 v245, s23, v245
	v_lshrrev_b32_e32 v246, 4, v187
	v_lshlrev_b32_e32 v246, 3, v246
	v_add_u32_e32 v246, s67, v246
	v_mul_u32_u24_e32 v245, 0x9000, v245
	v_lshl_add_u32 v245, v246, 1, v245
	s_add_u32 vcc_lo, s12, 0x5000
	s_addc_u32 vcc_hi, s13, 0
	global_load_dwordx4 v[134:137], v245, vcc
	global_load_dwordx4 v[138:141], v245, vcc offset:256
	s_add_u32 vcc_lo, s12, 0x7000
	s_addc_u32 vcc_hi, s13, 0
	global_load_dwordx4 v[142:145], v245, vcc
	global_load_dwordx4 v[146:149], v245, vcc offset:256
	s_add_u32 vcc_lo, s12, 0x95000
	s_addc_u32 vcc_hi, s13, 0
	global_load_dwordx4 v[150:153], v245, vcc
	global_load_dwordx4 v[154:157], v245, vcc offset:256
	s_add_u32 vcc_lo, s12, 0x97000
	s_addc_u32 vcc_hi, s13, 0
	global_load_dwordx4 v[158:161], v245, vcc
	global_load_dwordx4 v[190:193], v245, vcc offset:256
	s_add_u32 vcc_lo, s12, 0x125000
	s_addc_u32 vcc_hi, s13, 0
	global_load_dwordx4 v[194:197], v245, vcc
	global_load_dwordx4 v[198:201], v245, vcc offset:256
	s_add_u32 vcc_lo, s12, 0x127000
	s_addc_u32 vcc_hi, s13, 0
	global_load_dwordx4 v[202:205], v245, vcc
	global_load_dwordx4 v[206:209], v245, vcc offset:256
	s_add_u32 vcc_lo, s12, 0x1b5000
	s_addc_u32 vcc_hi, s13, 0
	global_load_dwordx4 v[210:213], v245, vcc
	global_load_dwordx4 v[214:217], v245, vcc offset:256
	s_add_u32 vcc_lo, s12, 0x1b7000
	s_addc_u32 vcc_hi, s13, 0
	global_load_dwordx4 v[218:221], v245, vcc
	global_load_dwordx4 v[222:225], v245, vcc offset:256
	s_waitcnt vmcnt(13)
	v_lshlrev_b32_e32 v246, 16, v142
	v_and_b32_e32 v247, 0xffff0000, v142
	v_max_f32_e32 v246, 0xda24260, v246
	v_max_f32_e32 v247, 0xda24260, v247
	v_rcp_f32_e32 v246, v246
	v_rcp_f32_e32 v247, v247
	v_lshlrev_b32_e32 v142, 16, v134
	v_and_b32_e32 v134, 0xffff0000, v134
	v_mul_f32_e32 v246, v246, v142
	v_mul_f32_e32 v247, v247, v134
	v_pk_mul_f32 v[130:131], v[130:131], v[246:247]
	v_lshlrev_b32_e32 v246, 16, v143
	v_and_b32_e32 v247, 0xffff0000, v143
	v_max_f32_e32 v246, 0xda24260, v246
	v_max_f32_e32 v247, 0xda24260, v247
	v_rcp_f32_e32 v246, v246
	v_rcp_f32_e32 v247, v247
	v_lshlrev_b32_e32 v143, 16, v135
	v_and_b32_e32 v135, 0xffff0000, v135
	v_mul_f32_e32 v246, v246, v143
	v_mul_f32_e32 v247, v247, v135
	v_pk_mul_f32 v[132:133], v[132:133], v[246:247]
	v_lshlrev_b32_e32 v246, 16, v144
	v_and_b32_e32 v247, 0xffff0000, v144
	v_max_f32_e32 v246, 0xda24260, v246
	v_max_f32_e32 v247, 0xda24260, v247
	v_rcp_f32_e32 v246, v246
	v_rcp_f32_e32 v247, v247
	v_lshlrev_b32_e32 v144, 16, v136
	v_and_b32_e32 v136, 0xffff0000, v136
	v_mul_f32_e32 v246, v246, v144
	v_mul_f32_e32 v247, v247, v136
	v_pk_mul_f32 v[126:127], v[126:127], v[246:247]
	v_lshlrev_b32_e32 v246, 16, v145
	v_and_b32_e32 v247, 0xffff0000, v145
	v_max_f32_e32 v246, 0xda24260, v246
	v_max_f32_e32 v247, 0xda24260, v247
	v_rcp_f32_e32 v246, v246
	v_rcp_f32_e32 v247, v247
	v_lshlrev_b32_e32 v145, 16, v137
	v_and_b32_e32 v137, 0xffff0000, v137
	v_mul_f32_e32 v246, v246, v145
	v_mul_f32_e32 v247, v247, v137
	v_pk_mul_f32 v[128:129], v[128:129], v[246:247]
	s_waitcnt vmcnt(12)
	v_lshlrev_b32_e32 v246, 16, v146
	v_and_b32_e32 v247, 0xffff0000, v146
	v_max_f32_e32 v246, 0xda24260, v246
	v_max_f32_e32 v247, 0xda24260, v247
	v_rcp_f32_e32 v246, v246
	v_rcp_f32_e32 v247, v247
	v_lshlrev_b32_e32 v146, 16, v138
	v_and_b32_e32 v138, 0xffff0000, v138
	v_mul_f32_e32 v246, v246, v146
	v_mul_f32_e32 v247, v247, v138
	v_pk_mul_f32 v[122:123], v[122:123], v[246:247]
	v_lshlrev_b32_e32 v246, 16, v147
	v_and_b32_e32 v247, 0xffff0000, v147
	v_max_f32_e32 v246, 0xda24260, v246
	v_max_f32_e32 v247, 0xda24260, v247
	v_rcp_f32_e32 v246, v246
	v_rcp_f32_e32 v247, v247
	v_lshlrev_b32_e32 v147, 16, v139
	v_and_b32_e32 v139, 0xffff0000, v139
	v_mul_f32_e32 v246, v246, v147
	v_mul_f32_e32 v247, v247, v139
	v_pk_mul_f32 v[124:125], v[124:125], v[246:247]
	v_lshlrev_b32_e32 v246, 16, v148
	v_and_b32_e32 v247, 0xffff0000, v148
	v_max_f32_e32 v246, 0xda24260, v246
	v_max_f32_e32 v247, 0xda24260, v247
	v_rcp_f32_e32 v246, v246
	v_rcp_f32_e32 v247, v247
	v_lshlrev_b32_e32 v148, 16, v140
	v_and_b32_e32 v140, 0xffff0000, v140
	v_mul_f32_e32 v246, v246, v148
	v_mul_f32_e32 v247, v247, v140
	v_pk_mul_f32 v[118:119], v[118:119], v[246:247]
	v_lshlrev_b32_e32 v246, 16, v149
	v_and_b32_e32 v247, 0xffff0000, v149
	v_max_f32_e32 v246, 0xda24260, v246
	v_max_f32_e32 v247, 0xda24260, v247
	v_rcp_f32_e32 v246, v246
	v_rcp_f32_e32 v247, v247
	v_lshlrev_b32_e32 v149, 16, v141
	v_and_b32_e32 v141, 0xffff0000, v141
	v_mul_f32_e32 v246, v246, v149
	v_mul_f32_e32 v247, v247, v141
	v_pk_mul_f32 v[120:121], v[120:121], v[246:247]
	s_add_u32 vcc_lo, s12, 0x485000
	s_addc_u32 vcc_hi, s13, 0
	global_load_dwordx4 v[134:137], v245, vcc
	global_load_dwordx4 v[138:141], v245, vcc offset:256
	s_add_u32 vcc_lo, s12, 0x487000
	s_addc_u32 vcc_hi, s13, 0
	global_load_dwordx4 v[142:145], v245, vcc
	global_load_dwordx4 v[146:149], v245, vcc offset:256
	s_waitcnt vmcnt(13)
	v_lshlrev_b32_e32 v246, 16, v158
	v_and_b32_e32 v247, 0xffff0000, v158
	v_max_f32_e32 v246, 0xda24260, v246
	v_max_f32_e32 v247, 0xda24260, v247
	v_rcp_f32_e32 v246, v246
	v_rcp_f32_e32 v247, v247
	v_lshlrev_b32_e32 v158, 16, v150
	v_and_b32_e32 v150, 0xffff0000, v150
	v_mul_f32_e32 v246, v246, v158
	v_mul_f32_e32 v247, v247, v150
	v_pk_mul_f32 v[114:115], v[114:115], v[246:247]
	v_lshlrev_b32_e32 v246, 16, v159
	v_and_b32_e32 v247, 0xffff0000, v159
	v_max_f32_e32 v246, 0xda24260, v246
	v_max_f32_e32 v247, 0xda24260, v247
	v_rcp_f32_e32 v246, v246
	v_rcp_f32_e32 v247, v247
	v_lshlrev_b32_e32 v159, 16, v151
	v_and_b32_e32 v151, 0xffff0000, v151
	v_mul_f32_e32 v246, v246, v159
	v_mul_f32_e32 v247, v247, v151
	v_pk_mul_f32 v[116:117], v[116:117], v[246:247]
	v_lshlrev_b32_e32 v246, 16, v160
	v_and_b32_e32 v247, 0xffff0000, v160
	v_max_f32_e32 v246, 0xda24260, v246
	v_max_f32_e32 v247, 0xda24260, v247
	v_rcp_f32_e32 v246, v246
	v_rcp_f32_e32 v247, v247
	v_lshlrev_b32_e32 v160, 16, v152
	v_and_b32_e32 v152, 0xffff0000, v152
	v_mul_f32_e32 v246, v246, v160
	v_mul_f32_e32 v247, v247, v152
	v_pk_mul_f32 v[110:111], v[110:111], v[246:247]
	v_lshlrev_b32_e32 v246, 16, v161
	v_and_b32_e32 v247, 0xffff0000, v161
	v_max_f32_e32 v246, 0xda24260, v246
	v_max_f32_e32 v247, 0xda24260, v247
	v_rcp_f32_e32 v246, v246
	v_rcp_f32_e32 v247, v247
	v_lshlrev_b32_e32 v161, 16, v153
	v_and_b32_e32 v153, 0xffff0000, v153
	v_mul_f32_e32 v246, v246, v161
	v_mul_f32_e32 v247, v247, v153
	v_pk_mul_f32 v[112:113], v[112:113], v[246:247]
	s_waitcnt vmcnt(12)
	v_lshlrev_b32_e32 v246, 16, v190
	v_and_b32_e32 v247, 0xffff0000, v190
	v_max_f32_e32 v246, 0xda24260, v246
	v_max_f32_e32 v247, 0xda24260, v247
	v_rcp_f32_e32 v246, v246
	v_rcp_f32_e32 v247, v247
	v_lshlrev_b32_e32 v190, 16, v154
	v_and_b32_e32 v154, 0xffff0000, v154
	v_mul_f32_e32 v246, v246, v190
	v_mul_f32_e32 v247, v247, v154
	v_pk_mul_f32 v[106:107], v[106:107], v[246:247]
	v_lshlrev_b32_e32 v246, 16, v191
	v_and_b32_e32 v247, 0xffff0000, v191
	v_max_f32_e32 v246, 0xda24260, v246
	v_max_f32_e32 v247, 0xda24260, v247
	v_rcp_f32_e32 v246, v246
	v_rcp_f32_e32 v247, v247
	v_lshlrev_b32_e32 v191, 16, v155
	v_and_b32_e32 v155, 0xffff0000, v155
	v_mul_f32_e32 v246, v246, v191
	v_mul_f32_e32 v247, v247, v155
	v_pk_mul_f32 v[108:109], v[108:109], v[246:247]
	v_lshlrev_b32_e32 v246, 16, v192
	v_and_b32_e32 v247, 0xffff0000, v192
	v_max_f32_e32 v246, 0xda24260, v246
	v_max_f32_e32 v247, 0xda24260, v247
	v_rcp_f32_e32 v246, v246
	v_rcp_f32_e32 v247, v247
	v_lshlrev_b32_e32 v192, 16, v156
	v_and_b32_e32 v156, 0xffff0000, v156
	v_mul_f32_e32 v246, v246, v192
	v_mul_f32_e32 v247, v247, v156
	v_pk_mul_f32 v[102:103], v[102:103], v[246:247]
	v_lshlrev_b32_e32 v246, 16, v193
	v_and_b32_e32 v247, 0xffff0000, v193
	v_max_f32_e32 v246, 0xda24260, v246
	v_max_f32_e32 v247, 0xda24260, v247
	v_rcp_f32_e32 v246, v246
	v_rcp_f32_e32 v247, v247
	v_lshlrev_b32_e32 v193, 16, v157
	v_and_b32_e32 v157, 0xffff0000, v157
	v_mul_f32_e32 v246, v246, v193
	v_mul_f32_e32 v247, v247, v157
	v_pk_mul_f32 v[104:105], v[104:105], v[246:247]
	s_add_u32 vcc_lo, s12, 0x515000
	s_addc_u32 vcc_hi, s13, 0
	global_load_dwordx4 v[150:153], v245, vcc
	global_load_dwordx4 v[154:157], v245, vcc offset:256
	s_add_u32 vcc_lo, s12, 0x517000
	s_addc_u32 vcc_hi, s13, 0
	global_load_dwordx4 v[158:161], v245, vcc
	global_load_dwordx4 v[190:193], v245, vcc offset:256
	s_waitcnt vmcnt(13)
	v_lshlrev_b32_e32 v246, 16, v202
	v_and_b32_e32 v247, 0xffff0000, v202
	v_max_f32_e32 v246, 0xda24260, v246
	v_max_f32_e32 v247, 0xda24260, v247
	v_rcp_f32_e32 v246, v246
	v_rcp_f32_e32 v247, v247
	v_lshlrev_b32_e32 v202, 16, v194
	v_and_b32_e32 v194, 0xffff0000, v194
	v_mul_f32_e32 v246, v246, v202
	v_mul_f32_e32 v247, v247, v194
	v_pk_mul_f32 v[98:99], v[98:99], v[246:247]
	v_lshlrev_b32_e32 v246, 16, v203
	v_and_b32_e32 v247, 0xffff0000, v203
	v_max_f32_e32 v246, 0xda24260, v246
	v_max_f32_e32 v247, 0xda24260, v247
	v_rcp_f32_e32 v246, v246
	v_rcp_f32_e32 v247, v247
	v_lshlrev_b32_e32 v203, 16, v195
	v_and_b32_e32 v195, 0xffff0000, v195
	v_mul_f32_e32 v246, v246, v203
	v_mul_f32_e32 v247, v247, v195
	v_pk_mul_f32 v[100:101], v[100:101], v[246:247]
	v_lshlrev_b32_e32 v246, 16, v204
	v_and_b32_e32 v247, 0xffff0000, v204
	v_max_f32_e32 v246, 0xda24260, v246
	v_max_f32_e32 v247, 0xda24260, v247
	v_rcp_f32_e32 v246, v246
	v_rcp_f32_e32 v247, v247
	v_lshlrev_b32_e32 v204, 16, v196
	v_and_b32_e32 v196, 0xffff0000, v196
	v_mul_f32_e32 v246, v246, v204
	v_mul_f32_e32 v247, v247, v196
	v_pk_mul_f32 v[94:95], v[94:95], v[246:247]
	v_lshlrev_b32_e32 v246, 16, v205
	v_and_b32_e32 v247, 0xffff0000, v205
	v_max_f32_e32 v246, 0xda24260, v246
	v_max_f32_e32 v247, 0xda24260, v247
	v_rcp_f32_e32 v246, v246
	v_rcp_f32_e32 v247, v247
	v_lshlrev_b32_e32 v205, 16, v197
	v_and_b32_e32 v197, 0xffff0000, v197
	v_mul_f32_e32 v246, v246, v205
	v_mul_f32_e32 v247, v247, v197
	v_pk_mul_f32 v[96:97], v[96:97], v[246:247]
	s_waitcnt vmcnt(12)
	v_lshlrev_b32_e32 v246, 16, v206
	v_and_b32_e32 v247, 0xffff0000, v206
	v_max_f32_e32 v246, 0xda24260, v246
	v_max_f32_e32 v247, 0xda24260, v247
	v_rcp_f32_e32 v246, v246
	v_rcp_f32_e32 v247, v247
	v_lshlrev_b32_e32 v206, 16, v198
	v_and_b32_e32 v198, 0xffff0000, v198
	v_mul_f32_e32 v246, v246, v206
	v_mul_f32_e32 v247, v247, v198
	v_pk_mul_f32 v[90:91], v[90:91], v[246:247]
	v_lshlrev_b32_e32 v246, 16, v207
	v_and_b32_e32 v247, 0xffff0000, v207
	v_max_f32_e32 v246, 0xda24260, v246
	v_max_f32_e32 v247, 0xda24260, v247
	v_rcp_f32_e32 v246, v246
	v_rcp_f32_e32 v247, v247
	v_lshlrev_b32_e32 v207, 16, v199
	v_and_b32_e32 v199, 0xffff0000, v199
	v_mul_f32_e32 v246, v246, v207
	v_mul_f32_e32 v247, v247, v199
	v_pk_mul_f32 v[92:93], v[92:93], v[246:247]
	v_lshlrev_b32_e32 v246, 16, v208
	v_and_b32_e32 v247, 0xffff0000, v208
	v_max_f32_e32 v246, 0xda24260, v246
	v_max_f32_e32 v247, 0xda24260, v247
	v_rcp_f32_e32 v246, v246
	v_rcp_f32_e32 v247, v247
	v_lshlrev_b32_e32 v208, 16, v200
	v_and_b32_e32 v200, 0xffff0000, v200
	v_mul_f32_e32 v246, v246, v208
	v_mul_f32_e32 v247, v247, v200
	v_pk_mul_f32 v[86:87], v[86:87], v[246:247]
	v_lshlrev_b32_e32 v246, 16, v209
	v_and_b32_e32 v247, 0xffff0000, v209
	v_max_f32_e32 v246, 0xda24260, v246
	v_max_f32_e32 v247, 0xda24260, v247
	v_rcp_f32_e32 v246, v246
	v_rcp_f32_e32 v247, v247
	v_lshlrev_b32_e32 v209, 16, v201
	v_and_b32_e32 v201, 0xffff0000, v201
	v_mul_f32_e32 v246, v246, v209
	v_mul_f32_e32 v247, v247, v201
	v_pk_mul_f32 v[88:89], v[88:89], v[246:247]
	s_add_u32 vcc_lo, s12, 0x5a5000
	s_addc_u32 vcc_hi, s13, 0
	global_load_dwordx4 v[194:197], v245, vcc
	global_load_dwordx4 v[198:201], v245, vcc offset:256
	s_add_u32 vcc_lo, s12, 0x5a7000
	s_addc_u32 vcc_hi, s13, 0
	global_load_dwordx4 v[202:205], v245, vcc
	global_load_dwordx4 v[206:209], v245, vcc offset:256
	s_waitcnt vmcnt(13)
	v_lshlrev_b32_e32 v246, 16, v218
	v_and_b32_e32 v247, 0xffff0000, v218
	v_max_f32_e32 v246, 0xda24260, v246
	v_max_f32_e32 v247, 0xda24260, v247
	v_rcp_f32_e32 v246, v246
	v_rcp_f32_e32 v247, v247
	v_lshlrev_b32_e32 v218, 16, v210
	v_and_b32_e32 v210, 0xffff0000, v210
	v_mul_f32_e32 v246, v246, v218
	v_mul_f32_e32 v247, v247, v210
	v_pk_mul_f32 v[82:83], v[82:83], v[246:247]
	v_lshlrev_b32_e32 v246, 16, v219
	v_and_b32_e32 v247, 0xffff0000, v219
	v_max_f32_e32 v246, 0xda24260, v246
	v_max_f32_e32 v247, 0xda24260, v247
	v_rcp_f32_e32 v246, v246
	v_rcp_f32_e32 v247, v247
	v_lshlrev_b32_e32 v219, 16, v211
	v_and_b32_e32 v211, 0xffff0000, v211
	v_mul_f32_e32 v246, v246, v219
	v_mul_f32_e32 v247, v247, v211
	v_pk_mul_f32 v[84:85], v[84:85], v[246:247]
	v_lshlrev_b32_e32 v246, 16, v220
	v_and_b32_e32 v247, 0xffff0000, v220
	v_max_f32_e32 v246, 0xda24260, v246
	v_max_f32_e32 v247, 0xda24260, v247
	v_rcp_f32_e32 v246, v246
	v_rcp_f32_e32 v247, v247
	v_lshlrev_b32_e32 v220, 16, v212
	v_and_b32_e32 v212, 0xffff0000, v212
	v_mul_f32_e32 v246, v246, v220
	v_mul_f32_e32 v247, v247, v212
	v_pk_mul_f32 v[78:79], v[78:79], v[246:247]
	v_lshlrev_b32_e32 v246, 16, v221
	v_and_b32_e32 v247, 0xffff0000, v221
	v_max_f32_e32 v246, 0xda24260, v246
	v_max_f32_e32 v247, 0xda24260, v247
	v_rcp_f32_e32 v246, v246
	v_rcp_f32_e32 v247, v247
	v_lshlrev_b32_e32 v221, 16, v213
	v_and_b32_e32 v213, 0xffff0000, v213
	v_mul_f32_e32 v246, v246, v221
	v_mul_f32_e32 v247, v247, v213
	v_pk_mul_f32 v[80:81], v[80:81], v[246:247]
	s_waitcnt vmcnt(12)
	v_lshlrev_b32_e32 v246, 16, v222
	v_and_b32_e32 v247, 0xffff0000, v222
	v_max_f32_e32 v246, 0xda24260, v246
	v_max_f32_e32 v247, 0xda24260, v247
	v_rcp_f32_e32 v246, v246
	v_rcp_f32_e32 v247, v247
	v_lshlrev_b32_e32 v222, 16, v214
	v_and_b32_e32 v214, 0xffff0000, v214
	v_mul_f32_e32 v246, v246, v222
	v_mul_f32_e32 v247, v247, v214
	v_pk_mul_f32 v[74:75], v[74:75], v[246:247]
	v_lshlrev_b32_e32 v246, 16, v223
	v_and_b32_e32 v247, 0xffff0000, v223
	v_max_f32_e32 v246, 0xda24260, v246
	v_max_f32_e32 v247, 0xda24260, v247
	v_rcp_f32_e32 v246, v246
	v_rcp_f32_e32 v247, v247
	v_lshlrev_b32_e32 v223, 16, v215
	v_and_b32_e32 v215, 0xffff0000, v215
	v_mul_f32_e32 v246, v246, v223
	v_mul_f32_e32 v247, v247, v215
	v_pk_mul_f32 v[76:77], v[76:77], v[246:247]
	v_lshlrev_b32_e32 v246, 16, v224
	v_and_b32_e32 v247, 0xffff0000, v224
	v_max_f32_e32 v246, 0xda24260, v246
	v_max_f32_e32 v247, 0xda24260, v247
	v_rcp_f32_e32 v246, v246
	v_rcp_f32_e32 v247, v247
	v_lshlrev_b32_e32 v224, 16, v216
	v_and_b32_e32 v216, 0xffff0000, v216
	v_mul_f32_e32 v246, v246, v224
	v_mul_f32_e32 v247, v247, v216
	v_pk_mul_f32 v[70:71], v[70:71], v[246:247]
	v_lshlrev_b32_e32 v246, 16, v225
	v_and_b32_e32 v247, 0xffff0000, v225
	v_max_f32_e32 v246, 0xda24260, v246
	v_max_f32_e32 v247, 0xda24260, v247
	v_rcp_f32_e32 v246, v246
	v_rcp_f32_e32 v247, v247
	v_lshlrev_b32_e32 v225, 16, v217
	v_and_b32_e32 v217, 0xffff0000, v217
	v_mul_f32_e32 v246, v246, v225
	v_mul_f32_e32 v247, v247, v217
	v_pk_mul_f32 v[72:73], v[72:73], v[246:247]
	s_add_u32 vcc_lo, s12, 0x635000
	s_addc_u32 vcc_hi, s13, 0
	global_load_dwordx4 v[210:213], v245, vcc
	global_load_dwordx4 v[214:217], v245, vcc offset:256
	s_add_u32 vcc_lo, s12, 0x637000
	s_addc_u32 vcc_hi, s13, 0
	global_load_dwordx4 v[218:221], v245, vcc
	global_load_dwordx4 v[222:225], v245, vcc offset:256
	s_waitcnt vmcnt(13)
	v_lshlrev_b32_e32 v246, 16, v142
	v_and_b32_e32 v247, 0xffff0000, v142
	v_max_f32_e32 v246, 0xda24260, v246
	v_max_f32_e32 v247, 0xda24260, v247
	v_rcp_f32_e32 v246, v246
	v_rcp_f32_e32 v247, v247
	v_lshlrev_b32_e32 v142, 16, v134
	v_and_b32_e32 v134, 0xffff0000, v134
	v_mul_f32_e32 v246, v246, v142
	v_mul_f32_e32 v247, v247, v134
	v_pk_mul_f32 v[66:67], v[66:67], v[246:247]
	v_lshlrev_b32_e32 v246, 16, v143
	v_and_b32_e32 v247, 0xffff0000, v143
	v_max_f32_e32 v246, 0xda24260, v246
	v_max_f32_e32 v247, 0xda24260, v247
	v_rcp_f32_e32 v246, v246
	v_rcp_f32_e32 v247, v247
	v_lshlrev_b32_e32 v143, 16, v135
	v_and_b32_e32 v135, 0xffff0000, v135
	v_mul_f32_e32 v246, v246, v143
	v_mul_f32_e32 v247, v247, v135
	v_pk_mul_f32 v[68:69], v[68:69], v[246:247]
	v_lshlrev_b32_e32 v246, 16, v144
	v_and_b32_e32 v247, 0xffff0000, v144
	v_max_f32_e32 v246, 0xda24260, v246
	v_max_f32_e32 v247, 0xda24260, v247
	v_rcp_f32_e32 v246, v246
	v_rcp_f32_e32 v247, v247
	v_lshlrev_b32_e32 v144, 16, v136
	v_and_b32_e32 v136, 0xffff0000, v136
	v_mul_f32_e32 v246, v246, v144
	v_mul_f32_e32 v247, v247, v136
	v_pk_mul_f32 v[62:63], v[62:63], v[246:247]
	v_lshlrev_b32_e32 v246, 16, v145
	v_and_b32_e32 v247, 0xffff0000, v145
	v_max_f32_e32 v246, 0xda24260, v246
	v_max_f32_e32 v247, 0xda24260, v247
	v_rcp_f32_e32 v246, v246
	v_rcp_f32_e32 v247, v247
	v_lshlrev_b32_e32 v145, 16, v137
	v_and_b32_e32 v137, 0xffff0000, v137
	v_mul_f32_e32 v246, v246, v145
	v_mul_f32_e32 v247, v247, v137
	v_pk_mul_f32 v[64:65], v[64:65], v[246:247]
	s_waitcnt vmcnt(12)
	v_lshlrev_b32_e32 v246, 16, v146
	v_and_b32_e32 v247, 0xffff0000, v146
	v_max_f32_e32 v246, 0xda24260, v246
	v_max_f32_e32 v247, 0xda24260, v247
	v_rcp_f32_e32 v246, v246
	v_rcp_f32_e32 v247, v247
	v_lshlrev_b32_e32 v146, 16, v138
	v_and_b32_e32 v138, 0xffff0000, v138
	v_mul_f32_e32 v246, v246, v146
	v_mul_f32_e32 v247, v247, v138
	v_pk_mul_f32 v[58:59], v[58:59], v[246:247]
	v_lshlrev_b32_e32 v246, 16, v147
	v_and_b32_e32 v247, 0xffff0000, v147
	v_max_f32_e32 v246, 0xda24260, v246
	v_max_f32_e32 v247, 0xda24260, v247
	v_rcp_f32_e32 v246, v246
	v_rcp_f32_e32 v247, v247
	v_lshlrev_b32_e32 v147, 16, v139
	v_and_b32_e32 v139, 0xffff0000, v139
	v_mul_f32_e32 v246, v246, v147
	v_mul_f32_e32 v247, v247, v139
	v_pk_mul_f32 v[60:61], v[60:61], v[246:247]
	v_lshlrev_b32_e32 v246, 16, v148
	v_and_b32_e32 v247, 0xffff0000, v148
	v_max_f32_e32 v246, 0xda24260, v246
	v_max_f32_e32 v247, 0xda24260, v247
	v_rcp_f32_e32 v246, v246
	v_rcp_f32_e32 v247, v247
	v_lshlrev_b32_e32 v148, 16, v140
	v_and_b32_e32 v140, 0xffff0000, v140
	v_mul_f32_e32 v246, v246, v148
	v_mul_f32_e32 v247, v247, v140
	v_pk_mul_f32 v[54:55], v[54:55], v[246:247]
	v_lshlrev_b32_e32 v246, 16, v149
	v_and_b32_e32 v247, 0xffff0000, v149
	v_max_f32_e32 v246, 0xda24260, v246
	v_max_f32_e32 v247, 0xda24260, v247
	v_rcp_f32_e32 v246, v246
	v_rcp_f32_e32 v247, v247
	v_lshlrev_b32_e32 v149, 16, v141
	v_and_b32_e32 v141, 0xffff0000, v141
	v_mul_f32_e32 v246, v246, v149
	v_mul_f32_e32 v247, v247, v141
	v_pk_mul_f32 v[56:57], v[56:57], v[246:247]
	s_waitcnt vmcnt(9)
	v_lshlrev_b32_e32 v246, 16, v158
	v_and_b32_e32 v247, 0xffff0000, v158
	v_max_f32_e32 v246, 0xda24260, v246
	v_max_f32_e32 v247, 0xda24260, v247
	v_rcp_f32_e32 v246, v246
	v_rcp_f32_e32 v247, v247
	v_lshlrev_b32_e32 v158, 16, v150
	v_and_b32_e32 v150, 0xffff0000, v150
	v_mul_f32_e32 v246, v246, v158
	v_mul_f32_e32 v247, v247, v150
	v_pk_mul_f32 v[50:51], v[50:51], v[246:247]
	v_lshlrev_b32_e32 v246, 16, v159
	v_and_b32_e32 v247, 0xffff0000, v159
	v_max_f32_e32 v246, 0xda24260, v246
	v_max_f32_e32 v247, 0xda24260, v247
	v_rcp_f32_e32 v246, v246
	v_rcp_f32_e32 v247, v247
	v_lshlrev_b32_e32 v159, 16, v151
	v_and_b32_e32 v151, 0xffff0000, v151
	v_mul_f32_e32 v246, v246, v159
	v_mul_f32_e32 v247, v247, v151
	v_pk_mul_f32 v[52:53], v[52:53], v[246:247]
	v_lshlrev_b32_e32 v246, 16, v160
	v_and_b32_e32 v247, 0xffff0000, v160
	v_max_f32_e32 v246, 0xda24260, v246
	v_max_f32_e32 v247, 0xda24260, v247
	v_rcp_f32_e32 v246, v246
	v_rcp_f32_e32 v247, v247
	v_lshlrev_b32_e32 v160, 16, v152
	v_and_b32_e32 v152, 0xffff0000, v152
	v_mul_f32_e32 v246, v246, v160
	v_mul_f32_e32 v247, v247, v152
	v_pk_mul_f32 v[46:47], v[46:47], v[246:247]
	v_lshlrev_b32_e32 v246, 16, v161
	v_and_b32_e32 v247, 0xffff0000, v161
	v_max_f32_e32 v246, 0xda24260, v246
	v_max_f32_e32 v247, 0xda24260, v247
	v_rcp_f32_e32 v246, v246
	v_rcp_f32_e32 v247, v247
	v_lshlrev_b32_e32 v161, 16, v153
	v_and_b32_e32 v153, 0xffff0000, v153
	v_mul_f32_e32 v246, v246, v161
	v_mul_f32_e32 v247, v247, v153
	v_pk_mul_f32 v[48:49], v[48:49], v[246:247]
	s_waitcnt vmcnt(8)
	v_lshlrev_b32_e32 v246, 16, v190
	v_and_b32_e32 v247, 0xffff0000, v190
	v_max_f32_e32 v246, 0xda24260, v246
	v_max_f32_e32 v247, 0xda24260, v247
	v_rcp_f32_e32 v246, v246
	v_rcp_f32_e32 v247, v247
	v_lshlrev_b32_e32 v190, 16, v154
	v_and_b32_e32 v154, 0xffff0000, v154
	v_mul_f32_e32 v246, v246, v190
	v_mul_f32_e32 v247, v247, v154
	v_pk_mul_f32 v[42:43], v[42:43], v[246:247]
	v_lshlrev_b32_e32 v246, 16, v191
	v_and_b32_e32 v247, 0xffff0000, v191
	v_max_f32_e32 v246, 0xda24260, v246
	v_max_f32_e32 v247, 0xda24260, v247
	v_rcp_f32_e32 v246, v246
	v_rcp_f32_e32 v247, v247
	v_lshlrev_b32_e32 v191, 16, v155
	v_and_b32_e32 v155, 0xffff0000, v155
	v_mul_f32_e32 v246, v246, v191
	v_mul_f32_e32 v247, v247, v155
	v_pk_mul_f32 v[44:45], v[44:45], v[246:247]
	v_lshlrev_b32_e32 v246, 16, v192
	v_and_b32_e32 v247, 0xffff0000, v192
	v_max_f32_e32 v246, 0xda24260, v246
	v_max_f32_e32 v247, 0xda24260, v247
	v_rcp_f32_e32 v246, v246
	v_rcp_f32_e32 v247, v247
	v_lshlrev_b32_e32 v192, 16, v156
	v_and_b32_e32 v156, 0xffff0000, v156
	v_mul_f32_e32 v246, v246, v192
	v_mul_f32_e32 v247, v247, v156
	v_pk_mul_f32 v[38:39], v[38:39], v[246:247]
	v_lshlrev_b32_e32 v246, 16, v193
	v_and_b32_e32 v247, 0xffff0000, v193
	v_max_f32_e32 v246, 0xda24260, v246
	v_max_f32_e32 v247, 0xda24260, v247
	v_rcp_f32_e32 v246, v246
	v_rcp_f32_e32 v247, v247
	v_lshlrev_b32_e32 v193, 16, v157
	v_and_b32_e32 v157, 0xffff0000, v157
	v_mul_f32_e32 v246, v246, v193
	v_mul_f32_e32 v247, v247, v157
	v_pk_mul_f32 v[40:41], v[40:41], v[246:247]
	s_waitcnt vmcnt(5)
	v_lshlrev_b32_e32 v246, 16, v202
	v_and_b32_e32 v247, 0xffff0000, v202
	v_max_f32_e32 v246, 0xda24260, v246
	v_max_f32_e32 v247, 0xda24260, v247
	v_rcp_f32_e32 v246, v246
	v_rcp_f32_e32 v247, v247
	v_lshlrev_b32_e32 v202, 16, v194
	v_and_b32_e32 v194, 0xffff0000, v194
	v_mul_f32_e32 v246, v246, v202
	v_mul_f32_e32 v247, v247, v194
	v_pk_mul_f32 v[34:35], v[34:35], v[246:247]
	v_lshlrev_b32_e32 v246, 16, v203
	v_and_b32_e32 v247, 0xffff0000, v203
	v_max_f32_e32 v246, 0xda24260, v246
	v_max_f32_e32 v247, 0xda24260, v247
	v_rcp_f32_e32 v246, v246
	v_rcp_f32_e32 v247, v247
	v_lshlrev_b32_e32 v203, 16, v195
	v_and_b32_e32 v195, 0xffff0000, v195
	v_mul_f32_e32 v246, v246, v203
	v_mul_f32_e32 v247, v247, v195
	v_pk_mul_f32 v[36:37], v[36:37], v[246:247]
	v_lshlrev_b32_e32 v246, 16, v204
	v_and_b32_e32 v247, 0xffff0000, v204
	v_max_f32_e32 v246, 0xda24260, v246
	v_max_f32_e32 v247, 0xda24260, v247
	v_rcp_f32_e32 v246, v246
	v_rcp_f32_e32 v247, v247
	v_lshlrev_b32_e32 v204, 16, v196
	v_and_b32_e32 v196, 0xffff0000, v196
	v_mul_f32_e32 v246, v246, v204
	v_mul_f32_e32 v247, v247, v196
	v_pk_mul_f32 v[30:31], v[30:31], v[246:247]
	v_lshlrev_b32_e32 v246, 16, v205
	v_and_b32_e32 v247, 0xffff0000, v205
	v_max_f32_e32 v246, 0xda24260, v246
	v_max_f32_e32 v247, 0xda24260, v247
	v_rcp_f32_e32 v246, v246
	v_rcp_f32_e32 v247, v247
	v_lshlrev_b32_e32 v205, 16, v197
	v_and_b32_e32 v197, 0xffff0000, v197
	v_mul_f32_e32 v246, v246, v205
	v_mul_f32_e32 v247, v247, v197
	v_pk_mul_f32 v[32:33], v[32:33], v[246:247]
	s_waitcnt vmcnt(4)
	v_lshlrev_b32_e32 v246, 16, v206
	v_and_b32_e32 v247, 0xffff0000, v206
	v_max_f32_e32 v246, 0xda24260, v246
	v_max_f32_e32 v247, 0xda24260, v247
	v_rcp_f32_e32 v246, v246
	v_rcp_f32_e32 v247, v247
	v_lshlrev_b32_e32 v206, 16, v198
	v_and_b32_e32 v198, 0xffff0000, v198
	v_mul_f32_e32 v246, v246, v206
	v_mul_f32_e32 v247, v247, v198
	v_pk_mul_f32 v[26:27], v[26:27], v[246:247]
	v_lshlrev_b32_e32 v246, 16, v207
	v_and_b32_e32 v247, 0xffff0000, v207
	v_max_f32_e32 v246, 0xda24260, v246
	v_max_f32_e32 v247, 0xda24260, v247
	v_rcp_f32_e32 v246, v246
	v_rcp_f32_e32 v247, v247
	v_lshlrev_b32_e32 v207, 16, v199
	v_and_b32_e32 v199, 0xffff0000, v199
	v_mul_f32_e32 v246, v246, v207
	v_mul_f32_e32 v247, v247, v199
	v_pk_mul_f32 v[28:29], v[28:29], v[246:247]
	v_lshlrev_b32_e32 v246, 16, v208
	v_and_b32_e32 v247, 0xffff0000, v208
	v_max_f32_e32 v246, 0xda24260, v246
	v_max_f32_e32 v247, 0xda24260, v247
	v_rcp_f32_e32 v246, v246
	v_rcp_f32_e32 v247, v247
	v_lshlrev_b32_e32 v208, 16, v200
	v_and_b32_e32 v200, 0xffff0000, v200
	v_mul_f32_e32 v246, v246, v208
	v_mul_f32_e32 v247, v247, v200
	v_pk_mul_f32 v[22:23], v[22:23], v[246:247]
	v_lshlrev_b32_e32 v246, 16, v209
	v_and_b32_e32 v247, 0xffff0000, v209
	v_max_f32_e32 v246, 0xda24260, v246
	v_max_f32_e32 v247, 0xda24260, v247
	v_rcp_f32_e32 v246, v246
	v_rcp_f32_e32 v247, v247
	v_lshlrev_b32_e32 v209, 16, v201
	v_and_b32_e32 v201, 0xffff0000, v201
	v_mul_f32_e32 v246, v246, v209
	v_mul_f32_e32 v247, v247, v201
	v_pk_mul_f32 v[24:25], v[24:25], v[246:247]
	s_waitcnt vmcnt(1)
	v_lshlrev_b32_e32 v246, 16, v218
	v_and_b32_e32 v247, 0xffff0000, v218
	v_max_f32_e32 v246, 0xda24260, v246
	v_max_f32_e32 v247, 0xda24260, v247
	v_rcp_f32_e32 v246, v246
	v_rcp_f32_e32 v247, v247
	v_lshlrev_b32_e32 v218, 16, v210
	v_and_b32_e32 v210, 0xffff0000, v210
	v_mul_f32_e32 v246, v246, v218
	v_mul_f32_e32 v247, v247, v210
	v_pk_mul_f32 v[18:19], v[18:19], v[246:247]
	v_lshlrev_b32_e32 v246, 16, v219
	v_and_b32_e32 v247, 0xffff0000, v219
	v_max_f32_e32 v246, 0xda24260, v246
	v_max_f32_e32 v247, 0xda24260, v247
	v_rcp_f32_e32 v246, v246
	v_rcp_f32_e32 v247, v247
	v_lshlrev_b32_e32 v219, 16, v211
	v_and_b32_e32 v211, 0xffff0000, v211
	v_mul_f32_e32 v246, v246, v219
	v_mul_f32_e32 v247, v247, v211
	v_pk_mul_f32 v[20:21], v[20:21], v[246:247]
	v_lshlrev_b32_e32 v246, 16, v220
	v_and_b32_e32 v247, 0xffff0000, v220
	v_max_f32_e32 v246, 0xda24260, v246
	v_max_f32_e32 v247, 0xda24260, v247
	v_rcp_f32_e32 v246, v246
	v_rcp_f32_e32 v247, v247
	v_lshlrev_b32_e32 v220, 16, v212
	v_and_b32_e32 v212, 0xffff0000, v212
	v_mul_f32_e32 v246, v246, v220
	v_mul_f32_e32 v247, v247, v212
	v_pk_mul_f32 v[14:15], v[14:15], v[246:247]
	v_lshlrev_b32_e32 v246, 16, v221
	v_and_b32_e32 v247, 0xffff0000, v221
	v_max_f32_e32 v246, 0xda24260, v246
	v_max_f32_e32 v247, 0xda24260, v247
	v_rcp_f32_e32 v246, v246
	v_rcp_f32_e32 v247, v247
	v_lshlrev_b32_e32 v221, 16, v213
	v_and_b32_e32 v213, 0xffff0000, v213
	v_mul_f32_e32 v246, v246, v221
	v_mul_f32_e32 v247, v247, v213
	v_pk_mul_f32 v[16:17], v[16:17], v[246:247]
	s_waitcnt vmcnt(0)
	v_lshlrev_b32_e32 v246, 16, v222
	v_and_b32_e32 v247, 0xffff0000, v222
	v_max_f32_e32 v246, 0xda24260, v246
	v_max_f32_e32 v247, 0xda24260, v247
	v_rcp_f32_e32 v246, v246
	v_rcp_f32_e32 v247, v247
	v_lshlrev_b32_e32 v222, 16, v214
	v_and_b32_e32 v214, 0xffff0000, v214
	v_mul_f32_e32 v246, v246, v222
	v_mul_f32_e32 v247, v247, v214
	v_pk_mul_f32 v[10:11], v[10:11], v[246:247]
	v_lshlrev_b32_e32 v246, 16, v223
	v_and_b32_e32 v247, 0xffff0000, v223
	v_max_f32_e32 v246, 0xda24260, v246
	v_max_f32_e32 v247, 0xda24260, v247
	v_rcp_f32_e32 v246, v246
	v_rcp_f32_e32 v247, v247
	v_lshlrev_b32_e32 v223, 16, v215
	v_and_b32_e32 v215, 0xffff0000, v215
	v_mul_f32_e32 v246, v246, v223
	v_mul_f32_e32 v247, v247, v215
	v_pk_mul_f32 v[12:13], v[12:13], v[246:247]
	v_lshlrev_b32_e32 v246, 16, v224
	v_and_b32_e32 v247, 0xffff0000, v224
	v_max_f32_e32 v246, 0xda24260, v246
	v_max_f32_e32 v247, 0xda24260, v247
	v_rcp_f32_e32 v246, v246
	v_rcp_f32_e32 v247, v247
	v_lshlrev_b32_e32 v224, 16, v216
	v_and_b32_e32 v216, 0xffff0000, v216
	v_mul_f32_e32 v246, v246, v224
	v_mul_f32_e32 v247, v247, v216
	v_pk_mul_f32 v[6:7], v[6:7], v[246:247]
	v_lshlrev_b32_e32 v246, 16, v225
	v_and_b32_e32 v247, 0xffff0000, v225
	v_max_f32_e32 v246, 0xda24260, v246
	v_max_f32_e32 v247, 0xda24260, v247
	v_rcp_f32_e32 v246, v246
	v_rcp_f32_e32 v247, v247
	v_lshlrev_b32_e32 v225, 16, v217
	v_and_b32_e32 v217, 0xffff0000, v217
	v_mul_f32_e32 v246, v246, v225
	v_mul_f32_e32 v247, v247, v217
	v_pk_mul_f32 v[8:9], v[8:9], v[246:247]
	s_branch .LBB0_1198
.LBB0_1201:
	v_or_b32_e32 v246, s64, v188
	v_add_u32_e32 v245, s23, v1
	v_mul_u32_u24_e32 v247, 0x9000, v245
	v_lshl_add_u32 v247, v246, 1, v247
	s_add_u32 vcc_lo, s12, 0x7000
	s_addc_u32 vcc_hi, s13, 0
	global_load_dwordx4 v[134:137], v247, vcc
	global_load_dwordx4 v[138:141], v247, vcc offset:256
	s_add_u32 vcc_lo, s12, 0x97000
	s_addc_u32 vcc_hi, s13, 0
	global_load_dwordx4 v[142:145], v247, vcc
	global_load_dwordx4 v[146:149], v247, vcc offset:256
	s_add_u32 vcc_lo, s12, 0x127000
	s_addc_u32 vcc_hi, s13, 0
	global_load_dwordx4 v[150:153], v247, vcc
	global_load_dwordx4 v[154:157], v247, vcc offset:256
	s_add_u32 vcc_lo, s12, 0x1b7000
	s_addc_u32 vcc_hi, s13, 0
	global_load_dwordx4 v[158:161], v247, vcc
	global_load_dwordx4 v[190:193], v247, vcc offset:256
	s_add_u32 vcc_lo, s12, 0x487000
	s_addc_u32 vcc_hi, s13, 0
	global_load_dwordx4 v[194:197], v247, vcc
	global_load_dwordx4 v[198:201], v247, vcc offset:256
	s_add_u32 vcc_lo, s12, 0x517000
	s_addc_u32 vcc_hi, s13, 0
	global_load_dwordx4 v[202:205], v247, vcc
	global_load_dwordx4 v[206:209], v247, vcc offset:256
	s_add_u32 vcc_lo, s12, 0x5a7000
	s_addc_u32 vcc_hi, s13, 0
	global_load_dwordx4 v[210:213], v247, vcc
	global_load_dwordx4 v[214:217], v247, vcc offset:256
	s_add_u32 vcc_lo, s12, 0x637000
	s_addc_u32 vcc_hi, s13, 0
	global_load_dwordx4 v[218:221], v247, vcc
	global_load_dwordx4 v[222:225], v247, vcc offset:256
	v_lshlrev_b32_e32 v245, 13, v245
	v_lshl_add_u32 v245, v246, 1, v245
	s_and_b64 vcc, exec, s[20:21]
	s_cbranch_vccz .LBB0_1203
	s_barrier
.LBB0_1203:
	s_waitcnt vmcnt(15)
	v_lshlrev_b32_e32 v246, 16, v134
	v_and_b32_e32 v247, 0xffff0000, v134
	v_pk_mul_f32 v[130:131], v[130:131], v[246:247]
	v_lshlrev_b32_e32 v246, 16, v135
	v_and_b32_e32 v247, 0xffff0000, v135
	v_pk_mul_f32 v[132:133], v[132:133], v[246:247]
	v_lshlrev_b32_e32 v246, 16, v136
	v_and_b32_e32 v247, 0xffff0000, v136
	v_pk_mul_f32 v[126:127], v[126:127], v[246:247]
	v_lshlrev_b32_e32 v246, 16, v137
	v_and_b32_e32 v247, 0xffff0000, v137
	v_pk_mul_f32 v[128:129], v[128:129], v[246:247]
	v_cvt_pk_bf16_f32 v134, v130, v131
	v_cvt_pk_bf16_f32 v135, v132, v133
	v_cvt_pk_bf16_f32 v136, v126, v127
	v_cvt_pk_bf16_f32 v137, v128, v129
	global_store_dwordx4 v245, v[134:137], s[16:17]
	s_waitcnt vmcnt(15)
	v_lshlrev_b32_e32 v246, 16, v138
	v_and_b32_e32 v247, 0xffff0000, v138
	v_pk_mul_f32 v[122:123], v[122:123], v[246:247]
	v_lshlrev_b32_e32 v246, 16, v139
	v_and_b32_e32 v247, 0xffff0000, v139
	v_pk_mul_f32 v[124:125], v[124:125], v[246:247]
	v_lshlrev_b32_e32 v246, 16, v140
	v_and_b32_e32 v247, 0xffff0000, v140
	v_pk_mul_f32 v[118:119], v[118:119], v[246:247]
	v_lshlrev_b32_e32 v246, 16, v141
	v_and_b32_e32 v247, 0xffff0000, v141
	v_pk_mul_f32 v[120:121], v[120:121], v[246:247]
	v_cvt_pk_bf16_f32 v138, v122, v123
	v_cvt_pk_bf16_f32 v139, v124, v125
	v_cvt_pk_bf16_f32 v140, v118, v119
	v_cvt_pk_bf16_f32 v141, v120, v121
	global_store_dwordx4 v245, v[138:141], s[16:17] offset:256
	s_add_u32 vcc_lo, s16, 0x20000
	s_addc_u32 vcc_hi, s17, 0
	s_waitcnt vmcnt(15)
	v_lshlrev_b32_e32 v246, 16, v142
	v_and_b32_e32 v247, 0xffff0000, v142
	v_pk_mul_f32 v[114:115], v[114:115], v[246:247]
	v_lshlrev_b32_e32 v246, 16, v143
	v_and_b32_e32 v247, 0xffff0000, v143
	v_pk_mul_f32 v[116:117], v[116:117], v[246:247]
	v_lshlrev_b32_e32 v246, 16, v144
	v_and_b32_e32 v247, 0xffff0000, v144
	v_pk_mul_f32 v[110:111], v[110:111], v[246:247]
	v_lshlrev_b32_e32 v246, 16, v145
	v_and_b32_e32 v247, 0xffff0000, v145
	v_pk_mul_f32 v[112:113], v[112:113], v[246:247]
	v_cvt_pk_bf16_f32 v142, v114, v115
	v_cvt_pk_bf16_f32 v143, v116, v117
	v_cvt_pk_bf16_f32 v144, v110, v111
	v_cvt_pk_bf16_f32 v145, v112, v113
	global_store_dwordx4 v245, v[142:145], vcc
	s_waitcnt vmcnt(15)
	v_lshlrev_b32_e32 v246, 16, v146
	v_and_b32_e32 v247, 0xffff0000, v146
	v_pk_mul_f32 v[106:107], v[106:107], v[246:247]
	v_lshlrev_b32_e32 v246, 16, v147
	v_and_b32_e32 v247, 0xffff0000, v147
	v_pk_mul_f32 v[108:109], v[108:109], v[246:247]
	v_lshlrev_b32_e32 v246, 16, v148
	v_and_b32_e32 v247, 0xffff0000, v148
	v_pk_mul_f32 v[102:103], v[102:103], v[246:247]
	v_lshlrev_b32_e32 v246, 16, v149
	v_and_b32_e32 v247, 0xffff0000, v149
	v_pk_mul_f32 v[104:105], v[104:105], v[246:247]
	v_cvt_pk_bf16_f32 v146, v106, v107
	v_cvt_pk_bf16_f32 v147, v108, v109
	v_cvt_pk_bf16_f32 v148, v102, v103
	v_cvt_pk_bf16_f32 v149, v104, v105
	global_store_dwordx4 v245, v[146:149], vcc offset:256
	s_add_u32 vcc_lo, s16, 0x40000
	s_addc_u32 vcc_hi, s17, 0
	s_waitcnt vmcnt(15)
	v_lshlrev_b32_e32 v246, 16, v150
	v_and_b32_e32 v247, 0xffff0000, v150
	v_pk_mul_f32 v[98:99], v[98:99], v[246:247]
	v_lshlrev_b32_e32 v246, 16, v151
	v_and_b32_e32 v247, 0xffff0000, v151
	v_pk_mul_f32 v[100:101], v[100:101], v[246:247]
	v_lshlrev_b32_e32 v246, 16, v152
	v_and_b32_e32 v247, 0xffff0000, v152
	v_pk_mul_f32 v[94:95], v[94:95], v[246:247]
	v_lshlrev_b32_e32 v246, 16, v153
	v_and_b32_e32 v247, 0xffff0000, v153
	v_pk_mul_f32 v[96:97], v[96:97], v[246:247]
	v_cvt_pk_bf16_f32 v150, v98, v99
	v_cvt_pk_bf16_f32 v151, v100, v101
	v_cvt_pk_bf16_f32 v152, v94, v95
	v_cvt_pk_bf16_f32 v153, v96, v97
	global_store_dwordx4 v245, v[150:153], vcc
	s_waitcnt vmcnt(15)
	v_lshlrev_b32_e32 v246, 16, v154
	v_and_b32_e32 v247, 0xffff0000, v154
	v_pk_mul_f32 v[90:91], v[90:91], v[246:247]
	v_lshlrev_b32_e32 v246, 16, v155
	v_and_b32_e32 v247, 0xffff0000, v155
	v_pk_mul_f32 v[92:93], v[92:93], v[246:247]
	v_lshlrev_b32_e32 v246, 16, v156
	v_and_b32_e32 v247, 0xffff0000, v156
	v_pk_mul_f32 v[86:87], v[86:87], v[246:247]
	v_lshlrev_b32_e32 v246, 16, v157
	v_and_b32_e32 v247, 0xffff0000, v157
	v_pk_mul_f32 v[88:89], v[88:89], v[246:247]
	v_cvt_pk_bf16_f32 v154, v90, v91
	v_cvt_pk_bf16_f32 v155, v92, v93
	v_cvt_pk_bf16_f32 v156, v86, v87
	v_cvt_pk_bf16_f32 v157, v88, v89
	global_store_dwordx4 v245, v[154:157], vcc offset:256
	s_add_u32 vcc_lo, s16, 0x60000
	s_addc_u32 vcc_hi, s17, 0
	s_waitcnt vmcnt(15)
	v_lshlrev_b32_e32 v246, 16, v158
	v_and_b32_e32 v247, 0xffff0000, v158
	v_pk_mul_f32 v[82:83], v[82:83], v[246:247]
	v_lshlrev_b32_e32 v246, 16, v159
	v_and_b32_e32 v247, 0xffff0000, v159
	v_pk_mul_f32 v[84:85], v[84:85], v[246:247]
	v_lshlrev_b32_e32 v246, 16, v160
	v_and_b32_e32 v247, 0xffff0000, v160
	v_pk_mul_f32 v[78:79], v[78:79], v[246:247]
	v_lshlrev_b32_e32 v246, 16, v161
	v_and_b32_e32 v247, 0xffff0000, v161
	v_pk_mul_f32 v[80:81], v[80:81], v[246:247]
	v_cvt_pk_bf16_f32 v158, v82, v83
	v_cvt_pk_bf16_f32 v159, v84, v85
	v_cvt_pk_bf16_f32 v160, v78, v79
	v_cvt_pk_bf16_f32 v161, v80, v81
	global_store_dwordx4 v245, v[158:161], vcc
	s_waitcnt vmcnt(15)
	v_lshlrev_b32_e32 v246, 16, v190
	v_and_b32_e32 v247, 0xffff0000, v190
	v_pk_mul_f32 v[74:75], v[74:75], v[246:247]
	v_lshlrev_b32_e32 v246, 16, v191
	v_and_b32_e32 v247, 0xffff0000, v191
	v_pk_mul_f32 v[76:77], v[76:77], v[246:247]
	v_lshlrev_b32_e32 v246, 16, v192
	v_and_b32_e32 v247, 0xffff0000, v192
	v_pk_mul_f32 v[70:71], v[70:71], v[246:247]
	v_lshlrev_b32_e32 v246, 16, v193
	v_and_b32_e32 v247, 0xffff0000, v193
	v_pk_mul_f32 v[72:73], v[72:73], v[246:247]
	v_cvt_pk_bf16_f32 v190, v74, v75
	v_cvt_pk_bf16_f32 v191, v76, v77
	v_cvt_pk_bf16_f32 v192, v70, v71
	v_cvt_pk_bf16_f32 v193, v72, v73
	global_store_dwordx4 v245, v[190:193], vcc offset:256
	s_add_u32 vcc_lo, s16, 0x100000
	s_addc_u32 vcc_hi, s17, 0
	s_waitcnt vmcnt(15)
	v_lshlrev_b32_e32 v246, 16, v194
	v_and_b32_e32 v247, 0xffff0000, v194
	v_pk_mul_f32 v[66:67], v[66:67], v[246:247]
	v_lshlrev_b32_e32 v246, 16, v195
	v_and_b32_e32 v247, 0xffff0000, v195
	v_pk_mul_f32 v[68:69], v[68:69], v[246:247]
	v_lshlrev_b32_e32 v246, 16, v196
	v_and_b32_e32 v247, 0xffff0000, v196
	v_pk_mul_f32 v[62:63], v[62:63], v[246:247]
	v_lshlrev_b32_e32 v246, 16, v197
	v_and_b32_e32 v247, 0xffff0000, v197
	v_pk_mul_f32 v[64:65], v[64:65], v[246:247]
	v_cvt_pk_bf16_f32 v194, v66, v67
	v_cvt_pk_bf16_f32 v195, v68, v69
	v_cvt_pk_bf16_f32 v196, v62, v63
	v_cvt_pk_bf16_f32 v197, v64, v65
	global_store_dwordx4 v245, v[194:197], vcc
	s_waitcnt vmcnt(15)
	v_lshlrev_b32_e32 v246, 16, v198
	v_and_b32_e32 v247, 0xffff0000, v198
	v_pk_mul_f32 v[58:59], v[58:59], v[246:247]
	v_lshlrev_b32_e32 v246, 16, v199
	v_and_b32_e32 v247, 0xffff0000, v199
	v_pk_mul_f32 v[60:61], v[60:61], v[246:247]
	v_lshlrev_b32_e32 v246, 16, v200
	v_and_b32_e32 v247, 0xffff0000, v200
	v_pk_mul_f32 v[54:55], v[54:55], v[246:247]
	v_lshlrev_b32_e32 v246, 16, v201
	v_and_b32_e32 v247, 0xffff0000, v201
	v_pk_mul_f32 v[56:57], v[56:57], v[246:247]
	v_cvt_pk_bf16_f32 v198, v58, v59
	v_cvt_pk_bf16_f32 v199, v60, v61
	v_cvt_pk_bf16_f32 v200, v54, v55
	v_cvt_pk_bf16_f32 v201, v56, v57
	global_store_dwordx4 v245, v[198:201], vcc offset:256
	s_add_u32 vcc_lo, s16, 0x120000
	s_addc_u32 vcc_hi, s17, 0
	s_waitcnt vmcnt(15)
	v_lshlrev_b32_e32 v246, 16, v202
	v_and_b32_e32 v247, 0xffff0000, v202
	v_pk_mul_f32 v[50:51], v[50:51], v[246:247]
	v_lshlrev_b32_e32 v246, 16, v203
	v_and_b32_e32 v247, 0xffff0000, v203
	v_pk_mul_f32 v[52:53], v[52:53], v[246:247]
	v_lshlrev_b32_e32 v246, 16, v204
	v_and_b32_e32 v247, 0xffff0000, v204
	v_pk_mul_f32 v[46:47], v[46:47], v[246:247]
	v_lshlrev_b32_e32 v246, 16, v205
	v_and_b32_e32 v247, 0xffff0000, v205
	v_pk_mul_f32 v[48:49], v[48:49], v[246:247]
	v_cvt_pk_bf16_f32 v202, v50, v51
	v_cvt_pk_bf16_f32 v203, v52, v53
	v_cvt_pk_bf16_f32 v204, v46, v47
	v_cvt_pk_bf16_f32 v205, v48, v49
	global_store_dwordx4 v245, v[202:205], vcc
	s_waitcnt vmcnt(15)
	v_lshlrev_b32_e32 v246, 16, v206
	v_and_b32_e32 v247, 0xffff0000, v206
	v_pk_mul_f32 v[42:43], v[42:43], v[246:247]
	v_lshlrev_b32_e32 v246, 16, v207
	v_and_b32_e32 v247, 0xffff0000, v207
	v_pk_mul_f32 v[44:45], v[44:45], v[246:247]
	v_lshlrev_b32_e32 v246, 16, v208
	v_and_b32_e32 v247, 0xffff0000, v208
	v_pk_mul_f32 v[38:39], v[38:39], v[246:247]
	v_lshlrev_b32_e32 v246, 16, v209
	v_and_b32_e32 v247, 0xffff0000, v209
	v_pk_mul_f32 v[40:41], v[40:41], v[246:247]
	v_cvt_pk_bf16_f32 v206, v42, v43
	v_cvt_pk_bf16_f32 v207, v44, v45
	v_cvt_pk_bf16_f32 v208, v38, v39
	v_cvt_pk_bf16_f32 v209, v40, v41
	global_store_dwordx4 v245, v[206:209], vcc offset:256
	s_add_u32 vcc_lo, s16, 0x140000
	s_addc_u32 vcc_hi, s17, 0
	s_waitcnt vmcnt(15)
	v_lshlrev_b32_e32 v246, 16, v210
	v_and_b32_e32 v247, 0xffff0000, v210
	v_pk_mul_f32 v[34:35], v[34:35], v[246:247]
	v_lshlrev_b32_e32 v246, 16, v211
	v_and_b32_e32 v247, 0xffff0000, v211
	v_pk_mul_f32 v[36:37], v[36:37], v[246:247]
	v_lshlrev_b32_e32 v246, 16, v212
	v_and_b32_e32 v247, 0xffff0000, v212
	v_pk_mul_f32 v[30:31], v[30:31], v[246:247]
	v_lshlrev_b32_e32 v246, 16, v213
	v_and_b32_e32 v247, 0xffff0000, v213
	v_pk_mul_f32 v[32:33], v[32:33], v[246:247]
	v_cvt_pk_bf16_f32 v210, v34, v35
	v_cvt_pk_bf16_f32 v211, v36, v37
	v_cvt_pk_bf16_f32 v212, v30, v31
	v_cvt_pk_bf16_f32 v213, v32, v33
	global_store_dwordx4 v245, v[210:213], vcc
	s_waitcnt vmcnt(15)
	v_lshlrev_b32_e32 v246, 16, v214
	v_and_b32_e32 v247, 0xffff0000, v214
	v_pk_mul_f32 v[26:27], v[26:27], v[246:247]
	v_lshlrev_b32_e32 v246, 16, v215
	v_and_b32_e32 v247, 0xffff0000, v215
	v_pk_mul_f32 v[28:29], v[28:29], v[246:247]
	v_lshlrev_b32_e32 v246, 16, v216
	v_and_b32_e32 v247, 0xffff0000, v216
	v_pk_mul_f32 v[22:23], v[22:23], v[246:247]
	v_lshlrev_b32_e32 v246, 16, v217
	v_and_b32_e32 v247, 0xffff0000, v217
	v_pk_mul_f32 v[24:25], v[24:25], v[246:247]
	v_cvt_pk_bf16_f32 v214, v26, v27
	v_cvt_pk_bf16_f32 v215, v28, v29
	v_cvt_pk_bf16_f32 v216, v22, v23
	v_cvt_pk_bf16_f32 v217, v24, v25
	global_store_dwordx4 v245, v[214:217], vcc offset:256
	s_add_u32 vcc_lo, s16, 0x160000
	s_addc_u32 vcc_hi, s17, 0
	s_waitcnt vmcnt(15)
	v_lshlrev_b32_e32 v246, 16, v218
	v_and_b32_e32 v247, 0xffff0000, v218
	v_pk_mul_f32 v[18:19], v[18:19], v[246:247]
	v_lshlrev_b32_e32 v246, 16, v219
	v_and_b32_e32 v247, 0xffff0000, v219
	v_pk_mul_f32 v[20:21], v[20:21], v[246:247]
	v_lshlrev_b32_e32 v246, 16, v220
	v_and_b32_e32 v247, 0xffff0000, v220
	v_pk_mul_f32 v[14:15], v[14:15], v[246:247]
	v_lshlrev_b32_e32 v246, 16, v221
	v_and_b32_e32 v247, 0xffff0000, v221
	v_pk_mul_f32 v[16:17], v[16:17], v[246:247]
	v_cvt_pk_bf16_f32 v218, v18, v19
	v_cvt_pk_bf16_f32 v219, v20, v21
	v_cvt_pk_bf16_f32 v220, v14, v15
	v_cvt_pk_bf16_f32 v221, v16, v17
	global_store_dwordx4 v245, v[218:221], vcc
	s_waitcnt vmcnt(15)
	v_lshlrev_b32_e32 v246, 16, v222
	v_and_b32_e32 v247, 0xffff0000, v222
	v_pk_mul_f32 v[10:11], v[10:11], v[246:247]
	v_lshlrev_b32_e32 v246, 16, v223
	v_and_b32_e32 v247, 0xffff0000, v223
	v_pk_mul_f32 v[12:13], v[12:13], v[246:247]
	v_lshlrev_b32_e32 v246, 16, v224
	v_and_b32_e32 v247, 0xffff0000, v224
	v_pk_mul_f32 v[6:7], v[6:7], v[246:247]
	v_lshlrev_b32_e32 v246, 16, v225
	v_and_b32_e32 v247, 0xffff0000, v225
	v_pk_mul_f32 v[8:9], v[8:9], v[246:247]
	v_cvt_pk_bf16_f32 v222, v10, v11
	v_cvt_pk_bf16_f32 v223, v12, v13
	v_cvt_pk_bf16_f32 v224, v6, v7
	v_cvt_pk_bf16_f32 v225, v8, v9
	global_store_dwordx4 v245, v[222:225], vcc offset:256
	s_and_b64 vcc, exec, s[6:7]
	s_mov_b64 s[6:7], -1
	s_cbranch_vccnz .LBB0_1188
	s_andn2_b64 vcc, exec, s[14:15]
	s_cbranch_vccnz .LBB0_1187
	s_barrier
	s_branch .LBB0_1187

.LBB0_1281:
	ds_read_b128 v[146:149], v152
	ds_read_b128 v[156:159], v152 offset:1024
	ds_read_b128 v[160:163], v152 offset:2048
	ds_read_b128 v[164:167], v152 offset:3072
	ds_read_b128 v[168:171], v153
	ds_read_b128 v[172:175], v153 offset:1024
	ds_read_b128 v[176:179], v153 offset:2048
	ds_read_b128 v[180:183], v153 offset:3072
	s_add_u32 s40, s38, 0xfff00080
	s_addc_u32 s41, s39, -1
	s_cmp_eq_u32 s72, 60
	s_cselect_b32 s43, s27, s41
	s_cselect_b32 s42, s35, s40
	s_cselect_b32 s41, s15, s71
	s_cselect_b32 s40, s37, s70
	s_add_i32 m0, s49, 0xc000
	ds_read_b128 v[188:191], v154
	ds_read_b128 v[192:195], v154 offset:1024
	ds_read_b128 v[196:199], v154 offset:2048
	ds_read_b128 v[200:203], v154 offset:3072
	ds_read_b128 v[204:207], v154 offset:4096
	ds_read_b128 v[208:211], v154 offset:5120
	ds_read_b128 v[212:215], v154 offset:6144
	ds_read_b128 v[216:219], v154 offset:7168
	global_load_lds_dwordx4 v140, s[38:39]
	s_add_i32 m0, s49, 0xe000
	s_nop 0
	global_load_lds_dwordx4 v138, s[38:39]
	s_waitcnt vmcnt(8)
	s_waitcnt lgkmcnt(0)
	s_barrier
	s_setprio 1
	s_waitcnt lgkmcnt(0)
	v_mfma_f32_16x16x32_bf16 v[126:129], v[146:149], v[188:191], v[126:129]
	v_mfma_f32_16x16x32_bf16 v[122:125], v[160:163], v[188:191], v[122:125]
	v_mfma_f32_16x16x32_bf16 v[110:113], v[146:149], v[196:199], v[110:113]
	v_mfma_f32_16x16x32_bf16 v[106:109], v[160:163], v[196:199], v[106:109]
	v_mfma_f32_16x16x32_bf16 v[94:97], v[146:149], v[204:207], v[94:97]
	v_mfma_f32_16x16x32_bf16 v[90:93], v[160:163], v[204:207], v[90:93]
	v_mfma_f32_16x16x32_bf16 v[78:81], v[146:149], v[212:215], v[78:81]
	v_mfma_f32_16x16x32_bf16 v[74:77], v[160:163], v[212:215], v[74:77]
	v_mfma_f32_16x16x32_bf16 v[126:129], v[156:159], v[192:195], v[126:129]
	v_mfma_f32_16x16x32_bf16 v[122:125], v[164:167], v[192:195], v[122:125]
	v_mfma_f32_16x16x32_bf16 v[110:113], v[156:159], v[200:203], v[110:113]
	v_mfma_f32_16x16x32_bf16 v[106:109], v[164:167], v[200:203], v[106:109]
	v_mfma_f32_16x16x32_bf16 v[94:97], v[156:159], v[208:211], v[94:97]
	v_mfma_f32_16x16x32_bf16 v[90:93], v[164:167], v[208:211], v[90:93]
	v_mfma_f32_16x16x32_bf16 v[78:81], v[156:159], v[216:219], v[78:81]
	v_mfma_f32_16x16x32_bf16 v[74:77], v[164:167], v[216:219], v[74:77]
	s_setprio 0
	s_setprio 1
	v_mfma_f32_16x16x32_bf16 v[118:121], v[168:171], v[188:191], v[118:121]
	v_mfma_f32_16x16x32_bf16 v[114:117], v[176:179], v[188:191], v[114:117]
	v_mfma_f32_16x16x32_bf16 v[102:105], v[168:171], v[196:199], v[102:105]
	v_mfma_f32_16x16x32_bf16 v[98:101], v[176:179], v[196:199], v[98:101]
	v_mfma_f32_16x16x32_bf16 v[86:89], v[168:171], v[204:207], v[86:89]
	v_mfma_f32_16x16x32_bf16 v[82:85], v[176:179], v[204:207], v[82:85]
	v_mfma_f32_16x16x32_bf16 v[70:73], v[168:171], v[212:215], v[70:73]
	v_mfma_f32_16x16x32_bf16 v[66:69], v[176:179], v[212:215], v[66:69]
	v_mfma_f32_16x16x32_bf16 v[118:121], v[172:175], v[192:195], v[118:121]
	v_mfma_f32_16x16x32_bf16 v[114:117], v[180:183], v[192:195], v[114:117]
	v_mfma_f32_16x16x32_bf16 v[102:105], v[172:175], v[200:203], v[102:105]
	v_mfma_f32_16x16x32_bf16 v[98:101], v[180:183], v[200:203], v[98:101]
	v_mfma_f32_16x16x32_bf16 v[86:89], v[172:175], v[208:211], v[86:89]
	v_mfma_f32_16x16x32_bf16 v[82:85], v[180:183], v[208:211], v[82:85]
	v_mfma_f32_16x16x32_bf16 v[70:73], v[172:175], v[216:219], v[70:73]
	v_mfma_f32_16x16x32_bf16 v[66:69], v[180:183], v[216:219], v[66:69]
	s_setprio 0
	s_barrier
	s_add_i32 s73, s68, s47
	v_lshl_add_u64 v[184:185], s[40:41], 0, v[132:133]
	s_mov_b32 m0, s73
	ds_read_b128 v[188:191], v154 offset:16384
	ds_read_b128 v[192:195], v154 offset:17408
	ds_read_b128 v[196:199], v154 offset:18432
	ds_read_b128 v[200:203], v154 offset:19456
	ds_read_b128 v[204:207], v154 offset:20480
	ds_read_b128 v[208:211], v154 offset:21504
	ds_read_b128 v[212:215], v154 offset:22528
	ds_read_b128 v[216:219], v154 offset:23552
	global_load_lds_dwordx4 v[184:185], off
	s_add_i32 m0, s73, 0x2000
	s_add_u32 s74, s40, 0x100000
	v_lshl_add_u64 v[220:221], s[40:41], 0, v[136:137]
	s_addc_u32 s75, s41, 0
	s_add_i32 s73, s69, s47
	global_load_lds_dwordx4 v[220:221], off
	s_mov_b32 m0, s73
	v_lshl_add_u64 v[224:225], s[42:43], 0, v[134:135]
	global_load_lds_dwordx4 v132, s[74:75]
	s_add_i32 m0, s73, 0x2000
	s_nop 0
	global_load_lds_dwordx4 v136, s[74:75]
	v_lshl_add_u64 v[222:223], s[42:43], 0, v[130:131]
	s_mov_b32 m0, s49
	s_nop 0
	global_load_lds_dwordx4 v[222:223], off
	s_mov_b32 m0, s56
	s_nop 0
	global_load_lds_dwordx4 v[224:225], off
	s_waitcnt vmcnt(8)
	s_waitcnt lgkmcnt(0)
	s_barrier
	s_setprio 1
	s_waitcnt lgkmcnt(0)
	v_mfma_f32_16x16x32_bf16 v[62:65], v[146:149], v[188:191], v[62:65]
	v_mfma_f32_16x16x32_bf16 v[58:61], v[160:163], v[188:191], v[58:61]
	v_mfma_f32_16x16x32_bf16 v[46:49], v[146:149], v[196:199], v[46:49]
	v_mfma_f32_16x16x32_bf16 v[42:45], v[160:163], v[196:199], v[42:45]
	v_mfma_f32_16x16x32_bf16 v[30:33], v[146:149], v[204:207], v[30:33]
	v_mfma_f32_16x16x32_bf16 v[26:29], v[160:163], v[204:207], v[26:29]
	v_mfma_f32_16x16x32_bf16 v[14:17], v[146:149], v[212:215], v[14:17]
	v_mfma_f32_16x16x32_bf16 v[10:13], v[160:163], v[212:215], v[10:13]
	v_mfma_f32_16x16x32_bf16 v[62:65], v[156:159], v[192:195], v[62:65]
	v_mfma_f32_16x16x32_bf16 v[58:61], v[164:167], v[192:195], v[58:61]
	v_mfma_f32_16x16x32_bf16 v[46:49], v[156:159], v[200:203], v[46:49]
	v_mfma_f32_16x16x32_bf16 v[42:45], v[164:167], v[200:203], v[42:45]
	v_mfma_f32_16x16x32_bf16 v[30:33], v[156:159], v[208:211], v[30:33]
	v_mfma_f32_16x16x32_bf16 v[26:29], v[164:167], v[208:211], v[26:29]
	v_mfma_f32_16x16x32_bf16 v[14:17], v[156:159], v[216:219], v[14:17]
	v_mfma_f32_16x16x32_bf16 v[10:13], v[164:167], v[216:219], v[10:13]
	s_setprio 0
	s_setprio 1
	v_mfma_f32_16x16x32_bf16 v[54:57], v[168:171], v[188:191], v[54:57]
	v_mfma_f32_16x16x32_bf16 v[50:53], v[176:179], v[188:191], v[50:53]
	v_mfma_f32_16x16x32_bf16 v[38:41], v[168:171], v[196:199], v[38:41]
	v_mfma_f32_16x16x32_bf16 v[34:37], v[176:179], v[196:199], v[34:37]
	v_mfma_f32_16x16x32_bf16 v[22:25], v[168:171], v[204:207], v[22:25]
	v_mfma_f32_16x16x32_bf16 v[18:21], v[176:179], v[204:207], v[18:21]
	v_mfma_f32_16x16x32_bf16 v[6:9], v[168:171], v[212:215], v[6:9]
	v_mfma_f32_16x16x32_bf16 v[2:5], v[176:179], v[212:215], v[2:5]
	v_mfma_f32_16x16x32_bf16 v[54:57], v[172:175], v[192:195], v[54:57]
	v_mfma_f32_16x16x32_bf16 v[50:53], v[180:183], v[192:195], v[50:53]
	v_mfma_f32_16x16x32_bf16 v[38:41], v[172:175], v[200:203], v[38:41]
	v_mfma_f32_16x16x32_bf16 v[34:37], v[180:183], v[200:203], v[34:37]
	v_mfma_f32_16x16x32_bf16 v[22:25], v[172:175], v[208:211], v[22:25]
	v_mfma_f32_16x16x32_bf16 v[18:21], v[180:183], v[208:211], v[18:21]
	v_mfma_f32_16x16x32_bf16 v[6:9], v[172:175], v[216:219], v[6:9]
	v_mfma_f32_16x16x32_bf16 v[2:5], v[180:183], v[216:219], v[2:5]
	s_setprio 0
	s_barrier
	s_add_i32 s73, 0, 0x18000
	s_add_i32 s74, 0, 0x1c000
	v_add_u32_e32 v164, s73, v150
	v_add_u32_e32 v180, s74, v150
	ds_read_b128 v[146:149], v164
	ds_read_b128 v[156:159], v164 offset:1024
	ds_read_b128 v[160:163], v164 offset:2048
	ds_read_b128 v[164:167], v164 offset:3072
	ds_read_b128 v[168:171], v180
	ds_read_b128 v[172:175], v180 offset:1024
	ds_read_b128 v[176:179], v180 offset:2048
	ds_read_b128 v[180:183], v180 offset:3072
	s_add_u32 s42, s42, 0x100000
	s_addc_u32 s43, s43, 0
	s_mov_b32 m0, s57
	ds_read_b128 v[188:191], v154 offset:32768
	ds_read_b128 v[192:195], v154 offset:33792
	ds_read_b128 v[196:199], v154 offset:34816
	ds_read_b128 v[200:203], v154 offset:35840
	ds_read_b128 v[204:207], v154 offset:36864
	ds_read_b128 v[208:211], v154 offset:37888
	ds_read_b128 v[212:215], v154 offset:38912
	ds_read_b128 v[216:219], v154 offset:39936
	global_load_lds_dwordx4 v130, s[42:43]
	s_mov_b32 m0, s60
	s_nop 0
	global_load_lds_dwordx4 v134, s[42:43]
	s_waitcnt vmcnt(8)
	s_waitcnt lgkmcnt(0)
	s_barrier
	s_setprio 1
	s_waitcnt lgkmcnt(0)
	v_mfma_f32_16x16x32_bf16 v[126:129], v[146:149], v[188:191], v[126:129]
	v_mfma_f32_16x16x32_bf16 v[122:125], v[160:163], v[188:191], v[122:125]
	v_mfma_f32_16x16x32_bf16 v[110:113], v[146:149], v[196:199], v[110:113]
	v_mfma_f32_16x16x32_bf16 v[106:109], v[160:163], v[196:199], v[106:109]
	v_mfma_f32_16x16x32_bf16 v[94:97], v[146:149], v[204:207], v[94:97]
	v_mfma_f32_16x16x32_bf16 v[90:93], v[160:163], v[204:207], v[90:93]
	v_mfma_f32_16x16x32_bf16 v[78:81], v[146:149], v[212:215], v[78:81]
	v_mfma_f32_16x16x32_bf16 v[74:77], v[160:163], v[212:215], v[74:77]
	v_mfma_f32_16x16x32_bf16 v[126:129], v[156:159], v[192:195], v[126:129]
	v_mfma_f32_16x16x32_bf16 v[122:125], v[164:167], v[192:195], v[122:125]
	v_mfma_f32_16x16x32_bf16 v[110:113], v[156:159], v[200:203], v[110:113]
	v_mfma_f32_16x16x32_bf16 v[106:109], v[164:167], v[200:203], v[106:109]
	v_mfma_f32_16x16x32_bf16 v[94:97], v[156:159], v[208:211], v[94:97]
	v_mfma_f32_16x16x32_bf16 v[90:93], v[164:167], v[208:211], v[90:93]
	v_mfma_f32_16x16x32_bf16 v[78:81], v[156:159], v[216:219], v[78:81]
	v_mfma_f32_16x16x32_bf16 v[74:77], v[164:167], v[216:219], v[74:77]
	s_setprio 0
	s_setprio 1
	v_mfma_f32_16x16x32_bf16 v[118:121], v[168:171], v[188:191], v[118:121]
	v_mfma_f32_16x16x32_bf16 v[114:117], v[176:179], v[188:191], v[114:117]
	v_mfma_f32_16x16x32_bf16 v[102:105], v[168:171], v[196:199], v[102:105]
	v_mfma_f32_16x16x32_bf16 v[98:101], v[176:179], v[196:199], v[98:101]
	v_mfma_f32_16x16x32_bf16 v[86:89], v[168:171], v[204:207], v[86:89]
	v_mfma_f32_16x16x32_bf16 v[82:85], v[176:179], v[204:207], v[82:85]
	v_mfma_f32_16x16x32_bf16 v[70:73], v[168:171], v[212:215], v[70:73]
	v_mfma_f32_16x16x32_bf16 v[66:69], v[176:179], v[212:215], v[66:69]
	v_mfma_f32_16x16x32_bf16 v[118:121], v[172:175], v[192:195], v[118:121]
	v_mfma_f32_16x16x32_bf16 v[114:117], v[180:183], v[192:195], v[114:117]
	v_mfma_f32_16x16x32_bf16 v[102:105], v[172:175], v[200:203], v[102:105]
	v_mfma_f32_16x16x32_bf16 v[98:101], v[180:183], v[200:203], v[98:101]
	v_mfma_f32_16x16x32_bf16 v[86:89], v[172:175], v[208:211], v[86:89]
	v_mfma_f32_16x16x32_bf16 v[82:85], v[180:183], v[208:211], v[82:85]
	v_mfma_f32_16x16x32_bf16 v[70:73], v[172:175], v[216:219], v[70:73]
	v_mfma_f32_16x16x32_bf16 v[66:69], v[180:183], v[216:219], v[66:69]
	s_setprio 0
	s_barrier
	s_add_i32 s42, s73, s47
	v_lshl_add_u64 v[184:185], v[184:185], 0, s[22:23]
	s_mov_b32 m0, s42
	ds_read_b128 v[188:191], v154 offset:49152
	ds_read_b128 v[192:195], v154 offset:50176
	ds_read_b128 v[196:199], v154 offset:51200
	ds_read_b128 v[200:203], v154 offset:52224
	ds_read_b128 v[204:207], v154 offset:53248
	ds_read_b128 v[208:211], v154 offset:54272
	ds_read_b128 v[212:215], v154 offset:55296
	ds_read_b128 v[216:219], v154 offset:56320
	global_load_lds_dwordx4 v[184:185], off
	s_add_i32 m0, s42, 0x2000
	s_add_u32 s40, s40, 0x100080
	v_lshl_add_u64 v[184:185], v[220:221], 0, s[22:23]
	s_addc_u32 s41, s41, 0
	s_add_i32 s42, s74, s47
	global_load_lds_dwordx4 v[184:185], off
	s_mov_b32 m0, s42
	s_nop 0
	global_load_lds_dwordx4 v132, s[40:41]
	s_add_i32 m0, s42, 0x2000
	s_nop 0
	global_load_lds_dwordx4 v136, s[40:41]
	v_lshl_add_u64 v[184:185], v[222:223], 0, s[22:23]
	s_mov_b32 m0, s63
	s_nop 0
	global_load_lds_dwordx4 v[184:185], off
	v_lshl_add_u64 v[184:185], v[224:225], 0, s[22:23]
	s_mov_b32 m0, s64
	s_nop 0
	global_load_lds_dwordx4 v[184:185], off
	s_waitcnt vmcnt(8)
	s_waitcnt lgkmcnt(0)
	s_barrier
	s_setprio 1
	s_waitcnt lgkmcnt(0)
	v_mfma_f32_16x16x32_bf16 v[62:65], v[146:149], v[188:191], v[62:65]
	v_mfma_f32_16x16x32_bf16 v[58:61], v[160:163], v[188:191], v[58:61]
	v_mfma_f32_16x16x32_bf16 v[46:49], v[146:149], v[196:199], v[46:49]
	v_mfma_f32_16x16x32_bf16 v[42:45], v[160:163], v[196:199], v[42:45]
	v_mfma_f32_16x16x32_bf16 v[30:33], v[146:149], v[204:207], v[30:33]
	v_mfma_f32_16x16x32_bf16 v[26:29], v[160:163], v[204:207], v[26:29]
	v_mfma_f32_16x16x32_bf16 v[14:17], v[146:149], v[212:215], v[14:17]
	v_mfma_f32_16x16x32_bf16 v[10:13], v[160:163], v[212:215], v[10:13]
	v_mfma_f32_16x16x32_bf16 v[62:65], v[156:159], v[192:195], v[62:65]
	v_mfma_f32_16x16x32_bf16 v[58:61], v[164:167], v[192:195], v[58:61]
	v_mfma_f32_16x16x32_bf16 v[46:49], v[156:159], v[200:203], v[46:49]
	v_mfma_f32_16x16x32_bf16 v[42:45], v[164:167], v[200:203], v[42:45]
	v_mfma_f32_16x16x32_bf16 v[30:33], v[156:159], v[208:211], v[30:33]
	v_mfma_f32_16x16x32_bf16 v[26:29], v[164:167], v[208:211], v[26:29]
	v_mfma_f32_16x16x32_bf16 v[14:17], v[156:159], v[216:219], v[14:17]
	v_mfma_f32_16x16x32_bf16 v[10:13], v[164:167], v[216:219], v[10:13]
	s_setprio 0
	s_setprio 1
	v_mfma_f32_16x16x32_bf16 v[54:57], v[168:171], v[188:191], v[54:57]
	v_mfma_f32_16x16x32_bf16 v[50:53], v[176:179], v[188:191], v[50:53]
	v_mfma_f32_16x16x32_bf16 v[38:41], v[168:171], v[196:199], v[38:41]
	v_mfma_f32_16x16x32_bf16 v[34:37], v[176:179], v[196:199], v[34:37]
	v_mfma_f32_16x16x32_bf16 v[22:25], v[168:171], v[204:207], v[22:25]
	v_mfma_f32_16x16x32_bf16 v[18:21], v[176:179], v[204:207], v[18:21]
	v_mfma_f32_16x16x32_bf16 v[6:9], v[168:171], v[212:215], v[6:9]
	v_mfma_f32_16x16x32_bf16 v[2:5], v[176:179], v[212:215], v[2:5]
	v_mfma_f32_16x16x32_bf16 v[54:57], v[172:175], v[192:195], v[54:57]
	v_mfma_f32_16x16x32_bf16 v[50:53], v[180:183], v[192:195], v[50:53]
	v_mfma_f32_16x16x32_bf16 v[38:41], v[172:175], v[200:203], v[38:41]
	v_mfma_f32_16x16x32_bf16 v[34:37], v[180:183], v[200:203], v[34:37]
	v_mfma_f32_16x16x32_bf16 v[22:25], v[172:175], v[208:211], v[22:25]
	v_mfma_f32_16x16x32_bf16 v[18:21], v[180:183], v[208:211], v[18:21]
	v_mfma_f32_16x16x32_bf16 v[6:9], v[172:175], v[216:219], v[6:9]
	v_mfma_f32_16x16x32_bf16 v[2:5], v[180:183], v[216:219], v[2:5]
	s_setprio 0
	s_barrier
	s_add_i32 s72, s72, 2
	s_add_u32 s70, s70, 0x100
	s_addc_u32 s71, s71, 0
	s_add_u32 s38, s38, 0x100
	s_addc_u32 s39, s39, 0
	s_cmp_gt_u32 s72, 61
	s_cbranch_scc0 .LBB0_1281
	s_and_b64 vcc, exec, s[24:25]
	s_cbranch_vccz .LBB0_1284
	s_barrier

.LBB0_1368:
	ds_read_b128 v[146:149], v196
	ds_read_b128 v[150:153], v196 offset:1024
	ds_read_b128 v[154:157], v196 offset:2048
	ds_read_b128 v[158:161], v196 offset:3072
	ds_read_b128 v[162:165], v197
	ds_read_b128 v[166:169], v197 offset:1024
	ds_read_b128 v[170:173], v197 offset:2048
	ds_read_b128 v[174:177], v197 offset:3072
	s_add_u32 s34, s30, 0xfff00080
	s_addc_u32 s35, s31, -1
	s_cmp_eq_u32 s71, 60
	s_cselect_b32 s37, s11, s35
	s_cselect_b32 s36, s27, s34
	s_cselect_b32 s35, s25, s70
	s_cselect_b32 s34, s24, s69
	s_add_i32 m0, s42, 0xc000
	ds_read_b128 v[202:205], v198
	ds_read_b128 v[206:209], v198 offset:1024
	ds_read_b128 v[210:213], v198 offset:2048
	ds_read_b128 v[214:217], v198 offset:3072
	ds_read_b128 v[218:221], v198 offset:4096
	ds_read_b128 v[222:225], v198 offset:5120
	ds_read_b128 v[226:229], v198 offset:6144
	ds_read_b128 v[230:233], v198 offset:7168
	global_load_lds_dwordx4 v140, s[30:31]
	s_add_i32 m0, s42, 0xe000
	s_nop 0
	global_load_lds_dwordx4 v138, s[30:31]
	s_waitcnt vmcnt(8)
	s_waitcnt lgkmcnt(0)
	s_barrier
	s_setprio 1
	s_waitcnt lgkmcnt(0)
	v_mfma_f32_16x16x32_bf16 v[126:129], v[146:149], v[202:205], v[126:129]
	v_mfma_f32_16x16x32_bf16 v[122:125], v[154:157], v[202:205], v[122:125]
	v_mfma_f32_16x16x32_bf16 v[110:113], v[146:149], v[210:213], v[110:113]
	v_mfma_f32_16x16x32_bf16 v[106:109], v[154:157], v[210:213], v[106:109]
	v_mfma_f32_16x16x32_bf16 v[94:97], v[146:149], v[218:221], v[94:97]
	v_mfma_f32_16x16x32_bf16 v[90:93], v[154:157], v[218:221], v[90:93]
	v_mfma_f32_16x16x32_bf16 v[78:81], v[146:149], v[226:229], v[78:81]
	v_mfma_f32_16x16x32_bf16 v[74:77], v[154:157], v[226:229], v[74:77]
	v_mfma_f32_16x16x32_bf16 v[126:129], v[150:153], v[206:209], v[126:129]
	v_mfma_f32_16x16x32_bf16 v[122:125], v[158:161], v[206:209], v[122:125]
	v_mfma_f32_16x16x32_bf16 v[110:113], v[150:153], v[214:217], v[110:113]
	v_mfma_f32_16x16x32_bf16 v[106:109], v[158:161], v[214:217], v[106:109]
	v_mfma_f32_16x16x32_bf16 v[94:97], v[150:153], v[222:225], v[94:97]
	v_mfma_f32_16x16x32_bf16 v[90:93], v[158:161], v[222:225], v[90:93]
	v_mfma_f32_16x16x32_bf16 v[78:81], v[150:153], v[230:233], v[78:81]
	v_mfma_f32_16x16x32_bf16 v[74:77], v[158:161], v[230:233], v[74:77]
	s_setprio 0
	s_setprio 1
	v_mfma_f32_16x16x32_bf16 v[118:121], v[162:165], v[202:205], v[118:121]
	v_mfma_f32_16x16x32_bf16 v[114:117], v[170:173], v[202:205], v[114:117]
	v_mfma_f32_16x16x32_bf16 v[102:105], v[162:165], v[210:213], v[102:105]
	v_mfma_f32_16x16x32_bf16 v[98:101], v[170:173], v[210:213], v[98:101]
	v_mfma_f32_16x16x32_bf16 v[86:89], v[162:165], v[218:221], v[86:89]
	v_mfma_f32_16x16x32_bf16 v[82:85], v[170:173], v[218:221], v[82:85]
	v_mfma_f32_16x16x32_bf16 v[70:73], v[162:165], v[226:229], v[70:73]
	v_mfma_f32_16x16x32_bf16 v[66:69], v[170:173], v[226:229], v[66:69]
	v_mfma_f32_16x16x32_bf16 v[118:121], v[166:169], v[206:209], v[118:121]
	v_mfma_f32_16x16x32_bf16 v[114:117], v[174:177], v[206:209], v[114:117]
	v_mfma_f32_16x16x32_bf16 v[102:105], v[166:169], v[214:217], v[102:105]
	v_mfma_f32_16x16x32_bf16 v[98:101], v[174:177], v[214:217], v[98:101]
	v_mfma_f32_16x16x32_bf16 v[86:89], v[166:169], v[222:225], v[86:89]
	v_mfma_f32_16x16x32_bf16 v[82:85], v[174:177], v[222:225], v[82:85]
	v_mfma_f32_16x16x32_bf16 v[70:73], v[166:169], v[230:233], v[70:73]
	v_mfma_f32_16x16x32_bf16 v[66:69], v[174:177], v[230:233], v[66:69]
	s_setprio 0
	s_barrier
	s_add_i32 s72, s62, s41
	v_lshl_add_u64 v[234:235], s[34:35], 0, v[134:135]
	s_mov_b32 m0, s72
	ds_read_b128 v[202:205], v198 offset:16384
	ds_read_b128 v[206:209], v198 offset:17408
	ds_read_b128 v[210:213], v198 offset:18432
	ds_read_b128 v[214:217], v198 offset:19456
	ds_read_b128 v[218:221], v198 offset:20480
	ds_read_b128 v[222:225], v198 offset:21504
	ds_read_b128 v[226:229], v198 offset:22528
	ds_read_b128 v[230:233], v198 offset:23552
	global_load_lds_dwordx4 v[234:235], off
	s_add_i32 m0, s72, 0x2000
	s_add_u32 s72, s34, 0x100000
	v_lshl_add_u64 v[236:237], s[34:35], 0, v[130:131]
	s_addc_u32 s73, s35, 0
	s_add_i32 s74, s63, s41
	global_load_lds_dwordx4 v[236:237], off
	s_mov_b32 m0, s74
	v_lshl_add_u64 v[240:241], s[36:37], 0, v[132:133]
	global_load_lds_dwordx4 v134, s[72:73]
	s_add_i32 m0, s74, 0x2000
	s_nop 0
	global_load_lds_dwordx4 v130, s[72:73]
	v_lshl_add_u64 v[238:239], s[36:37], 0, v[136:137]
	s_mov_b32 m0, s42
	s_nop 0
	global_load_lds_dwordx4 v[238:239], off
	s_mov_b32 m0, s43
	s_nop 0
	global_load_lds_dwordx4 v[240:241], off
	s_waitcnt vmcnt(8)
	s_waitcnt lgkmcnt(0)
	s_barrier
	s_setprio 1
	s_waitcnt lgkmcnt(0)
	v_mfma_f32_16x16x32_bf16 v[62:65], v[146:149], v[202:205], v[62:65]
	v_mfma_f32_16x16x32_bf16 v[58:61], v[154:157], v[202:205], v[58:61]
	v_mfma_f32_16x16x32_bf16 v[46:49], v[146:149], v[210:213], v[46:49]
	v_mfma_f32_16x16x32_bf16 v[42:45], v[154:157], v[210:213], v[42:45]
	v_mfma_f32_16x16x32_bf16 v[30:33], v[146:149], v[218:221], v[30:33]
	v_mfma_f32_16x16x32_bf16 v[26:29], v[154:157], v[218:221], v[26:29]
	v_mfma_f32_16x16x32_bf16 v[14:17], v[146:149], v[226:229], v[14:17]
	v_mfma_f32_16x16x32_bf16 v[10:13], v[154:157], v[226:229], v[10:13]
	v_mfma_f32_16x16x32_bf16 v[62:65], v[150:153], v[206:209], v[62:65]
	v_mfma_f32_16x16x32_bf16 v[58:61], v[158:161], v[206:209], v[58:61]
	v_mfma_f32_16x16x32_bf16 v[46:49], v[150:153], v[214:217], v[46:49]
	v_mfma_f32_16x16x32_bf16 v[42:45], v[158:161], v[214:217], v[42:45]
	v_mfma_f32_16x16x32_bf16 v[30:33], v[150:153], v[222:225], v[30:33]
	v_mfma_f32_16x16x32_bf16 v[26:29], v[158:161], v[222:225], v[26:29]
	v_mfma_f32_16x16x32_bf16 v[14:17], v[150:153], v[230:233], v[14:17]
	v_mfma_f32_16x16x32_bf16 v[10:13], v[158:161], v[230:233], v[10:13]
	s_setprio 0
	s_setprio 1
	v_mfma_f32_16x16x32_bf16 v[54:57], v[162:165], v[202:205], v[54:57]
	v_mfma_f32_16x16x32_bf16 v[50:53], v[170:173], v[202:205], v[50:53]
	v_mfma_f32_16x16x32_bf16 v[38:41], v[162:165], v[210:213], v[38:41]
	v_mfma_f32_16x16x32_bf16 v[34:37], v[170:173], v[210:213], v[34:37]
	v_mfma_f32_16x16x32_bf16 v[22:25], v[162:165], v[218:221], v[22:25]
	v_mfma_f32_16x16x32_bf16 v[18:21], v[170:173], v[218:221], v[18:21]
	v_mfma_f32_16x16x32_bf16 v[6:9], v[162:165], v[226:229], v[6:9]
	v_mfma_f32_16x16x32_bf16 v[2:5], v[170:173], v[226:229], v[2:5]
	v_mfma_f32_16x16x32_bf16 v[54:57], v[166:169], v[206:209], v[54:57]
	v_mfma_f32_16x16x32_bf16 v[50:53], v[174:177], v[206:209], v[50:53]
	v_mfma_f32_16x16x32_bf16 v[38:41], v[166:169], v[214:217], v[38:41]
	v_mfma_f32_16x16x32_bf16 v[34:37], v[174:177], v[214:217], v[34:37]
	v_mfma_f32_16x16x32_bf16 v[22:25], v[166:169], v[222:225], v[22:25]
	v_mfma_f32_16x16x32_bf16 v[18:21], v[174:177], v[222:225], v[18:21]
	v_mfma_f32_16x16x32_bf16 v[6:9], v[166:169], v[230:233], v[6:9]
	v_mfma_f32_16x16x32_bf16 v[2:5], v[174:177], v[230:233], v[2:5]
	s_setprio 0
	s_barrier
	s_add_i32 s72, 0, 0x18000
	s_add_i32 s73, 0, 0x1c000
	v_add_u32_e32 v158, s72, v178
	v_add_u32_e32 v174, s73, v178
	ds_read_b128 v[146:149], v158
	ds_read_b128 v[150:153], v158 offset:1024
	ds_read_b128 v[154:157], v158 offset:2048
	ds_read_b128 v[158:161], v158 offset:3072
	ds_read_b128 v[162:165], v174
	ds_read_b128 v[166:169], v174 offset:1024
	ds_read_b128 v[170:173], v174 offset:2048
	ds_read_b128 v[174:177], v174 offset:3072
	s_add_u32 s36, s36, 0x100000
	s_addc_u32 s37, s37, 0
	s_mov_b32 m0, s44
	ds_read_b128 v[202:205], v198 offset:32768
	ds_read_b128 v[206:209], v198 offset:33792
	ds_read_b128 v[210:213], v198 offset:34816
	ds_read_b128 v[214:217], v198 offset:35840
	ds_read_b128 v[218:221], v198 offset:36864
	ds_read_b128 v[222:225], v198 offset:37888
	ds_read_b128 v[226:229], v198 offset:38912
	ds_read_b128 v[230:233], v198 offset:39936
	global_load_lds_dwordx4 v136, s[36:37]
	s_mov_b32 m0, s45
	s_nop 0
	global_load_lds_dwordx4 v132, s[36:37]
	s_waitcnt vmcnt(8)
	s_waitcnt lgkmcnt(0)
	s_barrier
	s_setprio 1
	s_waitcnt lgkmcnt(0)
	v_mfma_f32_16x16x32_bf16 v[126:129], v[146:149], v[202:205], v[126:129]
	v_mfma_f32_16x16x32_bf16 v[122:125], v[154:157], v[202:205], v[122:125]
	v_mfma_f32_16x16x32_bf16 v[110:113], v[146:149], v[210:213], v[110:113]
	v_mfma_f32_16x16x32_bf16 v[106:109], v[154:157], v[210:213], v[106:109]
	v_mfma_f32_16x16x32_bf16 v[94:97], v[146:149], v[218:221], v[94:97]
	v_mfma_f32_16x16x32_bf16 v[90:93], v[154:157], v[218:221], v[90:93]
	v_mfma_f32_16x16x32_bf16 v[78:81], v[146:149], v[226:229], v[78:81]
	v_mfma_f32_16x16x32_bf16 v[74:77], v[154:157], v[226:229], v[74:77]
	v_mfma_f32_16x16x32_bf16 v[126:129], v[150:153], v[206:209], v[126:129]
	v_mfma_f32_16x16x32_bf16 v[122:125], v[158:161], v[206:209], v[122:125]
	v_mfma_f32_16x16x32_bf16 v[110:113], v[150:153], v[214:217], v[110:113]
	v_mfma_f32_16x16x32_bf16 v[106:109], v[158:161], v[214:217], v[106:109]
	v_mfma_f32_16x16x32_bf16 v[94:97], v[150:153], v[222:225], v[94:97]
	v_mfma_f32_16x16x32_bf16 v[90:93], v[158:161], v[222:225], v[90:93]
	v_mfma_f32_16x16x32_bf16 v[78:81], v[150:153], v[230:233], v[78:81]
	v_mfma_f32_16x16x32_bf16 v[74:77], v[158:161], v[230:233], v[74:77]
	s_setprio 0
	s_setprio 1
	v_mfma_f32_16x16x32_bf16 v[118:121], v[162:165], v[202:205], v[118:121]
	v_mfma_f32_16x16x32_bf16 v[114:117], v[170:173], v[202:205], v[114:117]
	v_mfma_f32_16x16x32_bf16 v[102:105], v[162:165], v[210:213], v[102:105]
	v_mfma_f32_16x16x32_bf16 v[98:101], v[170:173], v[210:213], v[98:101]
	v_mfma_f32_16x16x32_bf16 v[86:89], v[162:165], v[218:221], v[86:89]
	v_mfma_f32_16x16x32_bf16 v[82:85], v[170:173], v[218:221], v[82:85]
	v_mfma_f32_16x16x32_bf16 v[70:73], v[162:165], v[226:229], v[70:73]
	v_mfma_f32_16x16x32_bf16 v[66:69], v[170:173], v[226:229], v[66:69]
	v_mfma_f32_16x16x32_bf16 v[118:121], v[166:169], v[206:209], v[118:121]
	v_mfma_f32_16x16x32_bf16 v[114:117], v[174:177], v[206:209], v[114:117]
	v_mfma_f32_16x16x32_bf16 v[102:105], v[166:169], v[214:217], v[102:105]
	v_mfma_f32_16x16x32_bf16 v[98:101], v[174:177], v[214:217], v[98:101]
	v_mfma_f32_16x16x32_bf16 v[86:89], v[166:169], v[222:225], v[86:89]
	v_mfma_f32_16x16x32_bf16 v[82:85], v[174:177], v[222:225], v[82:85]
	v_mfma_f32_16x16x32_bf16 v[70:73], v[166:169], v[230:233], v[70:73]
	v_mfma_f32_16x16x32_bf16 v[66:69], v[174:177], v[230:233], v[66:69]
	s_setprio 0
	s_barrier
	s_add_i32 s36, s72, s41
	v_lshl_add_u64 v[234:235], v[234:235], 0, s[20:21]
	s_mov_b32 m0, s36
	ds_read_b128 v[202:205], v198 offset:49152
	ds_read_b128 v[206:209], v198 offset:50176
	ds_read_b128 v[210:213], v198 offset:51200
	ds_read_b128 v[214:217], v198 offset:52224
	ds_read_b128 v[218:221], v198 offset:53248
	ds_read_b128 v[222:225], v198 offset:54272
	ds_read_b128 v[226:229], v198 offset:55296
	ds_read_b128 v[230:233], v198 offset:56320
	global_load_lds_dwordx4 v[234:235], off
	s_add_i32 m0, s36, 0x2000
	s_add_u32 s34, s34, 0x100080
	v_lshl_add_u64 v[234:235], v[236:237], 0, s[20:21]
	s_addc_u32 s35, s35, 0
	s_add_i32 s36, s73, s41
	global_load_lds_dwordx4 v[234:235], off
	s_mov_b32 m0, s36
	s_nop 0
	global_load_lds_dwordx4 v134, s[34:35]
	s_add_i32 m0, s36, 0x2000
	s_nop 0
	global_load_lds_dwordx4 v130, s[34:35]
	v_lshl_add_u64 v[234:235], v[238:239], 0, s[20:21]
	s_mov_b32 m0, s56
	s_nop 0
	global_load_lds_dwordx4 v[234:235], off
	v_lshl_add_u64 v[234:235], v[240:241], 0, s[20:21]
	s_mov_b32 m0, s57
	s_nop 0
	global_load_lds_dwordx4 v[234:235], off
	s_waitcnt vmcnt(8)
	s_waitcnt lgkmcnt(0)
	s_barrier
	s_setprio 1
	s_waitcnt lgkmcnt(0)
	v_mfma_f32_16x16x32_bf16 v[62:65], v[146:149], v[202:205], v[62:65]
	v_mfma_f32_16x16x32_bf16 v[58:61], v[154:157], v[202:205], v[58:61]
	v_mfma_f32_16x16x32_bf16 v[46:49], v[146:149], v[210:213], v[46:49]
	v_mfma_f32_16x16x32_bf16 v[42:45], v[154:157], v[210:213], v[42:45]
	v_mfma_f32_16x16x32_bf16 v[30:33], v[146:149], v[218:221], v[30:33]
	v_mfma_f32_16x16x32_bf16 v[26:29], v[154:157], v[218:221], v[26:29]
	v_mfma_f32_16x16x32_bf16 v[14:17], v[146:149], v[226:229], v[14:17]
	v_mfma_f32_16x16x32_bf16 v[10:13], v[154:157], v[226:229], v[10:13]
	v_mfma_f32_16x16x32_bf16 v[62:65], v[150:153], v[206:209], v[62:65]
	v_mfma_f32_16x16x32_bf16 v[58:61], v[158:161], v[206:209], v[58:61]
	v_mfma_f32_16x16x32_bf16 v[46:49], v[150:153], v[214:217], v[46:49]
	v_mfma_f32_16x16x32_bf16 v[42:45], v[158:161], v[214:217], v[42:45]
	v_mfma_f32_16x16x32_bf16 v[30:33], v[150:153], v[222:225], v[30:33]
	v_mfma_f32_16x16x32_bf16 v[26:29], v[158:161], v[222:225], v[26:29]
	v_mfma_f32_16x16x32_bf16 v[14:17], v[150:153], v[230:233], v[14:17]
	v_mfma_f32_16x16x32_bf16 v[10:13], v[158:161], v[230:233], v[10:13]
	s_setprio 0
	s_setprio 1
	v_mfma_f32_16x16x32_bf16 v[54:57], v[162:165], v[202:205], v[54:57]
	v_mfma_f32_16x16x32_bf16 v[50:53], v[170:173], v[202:205], v[50:53]
	v_mfma_f32_16x16x32_bf16 v[38:41], v[162:165], v[210:213], v[38:41]
	v_mfma_f32_16x16x32_bf16 v[34:37], v[170:173], v[210:213], v[34:37]
	v_mfma_f32_16x16x32_bf16 v[22:25], v[162:165], v[218:221], v[22:25]
	v_mfma_f32_16x16x32_bf16 v[18:21], v[170:173], v[218:221], v[18:21]
	v_mfma_f32_16x16x32_bf16 v[6:9], v[162:165], v[226:229], v[6:9]
	v_mfma_f32_16x16x32_bf16 v[2:5], v[170:173], v[226:229], v[2:5]
	v_mfma_f32_16x16x32_bf16 v[54:57], v[166:169], v[206:209], v[54:57]
	v_mfma_f32_16x16x32_bf16 v[50:53], v[174:177], v[206:209], v[50:53]
	v_mfma_f32_16x16x32_bf16 v[38:41], v[166:169], v[214:217], v[38:41]
	v_mfma_f32_16x16x32_bf16 v[34:37], v[174:177], v[214:217], v[34:37]
	v_mfma_f32_16x16x32_bf16 v[22:25], v[166:169], v[222:225], v[22:25]
	v_mfma_f32_16x16x32_bf16 v[18:21], v[174:177], v[222:225], v[18:21]
	v_mfma_f32_16x16x32_bf16 v[6:9], v[166:169], v[230:233], v[6:9]
	v_mfma_f32_16x16x32_bf16 v[2:5], v[174:177], v[230:233], v[2:5]
	s_setprio 0
	s_barrier
	s_add_i32 s71, s71, 2
	s_add_u32 s69, s69, 0x100
	s_addc_u32 s70, s70, 0
	s_add_u32 s30, s30, 0x100
	s_addc_u32 s31, s31, 0
	s_cmp_gt_u32 s71, 61
	s_cbranch_scc0 .LBB0_1368
	s_and_b64 vcc, exec, s[22:23]
	s_cbranch_vccz .LBB0_1371
	s_barrier

.LBB0_1483:
	ds_read_b128 v[146:149], v152
	ds_read_b128 v[156:159], v152 offset:1024
	ds_read_b128 v[160:163], v152 offset:2048
	ds_read_b128 v[164:167], v152 offset:3072
	ds_read_b128 v[168:171], v153
	ds_read_b128 v[172:175], v153 offset:1024
	ds_read_b128 v[176:179], v153 offset:2048
	ds_read_b128 v[180:183], v153 offset:3072
	s_add_u32 s38, s10, 0xfffc0080
	s_addc_u32 s39, s11, -1
	s_cmp_eq_u32 s66, 12
	s_cselect_b32 s41, s25, s39
	s_cselect_b32 s40, s27, s38
	s_cselect_b32 s39, s29, s65
	s_cselect_b32 s38, s28, s64
	s_add_i32 m0, s35, 0xc000
	ds_read_b128 v[188:191], v154
	ds_read_b128 v[192:195], v154 offset:1024
	ds_read_b128 v[196:199], v154 offset:2048
	ds_read_b128 v[200:203], v154 offset:3072
	ds_read_b128 v[204:207], v154 offset:4096
	ds_read_b128 v[208:211], v154 offset:5120
	ds_read_b128 v[212:215], v154 offset:6144
	ds_read_b128 v[216:219], v154 offset:7168
	global_load_lds_dwordx4 v140, s[10:11]
	s_add_i32 m0, s35, 0xe000
	s_nop 0
	global_load_lds_dwordx4 v138, s[10:11]
	s_waitcnt vmcnt(8)
	s_waitcnt lgkmcnt(0)
	s_barrier
	s_setprio 1
	s_waitcnt lgkmcnt(0)
	v_mfma_f32_16x16x32_bf16 v[126:129], v[146:149], v[188:191], v[126:129]
	v_mfma_f32_16x16x32_bf16 v[122:125], v[160:163], v[188:191], v[122:125]
	v_mfma_f32_16x16x32_bf16 v[110:113], v[146:149], v[196:199], v[110:113]
	v_mfma_f32_16x16x32_bf16 v[106:109], v[160:163], v[196:199], v[106:109]
	v_mfma_f32_16x16x32_bf16 v[94:97], v[146:149], v[204:207], v[94:97]
	v_mfma_f32_16x16x32_bf16 v[90:93], v[160:163], v[204:207], v[90:93]
	v_mfma_f32_16x16x32_bf16 v[78:81], v[146:149], v[212:215], v[78:81]
	v_mfma_f32_16x16x32_bf16 v[74:77], v[160:163], v[212:215], v[74:77]
	v_mfma_f32_16x16x32_bf16 v[126:129], v[156:159], v[192:195], v[126:129]
	v_mfma_f32_16x16x32_bf16 v[122:125], v[164:167], v[192:195], v[122:125]
	v_mfma_f32_16x16x32_bf16 v[110:113], v[156:159], v[200:203], v[110:113]
	v_mfma_f32_16x16x32_bf16 v[106:109], v[164:167], v[200:203], v[106:109]
	v_mfma_f32_16x16x32_bf16 v[94:97], v[156:159], v[208:211], v[94:97]
	v_mfma_f32_16x16x32_bf16 v[90:93], v[164:167], v[208:211], v[90:93]
	v_mfma_f32_16x16x32_bf16 v[78:81], v[156:159], v[216:219], v[78:81]
	v_mfma_f32_16x16x32_bf16 v[74:77], v[164:167], v[216:219], v[74:77]
	s_setprio 0
	s_setprio 1
	v_mfma_f32_16x16x32_bf16 v[118:121], v[168:171], v[188:191], v[118:121]
	v_mfma_f32_16x16x32_bf16 v[114:117], v[176:179], v[188:191], v[114:117]
	v_mfma_f32_16x16x32_bf16 v[102:105], v[168:171], v[196:199], v[102:105]
	v_mfma_f32_16x16x32_bf16 v[98:101], v[176:179], v[196:199], v[98:101]
	v_mfma_f32_16x16x32_bf16 v[86:89], v[168:171], v[204:207], v[86:89]
	v_mfma_f32_16x16x32_bf16 v[82:85], v[176:179], v[204:207], v[82:85]
	v_mfma_f32_16x16x32_bf16 v[70:73], v[168:171], v[212:215], v[70:73]
	v_mfma_f32_16x16x32_bf16 v[66:69], v[176:179], v[212:215], v[66:69]
	v_mfma_f32_16x16x32_bf16 v[118:121], v[172:175], v[192:195], v[118:121]
	v_mfma_f32_16x16x32_bf16 v[114:117], v[180:183], v[192:195], v[114:117]
	v_mfma_f32_16x16x32_bf16 v[102:105], v[172:175], v[200:203], v[102:105]
	v_mfma_f32_16x16x32_bf16 v[98:101], v[180:183], v[200:203], v[98:101]
	v_mfma_f32_16x16x32_bf16 v[86:89], v[172:175], v[208:211], v[86:89]
	v_mfma_f32_16x16x32_bf16 v[82:85], v[180:183], v[208:211], v[82:85]
	v_mfma_f32_16x16x32_bf16 v[70:73], v[172:175], v[216:219], v[70:73]
	v_mfma_f32_16x16x32_bf16 v[66:69], v[180:183], v[216:219], v[66:69]
	s_setprio 0
	s_barrier
	s_add_i32 s67, s62, s45
	v_lshl_add_u64 v[184:185], s[38:39], 0, v[132:133]
	s_mov_b32 m0, s67
	ds_read_b128 v[188:191], v154 offset:16384
	ds_read_b128 v[192:195], v154 offset:17408
	ds_read_b128 v[196:199], v154 offset:18432
	ds_read_b128 v[200:203], v154 offset:19456
	ds_read_b128 v[204:207], v154 offset:20480
	ds_read_b128 v[208:211], v154 offset:21504
	ds_read_b128 v[212:215], v154 offset:22528
	ds_read_b128 v[216:219], v154 offset:23552
	global_load_lds_dwordx4 v[184:185], off
	s_add_i32 m0, s67, 0x2000
	s_add_u32 s68, s38, 0x40000
	v_lshl_add_u64 v[220:221], s[38:39], 0, v[136:137]
	s_addc_u32 s69, s39, 0
	s_add_i32 s67, s63, s45
	global_load_lds_dwordx4 v[220:221], off
	s_mov_b32 m0, s67
	v_lshl_add_u64 v[224:225], s[40:41], 0, v[134:135]
	global_load_lds_dwordx4 v132, s[68:69]
	s_add_i32 m0, s67, 0x2000
	s_nop 0
	global_load_lds_dwordx4 v136, s[68:69]
	v_lshl_add_u64 v[222:223], s[40:41], 0, v[130:131]
	s_mov_b32 m0, s35
	s_nop 0
	global_load_lds_dwordx4 v[222:223], off
	s_mov_b32 m0, s37
	s_nop 0
	global_load_lds_dwordx4 v[224:225], off
	s_waitcnt vmcnt(8)
	s_waitcnt lgkmcnt(0)
	s_barrier
	s_setprio 1
	s_waitcnt lgkmcnt(0)
	v_mfma_f32_16x16x32_bf16 v[62:65], v[146:149], v[188:191], v[62:65]
	v_mfma_f32_16x16x32_bf16 v[58:61], v[160:163], v[188:191], v[58:61]
	v_mfma_f32_16x16x32_bf16 v[46:49], v[146:149], v[196:199], v[46:49]
	v_mfma_f32_16x16x32_bf16 v[42:45], v[160:163], v[196:199], v[42:45]
	v_mfma_f32_16x16x32_bf16 v[30:33], v[146:149], v[204:207], v[30:33]
	v_mfma_f32_16x16x32_bf16 v[26:29], v[160:163], v[204:207], v[26:29]
	v_mfma_f32_16x16x32_bf16 v[14:17], v[146:149], v[212:215], v[14:17]
	v_mfma_f32_16x16x32_bf16 v[10:13], v[160:163], v[212:215], v[10:13]
	v_mfma_f32_16x16x32_bf16 v[62:65], v[156:159], v[192:195], v[62:65]
	v_mfma_f32_16x16x32_bf16 v[58:61], v[164:167], v[192:195], v[58:61]
	v_mfma_f32_16x16x32_bf16 v[46:49], v[156:159], v[200:203], v[46:49]
	v_mfma_f32_16x16x32_bf16 v[42:45], v[164:167], v[200:203], v[42:45]
	v_mfma_f32_16x16x32_bf16 v[30:33], v[156:159], v[208:211], v[30:33]
	v_mfma_f32_16x16x32_bf16 v[26:29], v[164:167], v[208:211], v[26:29]
	v_mfma_f32_16x16x32_bf16 v[14:17], v[156:159], v[216:219], v[14:17]
	v_mfma_f32_16x16x32_bf16 v[10:13], v[164:167], v[216:219], v[10:13]
	s_setprio 0
	s_setprio 1
	v_mfma_f32_16x16x32_bf16 v[54:57], v[168:171], v[188:191], v[54:57]
	v_mfma_f32_16x16x32_bf16 v[50:53], v[176:179], v[188:191], v[50:53]
	v_mfma_f32_16x16x32_bf16 v[38:41], v[168:171], v[196:199], v[38:41]
	v_mfma_f32_16x16x32_bf16 v[34:37], v[176:179], v[196:199], v[34:37]
	v_mfma_f32_16x16x32_bf16 v[22:25], v[168:171], v[204:207], v[22:25]
	v_mfma_f32_16x16x32_bf16 v[18:21], v[176:179], v[204:207], v[18:21]
	v_mfma_f32_16x16x32_bf16 v[6:9], v[168:171], v[212:215], v[6:9]
	v_mfma_f32_16x16x32_bf16 v[2:5], v[176:179], v[212:215], v[2:5]
	v_mfma_f32_16x16x32_bf16 v[54:57], v[172:175], v[192:195], v[54:57]
	v_mfma_f32_16x16x32_bf16 v[50:53], v[180:183], v[192:195], v[50:53]
	v_mfma_f32_16x16x32_bf16 v[38:41], v[172:175], v[200:203], v[38:41]
	v_mfma_f32_16x16x32_bf16 v[34:37], v[180:183], v[200:203], v[34:37]
	v_mfma_f32_16x16x32_bf16 v[22:25], v[172:175], v[208:211], v[22:25]
	v_mfma_f32_16x16x32_bf16 v[18:21], v[180:183], v[208:211], v[18:21]
	v_mfma_f32_16x16x32_bf16 v[6:9], v[172:175], v[216:219], v[6:9]
	v_mfma_f32_16x16x32_bf16 v[2:5], v[180:183], v[216:219], v[2:5]
	s_setprio 0
	s_barrier
	s_add_i32 s67, 0, 0x18000
	s_add_i32 s68, 0, 0x1c000
	v_add_u32_e32 v164, s67, v150
	v_add_u32_e32 v180, s68, v150
	ds_read_b128 v[146:149], v164
	ds_read_b128 v[156:159], v164 offset:1024
	ds_read_b128 v[160:163], v164 offset:2048
	ds_read_b128 v[164:167], v164 offset:3072
	ds_read_b128 v[168:171], v180
	ds_read_b128 v[172:175], v180 offset:1024
	ds_read_b128 v[176:179], v180 offset:2048
	ds_read_b128 v[180:183], v180 offset:3072
	s_add_u32 s40, s40, 0x40000
	s_addc_u32 s41, s41, 0
	s_mov_b32 m0, s46
	ds_read_b128 v[188:191], v154 offset:32768
	ds_read_b128 v[192:195], v154 offset:33792
	ds_read_b128 v[196:199], v154 offset:34816
	ds_read_b128 v[200:203], v154 offset:35840
	ds_read_b128 v[204:207], v154 offset:36864
	ds_read_b128 v[208:211], v154 offset:37888
	ds_read_b128 v[212:215], v154 offset:38912
	ds_read_b128 v[216:219], v154 offset:39936
	global_load_lds_dwordx4 v130, s[40:41]
	s_mov_b32 m0, s47
	s_nop 0
	global_load_lds_dwordx4 v134, s[40:41]
	s_waitcnt vmcnt(8)
	s_waitcnt lgkmcnt(0)
	s_barrier
	s_setprio 1
	s_waitcnt lgkmcnt(0)
	v_mfma_f32_16x16x32_bf16 v[126:129], v[146:149], v[188:191], v[126:129]
	v_mfma_f32_16x16x32_bf16 v[122:125], v[160:163], v[188:191], v[122:125]
	v_mfma_f32_16x16x32_bf16 v[110:113], v[146:149], v[196:199], v[110:113]
	v_mfma_f32_16x16x32_bf16 v[106:109], v[160:163], v[196:199], v[106:109]
	v_mfma_f32_16x16x32_bf16 v[94:97], v[146:149], v[204:207], v[94:97]
	v_mfma_f32_16x16x32_bf16 v[90:93], v[160:163], v[204:207], v[90:93]
	v_mfma_f32_16x16x32_bf16 v[78:81], v[146:149], v[212:215], v[78:81]
	v_mfma_f32_16x16x32_bf16 v[74:77], v[160:163], v[212:215], v[74:77]
	v_mfma_f32_16x16x32_bf16 v[126:129], v[156:159], v[192:195], v[126:129]
	v_mfma_f32_16x16x32_bf16 v[122:125], v[164:167], v[192:195], v[122:125]
	v_mfma_f32_16x16x32_bf16 v[110:113], v[156:159], v[200:203], v[110:113]
	v_mfma_f32_16x16x32_bf16 v[106:109], v[164:167], v[200:203], v[106:109]
	v_mfma_f32_16x16x32_bf16 v[94:97], v[156:159], v[208:211], v[94:97]
	v_mfma_f32_16x16x32_bf16 v[90:93], v[164:167], v[208:211], v[90:93]
	v_mfma_f32_16x16x32_bf16 v[78:81], v[156:159], v[216:219], v[78:81]
	v_mfma_f32_16x16x32_bf16 v[74:77], v[164:167], v[216:219], v[74:77]
	s_setprio 0
	s_setprio 1
	v_mfma_f32_16x16x32_bf16 v[118:121], v[168:171], v[188:191], v[118:121]
	v_mfma_f32_16x16x32_bf16 v[114:117], v[176:179], v[188:191], v[114:117]
	v_mfma_f32_16x16x32_bf16 v[102:105], v[168:171], v[196:199], v[102:105]
	v_mfma_f32_16x16x32_bf16 v[98:101], v[176:179], v[196:199], v[98:101]
	v_mfma_f32_16x16x32_bf16 v[86:89], v[168:171], v[204:207], v[86:89]
	v_mfma_f32_16x16x32_bf16 v[82:85], v[176:179], v[204:207], v[82:85]
	v_mfma_f32_16x16x32_bf16 v[70:73], v[168:171], v[212:215], v[70:73]
	v_mfma_f32_16x16x32_bf16 v[66:69], v[176:179], v[212:215], v[66:69]
	v_mfma_f32_16x16x32_bf16 v[118:121], v[172:175], v[192:195], v[118:121]
	v_mfma_f32_16x16x32_bf16 v[114:117], v[180:183], v[192:195], v[114:117]
	v_mfma_f32_16x16x32_bf16 v[102:105], v[172:175], v[200:203], v[102:105]
	v_mfma_f32_16x16x32_bf16 v[98:101], v[180:183], v[200:203], v[98:101]
	v_mfma_f32_16x16x32_bf16 v[86:89], v[172:175], v[208:211], v[86:89]
	v_mfma_f32_16x16x32_bf16 v[82:85], v[180:183], v[208:211], v[82:85]
	v_mfma_f32_16x16x32_bf16 v[70:73], v[172:175], v[216:219], v[70:73]
	v_mfma_f32_16x16x32_bf16 v[66:69], v[180:183], v[216:219], v[66:69]
	s_setprio 0
	s_barrier
	s_add_i32 s40, s67, s45
	v_lshl_add_u64 v[184:185], v[184:185], 0, s[20:21]
	s_mov_b32 m0, s40
	ds_read_b128 v[188:191], v154 offset:49152
	ds_read_b128 v[192:195], v154 offset:50176
	ds_read_b128 v[196:199], v154 offset:51200
	ds_read_b128 v[200:203], v154 offset:52224
	ds_read_b128 v[204:207], v154 offset:53248
	ds_read_b128 v[208:211], v154 offset:54272
	ds_read_b128 v[212:215], v154 offset:55296
	ds_read_b128 v[216:219], v154 offset:56320
	global_load_lds_dwordx4 v[184:185], off
	s_add_i32 m0, s40, 0x2000
	s_add_u32 s38, s38, 0x40080
	v_lshl_add_u64 v[184:185], v[220:221], 0, s[20:21]
	s_addc_u32 s39, s39, 0
	s_add_i32 s40, s68, s45
	global_load_lds_dwordx4 v[184:185], off
	s_mov_b32 m0, s40
	s_nop 0
	global_load_lds_dwordx4 v132, s[38:39]
	s_add_i32 m0, s40, 0x2000
	s_nop 0
	global_load_lds_dwordx4 v136, s[38:39]
	v_lshl_add_u64 v[184:185], v[222:223], 0, s[20:21]
	s_mov_b32 m0, s57
	s_nop 0
	global_load_lds_dwordx4 v[184:185], off
	v_lshl_add_u64 v[184:185], v[224:225], 0, s[20:21]
	s_mov_b32 m0, s60
	s_nop 0
	global_load_lds_dwordx4 v[184:185], off
	s_waitcnt vmcnt(8)
	s_waitcnt lgkmcnt(0)
	s_barrier
	s_setprio 1
	s_waitcnt lgkmcnt(0)
	v_mfma_f32_16x16x32_bf16 v[62:65], v[146:149], v[188:191], v[62:65]
	v_mfma_f32_16x16x32_bf16 v[58:61], v[160:163], v[188:191], v[58:61]
	v_mfma_f32_16x16x32_bf16 v[46:49], v[146:149], v[196:199], v[46:49]
	v_mfma_f32_16x16x32_bf16 v[42:45], v[160:163], v[196:199], v[42:45]
	v_mfma_f32_16x16x32_bf16 v[30:33], v[146:149], v[204:207], v[30:33]
	v_mfma_f32_16x16x32_bf16 v[26:29], v[160:163], v[204:207], v[26:29]
	v_mfma_f32_16x16x32_bf16 v[14:17], v[146:149], v[212:215], v[14:17]
	v_mfma_f32_16x16x32_bf16 v[10:13], v[160:163], v[212:215], v[10:13]
	v_mfma_f32_16x16x32_bf16 v[62:65], v[156:159], v[192:195], v[62:65]
	v_mfma_f32_16x16x32_bf16 v[58:61], v[164:167], v[192:195], v[58:61]
	v_mfma_f32_16x16x32_bf16 v[46:49], v[156:159], v[200:203], v[46:49]
	v_mfma_f32_16x16x32_bf16 v[42:45], v[164:167], v[200:203], v[42:45]
	v_mfma_f32_16x16x32_bf16 v[30:33], v[156:159], v[208:211], v[30:33]
	v_mfma_f32_16x16x32_bf16 v[26:29], v[164:167], v[208:211], v[26:29]
	v_mfma_f32_16x16x32_bf16 v[14:17], v[156:159], v[216:219], v[14:17]
	v_mfma_f32_16x16x32_bf16 v[10:13], v[164:167], v[216:219], v[10:13]
	s_setprio 0
	s_setprio 1
	v_mfma_f32_16x16x32_bf16 v[54:57], v[168:171], v[188:191], v[54:57]
	v_mfma_f32_16x16x32_bf16 v[50:53], v[176:179], v[188:191], v[50:53]
	v_mfma_f32_16x16x32_bf16 v[38:41], v[168:171], v[196:199], v[38:41]
	v_mfma_f32_16x16x32_bf16 v[34:37], v[176:179], v[196:199], v[34:37]
	v_mfma_f32_16x16x32_bf16 v[22:25], v[168:171], v[204:207], v[22:25]
	v_mfma_f32_16x16x32_bf16 v[18:21], v[176:179], v[204:207], v[18:21]
	v_mfma_f32_16x16x32_bf16 v[6:9], v[168:171], v[212:215], v[6:9]
	v_mfma_f32_16x16x32_bf16 v[2:5], v[176:179], v[212:215], v[2:5]
	v_mfma_f32_16x16x32_bf16 v[54:57], v[172:175], v[192:195], v[54:57]
	v_mfma_f32_16x16x32_bf16 v[50:53], v[180:183], v[192:195], v[50:53]
	v_mfma_f32_16x16x32_bf16 v[38:41], v[172:175], v[200:203], v[38:41]
	v_mfma_f32_16x16x32_bf16 v[34:37], v[180:183], v[200:203], v[34:37]
	v_mfma_f32_16x16x32_bf16 v[22:25], v[172:175], v[208:211], v[22:25]
	v_mfma_f32_16x16x32_bf16 v[18:21], v[180:183], v[208:211], v[18:21]
	v_mfma_f32_16x16x32_bf16 v[6:9], v[172:175], v[216:219], v[6:9]
	v_mfma_f32_16x16x32_bf16 v[2:5], v[180:183], v[216:219], v[2:5]
	s_setprio 0
	s_barrier
	s_add_i32 s66, s66, 2
	s_add_u32 s64, s64, 0x100
	s_addc_u32 s65, s65, 0
	s_add_u32 s10, s10, 0x100
	s_addc_u32 s11, s11, 0
	s_cmp_gt_u32 s66, 13
	s_cbranch_scc0 .LBB0_1483
	v_lshl_add_u32 v245, s34, 8, v1
	v_lshl_or_b32 v246, s36, 8, v151
	v_lshlrev_b32_e32 v245, 13, v245
	v_lshl_add_u32 v245, v246, 1, v245
	global_load_dwordx4 v[146:149], v245, s[16:17]
	global_load_dwordx4 v[156:159], v245, s[16:17] offset:256
	s_add_u32 s10, s16, 0x20000
	s_addc_u32 s11, s17, 0
	global_load_dwordx4 v[160:163], v245, s[10:11]
	global_load_dwordx4 v[164:167], v245, s[10:11] offset:256
	s_add_u32 s10, s16, 0x40000
	s_addc_u32 s11, s17, 0
	global_load_dwordx4 v[168:171], v245, s[10:11]
	global_load_dwordx4 v[172:175], v245, s[10:11] offset:256
	s_add_u32 s10, s16, 0x60000
	s_addc_u32 s11, s17, 0
	global_load_dwordx4 v[176:179], v245, s[10:11]
	global_load_dwordx4 v[180:183], v245, s[10:11] offset:256
	s_add_u32 s10, s16, 0x100000
	s_addc_u32 s11, s17, 0
	global_load_dwordx4 v[188:191], v245, s[10:11]
	global_load_dwordx4 v[192:195], v245, s[10:11] offset:256
	s_add_u32 s10, s16, 0x120000
	s_addc_u32 s11, s17, 0
	global_load_dwordx4 v[196:199], v245, s[10:11]
	global_load_dwordx4 v[200:203], v245, s[10:11] offset:256
	s_add_u32 s10, s16, 0x140000
	s_addc_u32 s11, s17, 0
	global_load_dwordx4 v[204:207], v245, s[10:11]
	global_load_dwordx4 v[208:211], v245, s[10:11] offset:256
	s_add_u32 s10, s16, 0x160000
	s_addc_u32 s11, s17, 0
	global_load_dwordx4 v[212:215], v245, s[10:11]
	global_load_dwordx4 v[216:219], v245, s[10:11] offset:256
	s_and_b64 vcc, exec, s[22:23]
	s_cbranch_vccz .LBB0_1486
	s_barrier

.LBB0_1644:
	v_add_u32_e32 v3, s75, v165
	ds_read_b128 v[134:137], v3
	ds_read_b128 v[138:141], v3 offset:1024
	ds_read_b128 v[142:145], v3 offset:2048
	ds_read_b128 v[146:149], v3 offset:3072
	v_add_u32_e32 v3, s76, v165
	s_add_u32 s16, s42, s44
	ds_read_b128 v[150:153], v3
	ds_read_b128 v[154:157], v3 offset:1024
	ds_read_b128 v[158:161], v3 offset:2048
	ds_read_b128 v[188:191], v3 offset:3072
	s_addc_u32 s17, s43, s45
	s_add_u32 s16, s16, 0x100
	s_addc_u32 s17, s17, 0
	s_add_u32 s46, s78, s44
	s_addc_u32 s47, s79, s45
	s_cmpk_eq_i32 s44, 0x1f00
	s_cselect_b32 s61, s39, s17
	s_cselect_b32 s60, s38, s16
	s_cselect_b32 s47, s28, s47
	s_cselect_b32 s46, s29, s46
	v_lshl_add_u64 v[4:5], v[180:181], 0, s[44:45]
	s_add_i32 m0, s63, 0xc000
	ds_read_b128 v[192:195], v185
	ds_read_b128 v[196:199], v185 offset:1024
	ds_read_b128 v[200:203], v185 offset:2048
	ds_read_b128 v[204:207], v185 offset:3072
	ds_read_b128 v[208:211], v185 offset:4096
	ds_read_b128 v[212:215], v185 offset:5120
	ds_read_b128 v[216:219], v185 offset:6144
	ds_read_b128 v[220:223], v185 offset:7168
	global_load_lds_dwordx4 v[4:5], off
	v_lshl_add_u64 v[4:5], v[178:179], 0, s[44:45]
	s_add_i32 m0, s63, 0xe000
	s_nop 0
	global_load_lds_dwordx4 v[4:5], off
	s_waitcnt vmcnt(8)
	s_waitcnt lgkmcnt(0)
	s_barrier
	s_setprio 1
	s_waitcnt lgkmcnt(0)
	v_mfma_f32_16x16x32_bf16 v[130:133], v[134:137], v[192:195], v[130:133]
	v_mfma_f32_16x16x32_bf16 v[126:129], v[142:145], v[192:195], v[126:129]
	v_mfma_f32_16x16x32_bf16 v[114:117], v[134:137], v[200:203], v[114:117]
	v_mfma_f32_16x16x32_bf16 v[110:113], v[142:145], v[200:203], v[110:113]
	v_mfma_f32_16x16x32_bf16 v[98:101], v[134:137], v[208:211], v[98:101]
	v_mfma_f32_16x16x32_bf16 v[94:97], v[142:145], v[208:211], v[94:97]
	v_mfma_f32_16x16x32_bf16 v[82:85], v[134:137], v[216:219], v[82:85]
	v_mfma_f32_16x16x32_bf16 v[78:81], v[142:145], v[216:219], v[78:81]
	v_mfma_f32_16x16x32_bf16 v[130:133], v[138:141], v[196:199], v[130:133]
	v_mfma_f32_16x16x32_bf16 v[126:129], v[146:149], v[196:199], v[126:129]
	v_mfma_f32_16x16x32_bf16 v[114:117], v[138:141], v[204:207], v[114:117]
	v_mfma_f32_16x16x32_bf16 v[110:113], v[146:149], v[204:207], v[110:113]
	v_mfma_f32_16x16x32_bf16 v[98:101], v[138:141], v[212:215], v[98:101]
	v_mfma_f32_16x16x32_bf16 v[94:97], v[146:149], v[212:215], v[94:97]
	v_mfma_f32_16x16x32_bf16 v[82:85], v[138:141], v[220:223], v[82:85]
	v_mfma_f32_16x16x32_bf16 v[78:81], v[146:149], v[220:223], v[78:81]
	s_setprio 0
	s_setprio 1
	v_mfma_f32_16x16x32_bf16 v[122:125], v[150:153], v[192:195], v[122:125]
	v_mfma_f32_16x16x32_bf16 v[118:121], v[158:161], v[192:195], v[118:121]
	v_mfma_f32_16x16x32_bf16 v[106:109], v[150:153], v[200:203], v[106:109]
	v_mfma_f32_16x16x32_bf16 v[102:105], v[158:161], v[200:203], v[102:105]
	v_mfma_f32_16x16x32_bf16 v[90:93], v[150:153], v[208:211], v[90:93]
	v_mfma_f32_16x16x32_bf16 v[86:89], v[158:161], v[208:211], v[86:89]
	v_mfma_f32_16x16x32_bf16 v[74:77], v[150:153], v[216:219], v[74:77]
	v_mfma_f32_16x16x32_bf16 v[70:73], v[158:161], v[216:219], v[70:73]
	v_mfma_f32_16x16x32_bf16 v[122:125], v[154:157], v[196:199], v[122:125]
	v_mfma_f32_16x16x32_bf16 v[118:121], v[188:191], v[196:199], v[118:121]
	v_mfma_f32_16x16x32_bf16 v[106:109], v[154:157], v[204:207], v[106:109]
	v_mfma_f32_16x16x32_bf16 v[102:105], v[188:191], v[204:207], v[102:105]
	v_mfma_f32_16x16x32_bf16 v[90:93], v[154:157], v[212:215], v[90:93]
	v_mfma_f32_16x16x32_bf16 v[86:89], v[188:191], v[212:215], v[86:89]
	v_mfma_f32_16x16x32_bf16 v[74:77], v[154:157], v[220:223], v[74:77]
	v_mfma_f32_16x16x32_bf16 v[70:73], v[188:191], v[220:223], v[70:73]
	s_setprio 0
	s_barrier
	s_add_i32 s16, s75, s62
	v_lshl_add_u64 v[162:163], s[46:47], 0, v[168:169]
	s_mov_b32 m0, s16
	ds_read_b128 v[192:195], v185 offset:16384
	ds_read_b128 v[196:199], v185 offset:17408
	ds_read_b128 v[200:203], v185 offset:18432
	ds_read_b128 v[204:207], v185 offset:19456
	ds_read_b128 v[208:211], v185 offset:20480
	ds_read_b128 v[212:215], v185 offset:21504
	ds_read_b128 v[216:219], v185 offset:22528
	ds_read_b128 v[220:223], v185 offset:23552
	global_load_lds_dwordx4 v[162:163], off
	s_add_i32 m0, s16, 0x2000
	s_add_u32 s16, s46, 0x100000
	v_lshl_add_u64 v[182:183], s[46:47], 0, v[172:173]
	s_addc_u32 s17, s47, 0
	s_add_i32 s81, s76, s62
	global_load_lds_dwordx4 v[182:183], off
	s_mov_b32 m0, s81
	v_lshl_add_u64 v[224:225], s[60:61], 0, v[166:167]
	global_load_lds_dwordx4 v168, s[16:17]
	s_add_i32 m0, s81, 0x2000
	v_lshl_add_u64 v[226:227], s[60:61], 0, v[170:171]
	global_load_lds_dwordx4 v172, s[16:17]
	s_mov_b32 m0, s63
	s_nop 0
	global_load_lds_dwordx4 v[224:225], off
	s_mov_b32 m0, s64
	s_nop 0
	global_load_lds_dwordx4 v[226:227], off
	s_waitcnt vmcnt(8)
	s_waitcnt lgkmcnt(0)
	s_barrier
	s_setprio 1
	s_waitcnt lgkmcnt(0)
	v_mfma_f32_16x16x32_bf16 v[66:69], v[134:137], v[192:195], v[66:69]
	v_mfma_f32_16x16x32_bf16 v[62:65], v[142:145], v[192:195], v[62:65]
	v_mfma_f32_16x16x32_bf16 v[50:53], v[134:137], v[200:203], v[50:53]
	v_mfma_f32_16x16x32_bf16 v[46:49], v[142:145], v[200:203], v[46:49]
	v_mfma_f32_16x16x32_bf16 v[34:37], v[134:137], v[208:211], v[34:37]
	v_mfma_f32_16x16x32_bf16 v[30:33], v[142:145], v[208:211], v[30:33]
	v_mfma_f32_16x16x32_bf16 v[18:21], v[134:137], v[216:219], v[18:21]
	v_mfma_f32_16x16x32_bf16 v[14:17], v[142:145], v[216:219], v[14:17]
	v_mfma_f32_16x16x32_bf16 v[66:69], v[138:141], v[196:199], v[66:69]
	v_mfma_f32_16x16x32_bf16 v[62:65], v[146:149], v[196:199], v[62:65]
	v_mfma_f32_16x16x32_bf16 v[50:53], v[138:141], v[204:207], v[50:53]
	v_mfma_f32_16x16x32_bf16 v[46:49], v[146:149], v[204:207], v[46:49]
	v_mfma_f32_16x16x32_bf16 v[34:37], v[138:141], v[212:215], v[34:37]
	v_mfma_f32_16x16x32_bf16 v[30:33], v[146:149], v[212:215], v[30:33]
	v_mfma_f32_16x16x32_bf16 v[18:21], v[138:141], v[220:223], v[18:21]
	v_mfma_f32_16x16x32_bf16 v[14:17], v[146:149], v[220:223], v[14:17]
	s_setprio 0
	s_setprio 1
	v_mfma_f32_16x16x32_bf16 v[58:61], v[150:153], v[192:195], v[58:61]
	v_mfma_f32_16x16x32_bf16 v[54:57], v[158:161], v[192:195], v[54:57]
	v_mfma_f32_16x16x32_bf16 v[42:45], v[150:153], v[200:203], v[42:45]
	v_mfma_f32_16x16x32_bf16 v[38:41], v[158:161], v[200:203], v[38:41]
	v_mfma_f32_16x16x32_bf16 v[26:29], v[150:153], v[208:211], v[26:29]
	v_mfma_f32_16x16x32_bf16 v[22:25], v[158:161], v[208:211], v[22:25]
	v_mfma_f32_16x16x32_bf16 v[10:13], v[150:153], v[216:219], v[10:13]
	v_mfma_f32_16x16x32_bf16 v[4:7], v[158:161], v[216:219], v[6:9]
	v_mfma_f32_16x16x32_bf16 v[58:61], v[154:157], v[196:199], v[58:61]
	v_mfma_f32_16x16x32_bf16 v[54:57], v[188:191], v[196:199], v[54:57]
	v_mfma_f32_16x16x32_bf16 v[42:45], v[154:157], v[204:207], v[42:45]
	v_mfma_f32_16x16x32_bf16 v[38:41], v[188:191], v[204:207], v[38:41]
	v_mfma_f32_16x16x32_bf16 v[26:29], v[154:157], v[212:215], v[26:29]
	v_mfma_f32_16x16x32_bf16 v[22:25], v[188:191], v[212:215], v[22:25]
	v_mfma_f32_16x16x32_bf16 v[10:13], v[154:157], v[220:223], v[10:13]
	v_mfma_f32_16x16x32_bf16 v[4:7], v[188:191], v[220:223], v[4:7]
	s_setprio 0
	s_barrier
	s_add_i32 s81, 0, 0x18000
	v_add_u32_e32 v3, s81, v165
	s_add_i32 s82, 0, 0x1c000
	ds_read_b128 v[134:137], v3
	ds_read_b128 v[138:141], v3 offset:1024
	ds_read_b128 v[142:145], v3 offset:2048
	ds_read_b128 v[146:149], v3 offset:3072
	v_add_u32_e32 v3, s82, v165
	ds_read_b128 v[150:153], v3
	ds_read_b128 v[154:157], v3 offset:1024
	ds_read_b128 v[158:161], v3 offset:2048
	ds_read_b128 v[188:191], v3 offset:3072
	s_add_u32 s16, s60, 0x480000
	s_addc_u32 s17, s61, 0
	s_mov_b32 m0, s65
	ds_read_b128 v[192:195], v185 offset:32768
	ds_read_b128 v[196:199], v185 offset:33792
	ds_read_b128 v[200:203], v185 offset:34816
	ds_read_b128 v[204:207], v185 offset:35840
	ds_read_b128 v[208:211], v185 offset:36864
	ds_read_b128 v[212:215], v185 offset:37888
	ds_read_b128 v[216:219], v185 offset:38912
	ds_read_b128 v[220:223], v185 offset:39936
	global_load_lds_dwordx4 v166, s[16:17]
	s_mov_b32 m0, s66
	s_nop 0
	global_load_lds_dwordx4 v170, s[16:17]
	s_waitcnt vmcnt(8)
	s_waitcnt lgkmcnt(0)
	s_barrier
	s_setprio 1
	s_waitcnt lgkmcnt(0)
	v_mfma_f32_16x16x32_bf16 v[130:133], v[134:137], v[192:195], v[130:133]
	v_mfma_f32_16x16x32_bf16 v[126:129], v[142:145], v[192:195], v[126:129]
	v_mfma_f32_16x16x32_bf16 v[114:117], v[134:137], v[200:203], v[114:117]
	v_mfma_f32_16x16x32_bf16 v[110:113], v[142:145], v[200:203], v[110:113]
	v_mfma_f32_16x16x32_bf16 v[98:101], v[134:137], v[208:211], v[98:101]
	v_mfma_f32_16x16x32_bf16 v[94:97], v[142:145], v[208:211], v[94:97]
	v_mfma_f32_16x16x32_bf16 v[82:85], v[134:137], v[216:219], v[82:85]
	v_mfma_f32_16x16x32_bf16 v[78:81], v[142:145], v[216:219], v[78:81]
	v_mfma_f32_16x16x32_bf16 v[130:133], v[138:141], v[196:199], v[130:133]
	v_mfma_f32_16x16x32_bf16 v[126:129], v[146:149], v[196:199], v[126:129]
	v_mfma_f32_16x16x32_bf16 v[114:117], v[138:141], v[204:207], v[114:117]
	v_mfma_f32_16x16x32_bf16 v[110:113], v[146:149], v[204:207], v[110:113]
	v_mfma_f32_16x16x32_bf16 v[98:101], v[138:141], v[212:215], v[98:101]
	v_mfma_f32_16x16x32_bf16 v[94:97], v[146:149], v[212:215], v[94:97]
	v_mfma_f32_16x16x32_bf16 v[82:85], v[138:141], v[220:223], v[82:85]
	v_mfma_f32_16x16x32_bf16 v[78:81], v[146:149], v[220:223], v[78:81]
	s_setprio 0
	s_setprio 1
	v_mfma_f32_16x16x32_bf16 v[122:125], v[150:153], v[192:195], v[122:125]
	v_mfma_f32_16x16x32_bf16 v[118:121], v[158:161], v[192:195], v[118:121]
	v_mfma_f32_16x16x32_bf16 v[106:109], v[150:153], v[200:203], v[106:109]
	v_mfma_f32_16x16x32_bf16 v[102:105], v[158:161], v[200:203], v[102:105]
	v_mfma_f32_16x16x32_bf16 v[90:93], v[150:153], v[208:211], v[90:93]
	v_mfma_f32_16x16x32_bf16 v[86:89], v[158:161], v[208:211], v[86:89]
	v_mfma_f32_16x16x32_bf16 v[74:77], v[150:153], v[216:219], v[74:77]
	v_mfma_f32_16x16x32_bf16 v[70:73], v[158:161], v[216:219], v[70:73]
	v_mfma_f32_16x16x32_bf16 v[122:125], v[154:157], v[196:199], v[122:125]
	v_mfma_f32_16x16x32_bf16 v[118:121], v[188:191], v[196:199], v[118:121]
	v_mfma_f32_16x16x32_bf16 v[106:109], v[154:157], v[204:207], v[106:109]
	v_mfma_f32_16x16x32_bf16 v[102:105], v[188:191], v[204:207], v[102:105]
	v_mfma_f32_16x16x32_bf16 v[90:93], v[154:157], v[212:215], v[90:93]
	v_mfma_f32_16x16x32_bf16 v[86:89], v[188:191], v[212:215], v[86:89]
	v_mfma_f32_16x16x32_bf16 v[74:77], v[154:157], v[220:223], v[74:77]
	v_mfma_f32_16x16x32_bf16 v[70:73], v[188:191], v[220:223], v[70:73]
	s_setprio 0
	s_barrier
	s_add_i32 s16, s81, s62
	v_lshl_add_u64 v[8:9], v[162:163], 0, s[14:15]
	s_mov_b32 m0, s16
	ds_read_b128 v[192:195], v185 offset:49152
	ds_read_b128 v[196:199], v185 offset:50176
	ds_read_b128 v[200:203], v185 offset:51200
	ds_read_b128 v[204:207], v185 offset:52224
	ds_read_b128 v[208:211], v185 offset:53248
	ds_read_b128 v[212:215], v185 offset:54272
	ds_read_b128 v[216:219], v185 offset:55296
	ds_read_b128 v[220:223], v185 offset:56320
	global_load_lds_dwordx4 v[8:9], off
	s_add_i32 m0, s16, 0x2000
	s_add_u32 s16, s46, 0x100080
	v_lshl_add_u64 v[8:9], v[182:183], 0, s[14:15]
	s_addc_u32 s17, s47, 0
	s_add_i32 s46, s82, s62
	global_load_lds_dwordx4 v[8:9], off
	s_mov_b32 m0, s46
	s_nop 0
	global_load_lds_dwordx4 v168, s[16:17]
	s_add_i32 m0, s46, 0x2000
	s_nop 0
	global_load_lds_dwordx4 v172, s[16:17]
	v_lshl_add_u64 v[8:9], v[224:225], 0, s[14:15]
	s_mov_b32 m0, s70
	s_nop 0
	global_load_lds_dwordx4 v[8:9], off
	v_lshl_add_u64 v[8:9], v[226:227], 0, s[14:15]
	s_mov_b32 m0, s71
	s_nop 0
	global_load_lds_dwordx4 v[8:9], off
	s_waitcnt vmcnt(8)
	s_waitcnt lgkmcnt(0)
	s_barrier
	s_setprio 1
	s_waitcnt lgkmcnt(0)
	v_mfma_f32_16x16x32_bf16 v[66:69], v[134:137], v[192:195], v[66:69]
	v_mfma_f32_16x16x32_bf16 v[62:65], v[142:145], v[192:195], v[62:65]
	v_mfma_f32_16x16x32_bf16 v[50:53], v[134:137], v[200:203], v[50:53]
	v_mfma_f32_16x16x32_bf16 v[46:49], v[142:145], v[200:203], v[46:49]
	v_mfma_f32_16x16x32_bf16 v[34:37], v[134:137], v[208:211], v[34:37]
	v_mfma_f32_16x16x32_bf16 v[30:33], v[142:145], v[208:211], v[30:33]
	v_mfma_f32_16x16x32_bf16 v[18:21], v[134:137], v[216:219], v[18:21]
	v_mfma_f32_16x16x32_bf16 v[14:17], v[142:145], v[216:219], v[14:17]
	v_mfma_f32_16x16x32_bf16 v[66:69], v[138:141], v[196:199], v[66:69]
	v_mfma_f32_16x16x32_bf16 v[62:65], v[146:149], v[196:199], v[62:65]
	v_mfma_f32_16x16x32_bf16 v[50:53], v[138:141], v[204:207], v[50:53]
	v_mfma_f32_16x16x32_bf16 v[46:49], v[146:149], v[204:207], v[46:49]
	v_mfma_f32_16x16x32_bf16 v[34:37], v[138:141], v[212:215], v[34:37]
	v_mfma_f32_16x16x32_bf16 v[30:33], v[146:149], v[212:215], v[30:33]
	v_mfma_f32_16x16x32_bf16 v[18:21], v[138:141], v[220:223], v[18:21]
	v_mfma_f32_16x16x32_bf16 v[14:17], v[146:149], v[220:223], v[14:17]
	s_setprio 0
	s_setprio 1
	v_mfma_f32_16x16x32_bf16 v[58:61], v[150:153], v[192:195], v[58:61]
	v_mfma_f32_16x16x32_bf16 v[54:57], v[158:161], v[192:195], v[54:57]
	v_mfma_f32_16x16x32_bf16 v[42:45], v[150:153], v[200:203], v[42:45]
	v_mfma_f32_16x16x32_bf16 v[38:41], v[158:161], v[200:203], v[38:41]
	v_mfma_f32_16x16x32_bf16 v[26:29], v[150:153], v[208:211], v[26:29]
	v_mfma_f32_16x16x32_bf16 v[22:25], v[158:161], v[208:211], v[22:25]
	v_mfma_f32_16x16x32_bf16 v[8:11], v[150:153], v[216:219], v[10:13]
	v_mfma_f32_16x16x32_bf16 v[4:7], v[158:161], v[216:219], v[4:7]
	v_mfma_f32_16x16x32_bf16 v[58:61], v[154:157], v[196:199], v[58:61]
	v_mfma_f32_16x16x32_bf16 v[54:57], v[188:191], v[196:199], v[54:57]
	v_mfma_f32_16x16x32_bf16 v[42:45], v[154:157], v[204:207], v[42:45]
	v_mfma_f32_16x16x32_bf16 v[38:41], v[188:191], v[204:207], v[38:41]
	v_mfma_f32_16x16x32_bf16 v[26:29], v[154:157], v[212:215], v[26:29]
	v_mfma_f32_16x16x32_bf16 v[22:25], v[188:191], v[212:215], v[22:25]
	v_mfma_f32_16x16x32_bf16 v[10:13], v[154:157], v[220:223], v[8:11]
	v_mfma_f32_16x16x32_bf16 v[6:9], v[188:191], v[220:223], v[4:7]
	s_setprio 0
	s_barrier
	s_add_i32 s80, s80, 2
	s_add_u32 s44, s44, 0x100
	s_addc_u32 s45, s45, 0
	s_cmp_gt_u32 s80, 61
	s_cbranch_scc1 .LBB0_1647
.LBB0_1645:
	s_cmpk_lg_i32 s44, 0x1000
	s_cbranch_scc1 .LBB0_1644
	v_and_b32_e32 v245, 15, v187
	v_or_b32_e32 v245, s68, v245
	v_add_u32_e32 v245, s26, v245
	v_lshrrev_b32_e32 v246, 4, v187
	v_lshlrev_b32_e32 v246, 3, v246
	v_add_u32_e32 v246, s37, v246
	v_mul_u32_u24_e32 v245, 0x9000, v245
	v_lshl_add_u32 v245, v246, 1, v245
	s_add_u32 vcc_lo, s30, 0x5000
	s_addc_u32 vcc_hi, s31, 0
	global_load_dwordx4 v[134:137], v245, vcc
	global_load_dwordx4 v[138:141], v245, vcc offset:256
	s_add_u32 vcc_lo, s30, 0x7000
	s_addc_u32 vcc_hi, s31, 0
	global_load_dwordx4 v[142:145], v245, vcc
	global_load_dwordx4 v[146:149], v245, vcc offset:256
	s_add_u32 vcc_lo, s30, 0x95000
	s_addc_u32 vcc_hi, s31, 0
	global_load_dwordx4 v[150:153], v245, vcc
	global_load_dwordx4 v[154:157], v245, vcc offset:256
	s_add_u32 vcc_lo, s30, 0x97000
	s_addc_u32 vcc_hi, s31, 0
	global_load_dwordx4 v[158:161], v245, vcc
	global_load_dwordx4 v[188:191], v245, vcc offset:256
	s_add_u32 vcc_lo, s30, 0x125000
	s_addc_u32 vcc_hi, s31, 0
	global_load_dwordx4 v[192:195], v245, vcc
	global_load_dwordx4 v[196:199], v245, vcc offset:256
	s_add_u32 vcc_lo, s30, 0x127000
	s_addc_u32 vcc_hi, s31, 0
	global_load_dwordx4 v[200:203], v245, vcc
	global_load_dwordx4 v[204:207], v245, vcc offset:256
	s_add_u32 vcc_lo, s30, 0x1b5000
	s_addc_u32 vcc_hi, s31, 0
	global_load_dwordx4 v[208:211], v245, vcc
	global_load_dwordx4 v[212:215], v245, vcc offset:256
	s_add_u32 vcc_lo, s30, 0x1b7000
	s_addc_u32 vcc_hi, s31, 0
	global_load_dwordx4 v[216:219], v245, vcc
	global_load_dwordx4 v[220:223], v245, vcc offset:256
	s_waitcnt vmcnt(13)
	v_lshlrev_b32_e32 v246, 16, v142
	v_and_b32_e32 v247, 0xffff0000, v142
	v_max_f32_e32 v246, 0xda24260, v246
	v_max_f32_e32 v247, 0xda24260, v247
	v_rcp_f32_e32 v246, v246
	v_rcp_f32_e32 v247, v247
	v_lshlrev_b32_e32 v142, 16, v134
	v_and_b32_e32 v134, 0xffff0000, v134
	v_mul_f32_e32 v246, v246, v142
	v_mul_f32_e32 v247, v247, v134
	v_pk_mul_f32 v[130:131], v[130:131], v[246:247]
	v_lshlrev_b32_e32 v246, 16, v143
	v_and_b32_e32 v247, 0xffff0000, v143
	v_max_f32_e32 v246, 0xda24260, v246
	v_max_f32_e32 v247, 0xda24260, v247
	v_rcp_f32_e32 v246, v246
	v_rcp_f32_e32 v247, v247
	v_lshlrev_b32_e32 v143, 16, v135
	v_and_b32_e32 v135, 0xffff0000, v135
	v_mul_f32_e32 v246, v246, v143
	v_mul_f32_e32 v247, v247, v135
	v_pk_mul_f32 v[132:133], v[132:133], v[246:247]
	v_lshlrev_b32_e32 v246, 16, v144
	v_and_b32_e32 v247, 0xffff0000, v144
	v_max_f32_e32 v246, 0xda24260, v246
	v_max_f32_e32 v247, 0xda24260, v247
	v_rcp_f32_e32 v246, v246
	v_rcp_f32_e32 v247, v247
	v_lshlrev_b32_e32 v144, 16, v136
	v_and_b32_e32 v136, 0xffff0000, v136
	v_mul_f32_e32 v246, v246, v144
	v_mul_f32_e32 v247, v247, v136
	v_pk_mul_f32 v[126:127], v[126:127], v[246:247]
	v_lshlrev_b32_e32 v246, 16, v145
	v_and_b32_e32 v247, 0xffff0000, v145
	v_max_f32_e32 v246, 0xda24260, v246
	v_max_f32_e32 v247, 0xda24260, v247
	v_rcp_f32_e32 v246, v246
	v_rcp_f32_e32 v247, v247
	v_lshlrev_b32_e32 v145, 16, v137
	v_and_b32_e32 v137, 0xffff0000, v137
	v_mul_f32_e32 v246, v246, v145
	v_mul_f32_e32 v247, v247, v137
	v_pk_mul_f32 v[128:129], v[128:129], v[246:247]
	s_waitcnt vmcnt(12)
	v_lshlrev_b32_e32 v246, 16, v146
	v_and_b32_e32 v247, 0xffff0000, v146
	v_max_f32_e32 v246, 0xda24260, v246
	v_max_f32_e32 v247, 0xda24260, v247
	v_rcp_f32_e32 v246, v246
	v_rcp_f32_e32 v247, v247
	v_lshlrev_b32_e32 v146, 16, v138
	v_and_b32_e32 v138, 0xffff0000, v138
	v_mul_f32_e32 v246, v246, v146
	v_mul_f32_e32 v247, v247, v138
	v_pk_mul_f32 v[122:123], v[122:123], v[246:247]
	v_lshlrev_b32_e32 v246, 16, v147
	v_and_b32_e32 v247, 0xffff0000, v147
	v_max_f32_e32 v246, 0xda24260, v246
	v_max_f32_e32 v247, 0xda24260, v247
	v_rcp_f32_e32 v246, v246
	v_rcp_f32_e32 v247, v247
	v_lshlrev_b32_e32 v147, 16, v139
	v_and_b32_e32 v139, 0xffff0000, v139
	v_mul_f32_e32 v246, v246, v147
	v_mul_f32_e32 v247, v247, v139
	v_pk_mul_f32 v[124:125], v[124:125], v[246:247]
	v_lshlrev_b32_e32 v246, 16, v148
	v_and_b32_e32 v247, 0xffff0000, v148
	v_max_f32_e32 v246, 0xda24260, v246
	v_max_f32_e32 v247, 0xda24260, v247
	v_rcp_f32_e32 v246, v246
	v_rcp_f32_e32 v247, v247
	v_lshlrev_b32_e32 v148, 16, v140
	v_and_b32_e32 v140, 0xffff0000, v140
	v_mul_f32_e32 v246, v246, v148
	v_mul_f32_e32 v247, v247, v140
	v_pk_mul_f32 v[118:119], v[118:119], v[246:247]
	v_lshlrev_b32_e32 v246, 16, v149
	v_and_b32_e32 v247, 0xffff0000, v149
	v_max_f32_e32 v246, 0xda24260, v246
	v_max_f32_e32 v247, 0xda24260, v247
	v_rcp_f32_e32 v246, v246
	v_rcp_f32_e32 v247, v247
	v_lshlrev_b32_e32 v149, 16, v141
	v_and_b32_e32 v141, 0xffff0000, v141
	v_mul_f32_e32 v246, v246, v149
	v_mul_f32_e32 v247, v247, v141
	v_pk_mul_f32 v[120:121], v[120:121], v[246:247]
	s_add_u32 vcc_lo, s30, 0x485000
	s_addc_u32 vcc_hi, s31, 0
	global_load_dwordx4 v[134:137], v245, vcc
	global_load_dwordx4 v[138:141], v245, vcc offset:256
	s_add_u32 vcc_lo, s30, 0x487000
	s_addc_u32 vcc_hi, s31, 0
	global_load_dwordx4 v[142:145], v245, vcc
	global_load_dwordx4 v[146:149], v245, vcc offset:256
	s_waitcnt vmcnt(13)
	v_lshlrev_b32_e32 v246, 16, v158
	v_and_b32_e32 v247, 0xffff0000, v158
	v_max_f32_e32 v246, 0xda24260, v246
	v_max_f32_e32 v247, 0xda24260, v247
	v_rcp_f32_e32 v246, v246
	v_rcp_f32_e32 v247, v247
	v_lshlrev_b32_e32 v158, 16, v150
	v_and_b32_e32 v150, 0xffff0000, v150
	v_mul_f32_e32 v246, v246, v158
	v_mul_f32_e32 v247, v247, v150
	v_pk_mul_f32 v[114:115], v[114:115], v[246:247]
	v_lshlrev_b32_e32 v246, 16, v159
	v_and_b32_e32 v247, 0xffff0000, v159
	v_max_f32_e32 v246, 0xda24260, v246
	v_max_f32_e32 v247, 0xda24260, v247
	v_rcp_f32_e32 v246, v246
	v_rcp_f32_e32 v247, v247
	v_lshlrev_b32_e32 v159, 16, v151
	v_and_b32_e32 v151, 0xffff0000, v151
	v_mul_f32_e32 v246, v246, v159
	v_mul_f32_e32 v247, v247, v151
	v_pk_mul_f32 v[116:117], v[116:117], v[246:247]
	v_lshlrev_b32_e32 v246, 16, v160
	v_and_b32_e32 v247, 0xffff0000, v160
	v_max_f32_e32 v246, 0xda24260, v246
	v_max_f32_e32 v247, 0xda24260, v247
	v_rcp_f32_e32 v246, v246
	v_rcp_f32_e32 v247, v247
	v_lshlrev_b32_e32 v160, 16, v152
	v_and_b32_e32 v152, 0xffff0000, v152
	v_mul_f32_e32 v246, v246, v160
	v_mul_f32_e32 v247, v247, v152
	v_pk_mul_f32 v[110:111], v[110:111], v[246:247]
	v_lshlrev_b32_e32 v246, 16, v161
	v_and_b32_e32 v247, 0xffff0000, v161
	v_max_f32_e32 v246, 0xda24260, v246
	v_max_f32_e32 v247, 0xda24260, v247
	v_rcp_f32_e32 v246, v246
	v_rcp_f32_e32 v247, v247
	v_lshlrev_b32_e32 v161, 16, v153
	v_and_b32_e32 v153, 0xffff0000, v153
	v_mul_f32_e32 v246, v246, v161
	v_mul_f32_e32 v247, v247, v153
	v_pk_mul_f32 v[112:113], v[112:113], v[246:247]
	s_waitcnt vmcnt(12)
	v_lshlrev_b32_e32 v246, 16, v188
	v_and_b32_e32 v247, 0xffff0000, v188
	v_max_f32_e32 v246, 0xda24260, v246
	v_max_f32_e32 v247, 0xda24260, v247
	v_rcp_f32_e32 v246, v246
	v_rcp_f32_e32 v247, v247
	v_lshlrev_b32_e32 v188, 16, v154
	v_and_b32_e32 v154, 0xffff0000, v154
	v_mul_f32_e32 v246, v246, v188
	v_mul_f32_e32 v247, v247, v154
	v_pk_mul_f32 v[106:107], v[106:107], v[246:247]
	v_lshlrev_b32_e32 v246, 16, v189
	v_and_b32_e32 v247, 0xffff0000, v189
	v_max_f32_e32 v246, 0xda24260, v246
	v_max_f32_e32 v247, 0xda24260, v247
	v_rcp_f32_e32 v246, v246
	v_rcp_f32_e32 v247, v247
	v_lshlrev_b32_e32 v189, 16, v155
	v_and_b32_e32 v155, 0xffff0000, v155
	v_mul_f32_e32 v246, v246, v189
	v_mul_f32_e32 v247, v247, v155
	v_pk_mul_f32 v[108:109], v[108:109], v[246:247]
	v_lshlrev_b32_e32 v246, 16, v190
	v_and_b32_e32 v247, 0xffff0000, v190
	v_max_f32_e32 v246, 0xda24260, v246
	v_max_f32_e32 v247, 0xda24260, v247
	v_rcp_f32_e32 v246, v246
	v_rcp_f32_e32 v247, v247
	v_lshlrev_b32_e32 v190, 16, v156
	v_and_b32_e32 v156, 0xffff0000, v156
	v_mul_f32_e32 v246, v246, v190
	v_mul_f32_e32 v247, v247, v156
	v_pk_mul_f32 v[102:103], v[102:103], v[246:247]
	v_lshlrev_b32_e32 v246, 16, v191
	v_and_b32_e32 v247, 0xffff0000, v191
	v_max_f32_e32 v246, 0xda24260, v246
	v_max_f32_e32 v247, 0xda24260, v247
	v_rcp_f32_e32 v246, v246
	v_rcp_f32_e32 v247, v247
	v_lshlrev_b32_e32 v191, 16, v157
	v_and_b32_e32 v157, 0xffff0000, v157
	v_mul_f32_e32 v246, v246, v191
	v_mul_f32_e32 v247, v247, v157
	v_pk_mul_f32 v[104:105], v[104:105], v[246:247]
	s_add_u32 vcc_lo, s30, 0x515000
	s_addc_u32 vcc_hi, s31, 0
	global_load_dwordx4 v[150:153], v245, vcc
	global_load_dwordx4 v[154:157], v245, vcc offset:256
	s_add_u32 vcc_lo, s30, 0x517000
	s_addc_u32 vcc_hi, s31, 0
	global_load_dwordx4 v[158:161], v245, vcc
	global_load_dwordx4 v[188:191], v245, vcc offset:256
	s_waitcnt vmcnt(13)
	v_lshlrev_b32_e32 v246, 16, v200
	v_and_b32_e32 v247, 0xffff0000, v200
	v_max_f32_e32 v246, 0xda24260, v246
	v_max_f32_e32 v247, 0xda24260, v247
	v_rcp_f32_e32 v246, v246
	v_rcp_f32_e32 v247, v247
	v_lshlrev_b32_e32 v200, 16, v192
	v_and_b32_e32 v192, 0xffff0000, v192
	v_mul_f32_e32 v246, v246, v200
	v_mul_f32_e32 v247, v247, v192
	v_pk_mul_f32 v[98:99], v[98:99], v[246:247]
	v_lshlrev_b32_e32 v246, 16, v201
	v_and_b32_e32 v247, 0xffff0000, v201
	v_max_f32_e32 v246, 0xda24260, v246
	v_max_f32_e32 v247, 0xda24260, v247
	v_rcp_f32_e32 v246, v246
	v_rcp_f32_e32 v247, v247
	v_lshlrev_b32_e32 v201, 16, v193
	v_and_b32_e32 v193, 0xffff0000, v193
	v_mul_f32_e32 v246, v246, v201
	v_mul_f32_e32 v247, v247, v193
	v_pk_mul_f32 v[100:101], v[100:101], v[246:247]
	v_lshlrev_b32_e32 v246, 16, v202
	v_and_b32_e32 v247, 0xffff0000, v202
	v_max_f32_e32 v246, 0xda24260, v246
	v_max_f32_e32 v247, 0xda24260, v247
	v_rcp_f32_e32 v246, v246
	v_rcp_f32_e32 v247, v247
	v_lshlrev_b32_e32 v202, 16, v194
	v_and_b32_e32 v194, 0xffff0000, v194
	v_mul_f32_e32 v246, v246, v202
	v_mul_f32_e32 v247, v247, v194
	v_pk_mul_f32 v[94:95], v[94:95], v[246:247]
	v_lshlrev_b32_e32 v246, 16, v203
	v_and_b32_e32 v247, 0xffff0000, v203
	v_max_f32_e32 v246, 0xda24260, v246
	v_max_f32_e32 v247, 0xda24260, v247
	v_rcp_f32_e32 v246, v246
	v_rcp_f32_e32 v247, v247
	v_lshlrev_b32_e32 v203, 16, v195
	v_and_b32_e32 v195, 0xffff0000, v195
	v_mul_f32_e32 v246, v246, v203
	v_mul_f32_e32 v247, v247, v195
	v_pk_mul_f32 v[96:97], v[96:97], v[246:247]
	s_waitcnt vmcnt(12)
	v_lshlrev_b32_e32 v246, 16, v204
	v_and_b32_e32 v247, 0xffff0000, v204
	v_max_f32_e32 v246, 0xda24260, v246
	v_max_f32_e32 v247, 0xda24260, v247
	v_rcp_f32_e32 v246, v246
	v_rcp_f32_e32 v247, v247
	v_lshlrev_b32_e32 v204, 16, v196
	v_and_b32_e32 v196, 0xffff0000, v196
	v_mul_f32_e32 v246, v246, v204
	v_mul_f32_e32 v247, v247, v196
	v_pk_mul_f32 v[90:91], v[90:91], v[246:247]
	v_lshlrev_b32_e32 v246, 16, v205
	v_and_b32_e32 v247, 0xffff0000, v205
	v_max_f32_e32 v246, 0xda24260, v246
	v_max_f32_e32 v247, 0xda24260, v247
	v_rcp_f32_e32 v246, v246
	v_rcp_f32_e32 v247, v247
	v_lshlrev_b32_e32 v205, 16, v197
	v_and_b32_e32 v197, 0xffff0000, v197
	v_mul_f32_e32 v246, v246, v205
	v_mul_f32_e32 v247, v247, v197
	v_pk_mul_f32 v[92:93], v[92:93], v[246:247]
	v_lshlrev_b32_e32 v246, 16, v206
	v_and_b32_e32 v247, 0xffff0000, v206
	v_max_f32_e32 v246, 0xda24260, v246
	v_max_f32_e32 v247, 0xda24260, v247
	v_rcp_f32_e32 v246, v246
	v_rcp_f32_e32 v247, v247
	v_lshlrev_b32_e32 v206, 16, v198
	v_and_b32_e32 v198, 0xffff0000, v198
	v_mul_f32_e32 v246, v246, v206
	v_mul_f32_e32 v247, v247, v198
	v_pk_mul_f32 v[86:87], v[86:87], v[246:247]
	v_lshlrev_b32_e32 v246, 16, v207
	v_and_b32_e32 v247, 0xffff0000, v207
	v_max_f32_e32 v246, 0xda24260, v246
	v_max_f32_e32 v247, 0xda24260, v247
	v_rcp_f32_e32 v246, v246
	v_rcp_f32_e32 v247, v247
	v_lshlrev_b32_e32 v207, 16, v199
	v_and_b32_e32 v199, 0xffff0000, v199
	v_mul_f32_e32 v246, v246, v207
	v_mul_f32_e32 v247, v247, v199
	v_pk_mul_f32 v[88:89], v[88:89], v[246:247]
	s_add_u32 vcc_lo, s30, 0x5a5000
	s_addc_u32 vcc_hi, s31, 0
	global_load_dwordx4 v[192:195], v245, vcc
	global_load_dwordx4 v[196:199], v245, vcc offset:256
	s_add_u32 vcc_lo, s30, 0x5a7000
	s_addc_u32 vcc_hi, s31, 0
	global_load_dwordx4 v[200:203], v245, vcc
	global_load_dwordx4 v[204:207], v245, vcc offset:256
	s_waitcnt vmcnt(13)
	v_lshlrev_b32_e32 v246, 16, v216
	v_and_b32_e32 v247, 0xffff0000, v216
	v_max_f32_e32 v246, 0xda24260, v246
	v_max_f32_e32 v247, 0xda24260, v247
	v_rcp_f32_e32 v246, v246
	v_rcp_f32_e32 v247, v247
	v_lshlrev_b32_e32 v216, 16, v208
	v_and_b32_e32 v208, 0xffff0000, v208
	v_mul_f32_e32 v246, v246, v216
	v_mul_f32_e32 v247, v247, v208
	v_pk_mul_f32 v[82:83], v[82:83], v[246:247]
	v_lshlrev_b32_e32 v246, 16, v217
	v_and_b32_e32 v247, 0xffff0000, v217
	v_max_f32_e32 v246, 0xda24260, v246
	v_max_f32_e32 v247, 0xda24260, v247
	v_rcp_f32_e32 v246, v246
	v_rcp_f32_e32 v247, v247
	v_lshlrev_b32_e32 v217, 16, v209
	v_and_b32_e32 v209, 0xffff0000, v209
	v_mul_f32_e32 v246, v246, v217
	v_mul_f32_e32 v247, v247, v209
	v_pk_mul_f32 v[84:85], v[84:85], v[246:247]
	v_lshlrev_b32_e32 v246, 16, v218
	v_and_b32_e32 v247, 0xffff0000, v218
	v_max_f32_e32 v246, 0xda24260, v246
	v_max_f32_e32 v247, 0xda24260, v247
	v_rcp_f32_e32 v246, v246
	v_rcp_f32_e32 v247, v247
	v_lshlrev_b32_e32 v218, 16, v210
	v_and_b32_e32 v210, 0xffff0000, v210
	v_mul_f32_e32 v246, v246, v218
	v_mul_f32_e32 v247, v247, v210
	v_pk_mul_f32 v[78:79], v[78:79], v[246:247]
	v_lshlrev_b32_e32 v246, 16, v219
	v_and_b32_e32 v247, 0xffff0000, v219
	v_max_f32_e32 v246, 0xda24260, v246
	v_max_f32_e32 v247, 0xda24260, v247
	v_rcp_f32_e32 v246, v246
	v_rcp_f32_e32 v247, v247
	v_lshlrev_b32_e32 v219, 16, v211
	v_and_b32_e32 v211, 0xffff0000, v211
	v_mul_f32_e32 v246, v246, v219
	v_mul_f32_e32 v247, v247, v211
	v_pk_mul_f32 v[80:81], v[80:81], v[246:247]
	s_waitcnt vmcnt(12)
	v_lshlrev_b32_e32 v246, 16, v220
	v_and_b32_e32 v247, 0xffff0000, v220
	v_max_f32_e32 v246, 0xda24260, v246
	v_max_f32_e32 v247, 0xda24260, v247
	v_rcp_f32_e32 v246, v246
	v_rcp_f32_e32 v247, v247
	v_lshlrev_b32_e32 v220, 16, v212
	v_and_b32_e32 v212, 0xffff0000, v212
	v_mul_f32_e32 v246, v246, v220
	v_mul_f32_e32 v247, v247, v212
	v_pk_mul_f32 v[74:75], v[74:75], v[246:247]
	v_lshlrev_b32_e32 v246, 16, v221
	v_and_b32_e32 v247, 0xffff0000, v221
	v_max_f32_e32 v246, 0xda24260, v246
	v_max_f32_e32 v247, 0xda24260, v247
	v_rcp_f32_e32 v246, v246
	v_rcp_f32_e32 v247, v247
	v_lshlrev_b32_e32 v221, 16, v213
	v_and_b32_e32 v213, 0xffff0000, v213
	v_mul_f32_e32 v246, v246, v221
	v_mul_f32_e32 v247, v247, v213
	v_pk_mul_f32 v[76:77], v[76:77], v[246:247]
	v_lshlrev_b32_e32 v246, 16, v222
	v_and_b32_e32 v247, 0xffff0000, v222
	v_max_f32_e32 v246, 0xda24260, v246
	v_max_f32_e32 v247, 0xda24260, v247
	v_rcp_f32_e32 v246, v246
	v_rcp_f32_e32 v247, v247
	v_lshlrev_b32_e32 v222, 16, v214
	v_and_b32_e32 v214, 0xffff0000, v214
	v_mul_f32_e32 v246, v246, v222
	v_mul_f32_e32 v247, v247, v214
	v_pk_mul_f32 v[70:71], v[70:71], v[246:247]
	v_lshlrev_b32_e32 v246, 16, v223
	v_and_b32_e32 v247, 0xffff0000, v223
	v_max_f32_e32 v246, 0xda24260, v246
	v_max_f32_e32 v247, 0xda24260, v247
	v_rcp_f32_e32 v246, v246
	v_rcp_f32_e32 v247, v247
	v_lshlrev_b32_e32 v223, 16, v215
	v_and_b32_e32 v215, 0xffff0000, v215
	v_mul_f32_e32 v246, v246, v223
	v_mul_f32_e32 v247, v247, v215
	v_pk_mul_f32 v[72:73], v[72:73], v[246:247]
	s_add_u32 vcc_lo, s30, 0x635000
	s_addc_u32 vcc_hi, s31, 0
	global_load_dwordx4 v[208:211], v245, vcc
	global_load_dwordx4 v[212:215], v245, vcc offset:256
	s_add_u32 vcc_lo, s30, 0x637000
	s_addc_u32 vcc_hi, s31, 0
	global_load_dwordx4 v[216:219], v245, vcc
	global_load_dwordx4 v[220:223], v245, vcc offset:256
	s_waitcnt vmcnt(13)
	v_lshlrev_b32_e32 v246, 16, v142
	v_and_b32_e32 v247, 0xffff0000, v142
	v_max_f32_e32 v246, 0xda24260, v246
	v_max_f32_e32 v247, 0xda24260, v247
	v_rcp_f32_e32 v246, v246
	v_rcp_f32_e32 v247, v247
	v_lshlrev_b32_e32 v142, 16, v134
	v_and_b32_e32 v134, 0xffff0000, v134
	v_mul_f32_e32 v246, v246, v142
	v_mul_f32_e32 v247, v247, v134
	v_pk_mul_f32 v[66:67], v[66:67], v[246:247]
	v_lshlrev_b32_e32 v246, 16, v143
	v_and_b32_e32 v247, 0xffff0000, v143
	v_max_f32_e32 v246, 0xda24260, v246
	v_max_f32_e32 v247, 0xda24260, v247
	v_rcp_f32_e32 v246, v246
	v_rcp_f32_e32 v247, v247
	v_lshlrev_b32_e32 v143, 16, v135
	v_and_b32_e32 v135, 0xffff0000, v135
	v_mul_f32_e32 v246, v246, v143
	v_mul_f32_e32 v247, v247, v135
	v_pk_mul_f32 v[68:69], v[68:69], v[246:247]
	v_lshlrev_b32_e32 v246, 16, v144
	v_and_b32_e32 v247, 0xffff0000, v144
	v_max_f32_e32 v246, 0xda24260, v246
	v_max_f32_e32 v247, 0xda24260, v247
	v_rcp_f32_e32 v246, v246
	v_rcp_f32_e32 v247, v247
	v_lshlrev_b32_e32 v144, 16, v136
	v_and_b32_e32 v136, 0xffff0000, v136
	v_mul_f32_e32 v246, v246, v144
	v_mul_f32_e32 v247, v247, v136
	v_pk_mul_f32 v[62:63], v[62:63], v[246:247]
	v_lshlrev_b32_e32 v246, 16, v145
	v_and_b32_e32 v247, 0xffff0000, v145
	v_max_f32_e32 v246, 0xda24260, v246
	v_max_f32_e32 v247, 0xda24260, v247
	v_rcp_f32_e32 v246, v246
	v_rcp_f32_e32 v247, v247
	v_lshlrev_b32_e32 v145, 16, v137
	v_and_b32_e32 v137, 0xffff0000, v137
	v_mul_f32_e32 v246, v246, v145
	v_mul_f32_e32 v247, v247, v137
	v_pk_mul_f32 v[64:65], v[64:65], v[246:247]
	s_waitcnt vmcnt(12)
	v_lshlrev_b32_e32 v246, 16, v146
	v_and_b32_e32 v247, 0xffff0000, v146
	v_max_f32_e32 v246, 0xda24260, v246
	v_max_f32_e32 v247, 0xda24260, v247
	v_rcp_f32_e32 v246, v246
	v_rcp_f32_e32 v247, v247
	v_lshlrev_b32_e32 v146, 16, v138
	v_and_b32_e32 v138, 0xffff0000, v138
	v_mul_f32_e32 v246, v246, v146
	v_mul_f32_e32 v247, v247, v138
	v_pk_mul_f32 v[58:59], v[58:59], v[246:247]
	v_lshlrev_b32_e32 v246, 16, v147
	v_and_b32_e32 v247, 0xffff0000, v147
	v_max_f32_e32 v246, 0xda24260, v246
	v_max_f32_e32 v247, 0xda24260, v247
	v_rcp_f32_e32 v246, v246
	v_rcp_f32_e32 v247, v247
	v_lshlrev_b32_e32 v147, 16, v139
	v_and_b32_e32 v139, 0xffff0000, v139
	v_mul_f32_e32 v246, v246, v147
	v_mul_f32_e32 v247, v247, v139
	v_pk_mul_f32 v[60:61], v[60:61], v[246:247]
	v_lshlrev_b32_e32 v246, 16, v148
	v_and_b32_e32 v247, 0xffff0000, v148
	v_max_f32_e32 v246, 0xda24260, v246
	v_max_f32_e32 v247, 0xda24260, v247
	v_rcp_f32_e32 v246, v246
	v_rcp_f32_e32 v247, v247
	v_lshlrev_b32_e32 v148, 16, v140
	v_and_b32_e32 v140, 0xffff0000, v140
	v_mul_f32_e32 v246, v246, v148
	v_mul_f32_e32 v247, v247, v140
	v_pk_mul_f32 v[54:55], v[54:55], v[246:247]
	v_lshlrev_b32_e32 v246, 16, v149
	v_and_b32_e32 v247, 0xffff0000, v149
	v_max_f32_e32 v246, 0xda24260, v246
	v_max_f32_e32 v247, 0xda24260, v247
	v_rcp_f32_e32 v246, v246
	v_rcp_f32_e32 v247, v247
	v_lshlrev_b32_e32 v149, 16, v141
	v_and_b32_e32 v141, 0xffff0000, v141
	v_mul_f32_e32 v246, v246, v149
	v_mul_f32_e32 v247, v247, v141
	v_pk_mul_f32 v[56:57], v[56:57], v[246:247]
	s_waitcnt vmcnt(9)
	v_lshlrev_b32_e32 v246, 16, v158
	v_and_b32_e32 v247, 0xffff0000, v158
	v_max_f32_e32 v246, 0xda24260, v246
	v_max_f32_e32 v247, 0xda24260, v247
	v_rcp_f32_e32 v246, v246
	v_rcp_f32_e32 v247, v247
	v_lshlrev_b32_e32 v158, 16, v150
	v_and_b32_e32 v150, 0xffff0000, v150
	v_mul_f32_e32 v246, v246, v158
	v_mul_f32_e32 v247, v247, v150
	v_pk_mul_f32 v[50:51], v[50:51], v[246:247]
	v_lshlrev_b32_e32 v246, 16, v159
	v_and_b32_e32 v247, 0xffff0000, v159
	v_max_f32_e32 v246, 0xda24260, v246
	v_max_f32_e32 v247, 0xda24260, v247
	v_rcp_f32_e32 v246, v246
	v_rcp_f32_e32 v247, v247
	v_lshlrev_b32_e32 v159, 16, v151
	v_and_b32_e32 v151, 0xffff0000, v151
	v_mul_f32_e32 v246, v246, v159
	v_mul_f32_e32 v247, v247, v151
	v_pk_mul_f32 v[52:53], v[52:53], v[246:247]
	v_lshlrev_b32_e32 v246, 16, v160
	v_and_b32_e32 v247, 0xffff0000, v160
	v_max_f32_e32 v246, 0xda24260, v246
	v_max_f32_e32 v247, 0xda24260, v247
	v_rcp_f32_e32 v246, v246
	v_rcp_f32_e32 v247, v247
	v_lshlrev_b32_e32 v160, 16, v152
	v_and_b32_e32 v152, 0xffff0000, v152
	v_mul_f32_e32 v246, v246, v160
	v_mul_f32_e32 v247, v247, v152
	v_pk_mul_f32 v[46:47], v[46:47], v[246:247]
	v_lshlrev_b32_e32 v246, 16, v161
	v_and_b32_e32 v247, 0xffff0000, v161
	v_max_f32_e32 v246, 0xda24260, v246
	v_max_f32_e32 v247, 0xda24260, v247
	v_rcp_f32_e32 v246, v246
	v_rcp_f32_e32 v247, v247
	v_lshlrev_b32_e32 v161, 16, v153
	v_and_b32_e32 v153, 0xffff0000, v153
	v_mul_f32_e32 v246, v246, v161
	v_mul_f32_e32 v247, v247, v153
	v_pk_mul_f32 v[48:49], v[48:49], v[246:247]
	s_waitcnt vmcnt(8)
	v_lshlrev_b32_e32 v246, 16, v188
	v_and_b32_e32 v247, 0xffff0000, v188
	v_max_f32_e32 v246, 0xda24260, v246
	v_max_f32_e32 v247, 0xda24260, v247
	v_rcp_f32_e32 v246, v246
	v_rcp_f32_e32 v247, v247
	v_lshlrev_b32_e32 v188, 16, v154
	v_and_b32_e32 v154, 0xffff0000, v154
	v_mul_f32_e32 v246, v246, v188
	v_mul_f32_e32 v247, v247, v154
	v_pk_mul_f32 v[42:43], v[42:43], v[246:247]
	v_lshlrev_b32_e32 v246, 16, v189
	v_and_b32_e32 v247, 0xffff0000, v189
	v_max_f32_e32 v246, 0xda24260, v246
	v_max_f32_e32 v247, 0xda24260, v247
	v_rcp_f32_e32 v246, v246
	v_rcp_f32_e32 v247, v247
	v_lshlrev_b32_e32 v189, 16, v155
	v_and_b32_e32 v155, 0xffff0000, v155
	v_mul_f32_e32 v246, v246, v189
	v_mul_f32_e32 v247, v247, v155
	v_pk_mul_f32 v[44:45], v[44:45], v[246:247]
	v_lshlrev_b32_e32 v246, 16, v190
	v_and_b32_e32 v247, 0xffff0000, v190
	v_max_f32_e32 v246, 0xda24260, v246
	v_max_f32_e32 v247, 0xda24260, v247
	v_rcp_f32_e32 v246, v246
	v_rcp_f32_e32 v247, v247
	v_lshlrev_b32_e32 v190, 16, v156
	v_and_b32_e32 v156, 0xffff0000, v156
	v_mul_f32_e32 v246, v246, v190
	v_mul_f32_e32 v247, v247, v156
	v_pk_mul_f32 v[38:39], v[38:39], v[246:247]
	v_lshlrev_b32_e32 v246, 16, v191
	v_and_b32_e32 v247, 0xffff0000, v191
	v_max_f32_e32 v246, 0xda24260, v246
	v_max_f32_e32 v247, 0xda24260, v247
	v_rcp_f32_e32 v246, v246
	v_rcp_f32_e32 v247, v247
	v_lshlrev_b32_e32 v191, 16, v157
	v_and_b32_e32 v157, 0xffff0000, v157
	v_mul_f32_e32 v246, v246, v191
	v_mul_f32_e32 v247, v247, v157
	v_pk_mul_f32 v[40:41], v[40:41], v[246:247]
	s_waitcnt vmcnt(5)
	v_lshlrev_b32_e32 v246, 16, v200
	v_and_b32_e32 v247, 0xffff0000, v200
	v_max_f32_e32 v246, 0xda24260, v246
	v_max_f32_e32 v247, 0xda24260, v247
	v_rcp_f32_e32 v246, v246
	v_rcp_f32_e32 v247, v247
	v_lshlrev_b32_e32 v200, 16, v192
	v_and_b32_e32 v192, 0xffff0000, v192
	v_mul_f32_e32 v246, v246, v200
	v_mul_f32_e32 v247, v247, v192
	v_pk_mul_f32 v[34:35], v[34:35], v[246:247]
	v_lshlrev_b32_e32 v246, 16, v201
	v_and_b32_e32 v247, 0xffff0000, v201
	v_max_f32_e32 v246, 0xda24260, v246
	v_max_f32_e32 v247, 0xda24260, v247
	v_rcp_f32_e32 v246, v246
	v_rcp_f32_e32 v247, v247
	v_lshlrev_b32_e32 v201, 16, v193
	v_and_b32_e32 v193, 0xffff0000, v193
	v_mul_f32_e32 v246, v246, v201
	v_mul_f32_e32 v247, v247, v193
	v_pk_mul_f32 v[36:37], v[36:37], v[246:247]
	v_lshlrev_b32_e32 v246, 16, v202
	v_and_b32_e32 v247, 0xffff0000, v202
	v_max_f32_e32 v246, 0xda24260, v246
	v_max_f32_e32 v247, 0xda24260, v247
	v_rcp_f32_e32 v246, v246
	v_rcp_f32_e32 v247, v247
	v_lshlrev_b32_e32 v202, 16, v194
	v_and_b32_e32 v194, 0xffff0000, v194
	v_mul_f32_e32 v246, v246, v202
	v_mul_f32_e32 v247, v247, v194
	v_pk_mul_f32 v[30:31], v[30:31], v[246:247]
	v_lshlrev_b32_e32 v246, 16, v203
	v_and_b32_e32 v247, 0xffff0000, v203
	v_max_f32_e32 v246, 0xda24260, v246
	v_max_f32_e32 v247, 0xda24260, v247
	v_rcp_f32_e32 v246, v246
	v_rcp_f32_e32 v247, v247
	v_lshlrev_b32_e32 v203, 16, v195
	v_and_b32_e32 v195, 0xffff0000, v195
	v_mul_f32_e32 v246, v246, v203
	v_mul_f32_e32 v247, v247, v195
	v_pk_mul_f32 v[32:33], v[32:33], v[246:247]
	s_waitcnt vmcnt(4)
	v_lshlrev_b32_e32 v246, 16, v204
	v_and_b32_e32 v247, 0xffff0000, v204
	v_max_f32_e32 v246, 0xda24260, v246
	v_max_f32_e32 v247, 0xda24260, v247
	v_rcp_f32_e32 v246, v246
	v_rcp_f32_e32 v247, v247
	v_lshlrev_b32_e32 v204, 16, v196
	v_and_b32_e32 v196, 0xffff0000, v196
	v_mul_f32_e32 v246, v246, v204
	v_mul_f32_e32 v247, v247, v196
	v_pk_mul_f32 v[26:27], v[26:27], v[246:247]
	v_lshlrev_b32_e32 v246, 16, v205
	v_and_b32_e32 v247, 0xffff0000, v205
	v_max_f32_e32 v246, 0xda24260, v246
	v_max_f32_e32 v247, 0xda24260, v247
	v_rcp_f32_e32 v246, v246
	v_rcp_f32_e32 v247, v247
	v_lshlrev_b32_e32 v205, 16, v197
	v_and_b32_e32 v197, 0xffff0000, v197
	v_mul_f32_e32 v246, v246, v205
	v_mul_f32_e32 v247, v247, v197
	v_pk_mul_f32 v[28:29], v[28:29], v[246:247]
	v_lshlrev_b32_e32 v246, 16, v206
	v_and_b32_e32 v247, 0xffff0000, v206
	v_max_f32_e32 v246, 0xda24260, v246
	v_max_f32_e32 v247, 0xda24260, v247
	v_rcp_f32_e32 v246, v246
	v_rcp_f32_e32 v247, v247
	v_lshlrev_b32_e32 v206, 16, v198
	v_and_b32_e32 v198, 0xffff0000, v198
	v_mul_f32_e32 v246, v246, v206
	v_mul_f32_e32 v247, v247, v198
	v_pk_mul_f32 v[22:23], v[22:23], v[246:247]
	v_lshlrev_b32_e32 v246, 16, v207
	v_and_b32_e32 v247, 0xffff0000, v207
	v_max_f32_e32 v246, 0xda24260, v246
	v_max_f32_e32 v247, 0xda24260, v247
	v_rcp_f32_e32 v246, v246
	v_rcp_f32_e32 v247, v247
	v_lshlrev_b32_e32 v207, 16, v199
	v_and_b32_e32 v199, 0xffff0000, v199
	v_mul_f32_e32 v246, v246, v207
	v_mul_f32_e32 v247, v247, v199
	v_pk_mul_f32 v[24:25], v[24:25], v[246:247]
	s_waitcnt vmcnt(1)
	v_lshlrev_b32_e32 v246, 16, v216
	v_and_b32_e32 v247, 0xffff0000, v216
	v_max_f32_e32 v246, 0xda24260, v246
	v_max_f32_e32 v247, 0xda24260, v247
	v_rcp_f32_e32 v246, v246
	v_rcp_f32_e32 v247, v247
	v_lshlrev_b32_e32 v216, 16, v208
	v_and_b32_e32 v208, 0xffff0000, v208
	v_mul_f32_e32 v246, v246, v216
	v_mul_f32_e32 v247, v247, v208
	v_pk_mul_f32 v[18:19], v[18:19], v[246:247]
	v_lshlrev_b32_e32 v246, 16, v217
	v_and_b32_e32 v247, 0xffff0000, v217
	v_max_f32_e32 v246, 0xda24260, v246
	v_max_f32_e32 v247, 0xda24260, v247
	v_rcp_f32_e32 v246, v246
	v_rcp_f32_e32 v247, v247
	v_lshlrev_b32_e32 v217, 16, v209
	v_and_b32_e32 v209, 0xffff0000, v209
	v_mul_f32_e32 v246, v246, v217
	v_mul_f32_e32 v247, v247, v209
	v_pk_mul_f32 v[20:21], v[20:21], v[246:247]
	v_lshlrev_b32_e32 v246, 16, v218
	v_and_b32_e32 v247, 0xffff0000, v218
	v_max_f32_e32 v246, 0xda24260, v246
	v_max_f32_e32 v247, 0xda24260, v247
	v_rcp_f32_e32 v246, v246
	v_rcp_f32_e32 v247, v247
	v_lshlrev_b32_e32 v218, 16, v210
	v_and_b32_e32 v210, 0xffff0000, v210
	v_mul_f32_e32 v246, v246, v218
	v_mul_f32_e32 v247, v247, v210
	v_pk_mul_f32 v[14:15], v[14:15], v[246:247]
	v_lshlrev_b32_e32 v246, 16, v219
	v_and_b32_e32 v247, 0xffff0000, v219
	v_max_f32_e32 v246, 0xda24260, v246
	v_max_f32_e32 v247, 0xda24260, v247
	v_rcp_f32_e32 v246, v246
	v_rcp_f32_e32 v247, v247
	v_lshlrev_b32_e32 v219, 16, v211
	v_and_b32_e32 v211, 0xffff0000, v211
	v_mul_f32_e32 v246, v246, v219
	v_mul_f32_e32 v247, v247, v211
	v_pk_mul_f32 v[16:17], v[16:17], v[246:247]
	s_waitcnt vmcnt(0)
	v_lshlrev_b32_e32 v246, 16, v220
	v_and_b32_e32 v247, 0xffff0000, v220
	v_max_f32_e32 v246, 0xda24260, v246
	v_max_f32_e32 v247, 0xda24260, v247
	v_rcp_f32_e32 v246, v246
	v_rcp_f32_e32 v247, v247
	v_lshlrev_b32_e32 v220, 16, v212
	v_and_b32_e32 v212, 0xffff0000, v212
	v_mul_f32_e32 v246, v246, v220
	v_mul_f32_e32 v247, v247, v212
	v_pk_mul_f32 v[10:11], v[10:11], v[246:247]
	v_lshlrev_b32_e32 v246, 16, v221
	v_and_b32_e32 v247, 0xffff0000, v221
	v_max_f32_e32 v246, 0xda24260, v246
	v_max_f32_e32 v247, 0xda24260, v247
	v_rcp_f32_e32 v246, v246
	v_rcp_f32_e32 v247, v247
	v_lshlrev_b32_e32 v221, 16, v213
	v_and_b32_e32 v213, 0xffff0000, v213
	v_mul_f32_e32 v246, v246, v221
	v_mul_f32_e32 v247, v247, v213
	v_pk_mul_f32 v[12:13], v[12:13], v[246:247]
	v_lshlrev_b32_e32 v246, 16, v222
	v_and_b32_e32 v247, 0xffff0000, v222
	v_max_f32_e32 v246, 0xda24260, v246
	v_max_f32_e32 v247, 0xda24260, v247
	v_rcp_f32_e32 v246, v246
	v_rcp_f32_e32 v247, v247
	v_lshlrev_b32_e32 v222, 16, v214
	v_and_b32_e32 v214, 0xffff0000, v214
	v_mul_f32_e32 v246, v246, v222
	v_mul_f32_e32 v247, v247, v214
	v_pk_mul_f32 v[6:7], v[6:7], v[246:247]
	v_lshlrev_b32_e32 v246, 16, v223
	v_and_b32_e32 v247, 0xffff0000, v223
	v_max_f32_e32 v246, 0xda24260, v246
	v_max_f32_e32 v247, 0xda24260, v247
	v_rcp_f32_e32 v246, v246
	v_rcp_f32_e32 v247, v247
	v_lshlrev_b32_e32 v223, 16, v215
	v_and_b32_e32 v215, 0xffff0000, v215
	v_mul_f32_e32 v246, v246, v223
	v_mul_f32_e32 v247, v247, v215
	v_pk_mul_f32 v[8:9], v[8:9], v[246:247]
	s_branch .LBB0_1644
.LBB0_1647:
	v_or_b32_e32 v246, s27, v184
	v_add_u32_e32 v245, s26, v1
	v_mul_u32_u24_e32 v247, 0x9000, v245
	v_lshl_add_u32 v247, v246, 1, v247
	s_add_u32 vcc_lo, s30, 0x7000
	s_addc_u32 vcc_hi, s31, 0
	global_load_dwordx4 v[134:137], v247, vcc
	global_load_dwordx4 v[138:141], v247, vcc offset:256
	s_add_u32 vcc_lo, s30, 0x97000
	s_addc_u32 vcc_hi, s31, 0
	global_load_dwordx4 v[142:145], v247, vcc
	global_load_dwordx4 v[146:149], v247, vcc offset:256
	s_add_u32 vcc_lo, s30, 0x127000
	s_addc_u32 vcc_hi, s31, 0
	global_load_dwordx4 v[150:153], v247, vcc
	global_load_dwordx4 v[154:157], v247, vcc offset:256
	s_add_u32 vcc_lo, s30, 0x1b7000
	s_addc_u32 vcc_hi, s31, 0
	global_load_dwordx4 v[158:161], v247, vcc
	global_load_dwordx4 v[188:191], v247, vcc offset:256
	s_add_u32 vcc_lo, s30, 0x487000
	s_addc_u32 vcc_hi, s31, 0
	global_load_dwordx4 v[192:195], v247, vcc
	global_load_dwordx4 v[196:199], v247, vcc offset:256
	s_add_u32 vcc_lo, s30, 0x517000
	s_addc_u32 vcc_hi, s31, 0
	global_load_dwordx4 v[200:203], v247, vcc
	global_load_dwordx4 v[204:207], v247, vcc offset:256
	s_add_u32 vcc_lo, s30, 0x5a7000
	s_addc_u32 vcc_hi, s31, 0
	global_load_dwordx4 v[208:211], v247, vcc
	global_load_dwordx4 v[212:215], v247, vcc offset:256
	s_add_u32 vcc_lo, s30, 0x637000
	s_addc_u32 vcc_hi, s31, 0
	global_load_dwordx4 v[216:219], v247, vcc
	global_load_dwordx4 v[220:223], v247, vcc offset:256
	v_lshlrev_b32_e32 v245, 13, v245
	v_lshl_add_u32 v245, v246, 1, v245
	s_and_b64 vcc, exec, s[34:35]
	s_cbranch_vccz .LBB0_1649
	s_barrier
.LBB0_1649:
	s_waitcnt vmcnt(15)
	v_lshlrev_b32_e32 v246, 16, v134
	v_and_b32_e32 v247, 0xffff0000, v134
	v_pk_mul_f32 v[130:131], v[130:131], v[246:247]
	v_lshlrev_b32_e32 v246, 16, v135
	v_and_b32_e32 v247, 0xffff0000, v135
	v_pk_mul_f32 v[132:133], v[132:133], v[246:247]
	v_lshlrev_b32_e32 v246, 16, v136
	v_and_b32_e32 v247, 0xffff0000, v136
	v_pk_mul_f32 v[126:127], v[126:127], v[246:247]
	v_lshlrev_b32_e32 v246, 16, v137
	v_and_b32_e32 v247, 0xffff0000, v137
	v_pk_mul_f32 v[128:129], v[128:129], v[246:247]
	v_cvt_pk_bf16_f32 v134, v130, v131
	v_cvt_pk_bf16_f32 v135, v132, v133
	v_cvt_pk_bf16_f32 v136, v126, v127
	v_cvt_pk_bf16_f32 v137, v128, v129
	global_store_dwordx4 v245, v[134:137], s[18:19] sc0 sc1
	s_waitcnt vmcnt(15)
	v_lshlrev_b32_e32 v246, 16, v138
	v_and_b32_e32 v247, 0xffff0000, v138
	v_pk_mul_f32 v[122:123], v[122:123], v[246:247]
	v_lshlrev_b32_e32 v246, 16, v139
	v_and_b32_e32 v247, 0xffff0000, v139
	v_pk_mul_f32 v[124:125], v[124:125], v[246:247]
	v_lshlrev_b32_e32 v246, 16, v140
	v_and_b32_e32 v247, 0xffff0000, v140
	v_pk_mul_f32 v[118:119], v[118:119], v[246:247]
	v_lshlrev_b32_e32 v246, 16, v141
	v_and_b32_e32 v247, 0xffff0000, v141
	v_pk_mul_f32 v[120:121], v[120:121], v[246:247]
	v_cvt_pk_bf16_f32 v138, v122, v123
	v_cvt_pk_bf16_f32 v139, v124, v125
	v_cvt_pk_bf16_f32 v140, v118, v119
	v_cvt_pk_bf16_f32 v141, v120, v121
	global_store_dwordx4 v245, v[138:141], s[18:19] offset:256 sc0 sc1
	s_add_u32 vcc_lo, s18, 0x20000
	s_addc_u32 vcc_hi, s19, 0
	s_waitcnt vmcnt(15)
	v_lshlrev_b32_e32 v246, 16, v142
	v_and_b32_e32 v247, 0xffff0000, v142
	v_pk_mul_f32 v[114:115], v[114:115], v[246:247]
	v_lshlrev_b32_e32 v246, 16, v143
	v_and_b32_e32 v247, 0xffff0000, v143
	v_pk_mul_f32 v[116:117], v[116:117], v[246:247]
	v_lshlrev_b32_e32 v246, 16, v144
	v_and_b32_e32 v247, 0xffff0000, v144
	v_pk_mul_f32 v[110:111], v[110:111], v[246:247]
	v_lshlrev_b32_e32 v246, 16, v145
	v_and_b32_e32 v247, 0xffff0000, v145
	v_pk_mul_f32 v[112:113], v[112:113], v[246:247]
	v_cvt_pk_bf16_f32 v142, v114, v115
	v_cvt_pk_bf16_f32 v143, v116, v117
	v_cvt_pk_bf16_f32 v144, v110, v111
	v_cvt_pk_bf16_f32 v145, v112, v113
	global_store_dwordx4 v245, v[142:145], vcc sc0 sc1
	s_waitcnt vmcnt(15)
	v_lshlrev_b32_e32 v246, 16, v146
	v_and_b32_e32 v247, 0xffff0000, v146
	v_pk_mul_f32 v[106:107], v[106:107], v[246:247]
	v_lshlrev_b32_e32 v246, 16, v147
	v_and_b32_e32 v247, 0xffff0000, v147
	v_pk_mul_f32 v[108:109], v[108:109], v[246:247]
	v_lshlrev_b32_e32 v246, 16, v148
	v_and_b32_e32 v247, 0xffff0000, v148
	v_pk_mul_f32 v[102:103], v[102:103], v[246:247]
	v_lshlrev_b32_e32 v246, 16, v149
	v_and_b32_e32 v247, 0xffff0000, v149
	v_pk_mul_f32 v[104:105], v[104:105], v[246:247]
	v_cvt_pk_bf16_f32 v146, v106, v107
	v_cvt_pk_bf16_f32 v147, v108, v109
	v_cvt_pk_bf16_f32 v148, v102, v103
	v_cvt_pk_bf16_f32 v149, v104, v105
	global_store_dwordx4 v245, v[146:149], vcc offset:256 sc0 sc1
	s_add_u32 vcc_lo, s18, 0x40000
	s_addc_u32 vcc_hi, s19, 0
	s_waitcnt vmcnt(15)
	v_lshlrev_b32_e32 v246, 16, v150
	v_and_b32_e32 v247, 0xffff0000, v150
	v_pk_mul_f32 v[98:99], v[98:99], v[246:247]
	v_lshlrev_b32_e32 v246, 16, v151
	v_and_b32_e32 v247, 0xffff0000, v151
	v_pk_mul_f32 v[100:101], v[100:101], v[246:247]
	v_lshlrev_b32_e32 v246, 16, v152
	v_and_b32_e32 v247, 0xffff0000, v152
	v_pk_mul_f32 v[94:95], v[94:95], v[246:247]
	v_lshlrev_b32_e32 v246, 16, v153
	v_and_b32_e32 v247, 0xffff0000, v153
	v_pk_mul_f32 v[96:97], v[96:97], v[246:247]
	v_cvt_pk_bf16_f32 v150, v98, v99
	v_cvt_pk_bf16_f32 v151, v100, v101
	v_cvt_pk_bf16_f32 v152, v94, v95
	v_cvt_pk_bf16_f32 v153, v96, v97
	global_store_dwordx4 v245, v[150:153], vcc sc0 sc1
	s_waitcnt vmcnt(15)
	v_lshlrev_b32_e32 v246, 16, v154
	v_and_b32_e32 v247, 0xffff0000, v154
	v_pk_mul_f32 v[90:91], v[90:91], v[246:247]
	v_lshlrev_b32_e32 v246, 16, v155
	v_and_b32_e32 v247, 0xffff0000, v155
	v_pk_mul_f32 v[92:93], v[92:93], v[246:247]
	v_lshlrev_b32_e32 v246, 16, v156
	v_and_b32_e32 v247, 0xffff0000, v156
	v_pk_mul_f32 v[86:87], v[86:87], v[246:247]
	v_lshlrev_b32_e32 v246, 16, v157
	v_and_b32_e32 v247, 0xffff0000, v157
	v_pk_mul_f32 v[88:89], v[88:89], v[246:247]
	v_cvt_pk_bf16_f32 v154, v90, v91
	v_cvt_pk_bf16_f32 v155, v92, v93
	v_cvt_pk_bf16_f32 v156, v86, v87
	v_cvt_pk_bf16_f32 v157, v88, v89
	global_store_dwordx4 v245, v[154:157], vcc offset:256 sc0 sc1
	s_add_u32 vcc_lo, s18, 0x60000
	s_addc_u32 vcc_hi, s19, 0
	s_waitcnt vmcnt(15)
	v_lshlrev_b32_e32 v246, 16, v158
	v_and_b32_e32 v247, 0xffff0000, v158
	v_pk_mul_f32 v[82:83], v[82:83], v[246:247]
	v_lshlrev_b32_e32 v246, 16, v159
	v_and_b32_e32 v247, 0xffff0000, v159
	v_pk_mul_f32 v[84:85], v[84:85], v[246:247]
	v_lshlrev_b32_e32 v246, 16, v160
	v_and_b32_e32 v247, 0xffff0000, v160
	v_pk_mul_f32 v[78:79], v[78:79], v[246:247]
	v_lshlrev_b32_e32 v246, 16, v161
	v_and_b32_e32 v247, 0xffff0000, v161
	v_pk_mul_f32 v[80:81], v[80:81], v[246:247]
	v_cvt_pk_bf16_f32 v158, v82, v83
	v_cvt_pk_bf16_f32 v159, v84, v85
	v_cvt_pk_bf16_f32 v160, v78, v79
	v_cvt_pk_bf16_f32 v161, v80, v81
	global_store_dwordx4 v245, v[158:161], vcc sc0 sc1
	s_waitcnt vmcnt(15)
	v_lshlrev_b32_e32 v246, 16, v188
	v_and_b32_e32 v247, 0xffff0000, v188
	v_pk_mul_f32 v[74:75], v[74:75], v[246:247]
	v_lshlrev_b32_e32 v246, 16, v189
	v_and_b32_e32 v247, 0xffff0000, v189
	v_pk_mul_f32 v[76:77], v[76:77], v[246:247]
	v_lshlrev_b32_e32 v246, 16, v190
	v_and_b32_e32 v247, 0xffff0000, v190
	v_pk_mul_f32 v[70:71], v[70:71], v[246:247]
	v_lshlrev_b32_e32 v246, 16, v191
	v_and_b32_e32 v247, 0xffff0000, v191
	v_pk_mul_f32 v[72:73], v[72:73], v[246:247]
	v_cvt_pk_bf16_f32 v188, v74, v75
	v_cvt_pk_bf16_f32 v189, v76, v77
	v_cvt_pk_bf16_f32 v190, v70, v71
	v_cvt_pk_bf16_f32 v191, v72, v73
	global_store_dwordx4 v245, v[188:191], vcc offset:256 sc0 sc1
	s_add_u32 vcc_lo, s18, 0x100000
	s_addc_u32 vcc_hi, s19, 0
	s_waitcnt vmcnt(15)
	v_lshlrev_b32_e32 v246, 16, v192
	v_and_b32_e32 v247, 0xffff0000, v192
	v_pk_mul_f32 v[66:67], v[66:67], v[246:247]
	v_lshlrev_b32_e32 v246, 16, v193
	v_and_b32_e32 v247, 0xffff0000, v193
	v_pk_mul_f32 v[68:69], v[68:69], v[246:247]
	v_lshlrev_b32_e32 v246, 16, v194
	v_and_b32_e32 v247, 0xffff0000, v194
	v_pk_mul_f32 v[62:63], v[62:63], v[246:247]
	v_lshlrev_b32_e32 v246, 16, v195
	v_and_b32_e32 v247, 0xffff0000, v195
	v_pk_mul_f32 v[64:65], v[64:65], v[246:247]
	v_cvt_pk_bf16_f32 v192, v66, v67
	v_cvt_pk_bf16_f32 v193, v68, v69
	v_cvt_pk_bf16_f32 v194, v62, v63
	v_cvt_pk_bf16_f32 v195, v64, v65
	global_store_dwordx4 v245, v[192:195], vcc sc0 sc1
	s_waitcnt vmcnt(15)
	v_lshlrev_b32_e32 v246, 16, v196
	v_and_b32_e32 v247, 0xffff0000, v196
	v_pk_mul_f32 v[58:59], v[58:59], v[246:247]
	v_lshlrev_b32_e32 v246, 16, v197
	v_and_b32_e32 v247, 0xffff0000, v197
	v_pk_mul_f32 v[60:61], v[60:61], v[246:247]
	v_lshlrev_b32_e32 v246, 16, v198
	v_and_b32_e32 v247, 0xffff0000, v198
	v_pk_mul_f32 v[54:55], v[54:55], v[246:247]
	v_lshlrev_b32_e32 v246, 16, v199
	v_and_b32_e32 v247, 0xffff0000, v199
	v_pk_mul_f32 v[56:57], v[56:57], v[246:247]
	v_cvt_pk_bf16_f32 v196, v58, v59
	v_cvt_pk_bf16_f32 v197, v60, v61
	v_cvt_pk_bf16_f32 v198, v54, v55
	v_cvt_pk_bf16_f32 v199, v56, v57
	global_store_dwordx4 v245, v[196:199], vcc offset:256 sc0 sc1
	s_add_u32 vcc_lo, s18, 0x120000
	s_addc_u32 vcc_hi, s19, 0
	s_waitcnt vmcnt(15)
	v_lshlrev_b32_e32 v246, 16, v200
	v_and_b32_e32 v247, 0xffff0000, v200
	v_pk_mul_f32 v[50:51], v[50:51], v[246:247]
	v_lshlrev_b32_e32 v246, 16, v201
	v_and_b32_e32 v247, 0xffff0000, v201
	v_pk_mul_f32 v[52:53], v[52:53], v[246:247]
	v_lshlrev_b32_e32 v246, 16, v202
	v_and_b32_e32 v247, 0xffff0000, v202
	v_pk_mul_f32 v[46:47], v[46:47], v[246:247]
	v_lshlrev_b32_e32 v246, 16, v203
	v_and_b32_e32 v247, 0xffff0000, v203
	v_pk_mul_f32 v[48:49], v[48:49], v[246:247]
	v_cvt_pk_bf16_f32 v200, v50, v51
	v_cvt_pk_bf16_f32 v201, v52, v53
	v_cvt_pk_bf16_f32 v202, v46, v47
	v_cvt_pk_bf16_f32 v203, v48, v49
	global_store_dwordx4 v245, v[200:203], vcc sc0 sc1
	s_waitcnt vmcnt(15)
	v_lshlrev_b32_e32 v246, 16, v204
	v_and_b32_e32 v247, 0xffff0000, v204
	v_pk_mul_f32 v[42:43], v[42:43], v[246:247]
	v_lshlrev_b32_e32 v246, 16, v205
	v_and_b32_e32 v247, 0xffff0000, v205
	v_pk_mul_f32 v[44:45], v[44:45], v[246:247]
	v_lshlrev_b32_e32 v246, 16, v206
	v_and_b32_e32 v247, 0xffff0000, v206
	v_pk_mul_f32 v[38:39], v[38:39], v[246:247]
	v_lshlrev_b32_e32 v246, 16, v207
	v_and_b32_e32 v247, 0xffff0000, v207
	v_pk_mul_f32 v[40:41], v[40:41], v[246:247]
	v_cvt_pk_bf16_f32 v204, v42, v43
	v_cvt_pk_bf16_f32 v205, v44, v45
	v_cvt_pk_bf16_f32 v206, v38, v39
	v_cvt_pk_bf16_f32 v207, v40, v41
	global_store_dwordx4 v245, v[204:207], vcc offset:256 sc0 sc1
	s_add_u32 vcc_lo, s18, 0x140000
	s_addc_u32 vcc_hi, s19, 0
	s_waitcnt vmcnt(15)
	v_lshlrev_b32_e32 v246, 16, v208
	v_and_b32_e32 v247, 0xffff0000, v208
	v_pk_mul_f32 v[34:35], v[34:35], v[246:247]
	v_lshlrev_b32_e32 v246, 16, v209
	v_and_b32_e32 v247, 0xffff0000, v209
	v_pk_mul_f32 v[36:37], v[36:37], v[246:247]
	v_lshlrev_b32_e32 v246, 16, v210
	v_and_b32_e32 v247, 0xffff0000, v210
	v_pk_mul_f32 v[30:31], v[30:31], v[246:247]
	v_lshlrev_b32_e32 v246, 16, v211
	v_and_b32_e32 v247, 0xffff0000, v211
	v_pk_mul_f32 v[32:33], v[32:33], v[246:247]
	v_cvt_pk_bf16_f32 v208, v34, v35
	v_cvt_pk_bf16_f32 v209, v36, v37
	v_cvt_pk_bf16_f32 v210, v30, v31
	v_cvt_pk_bf16_f32 v211, v32, v33
	global_store_dwordx4 v245, v[208:211], vcc sc0 sc1
	s_waitcnt vmcnt(15)
	v_lshlrev_b32_e32 v246, 16, v212
	v_and_b32_e32 v247, 0xffff0000, v212
	v_pk_mul_f32 v[26:27], v[26:27], v[246:247]
	v_lshlrev_b32_e32 v246, 16, v213
	v_and_b32_e32 v247, 0xffff0000, v213
	v_pk_mul_f32 v[28:29], v[28:29], v[246:247]
	v_lshlrev_b32_e32 v246, 16, v214
	v_and_b32_e32 v247, 0xffff0000, v214
	v_pk_mul_f32 v[22:23], v[22:23], v[246:247]
	v_lshlrev_b32_e32 v246, 16, v215
	v_and_b32_e32 v247, 0xffff0000, v215
	v_pk_mul_f32 v[24:25], v[24:25], v[246:247]
	v_cvt_pk_bf16_f32 v212, v26, v27
	v_cvt_pk_bf16_f32 v213, v28, v29
	v_cvt_pk_bf16_f32 v214, v22, v23
	v_cvt_pk_bf16_f32 v215, v24, v25
	global_store_dwordx4 v245, v[212:215], vcc offset:256 sc0 sc1
	s_add_u32 vcc_lo, s18, 0x160000
	s_addc_u32 vcc_hi, s19, 0
	s_waitcnt vmcnt(15)
	v_lshlrev_b32_e32 v246, 16, v216
	v_and_b32_e32 v247, 0xffff0000, v216
	v_pk_mul_f32 v[18:19], v[18:19], v[246:247]
	v_lshlrev_b32_e32 v246, 16, v217
	v_and_b32_e32 v247, 0xffff0000, v217
	v_pk_mul_f32 v[20:21], v[20:21], v[246:247]
	v_lshlrev_b32_e32 v246, 16, v218
	v_and_b32_e32 v247, 0xffff0000, v218
	v_pk_mul_f32 v[14:15], v[14:15], v[246:247]
	v_lshlrev_b32_e32 v246, 16, v219
	v_and_b32_e32 v247, 0xffff0000, v219
	v_pk_mul_f32 v[16:17], v[16:17], v[246:247]
	v_cvt_pk_bf16_f32 v216, v18, v19
	v_cvt_pk_bf16_f32 v217, v20, v21
	v_cvt_pk_bf16_f32 v218, v14, v15
	v_cvt_pk_bf16_f32 v219, v16, v17
	global_store_dwordx4 v245, v[216:219], vcc sc0 sc1
	s_waitcnt vmcnt(15)
	v_lshlrev_b32_e32 v246, 16, v220
	v_and_b32_e32 v247, 0xffff0000, v220
	v_pk_mul_f32 v[10:11], v[10:11], v[246:247]
	v_lshlrev_b32_e32 v246, 16, v221
	v_and_b32_e32 v247, 0xffff0000, v221
	v_pk_mul_f32 v[12:13], v[12:13], v[246:247]
	v_lshlrev_b32_e32 v246, 16, v222
	v_and_b32_e32 v247, 0xffff0000, v222
	v_pk_mul_f32 v[6:7], v[6:7], v[246:247]
	v_lshlrev_b32_e32 v246, 16, v223
	v_and_b32_e32 v247, 0xffff0000, v223
	v_pk_mul_f32 v[8:9], v[8:9], v[246:247]
	v_cvt_pk_bf16_f32 v220, v10, v11
	v_cvt_pk_bf16_f32 v221, v12, v13
	v_cvt_pk_bf16_f32 v222, v6, v7
	v_cvt_pk_bf16_f32 v223, v8, v9
	global_store_dwordx4 v245, v[220:223], vcc offset:256 sc0 sc1
	s_and_b64 vcc, exec, s[6:7]
	s_mov_b64 s[6:7], -1
	s_cbranch_vccnz .LBB0_1634
	s_andn2_b64 vcc, exec, s[12:13]
	s_cbranch_vccnz .LBB0_1633
	s_barrier
	s_branch .LBB0_1633

.LBB0_1653:
	s_add_u32 s36, s50, 0x8000
	s_addc_u32 s37, s51, 0
	s_waitcnt vmcnt(0)
	s_add_u32 s34, s50, 0x4200
	s_addc_u32 s35, s51, 0
	s_waitcnt lgkmcnt(0)
	s_barrier
	s_and_saveexec_b64 s[6:7], s[4:5]
	s_cbranch_execz .LBB0_1670
	s_mov_b64 s[12:13], exec
	s_waitcnt vmcnt(0)
	s_waitcnt vmcnt(0)
	v_mbcnt_lo_u32_b32 v1, s12, 0
	v_mbcnt_hi_u32_b32 v1, s13, v1
	v_cmp_eq_u32_e32 vcc, 0, v1
	s_and_saveexec_b64 s[14:15], vcc
	s_cbranch_execz .LBB0_1656
	s_bcnt1_i32_b64 s11, s[12:13]
	v_mov_b32_e32 v1, 0
	v_mov_b32_e32 v2, s11
	global_atomic_add v1, v2, s[36:37]

.LBB0_1689:
	ds_read_b128 v[142:145], v148
	ds_read_b128 v[152:155], v148 offset:1024
	ds_read_b128 v[156:159], v148 offset:2048
	ds_read_b128 v[160:163], v148 offset:3072
	ds_read_b128 v[166:169], v149
	ds_read_b128 v[170:173], v149 offset:1024
	ds_read_b128 v[174:177], v149 offset:2048
	ds_read_b128 v[178:181], v149 offset:3072
	s_add_u32 s6, s70, 0xfff00080
	s_addc_u32 s7, s71, -1
	s_cmp_eq_u32 s86, 60
	s_cselect_b32 s75, s61, s7
	s_cselect_b32 s74, s67, s6
	s_cselect_b32 s73, s47, s85
	s_cselect_b32 s72, s69, s84
	s_add_i32 m0, s28, 0xc000
	ds_read_b128 v[182:185], v150
	ds_read_b128 v[188:191], v150 offset:1024
	ds_read_b128 v[192:195], v150 offset:2048
	ds_read_b128 v[196:199], v150 offset:3072
	ds_read_b128 v[200:203], v150 offset:4096
	ds_read_b128 v[204:207], v150 offset:5120
	ds_read_b128 v[208:211], v150 offset:6144
	ds_read_b128 v[212:215], v150 offset:7168
	global_load_lds_dwordx4 v140, s[70:71]
	s_add_i32 m0, s28, 0xe000
	s_nop 0
	global_load_lds_dwordx4 v138, s[70:71]
	s_waitcnt vmcnt(8)
	s_waitcnt lgkmcnt(0)
	s_barrier
	s_setprio 1
	s_waitcnt lgkmcnt(0)
	v_mfma_f32_16x16x32_bf16 v[126:129], v[142:145], v[182:185], v[126:129]
	v_mfma_f32_16x16x32_bf16 v[122:125], v[156:159], v[182:185], v[122:125]
	v_mfma_f32_16x16x32_bf16 v[110:113], v[142:145], v[192:195], v[110:113]
	v_mfma_f32_16x16x32_bf16 v[106:109], v[156:159], v[192:195], v[106:109]
	v_mfma_f32_16x16x32_bf16 v[94:97], v[142:145], v[200:203], v[94:97]
	v_mfma_f32_16x16x32_bf16 v[90:93], v[156:159], v[200:203], v[90:93]
	v_mfma_f32_16x16x32_bf16 v[78:81], v[142:145], v[208:211], v[78:81]
	v_mfma_f32_16x16x32_bf16 v[74:77], v[156:159], v[208:211], v[74:77]
	v_mfma_f32_16x16x32_bf16 v[126:129], v[152:155], v[188:191], v[126:129]
	v_mfma_f32_16x16x32_bf16 v[122:125], v[160:163], v[188:191], v[122:125]
	v_mfma_f32_16x16x32_bf16 v[110:113], v[152:155], v[196:199], v[110:113]
	v_mfma_f32_16x16x32_bf16 v[106:109], v[160:163], v[196:199], v[106:109]
	v_mfma_f32_16x16x32_bf16 v[94:97], v[152:155], v[204:207], v[94:97]
	v_mfma_f32_16x16x32_bf16 v[90:93], v[160:163], v[204:207], v[90:93]
	v_mfma_f32_16x16x32_bf16 v[78:81], v[152:155], v[212:215], v[78:81]
	v_mfma_f32_16x16x32_bf16 v[74:77], v[160:163], v[212:215], v[74:77]
	s_setprio 0
	s_setprio 1
	v_mfma_f32_16x16x32_bf16 v[118:121], v[166:169], v[182:185], v[118:121]
	v_mfma_f32_16x16x32_bf16 v[114:117], v[174:177], v[182:185], v[114:117]
	v_mfma_f32_16x16x32_bf16 v[102:105], v[166:169], v[192:195], v[102:105]
	v_mfma_f32_16x16x32_bf16 v[98:101], v[174:177], v[192:195], v[98:101]
	v_mfma_f32_16x16x32_bf16 v[86:89], v[166:169], v[200:203], v[86:89]
	v_mfma_f32_16x16x32_bf16 v[82:85], v[174:177], v[200:203], v[82:85]
	v_mfma_f32_16x16x32_bf16 v[70:73], v[166:169], v[208:211], v[70:73]
	v_mfma_f32_16x16x32_bf16 v[66:69], v[174:177], v[208:211], v[66:69]
	v_mfma_f32_16x16x32_bf16 v[118:121], v[170:173], v[188:191], v[118:121]
	v_mfma_f32_16x16x32_bf16 v[114:117], v[178:181], v[188:191], v[114:117]
	v_mfma_f32_16x16x32_bf16 v[102:105], v[170:173], v[196:199], v[102:105]
	v_mfma_f32_16x16x32_bf16 v[98:101], v[178:181], v[196:199], v[98:101]
	v_mfma_f32_16x16x32_bf16 v[86:89], v[170:173], v[204:207], v[86:89]
	v_mfma_f32_16x16x32_bf16 v[82:85], v[178:181], v[204:207], v[82:85]
	v_mfma_f32_16x16x32_bf16 v[70:73], v[170:173], v[212:215], v[70:73]
	v_mfma_f32_16x16x32_bf16 v[66:69], v[178:181], v[212:215], v[66:69]
	s_setprio 0
	s_barrier
	s_add_i32 s6, s82, s27
	v_lshl_add_u64 v[216:217], s[72:73], 0, v[132:133]
	s_mov_b32 m0, s6
	ds_read_b128 v[182:185], v150 offset:16384
	ds_read_b128 v[188:191], v150 offset:17408
	ds_read_b128 v[192:195], v150 offset:18432
	ds_read_b128 v[196:199], v150 offset:19456
	ds_read_b128 v[200:203], v150 offset:20480
	ds_read_b128 v[204:207], v150 offset:21504
	ds_read_b128 v[208:211], v150 offset:22528
	ds_read_b128 v[212:215], v150 offset:23552
	global_load_lds_dwordx4 v[216:217], off
	s_add_i32 m0, s6, 0x2000
	s_add_u32 s6, s72, 0x100000
	v_lshl_add_u64 v[218:219], s[72:73], 0, v[136:137]
	s_addc_u32 s7, s73, 0
	s_add_i32 s16, s83, s27
	global_load_lds_dwordx4 v[218:219], off
	s_mov_b32 m0, s16
	v_lshl_add_u64 v[222:223], s[74:75], 0, v[134:135]
	global_load_lds_dwordx4 v132, s[6:7]
	s_add_i32 m0, s16, 0x2000
	s_nop 0
	global_load_lds_dwordx4 v136, s[6:7]
	v_lshl_add_u64 v[220:221], s[74:75], 0, v[130:131]
	s_mov_b32 m0, s28
	s_nop 0
	global_load_lds_dwordx4 v[220:221], off
	s_mov_b32 m0, s29
	s_nop 0
	global_load_lds_dwordx4 v[222:223], off
	s_waitcnt vmcnt(8)
	s_waitcnt lgkmcnt(0)
	s_barrier
	s_setprio 1
	s_waitcnt lgkmcnt(0)
	v_mfma_f32_16x16x32_bf16 v[62:65], v[142:145], v[182:185], v[62:65]
	v_mfma_f32_16x16x32_bf16 v[58:61], v[156:159], v[182:185], v[58:61]
	v_mfma_f32_16x16x32_bf16 v[46:49], v[142:145], v[192:195], v[46:49]
	v_mfma_f32_16x16x32_bf16 v[42:45], v[156:159], v[192:195], v[42:45]
	v_mfma_f32_16x16x32_bf16 v[30:33], v[142:145], v[200:203], v[30:33]
	v_mfma_f32_16x16x32_bf16 v[26:29], v[156:159], v[200:203], v[26:29]
	v_mfma_f32_16x16x32_bf16 v[14:17], v[142:145], v[208:211], v[14:17]
	v_mfma_f32_16x16x32_bf16 v[10:13], v[156:159], v[208:211], v[10:13]
	v_mfma_f32_16x16x32_bf16 v[62:65], v[152:155], v[188:191], v[62:65]
	v_mfma_f32_16x16x32_bf16 v[58:61], v[160:163], v[188:191], v[58:61]
	v_mfma_f32_16x16x32_bf16 v[46:49], v[152:155], v[196:199], v[46:49]
	v_mfma_f32_16x16x32_bf16 v[42:45], v[160:163], v[196:199], v[42:45]
	v_mfma_f32_16x16x32_bf16 v[30:33], v[152:155], v[204:207], v[30:33]
	v_mfma_f32_16x16x32_bf16 v[26:29], v[160:163], v[204:207], v[26:29]
	v_mfma_f32_16x16x32_bf16 v[14:17], v[152:155], v[212:215], v[14:17]
	v_mfma_f32_16x16x32_bf16 v[10:13], v[160:163], v[212:215], v[10:13]
	s_setprio 0
	s_setprio 1
	v_mfma_f32_16x16x32_bf16 v[54:57], v[166:169], v[182:185], v[54:57]
	v_mfma_f32_16x16x32_bf16 v[50:53], v[174:177], v[182:185], v[50:53]
	v_mfma_f32_16x16x32_bf16 v[38:41], v[166:169], v[192:195], v[38:41]
	v_mfma_f32_16x16x32_bf16 v[34:37], v[174:177], v[192:195], v[34:37]
	v_mfma_f32_16x16x32_bf16 v[22:25], v[166:169], v[200:203], v[22:25]
	v_mfma_f32_16x16x32_bf16 v[18:21], v[174:177], v[200:203], v[18:21]
	v_mfma_f32_16x16x32_bf16 v[6:9], v[166:169], v[208:211], v[6:9]
	v_mfma_f32_16x16x32_bf16 v[2:5], v[174:177], v[208:211], v[2:5]
	v_mfma_f32_16x16x32_bf16 v[54:57], v[170:173], v[188:191], v[54:57]
	v_mfma_f32_16x16x32_bf16 v[50:53], v[178:181], v[188:191], v[50:53]
	v_mfma_f32_16x16x32_bf16 v[38:41], v[170:173], v[196:199], v[38:41]
	v_mfma_f32_16x16x32_bf16 v[34:37], v[178:181], v[196:199], v[34:37]
	v_mfma_f32_16x16x32_bf16 v[22:25], v[170:173], v[204:207], v[22:25]
	v_mfma_f32_16x16x32_bf16 v[18:21], v[178:181], v[204:207], v[18:21]
	v_mfma_f32_16x16x32_bf16 v[6:9], v[170:173], v[212:215], v[6:9]
	v_mfma_f32_16x16x32_bf16 v[2:5], v[178:181], v[212:215], v[2:5]
	s_setprio 0
	s_barrier
	s_add_i32 s16, 0, 0x18000
	s_add_i32 s17, 0, 0x1c000
	v_add_u32_e32 v160, s16, v146
	v_add_u32_e32 v165, s17, v146
	ds_read_b128 v[142:145], v160
	ds_read_b128 v[152:155], v160 offset:1024
	ds_read_b128 v[156:159], v160 offset:2048
	ds_read_b128 v[160:163], v160 offset:3072
	ds_read_b128 v[166:169], v165
	ds_read_b128 v[170:173], v165 offset:1024
	ds_read_b128 v[174:177], v165 offset:2048
	ds_read_b128 v[178:181], v165 offset:3072
	s_add_u32 s6, s74, 0x100000
	s_addc_u32 s7, s75, 0
	s_mov_b32 m0, s56
	ds_read_b128 v[182:185], v150 offset:32768
	ds_read_b128 v[188:191], v150 offset:33792
	ds_read_b128 v[192:195], v150 offset:34816
	ds_read_b128 v[196:199], v150 offset:35840
	ds_read_b128 v[200:203], v150 offset:36864
	ds_read_b128 v[204:207], v150 offset:37888
	ds_read_b128 v[208:211], v150 offset:38912
	ds_read_b128 v[212:215], v150 offset:39936
	global_load_lds_dwordx4 v130, s[6:7]
	s_mov_b32 m0, s57
	s_nop 0
	global_load_lds_dwordx4 v134, s[6:7]
	s_waitcnt vmcnt(8)
	s_waitcnt lgkmcnt(0)
	s_barrier
	s_setprio 1
	s_waitcnt lgkmcnt(0)
	v_mfma_f32_16x16x32_bf16 v[126:129], v[142:145], v[182:185], v[126:129]
	v_mfma_f32_16x16x32_bf16 v[122:125], v[156:159], v[182:185], v[122:125]
	v_mfma_f32_16x16x32_bf16 v[110:113], v[142:145], v[192:195], v[110:113]
	v_mfma_f32_16x16x32_bf16 v[106:109], v[156:159], v[192:195], v[106:109]
	v_mfma_f32_16x16x32_bf16 v[94:97], v[142:145], v[200:203], v[94:97]
	v_mfma_f32_16x16x32_bf16 v[90:93], v[156:159], v[200:203], v[90:93]
	v_mfma_f32_16x16x32_bf16 v[78:81], v[142:145], v[208:211], v[78:81]
	v_mfma_f32_16x16x32_bf16 v[74:77], v[156:159], v[208:211], v[74:77]
	v_mfma_f32_16x16x32_bf16 v[126:129], v[152:155], v[188:191], v[126:129]
	v_mfma_f32_16x16x32_bf16 v[122:125], v[160:163], v[188:191], v[122:125]
	v_mfma_f32_16x16x32_bf16 v[110:113], v[152:155], v[196:199], v[110:113]
	v_mfma_f32_16x16x32_bf16 v[106:109], v[160:163], v[196:199], v[106:109]
	v_mfma_f32_16x16x32_bf16 v[94:97], v[152:155], v[204:207], v[94:97]
	v_mfma_f32_16x16x32_bf16 v[90:93], v[160:163], v[204:207], v[90:93]
	v_mfma_f32_16x16x32_bf16 v[78:81], v[152:155], v[212:215], v[78:81]
	v_mfma_f32_16x16x32_bf16 v[74:77], v[160:163], v[212:215], v[74:77]
	s_setprio 0
	s_setprio 1
	v_mfma_f32_16x16x32_bf16 v[118:121], v[166:169], v[182:185], v[118:121]
	v_mfma_f32_16x16x32_bf16 v[114:117], v[174:177], v[182:185], v[114:117]
	v_mfma_f32_16x16x32_bf16 v[102:105], v[166:169], v[192:195], v[102:105]
	v_mfma_f32_16x16x32_bf16 v[98:101], v[174:177], v[192:195], v[98:101]
	v_mfma_f32_16x16x32_bf16 v[86:89], v[166:169], v[200:203], v[86:89]
	v_mfma_f32_16x16x32_bf16 v[82:85], v[174:177], v[200:203], v[82:85]
	v_mfma_f32_16x16x32_bf16 v[70:73], v[166:169], v[208:211], v[70:73]
	v_mfma_f32_16x16x32_bf16 v[66:69], v[174:177], v[208:211], v[66:69]
	v_mfma_f32_16x16x32_bf16 v[118:121], v[170:173], v[188:191], v[118:121]
	v_mfma_f32_16x16x32_bf16 v[114:117], v[178:181], v[188:191], v[114:117]
	v_mfma_f32_16x16x32_bf16 v[102:105], v[170:173], v[196:199], v[102:105]
	v_mfma_f32_16x16x32_bf16 v[98:101], v[178:181], v[196:199], v[98:101]
	v_mfma_f32_16x16x32_bf16 v[86:89], v[170:173], v[204:207], v[86:89]
	v_mfma_f32_16x16x32_bf16 v[82:85], v[178:181], v[204:207], v[82:85]
	v_mfma_f32_16x16x32_bf16 v[70:73], v[170:173], v[212:215], v[70:73]
	v_mfma_f32_16x16x32_bf16 v[66:69], v[178:181], v[212:215], v[66:69]
	s_setprio 0
	s_barrier
	s_add_i32 s6, s16, s27
	v_lshl_add_u64 v[216:217], v[216:217], 0, s[40:41]
	s_mov_b32 m0, s6
	ds_read_b128 v[182:185], v150 offset:49152
	ds_read_b128 v[188:191], v150 offset:50176
	ds_read_b128 v[192:195], v150 offset:51200
	ds_read_b128 v[196:199], v150 offset:52224
	ds_read_b128 v[200:203], v150 offset:53248
	ds_read_b128 v[204:207], v150 offset:54272
	ds_read_b128 v[208:211], v150 offset:55296
	ds_read_b128 v[212:215], v150 offset:56320
	global_load_lds_dwordx4 v[216:217], off
	s_add_i32 m0, s6, 0x2000
	s_add_u32 s6, s72, 0x100080
	v_lshl_add_u64 v[216:217], v[218:219], 0, s[40:41]
	s_addc_u32 s7, s73, 0
	s_add_i32 s16, s17, s27
	global_load_lds_dwordx4 v[216:217], off
	s_mov_b32 m0, s16
	s_nop 0
	global_load_lds_dwordx4 v132, s[6:7]
	s_add_i32 m0, s16, 0x2000
	s_nop 0
	global_load_lds_dwordx4 v136, s[6:7]
	v_lshl_add_u64 v[216:217], v[220:221], 0, s[40:41]
	s_mov_b32 m0, s77
	s_nop 0
	global_load_lds_dwordx4 v[216:217], off
	v_lshl_add_u64 v[216:217], v[222:223], 0, s[40:41]
	s_mov_b32 m0, s78
	s_nop 0
	global_load_lds_dwordx4 v[216:217], off
	s_waitcnt vmcnt(8)
	s_waitcnt lgkmcnt(0)
	s_barrier
	s_setprio 1
	s_waitcnt lgkmcnt(0)
	v_mfma_f32_16x16x32_bf16 v[62:65], v[142:145], v[182:185], v[62:65]
	v_mfma_f32_16x16x32_bf16 v[58:61], v[156:159], v[182:185], v[58:61]
	v_mfma_f32_16x16x32_bf16 v[46:49], v[142:145], v[192:195], v[46:49]
	v_mfma_f32_16x16x32_bf16 v[42:45], v[156:159], v[192:195], v[42:45]
	v_mfma_f32_16x16x32_bf16 v[30:33], v[142:145], v[200:203], v[30:33]
	v_mfma_f32_16x16x32_bf16 v[26:29], v[156:159], v[200:203], v[26:29]
	v_mfma_f32_16x16x32_bf16 v[14:17], v[142:145], v[208:211], v[14:17]
	v_mfma_f32_16x16x32_bf16 v[10:13], v[156:159], v[208:211], v[10:13]
	v_mfma_f32_16x16x32_bf16 v[62:65], v[152:155], v[188:191], v[62:65]
	v_mfma_f32_16x16x32_bf16 v[58:61], v[160:163], v[188:191], v[58:61]
	v_mfma_f32_16x16x32_bf16 v[46:49], v[152:155], v[196:199], v[46:49]
	v_mfma_f32_16x16x32_bf16 v[42:45], v[160:163], v[196:199], v[42:45]
	v_mfma_f32_16x16x32_bf16 v[30:33], v[152:155], v[204:207], v[30:33]
	v_mfma_f32_16x16x32_bf16 v[26:29], v[160:163], v[204:207], v[26:29]
	v_mfma_f32_16x16x32_bf16 v[14:17], v[152:155], v[212:215], v[14:17]
	v_mfma_f32_16x16x32_bf16 v[10:13], v[160:163], v[212:215], v[10:13]
	s_setprio 0
	s_setprio 1
	v_mfma_f32_16x16x32_bf16 v[54:57], v[166:169], v[182:185], v[54:57]
	v_mfma_f32_16x16x32_bf16 v[50:53], v[174:177], v[182:185], v[50:53]
	v_mfma_f32_16x16x32_bf16 v[38:41], v[166:169], v[192:195], v[38:41]
	v_mfma_f32_16x16x32_bf16 v[34:37], v[174:177], v[192:195], v[34:37]
	v_mfma_f32_16x16x32_bf16 v[22:25], v[166:169], v[200:203], v[22:25]
	v_mfma_f32_16x16x32_bf16 v[18:21], v[174:177], v[200:203], v[18:21]
	v_mfma_f32_16x16x32_bf16 v[6:9], v[166:169], v[208:211], v[6:9]
	v_mfma_f32_16x16x32_bf16 v[2:5], v[174:177], v[208:211], v[2:5]
	v_mfma_f32_16x16x32_bf16 v[54:57], v[170:173], v[188:191], v[54:57]
	v_mfma_f32_16x16x32_bf16 v[50:53], v[178:181], v[188:191], v[50:53]
	v_mfma_f32_16x16x32_bf16 v[38:41], v[170:173], v[196:199], v[38:41]
	v_mfma_f32_16x16x32_bf16 v[34:37], v[178:181], v[196:199], v[34:37]
	v_mfma_f32_16x16x32_bf16 v[22:25], v[170:173], v[204:207], v[22:25]
	v_mfma_f32_16x16x32_bf16 v[18:21], v[178:181], v[204:207], v[18:21]
	v_mfma_f32_16x16x32_bf16 v[6:9], v[170:173], v[212:215], v[6:9]
	v_mfma_f32_16x16x32_bf16 v[2:5], v[178:181], v[212:215], v[2:5]
	s_setprio 0
	s_barrier
	s_add_i32 s86, s86, 2
	s_add_u32 s84, s84, 0x100
	s_addc_u32 s85, s85, 0
	s_add_u32 s70, s70, 0x100
	s_addc_u32 s71, s71, 0
	s_cmp_gt_u32 s86, 61
	s_cbranch_scc0 .LBB0_1689
	s_and_b64 vcc, exec, s[44:45]
	s_cbranch_vccz .LBB0_1692
	s_barrier
.LBB0_1692:
	v_lshl_add_u32 v144, s68, 8, v1
	v_lshl_or_b32 v142, s66, 8, v147
	v_ashrrev_i32_e32 v145, 31, v144
	s_cmp_lt_i32 s68, 64
	v_ashrrev_i32_e32 v143, 31, v142
	v_lshlrev_b64 v[152:153], 12, v[144:145]
	s_cselect_b32 s67, s13, s81
	s_cselect_b32 s66, s12, s80
	v_lshl_add_u64 v[160:161], v[152:153], 0, v[142:143]
	v_lshl_add_u64 v[162:163], v[160:161], 2, s[66:67]
	global_load_dwordx4 v[152:155], v[162:163], off
	global_load_dwordx4 v[156:159], v[162:163], off offset:16
	v_lshlrev_b64 v[160:161], 1, v[160:161]
	v_lshl_add_u64 v[166:167], s[24:25], 0, v[160:161]
	v_or_b32_e32 v160, 0x100, v160
	s_waitcnt vmcnt(0)
	v_pk_add_f32 v[128:129], v[128:129], v[154:155]
	v_pk_add_f32 v[168:169], v[126:127], v[152:153]
	v_pk_add_f32 v[158:159], v[124:125], v[158:159]
	v_pk_add_f32 v[156:157], v[122:123], v[156:157]
	s_nop 0
	v_cvt_pk_bf16_f32 v122, v168, v169
	s_nop 0
	v_cvt_pk_bf16_f32 v123, v128, v129
	v_mul_f32_e32 v129, v129, v129
	s_nop 0
	v_cvt_pk_bf16_f32 v124, v156, v157
	s_nop 0
	v_cvt_pk_bf16_f32 v125, v158, v159
	flat_store_dwordx4 v[166:167], v[122:125] sc0 sc1
	global_load_dwordx4 v[124:127], v[162:163], off offset:512
	s_nop 0
	global_load_dwordx4 v[152:155], v[162:163], off offset:528
	v_mul_f32_e32 v163, v169, v169
	v_and_b32_e32 v123, 64, v151
	v_mul_f32_e32 v157, v157, v157
	v_fmac_f32_e32 v163, v168, v168
	v_fmac_f32_e32 v129, v128, v128
	v_xor_b32_e32 v122, 16, v151
	v_add_u32_e32 v123, 64, v123
	v_mul_f32_e32 v159, v159, v159
	v_fmac_f32_e32 v157, v156, v156
	v_add_f32_e32 v128, v163, v129
	v_cmp_lt_i32_e32 vcc, v122, v123
	v_fmac_f32_e32 v159, v158, v158
	v_add_f32_e32 v128, v128, v157
	v_cndmask_b32_e32 v122, v151, v122, vcc
	v_add_f32_e32 v128, v159, v128
	v_lshlrev_b32_e32 v122, 2, v122
	v_xor_b32_e32 v162, 32, v151
	v_cmp_lt_i32_e32 vcc, v162, v123
	s_waitcnt vmcnt(0)
	v_pk_add_f32 v[120:121], v[120:121], v[126:127]
	v_pk_add_f32 v[118:119], v[118:119], v[124:125]
	v_pk_add_f32 v[126:127], v[114:115], v[152:153]
	v_mul_f32_e32 v114, v119, v119
	v_mul_f32_e32 v115, v121, v121
	v_pk_add_f32 v[124:125], v[116:117], v[154:155]
	v_mul_f32_e32 v116, v127, v127
	v_fmac_f32_e32 v114, v118, v118
	v_fmac_f32_e32 v115, v120, v120
	v_mul_f32_e32 v117, v125, v125
	v_fmac_f32_e32 v116, v126, v126
	v_add_f32_e32 v114, v114, v115
	v_fmac_f32_e32 v117, v124, v124
	v_add_f32_e32 v114, v114, v116
	v_add_f32_e32 v114, v117, v114
	v_add_f32_e32 v114, v128, v114
	ds_bpermute_b32 v115, v122, v114
	v_cndmask_b32_e32 v116, v151, v162, vcc
	v_lshlrev_b32_e32 v116, 2, v116
	v_lshl_add_u64 v[128:129], s[24:25], 0, v[160:161]
	s_nop 0
	v_cvt_pk_bf16_f32 v118, v118, v119
	s_waitcnt lgkmcnt(0)
	v_add_f32_e32 v114, v114, v115
	ds_bpermute_b32 v115, v116, v114
	s_nop 0
	v_cvt_pk_bf16_f32 v119, v120, v121
	s_nop 0
	v_cvt_pk_bf16_f32 v120, v126, v127
	s_nop 0
	v_cvt_pk_bf16_f32 v121, v124, v125
	flat_store_dwordx4 v[128:129], v[118:121] sc0 sc1
	s_and_saveexec_b64 s[68:69], s[8:9]
	s_cbranch_execz .LBB0_1694
	v_lshl_add_u64 v[118:119], v[144:145], 2, s[42:43]
	s_waitcnt lgkmcnt(0)
	v_add_f32_e32 v114, v114, v115
	flat_atomic_add_f32 v[118:119], v114
.LBB0_1694:
	s_or_b64 exec, exec, s[68:69]
	v_or_b32_e32 v114, 16, v144
	s_waitcnt lgkmcnt(0)
	v_ashrrev_i32_e32 v115, 31, v114
	v_lshlrev_b64 v[118:119], 12, v[114:115]
	v_lshl_add_u64 v[128:129], v[118:119], 0, v[142:143]
	v_lshl_add_u64 v[152:153], v[128:129], 2, s[66:67]
	global_load_dwordx4 v[118:121], v[152:153], off
	global_load_dwordx4 v[124:127], v[152:153], off offset:16
	v_lshlrev_b64 v[128:129], 1, v[128:129]
	v_lshl_add_u64 v[154:155], s[24:25], 0, v[128:129]
	v_or_b32_e32 v128, 0x100, v128
	s_waitcnt vmcnt(0)
	v_pk_add_f32 v[120:121], v[112:113], v[120:121]
	v_pk_add_f32 v[118:119], v[110:111], v[118:119]
	v_pk_add_f32 v[126:127], v[108:109], v[126:127]
	v_pk_add_f32 v[124:125], v[106:107], v[124:125]
	s_nop 0
	v_cvt_pk_bf16_f32 v106, v118, v119
	s_nop 0
	v_cvt_pk_bf16_f32 v107, v120, v121
	v_mul_f32_e32 v117, v119, v119
	s_nop 0
	v_cvt_pk_bf16_f32 v108, v124, v125
	s_nop 0
	v_cvt_pk_bf16_f32 v109, v126, v127
	flat_store_dwordx4 v[154:155], v[106:109] sc0 sc1
	global_load_dwordx4 v[106:109], v[152:153], off offset:512
	s_nop 0
	global_load_dwordx4 v[110:113], v[152:153], off offset:528
	v_mul_f32_e32 v119, v121, v121
	v_mul_f32_e32 v121, v125, v125
	v_fmac_f32_e32 v117, v118, v118
	v_fmac_f32_e32 v119, v120, v120
	v_mul_f32_e32 v123, v127, v127
	v_fmac_f32_e32 v121, v124, v124
	v_add_f32_e32 v117, v117, v119
	v_fmac_f32_e32 v123, v126, v126
	v_add_f32_e32 v117, v117, v121
	v_add_f32_e32 v117, v123, v117
	s_waitcnt vmcnt(0)
	v_pk_add_f32 v[104:105], v[104:105], v[108:109]
	v_pk_add_f32 v[102:103], v[102:103], v[106:107]
	v_pk_add_f32 v[108:109], v[98:99], v[110:111]
	v_mul_f32_e32 v98, v103, v103
	v_mul_f32_e32 v99, v105, v105
	v_pk_add_f32 v[106:107], v[100:101], v[112:113]
	v_mul_f32_e32 v100, v109, v109
	v_fmac_f32_e32 v98, v102, v102
	v_fmac_f32_e32 v99, v104, v104
	v_mul_f32_e32 v101, v107, v107
	v_fmac_f32_e32 v100, v108, v108
	v_add_f32_e32 v98, v98, v99
	v_add_f32_e32 v98, v98, v100
	v_fmac_f32_e32 v101, v106, v106
	v_add_f32_e32 v98, v101, v98
	v_add_f32_e32 v98, v117, v98
	ds_bpermute_b32 v99, v122, v98
	v_lshl_add_u64 v[110:111], s[24:25], 0, v[128:129]
	s_nop 0
	v_cvt_pk_bf16_f32 v100, v102, v103
	s_nop 0
	v_cvt_pk_bf16_f32 v101, v104, v105
	s_nop 0
	v_cvt_pk_bf16_f32 v102, v108, v109
	s_waitcnt lgkmcnt(0)
	v_add_f32_e32 v98, v98, v99
	ds_bpermute_b32 v99, v116, v98
	s_nop 0
	v_cvt_pk_bf16_f32 v103, v106, v107
	flat_store_dwordx4 v[110:111], v[100:103] sc0 sc1
	s_and_saveexec_b64 s[68:69], s[8:9]
	s_cbranch_execz .LBB0_1696
	v_lshl_add_u64 v[100:101], v[114:115], 2, s[42:43]
	s_waitcnt lgkmcnt(0)
	v_add_f32_e32 v98, v98, v99
	flat_atomic_add_f32 v[100:101], v98
.LBB0_1696:
	s_or_b64 exec, exec, s[68:69]
	v_or_b32_e32 v98, 32, v144
	s_waitcnt lgkmcnt(0)
	v_ashrrev_i32_e32 v99, 31, v98
	v_lshlrev_b64 v[100:101], 12, v[98:99]
	v_lshl_add_u64 v[108:109], v[100:101], 0, v[142:143]
	v_lshl_add_u64 v[110:111], v[108:109], 2, s[66:67]
	global_load_dwordx4 v[100:103], v[110:111], off
	global_load_dwordx4 v[104:107], v[110:111], off offset:16
	v_lshlrev_b64 v[108:109], 1, v[108:109]
	v_lshl_add_u64 v[112:113], s[24:25], 0, v[108:109]
	v_or_b32_e32 v108, 0x100, v108
	s_waitcnt vmcnt(0)
	v_pk_add_f32 v[102:103], v[96:97], v[102:103]
	v_pk_add_f32 v[100:101], v[94:95], v[100:101]
	v_pk_add_f32 v[106:107], v[92:93], v[106:107]
	v_pk_add_f32 v[104:105], v[90:91], v[104:105]
	s_nop 0
	v_cvt_pk_bf16_f32 v90, v100, v101
	s_nop 0
	v_cvt_pk_bf16_f32 v91, v102, v103
	v_mul_f32_e32 v101, v101, v101
	s_nop 0
	v_cvt_pk_bf16_f32 v92, v104, v105
	s_nop 0
	v_cvt_pk_bf16_f32 v93, v106, v107
	flat_store_dwordx4 v[112:113], v[90:93] sc0 sc1
	global_load_dwordx4 v[90:93], v[110:111], off offset:512
	s_nop 0
	global_load_dwordx4 v[94:97], v[110:111], off offset:528
	v_mul_f32_e32 v103, v103, v103
	v_mul_f32_e32 v105, v105, v105
	v_fmac_f32_e32 v101, v100, v100
	v_fmac_f32_e32 v103, v102, v102
	v_mul_f32_e32 v107, v107, v107
	v_fmac_f32_e32 v105, v104, v104
	v_add_f32_e32 v100, v101, v103
	v_fmac_f32_e32 v107, v106, v106
	v_add_f32_e32 v100, v100, v105
	v_add_f32_e32 v100, v107, v100
	s_waitcnt vmcnt(0)
	v_pk_add_f32 v[88:89], v[88:89], v[92:93]
	v_pk_add_f32 v[86:87], v[86:87], v[90:91]
	v_pk_add_f32 v[92:93], v[82:83], v[94:95]
	v_mul_f32_e32 v82, v87, v87
	v_mul_f32_e32 v83, v89, v89
	v_pk_add_f32 v[90:91], v[84:85], v[96:97]
	v_mul_f32_e32 v84, v93, v93
	v_fmac_f32_e32 v82, v86, v86
	v_fmac_f32_e32 v83, v88, v88
	v_mul_f32_e32 v85, v91, v91
	v_fmac_f32_e32 v84, v92, v92
	v_add_f32_e32 v82, v82, v83
	v_add_f32_e32 v82, v82, v84
	v_fmac_f32_e32 v85, v90, v90
	v_add_f32_e32 v82, v85, v82
	v_add_f32_e32 v82, v100, v82
	ds_bpermute_b32 v83, v122, v82
	v_lshl_add_u64 v[94:95], s[24:25], 0, v[108:109]
	s_nop 0
	v_cvt_pk_bf16_f32 v84, v86, v87
	s_nop 0
	v_cvt_pk_bf16_f32 v85, v88, v89
	s_nop 0
	v_cvt_pk_bf16_f32 v86, v92, v93
	s_waitcnt lgkmcnt(0)
	v_add_f32_e32 v82, v82, v83
	ds_bpermute_b32 v83, v116, v82
	s_nop 0
	v_cvt_pk_bf16_f32 v87, v90, v91
	flat_store_dwordx4 v[94:95], v[84:87] sc0 sc1
	s_and_saveexec_b64 s[68:69], s[8:9]
	s_cbranch_execz .LBB0_1698
	v_lshl_add_u64 v[84:85], v[98:99], 2, s[42:43]
	s_waitcnt lgkmcnt(0)
	v_add_f32_e32 v82, v82, v83
	flat_atomic_add_f32 v[84:85], v82
.LBB0_1698:
	s_or_b64 exec, exec, s[68:69]
	v_or_b32_e32 v82, 48, v144
	s_waitcnt lgkmcnt(0)
	v_ashrrev_i32_e32 v83, 31, v82
	v_lshlrev_b64 v[84:85], 12, v[82:83]
	v_lshl_add_u64 v[92:93], v[84:85], 0, v[142:143]
	v_lshl_add_u64 v[94:95], v[92:93], 2, s[66:67]
	global_load_dwordx4 v[84:87], v[94:95], off
	global_load_dwordx4 v[88:91], v[94:95], off offset:16
	v_lshlrev_b64 v[92:93], 1, v[92:93]
	v_lshl_add_u64 v[96:97], s[24:25], 0, v[92:93]
	v_or_b32_e32 v92, 0x100, v92
	s_waitcnt vmcnt(0)
	v_pk_add_f32 v[86:87], v[80:81], v[86:87]
	v_pk_add_f32 v[84:85], v[78:79], v[84:85]
	v_pk_add_f32 v[90:91], v[76:77], v[90:91]
	v_pk_add_f32 v[88:89], v[74:75], v[88:89]
	s_nop 0
	v_cvt_pk_bf16_f32 v74, v84, v85
	s_nop 0
	v_cvt_pk_bf16_f32 v75, v86, v87
	v_mul_f32_e32 v85, v85, v85
	s_nop 0
	v_cvt_pk_bf16_f32 v76, v88, v89
	s_nop 0
	v_cvt_pk_bf16_f32 v77, v90, v91
	flat_store_dwordx4 v[96:97], v[74:77] sc0 sc1
	global_load_dwordx4 v[74:77], v[94:95], off offset:512
	s_nop 0
	global_load_dwordx4 v[78:81], v[94:95], off offset:528
	v_mul_f32_e32 v87, v87, v87
	v_mul_f32_e32 v89, v89, v89
	v_fmac_f32_e32 v85, v84, v84
	v_fmac_f32_e32 v87, v86, v86
	v_mul_f32_e32 v91, v91, v91
	v_fmac_f32_e32 v89, v88, v88
	v_add_f32_e32 v84, v85, v87
	v_fmac_f32_e32 v91, v90, v90
	v_add_f32_e32 v84, v84, v89
	v_add_f32_e32 v84, v91, v84
	s_waitcnt vmcnt(0)
	v_pk_add_f32 v[72:73], v[72:73], v[76:77]
	v_pk_add_f32 v[70:71], v[70:71], v[74:75]
	v_pk_add_f32 v[76:77], v[66:67], v[78:79]
	v_mul_f32_e32 v66, v71, v71
	v_mul_f32_e32 v67, v73, v73
	v_pk_add_f32 v[74:75], v[68:69], v[80:81]
	v_mul_f32_e32 v68, v77, v77
	v_fmac_f32_e32 v66, v70, v70
	v_fmac_f32_e32 v67, v72, v72
	v_mul_f32_e32 v69, v75, v75
	v_fmac_f32_e32 v68, v76, v76
	v_add_f32_e32 v66, v66, v67
	v_add_f32_e32 v66, v66, v68
	v_fmac_f32_e32 v69, v74, v74
	v_add_f32_e32 v66, v69, v66
	v_add_f32_e32 v66, v84, v66
	ds_bpermute_b32 v67, v122, v66
	v_lshl_add_u64 v[78:79], s[24:25], 0, v[92:93]
	s_nop 0
	v_cvt_pk_bf16_f32 v68, v70, v71
	s_nop 0
	v_cvt_pk_bf16_f32 v69, v72, v73
	s_nop 0
	v_cvt_pk_bf16_f32 v70, v76, v77
	s_waitcnt lgkmcnt(0)
	v_add_f32_e32 v66, v66, v67
	ds_bpermute_b32 v67, v116, v66
	s_nop 0
	v_cvt_pk_bf16_f32 v71, v74, v75
	flat_store_dwordx4 v[78:79], v[68:71] sc0 sc1
	s_and_saveexec_b64 s[68:69], s[8:9]
	s_cbranch_execz .LBB0_1700
	v_lshl_add_u64 v[68:69], v[82:83], 2, s[42:43]
	s_waitcnt lgkmcnt(0)
	v_add_f32_e32 v66, v66, v67
	flat_atomic_add_f32 v[68:69], v66
.LBB0_1700:
	s_or_b64 exec, exec, s[68:69]
	v_add_u32_e32 v66, 0x80, v144
	s_waitcnt lgkmcnt(0)
	v_ashrrev_i32_e32 v67, 31, v66
	v_lshlrev_b64 v[68:69], 12, v[66:67]
	v_lshl_add_u64 v[76:77], v[68:69], 0, v[142:143]
	v_lshl_add_u64 v[78:79], v[76:77], 2, s[66:67]
	global_load_dwordx4 v[68:71], v[78:79], off
	global_load_dwordx4 v[72:75], v[78:79], off offset:16
	v_lshlrev_b64 v[76:77], 1, v[76:77]
	v_lshl_add_u64 v[80:81], s[24:25], 0, v[76:77]
	v_or_b32_e32 v76, 0x100, v76
	s_waitcnt vmcnt(0)
	v_pk_add_f32 v[70:71], v[64:65], v[70:71]
	v_pk_add_f32 v[68:69], v[62:63], v[68:69]
	v_pk_add_f32 v[74:75], v[60:61], v[74:75]
	v_pk_add_f32 v[72:73], v[58:59], v[72:73]
	s_nop 0
	v_cvt_pk_bf16_f32 v58, v68, v69
	s_nop 0
	v_cvt_pk_bf16_f32 v59, v70, v71
	v_mul_f32_e32 v69, v69, v69
	s_nop 0
	v_cvt_pk_bf16_f32 v60, v72, v73
	s_nop 0
	v_cvt_pk_bf16_f32 v61, v74, v75
	flat_store_dwordx4 v[80:81], v[58:61] sc0 sc1
	global_load_dwordx4 v[58:61], v[78:79], off offset:512
	s_nop 0
	global_load_dwordx4 v[62:65], v[78:79], off offset:528
	v_mul_f32_e32 v71, v71, v71
	v_mul_f32_e32 v73, v73, v73
	v_fmac_f32_e32 v69, v68, v68
	v_fmac_f32_e32 v71, v70, v70
	v_mul_f32_e32 v75, v75, v75
	v_fmac_f32_e32 v73, v72, v72
	v_add_f32_e32 v68, v69, v71
	v_fmac_f32_e32 v75, v74, v74
	v_add_f32_e32 v68, v68, v73
	v_add_f32_e32 v68, v75, v68
	s_waitcnt vmcnt(0)
	v_pk_add_f32 v[56:57], v[56:57], v[60:61]
	v_pk_add_f32 v[54:55], v[54:55], v[58:59]
	v_pk_add_f32 v[60:61], v[50:51], v[62:63]
	v_mul_f32_e32 v50, v55, v55
	v_mul_f32_e32 v51, v57, v57
	v_pk_add_f32 v[58:59], v[52:53], v[64:65]
	v_mul_f32_e32 v52, v61, v61
	v_fmac_f32_e32 v50, v54, v54
	v_fmac_f32_e32 v51, v56, v56
	v_mul_f32_e32 v53, v59, v59
	v_fmac_f32_e32 v52, v60, v60
	v_add_f32_e32 v50, v50, v51
	v_add_f32_e32 v50, v50, v52
	v_fmac_f32_e32 v53, v58, v58
	v_add_f32_e32 v50, v53, v50
	v_add_f32_e32 v50, v68, v50
	ds_bpermute_b32 v51, v122, v50
	v_lshl_add_u64 v[62:63], s[24:25], 0, v[76:77]
	s_nop 0
	v_cvt_pk_bf16_f32 v52, v54, v55
	s_nop 0
	v_cvt_pk_bf16_f32 v53, v56, v57
	s_nop 0
	v_cvt_pk_bf16_f32 v54, v60, v61
	s_waitcnt lgkmcnt(0)
	v_add_f32_e32 v50, v50, v51
	ds_bpermute_b32 v51, v116, v50
	s_nop 0
	v_cvt_pk_bf16_f32 v55, v58, v59
	flat_store_dwordx4 v[62:63], v[52:55] sc0 sc1
	s_and_saveexec_b64 s[68:69], s[8:9]
	s_cbranch_execz .LBB0_1702
	v_lshl_add_u64 v[52:53], v[66:67], 2, s[42:43]
	s_waitcnt lgkmcnt(0)
	v_add_f32_e32 v50, v50, v51
	flat_atomic_add_f32 v[52:53], v50
.LBB0_1702:
	s_or_b64 exec, exec, s[68:69]
	v_add_u32_e32 v50, 0x90, v144
	s_waitcnt lgkmcnt(0)
	v_ashrrev_i32_e32 v51, 31, v50
	v_lshlrev_b64 v[52:53], 12, v[50:51]
	v_lshl_add_u64 v[60:61], v[52:53], 0, v[142:143]
	v_lshl_add_u64 v[62:63], v[60:61], 2, s[66:67]
	global_load_dwordx4 v[52:55], v[62:63], off
	global_load_dwordx4 v[56:59], v[62:63], off offset:16
	v_lshlrev_b64 v[60:61], 1, v[60:61]
	v_lshl_add_u64 v[64:65], s[24:25], 0, v[60:61]
	v_or_b32_e32 v60, 0x100, v60
	s_waitcnt vmcnt(0)
	v_pk_add_f32 v[54:55], v[48:49], v[54:55]
	v_pk_add_f32 v[52:53], v[46:47], v[52:53]
	v_pk_add_f32 v[58:59], v[44:45], v[58:59]
	v_pk_add_f32 v[56:57], v[42:43], v[56:57]
	s_nop 0
	v_cvt_pk_bf16_f32 v42, v52, v53
	s_nop 0
	v_cvt_pk_bf16_f32 v43, v54, v55
	v_mul_f32_e32 v53, v53, v53
	s_nop 0
	v_cvt_pk_bf16_f32 v44, v56, v57
	s_nop 0
	v_cvt_pk_bf16_f32 v45, v58, v59
	flat_store_dwordx4 v[64:65], v[42:45] sc0 sc1
	global_load_dwordx4 v[42:45], v[62:63], off offset:512
	s_nop 0
	global_load_dwordx4 v[46:49], v[62:63], off offset:528
	v_mul_f32_e32 v55, v55, v55
	v_mul_f32_e32 v57, v57, v57
	v_fmac_f32_e32 v53, v52, v52
	v_fmac_f32_e32 v55, v54, v54
	v_mul_f32_e32 v59, v59, v59
	v_fmac_f32_e32 v57, v56, v56
	v_add_f32_e32 v52, v53, v55
	v_fmac_f32_e32 v59, v58, v58
	v_add_f32_e32 v52, v52, v57
	v_add_f32_e32 v52, v59, v52
	s_waitcnt vmcnt(0)
	v_pk_add_f32 v[40:41], v[40:41], v[44:45]
	v_pk_add_f32 v[38:39], v[38:39], v[42:43]
	v_pk_add_f32 v[44:45], v[34:35], v[46:47]
	v_mul_f32_e32 v34, v39, v39
	v_mul_f32_e32 v35, v41, v41
	v_pk_add_f32 v[42:43], v[36:37], v[48:49]
	v_mul_f32_e32 v36, v45, v45
	v_fmac_f32_e32 v34, v38, v38
	v_fmac_f32_e32 v35, v40, v40
	v_mul_f32_e32 v37, v43, v43
	v_fmac_f32_e32 v36, v44, v44
	v_add_f32_e32 v34, v34, v35
	v_add_f32_e32 v34, v34, v36
	v_fmac_f32_e32 v37, v42, v42
	v_add_f32_e32 v34, v37, v34
	v_add_f32_e32 v34, v52, v34
	ds_bpermute_b32 v35, v122, v34
	v_lshl_add_u64 v[46:47], s[24:25], 0, v[60:61]
	s_nop 0
	v_cvt_pk_bf16_f32 v36, v38, v39
	s_nop 0
	v_cvt_pk_bf16_f32 v37, v40, v41
	s_nop 0
	v_cvt_pk_bf16_f32 v38, v44, v45
	s_waitcnt lgkmcnt(0)
	v_add_f32_e32 v34, v34, v35
	ds_bpermute_b32 v35, v116, v34
	s_nop 0
	v_cvt_pk_bf16_f32 v39, v42, v43
	flat_store_dwordx4 v[46:47], v[36:39] sc0 sc1
	s_and_saveexec_b64 s[68:69], s[8:9]
	s_cbranch_execz .LBB0_1704
	v_lshl_add_u64 v[36:37], v[50:51], 2, s[42:43]
	s_waitcnt lgkmcnt(0)
	v_add_f32_e32 v34, v34, v35
	flat_atomic_add_f32 v[36:37], v34
.LBB0_1704:
	s_or_b64 exec, exec, s[68:69]
	v_add_u32_e32 v34, 0xa0, v144
	s_waitcnt lgkmcnt(0)
	v_ashrrev_i32_e32 v35, 31, v34
	v_lshlrev_b64 v[36:37], 12, v[34:35]
	v_lshl_add_u64 v[44:45], v[36:37], 0, v[142:143]
	v_lshl_add_u64 v[46:47], v[44:45], 2, s[66:67]
	global_load_dwordx4 v[36:39], v[46:47], off
	global_load_dwordx4 v[40:43], v[46:47], off offset:16
	v_lshlrev_b64 v[44:45], 1, v[44:45]
	v_lshl_add_u64 v[48:49], s[24:25], 0, v[44:45]
	v_or_b32_e32 v44, 0x100, v44
	s_waitcnt vmcnt(0)
	v_pk_add_f32 v[38:39], v[32:33], v[38:39]
	v_pk_add_f32 v[36:37], v[30:31], v[36:37]
	v_pk_add_f32 v[42:43], v[28:29], v[42:43]
	v_pk_add_f32 v[40:41], v[26:27], v[40:41]
	s_nop 0
	v_cvt_pk_bf16_f32 v26, v36, v37
	s_nop 0
	v_cvt_pk_bf16_f32 v27, v38, v39
	v_mul_f32_e32 v37, v37, v37
	s_nop 0
	v_cvt_pk_bf16_f32 v28, v40, v41
	s_nop 0
	v_cvt_pk_bf16_f32 v29, v42, v43
	flat_store_dwordx4 v[48:49], v[26:29] sc0 sc1
	global_load_dwordx4 v[26:29], v[46:47], off offset:512
	s_nop 0
	global_load_dwordx4 v[30:33], v[46:47], off offset:528
	v_mul_f32_e32 v39, v39, v39
	v_mul_f32_e32 v41, v41, v41
	v_fmac_f32_e32 v37, v36, v36
	v_fmac_f32_e32 v39, v38, v38
	v_mul_f32_e32 v43, v43, v43
	v_fmac_f32_e32 v41, v40, v40
	v_add_f32_e32 v36, v37, v39
	v_fmac_f32_e32 v43, v42, v42
	v_add_f32_e32 v36, v36, v41
	v_add_f32_e32 v36, v43, v36
	s_waitcnt vmcnt(0)
	v_pk_add_f32 v[24:25], v[24:25], v[28:29]
	v_pk_add_f32 v[22:23], v[22:23], v[26:27]
	v_pk_add_f32 v[28:29], v[18:19], v[30:31]
	v_mul_f32_e32 v18, v23, v23
	v_mul_f32_e32 v19, v25, v25
	v_pk_add_f32 v[26:27], v[20:21], v[32:33]
	v_mul_f32_e32 v20, v29, v29
	v_fmac_f32_e32 v18, v22, v22
	v_fmac_f32_e32 v19, v24, v24
	v_mul_f32_e32 v21, v27, v27
	v_fmac_f32_e32 v20, v28, v28
	v_add_f32_e32 v18, v18, v19
	v_add_f32_e32 v18, v18, v20
	v_fmac_f32_e32 v21, v26, v26
	v_add_f32_e32 v18, v21, v18
	v_add_f32_e32 v18, v36, v18
	ds_bpermute_b32 v19, v122, v18
	v_lshl_add_u64 v[30:31], s[24:25], 0, v[44:45]
	s_nop 0
	v_cvt_pk_bf16_f32 v20, v22, v23
	s_nop 0
	v_cvt_pk_bf16_f32 v21, v24, v25
	s_nop 0
	v_cvt_pk_bf16_f32 v22, v28, v29
	s_waitcnt lgkmcnt(0)
	v_add_f32_e32 v18, v18, v19
	ds_bpermute_b32 v19, v116, v18
	s_nop 0
	v_cvt_pk_bf16_f32 v23, v26, v27
	flat_store_dwordx4 v[30:31], v[20:23] sc0 sc1
	s_and_saveexec_b64 s[68:69], s[8:9]
	s_cbranch_execz .LBB0_1706
	v_lshl_add_u64 v[20:21], v[34:35], 2, s[42:43]
	s_waitcnt lgkmcnt(0)
	v_add_f32_e32 v18, v18, v19
	flat_atomic_add_f32 v[20:21], v18
.LBB0_1706:
	s_or_b64 exec, exec, s[68:69]
	v_add_u32_e32 v18, 0xb0, v144
	s_waitcnt lgkmcnt(0)
	v_ashrrev_i32_e32 v19, 31, v18
	v_lshlrev_b64 v[20:21], 12, v[18:19]
	v_lshl_add_u64 v[28:29], v[20:21], 0, v[142:143]
	v_lshl_add_u64 v[30:31], v[28:29], 2, s[66:67]
	global_load_dwordx4 v[20:23], v[30:31], off
	global_load_dwordx4 v[24:27], v[30:31], off offset:16
	v_lshlrev_b64 v[28:29], 1, v[28:29]
	v_lshl_add_u64 v[32:33], s[24:25], 0, v[28:29]
	v_or_b32_e32 v28, 0x100, v28
	s_waitcnt vmcnt(0)
	v_pk_add_f32 v[22:23], v[16:17], v[22:23]
	v_pk_add_f32 v[20:21], v[14:15], v[20:21]
	v_pk_add_f32 v[26:27], v[12:13], v[26:27]
	v_pk_add_f32 v[24:25], v[10:11], v[24:25]
	s_nop 0
	v_cvt_pk_bf16_f32 v10, v20, v21
	s_nop 0
	v_cvt_pk_bf16_f32 v11, v22, v23
	v_mul_f32_e32 v21, v21, v21
	s_nop 0
	v_cvt_pk_bf16_f32 v12, v24, v25
	s_nop 0
	v_cvt_pk_bf16_f32 v13, v26, v27
	flat_store_dwordx4 v[32:33], v[10:13] sc0 sc1
	global_load_dwordx4 v[10:13], v[30:31], off offset:512
	s_nop 0
	global_load_dwordx4 v[14:17], v[30:31], off offset:528
	v_mul_f32_e32 v23, v23, v23
	v_mul_f32_e32 v25, v25, v25
	v_fmac_f32_e32 v21, v20, v20
	v_fmac_f32_e32 v23, v22, v22
	v_mul_f32_e32 v27, v27, v27
	v_fmac_f32_e32 v25, v24, v24
	v_add_f32_e32 v20, v21, v23
	v_fmac_f32_e32 v27, v26, v26
	v_add_f32_e32 v20, v20, v25
	v_add_f32_e32 v20, v27, v20
	s_waitcnt vmcnt(0)
	v_pk_add_f32 v[8:9], v[8:9], v[12:13]
	v_pk_add_f32 v[6:7], v[6:7], v[10:11]
	v_pk_add_f32 v[12:13], v[2:3], v[14:15]
	v_mul_f32_e32 v2, v7, v7
	v_mul_f32_e32 v3, v9, v9
	v_pk_add_f32 v[10:11], v[4:5], v[16:17]
	v_mul_f32_e32 v4, v13, v13
	v_fmac_f32_e32 v2, v6, v6
	v_fmac_f32_e32 v3, v8, v8
	v_mul_f32_e32 v5, v11, v11
	v_fmac_f32_e32 v4, v12, v12
	v_add_f32_e32 v2, v2, v3
	v_add_f32_e32 v2, v2, v4
	v_fmac_f32_e32 v5, v10, v10
	v_add_f32_e32 v2, v5, v2
	v_add_f32_e32 v2, v20, v2
	ds_bpermute_b32 v3, v122, v2
	v_lshl_add_u64 v[14:15], s[24:25], 0, v[28:29]
	s_nop 0
	v_cvt_pk_bf16_f32 v4, v6, v7
	s_nop 0
	v_cvt_pk_bf16_f32 v5, v8, v9
	s_nop 0
	v_cvt_pk_bf16_f32 v6, v12, v13
	s_waitcnt lgkmcnt(0)
	v_add_f32_e32 v2, v2, v3
	ds_bpermute_b32 v3, v116, v2
	s_nop 0
	v_cvt_pk_bf16_f32 v7, v10, v11
	flat_store_dwordx4 v[14:15], v[4:7] sc0 sc1
	s_and_saveexec_b64 s[66:67], s[8:9]
	s_cbranch_execz .LBB0_1708
	v_lshl_add_u64 v[4:5], v[18:19], 2, s[42:43]
	s_waitcnt lgkmcnt(0)
	v_add_f32_e32 v2, v2, v3
	flat_atomic_add_f32 v[4:5], v2

.LBB0_1712:
	s_waitcnt vmcnt(0)
	s_waitcnt lgkmcnt(0)
	s_barrier
	s_and_saveexec_b64 s[8:9], s[4:5]
	s_cbranch_execz .LBB0_1728
	s_mov_b64 s[12:13], exec
	s_waitcnt vmcnt(0)
	s_waitcnt vmcnt(0)
	v_mbcnt_lo_u32_b32 v1, s12, 0
	v_mbcnt_hi_u32_b32 v1, s13, v1
	v_cmp_eq_u32_e32 vcc, 0, v1
	s_and_saveexec_b64 s[14:15], vcc
	s_cbranch_execz .LBB0_1715
	s_bcnt1_i32_b64 s6, s[12:13]
	v_mov_b32_e32 v1, 0
	v_mov_b32_e32 v2, s6
	global_atomic_add v1, v2, s[36:37]

.LBB0_1733:
	s_waitcnt vmcnt(0) lgkmcnt(0)
	v_lshlrev_b32_e32 v76, 16, v63
	v_and_b32_e32 v63, 0xffff0000, v63
	v_lshlrev_b32_e32 v79, 16, v65
	v_and_b32_e32 v65, 0xffff0000, v65
	v_max_f32_e64 v77, |v63|, |v63|
	v_max_f32_e64 v78, |v76|, |v76|
	v_max_f32_e64 v80, |v65|, |v65|
	v_max_f32_e64 v81, |v79|, |v79|
	v_lshlrev_b32_e32 v75, 16, v62
	v_and_b32_e32 v62, 0xffff0000, v62
	v_max_f32_e32 v77, v78, v77
	v_lshlrev_b32_e32 v78, 16, v64
	v_and_b32_e32 v64, 0xffff0000, v64
	v_max_f32_e32 v80, v81, v80
	v_lshlrev_b32_e32 v81, 16, v59
	v_and_b32_e32 v59, 0xffff0000, v59
	v_lshlrev_b32_e32 v84, 16, v61
	v_and_b32_e32 v61, 0xffff0000, v61
	v_max3_f32 v77, |v75|, |v62|, v77
	v_max3_f32 v80, |v78|, |v64|, v80
	v_max_f32_e64 v82, |v59|, |v59|
	v_max_f32_e64 v83, |v81|, |v81|
	v_max_f32_e64 v85, |v61|, |v61|
	v_max_f32_e64 v86, |v84|, |v84|
	v_max3_f32 v77, v77, 0, v80
	v_lshlrev_b32_e32 v80, 16, v58
	v_and_b32_e32 v58, 0xffff0000, v58
	v_max_f32_e32 v82, v83, v82
	v_lshlrev_b32_e32 v83, 16, v60
	v_and_b32_e32 v60, 0xffff0000, v60
	v_max_f32_e32 v85, v86, v85
	v_max3_f32 v82, |v80|, |v58|, v82
	v_max3_f32 v85, |v83|, |v60|, v85
	v_max3_f32 v77, v77, v82, v85
	v_lshlrev_b32_e32 v85, 16, v55
	v_and_b32_e32 v55, 0xffff0000, v55
	v_lshlrev_b32_e32 v88, 16, v57
	v_and_b32_e32 v57, 0xffff0000, v57
	v_max_f32_e64 v86, |v55|, |v55|
	v_max_f32_e64 v87, |v85|, |v85|
	v_max_f32_e64 v89, |v57|, |v57|
	v_max_f32_e64 v90, |v88|, |v88|
	v_lshlrev_b32_e32 v82, 16, v54
	v_and_b32_e32 v54, 0xffff0000, v54
	v_max_f32_e32 v86, v87, v86
	v_lshlrev_b32_e32 v87, 16, v56
	v_and_b32_e32 v56, 0xffff0000, v56
	v_max_f32_e32 v89, v90, v89
	v_max3_f32 v86, |v82|, |v54|, v86
	v_max3_f32 v89, |v87|, |v56|, v89
	v_max3_f32 v77, v77, v86, v89
	v_lshlrev_b32_e32 v89, 16, v51
	v_and_b32_e32 v51, 0xffff0000, v51
	v_lshlrev_b32_e32 v92, 16, v53
	v_and_b32_e32 v53, 0xffff0000, v53
	v_max_f32_e64 v90, |v51|, |v51|
	v_max_f32_e64 v91, |v89|, |v89|
	v_max_f32_e64 v93, |v53|, |v53|
	v_max_f32_e64 v94, |v92|, |v92|
	v_lshlrev_b32_e32 v86, 16, v50
	v_and_b32_e32 v50, 0xffff0000, v50
	v_max_f32_e32 v90, v91, v90
	v_lshlrev_b32_e32 v91, 16, v52
	v_and_b32_e32 v52, 0xffff0000, v52
	v_max_f32_e32 v93, v94, v93
	v_max3_f32 v90, |v86|, |v50|, v90
	v_max3_f32 v93, |v91|, |v52|, v93
	v_max3_f32 v77, v77, v90, v93
	v_lshlrev_b32_e32 v93, 16, v47
	v_and_b32_e32 v47, 0xffff0000, v47
	v_lshlrev_b32_e32 v96, 16, v49
	v_and_b32_e32 v49, 0xffff0000, v49
	v_max_f32_e64 v94, |v47|, |v47|
	v_max_f32_e64 v95, |v93|, |v93|
	v_max_f32_e64 v97, |v49|, |v49|
	v_max_f32_e64 v98, |v96|, |v96|
	v_lshlrev_b32_e32 v90, 16, v46
	v_and_b32_e32 v46, 0xffff0000, v46
	v_max_f32_e32 v94, v95, v94
	v_lshlrev_b32_e32 v95, 16, v48
	v_and_b32_e32 v48, 0xffff0000, v48
	v_max_f32_e32 v97, v98, v97
	v_max3_f32 v94, |v90|, |v46|, v94
	v_max3_f32 v97, |v95|, |v48|, v97
	v_max3_f32 v77, v77, v94, v97
	v_lshlrev_b32_e32 v97, 16, v43
	v_and_b32_e32 v43, 0xffff0000, v43
	v_lshlrev_b32_e32 v100, 16, v45
	v_and_b32_e32 v45, 0xffff0000, v45
	v_max_f32_e64 v98, |v43|, |v43|
	v_max_f32_e64 v99, |v97|, |v97|
	v_max_f32_e64 v101, |v45|, |v45|
	v_max_f32_e64 v102, |v100|, |v100|
	v_lshlrev_b32_e32 v94, 16, v42
	v_and_b32_e32 v42, 0xffff0000, v42
	v_max_f32_e32 v98, v99, v98
	v_lshlrev_b32_e32 v99, 16, v44
	v_and_b32_e32 v44, 0xffff0000, v44
	v_max_f32_e32 v101, v102, v101
	v_max3_f32 v98, |v94|, |v42|, v98
	v_max3_f32 v101, |v99|, |v44|, v101
	v_max3_f32 v77, v77, v98, v101
	v_lshlrev_b32_e32 v101, 16, v39
	v_and_b32_e32 v39, 0xffff0000, v39
	v_lshlrev_b32_e32 v104, 16, v41
	v_and_b32_e32 v41, 0xffff0000, v41
	v_max_f32_e64 v102, |v39|, |v39|
	v_max_f32_e64 v103, |v101|, |v101|
	v_max_f32_e64 v105, |v41|, |v41|
	v_max_f32_e64 v106, |v104|, |v104|
	v_lshlrev_b32_e32 v98, 16, v38
	v_and_b32_e32 v38, 0xffff0000, v38
	v_max_f32_e32 v102, v103, v102
	v_lshlrev_b32_e32 v103, 16, v40
	v_and_b32_e32 v40, 0xffff0000, v40
	v_max_f32_e32 v105, v106, v105
	v_max3_f32 v102, |v98|, |v38|, v102
	v_max3_f32 v105, |v103|, |v40|, v105
	v_lshlrev_b32_e32 v106, 16, v35
	v_and_b32_e32 v35, 0xffff0000, v35
	v_max3_f32 v77, v77, v102, v105
	v_lshlrev_b32_e32 v102, 16, v34
	v_and_b32_e32 v105, 0xffff0000, v34
	v_max_f32_e64 v34, |v35|, |v35|
	v_max_f32_e64 v107, |v106|, |v106|
	v_lshlrev_b32_e32 v109, 16, v37
	v_and_b32_e32 v110, 0xffff0000, v37
	v_max_f32_e32 v34, v107, v34
	v_lshlrev_b32_e32 v107, 16, v36
	v_and_b32_e32 v108, 0xffff0000, v36
	v_max_f32_e64 v36, |v110|, |v110|
	v_max_f32_e64 v37, |v109|, |v109|
	v_max_f32_e32 v36, v37, v36
	v_max3_f32 v34, |v102|, |v105|, v34
	v_max3_f32 v36, |v107|, |v108|, v36
	v_max3_f32 v34, v77, v34, v36
	ds_bpermute_b32 v36, v1, v34
	s_waitcnt lgkmcnt(0)
	v_max_f32_e32 v36, v36, v36
	v_max_f32_e32 v34, v34, v36
	ds_bpermute_b32 v36, v70, v34
	s_waitcnt lgkmcnt(0)
	v_max_f32_e32 v36, v36, v36
	v_max_f32_e32 v34, v34, v36
	ds_bpermute_b32 v36, v71, v34
	s_waitcnt lgkmcnt(0)
	v_max_f32_e32 v36, v36, v36
	v_max_f32_e32 v34, v34, v36
	ds_bpermute_b32 v36, v72, v34
	s_waitcnt lgkmcnt(0)
	v_max_f32_e32 v36, v36, v36
	v_max_f32_e32 v34, v34, v36
	ds_bpermute_b32 v36, v73, v34
	s_waitcnt lgkmcnt(0)
	v_max_f32_e32 v36, v36, v36
	v_max_f32_e32 v34, v34, v36
	ds_bpermute_b32 v36, v74, v34
	s_waitcnt lgkmcnt(0)
	v_max_f32_e32 v36, v36, v36
	v_max_f32_e32 v34, v34, v36
	v_div_scale_f32 v36, s[6:7], v34, v34, s15
	v_rcp_f32_e32 v37, v36
	s_nop 0
	v_fma_f32 v77, -v36, v37, 1.0
	v_fmac_f32_e32 v37, v77, v37
	v_div_scale_f32 v77, vcc, s15, v34, s15
	v_mul_f32_e32 v111, v77, v37
	v_fma_f32 v112, -v36, v111, v77
	v_fmac_f32_e32 v111, v112, v37
	v_fma_f32 v36, -v36, v111, v77
	v_div_fmas_f32 v36, v36, v37, v111
	v_div_fixup_f32 v36, v36, v34, s15
	v_cmp_lt_f32_e32 vcc, 0, v34
	s_nop 1
	v_cndmask_b32_e32 v77, 0, v36, vcc
	v_mul_f32_e32 v37, v77, v62
	v_mul_f32_e32 v36, v77, v75
	v_rndne_f32_e32 v37, v37
	v_mul_f32_e32 v62, v77, v76
	v_mul_f32_e32 v63, v77, v63
	v_rndne_f32_e32 v36, v36
	v_cvt_i32_f32_e32 v37, v37
	v_rndne_f32_e32 v62, v62
	v_rndne_f32_e32 v63, v63
	v_mul_f32_e32 v64, v77, v64
	v_cvt_i32_f32_e32 v36, v36
	v_cvt_i32_f32_sdwa v62, v62 dst_sel:WORD_1 dst_unused:UNUSED_PAD src0_sel:DWORD
	v_cvt_i32_f32_e32 v63, v63
	v_mul_f32_e32 v75, v77, v78
	v_rndne_f32_e32 v64, v64
	v_mul_f32_e32 v76, v77, v79
	v_mul_f32_e32 v65, v77, v65
	v_rndne_f32_e32 v75, v75
	v_cvt_i32_f32_e32 v64, v64
	v_rndne_f32_e32 v76, v76
	v_rndne_f32_e32 v65, v65
	v_cvt_i32_f32_e32 v75, v75
	v_cvt_i32_f32_sdwa v76, v76 dst_sel:WORD_1 dst_unused:UNUSED_PAD src0_sel:DWORD
	v_cvt_i32_f32_e32 v65, v65
	v_lshlrev_b32_e32 v37, 8, v37
	v_and_b32_e32 v37, 0xff00, v37
	v_and_b32_e32 v62, 0xff0000, v62
	v_perm_b32 v36, v63, v36, s26
	v_or3_b32 v36, v36, v37, v62
	v_lshlrev_b32_e32 v37, 8, v64
	v_and_b32_e32 v37, 0xff00, v37
	v_and_b32_e32 v62, 0xff0000, v76
	v_perm_b32 v63, v65, v75, s26
	v_or3_b32 v37, v63, v37, v62
	global_store_dwordx2 v[66:67], v[36:37], off sc0 sc1
	v_mul_f32_e32 v37, v77, v58
	v_mul_f32_e32 v36, v77, v80
	v_rndne_f32_e32 v37, v37
	v_mul_f32_e32 v58, v77, v81
	v_mul_f32_e32 v59, v77, v59
	v_rndne_f32_e32 v36, v36
	v_cvt_i32_f32_e32 v37, v37
	v_rndne_f32_e32 v58, v58
	v_rndne_f32_e32 v59, v59
	v_mul_f32_e32 v60, v77, v60
	v_cvt_i32_f32_e32 v36, v36
	v_cvt_i32_f32_sdwa v58, v58 dst_sel:WORD_1 dst_unused:UNUSED_PAD src0_sel:DWORD
	v_cvt_i32_f32_e32 v59, v59
	v_mul_f32_e32 v62, v77, v83
	v_rndne_f32_e32 v60, v60
	v_mul_f32_e32 v63, v77, v84
	v_mul_f32_e32 v61, v77, v61
	v_rndne_f32_e32 v62, v62
	v_cvt_i32_f32_e32 v60, v60
	v_rndne_f32_e32 v63, v63
	v_rndne_f32_e32 v61, v61
	v_cvt_i32_f32_e32 v62, v62
	v_cvt_i32_f32_sdwa v63, v63 dst_sel:WORD_1 dst_unused:UNUSED_PAD src0_sel:DWORD
	v_cvt_i32_f32_e32 v61, v61
	v_lshlrev_b32_e32 v37, 8, v37
	v_and_b32_e32 v37, 0xff00, v37
	v_and_b32_e32 v58, 0xff0000, v58
	v_perm_b32 v36, v59, v36, s26
	v_or3_b32 v36, v36, v37, v58
	v_lshlrev_b32_e32 v37, 8, v60
	v_and_b32_e32 v37, 0xff00, v37
	v_and_b32_e32 v58, 0xff0000, v63
	v_perm_b32 v59, v61, v62, s26
	v_or3_b32 v37, v59, v37, v58
	global_store_dwordx2 v[66:67], v[36:37], off offset:512 sc0 sc1
	v_mul_f32_e32 v37, v77, v54
	v_mul_f32_e32 v36, v77, v82
	v_rndne_f32_e32 v37, v37
	v_mul_f32_e32 v54, v77, v85
	v_mul_f32_e32 v55, v77, v55
	v_rndne_f32_e32 v36, v36
	v_cvt_i32_f32_e32 v37, v37
	v_rndne_f32_e32 v54, v54
	v_rndne_f32_e32 v55, v55
	v_mul_f32_e32 v56, v77, v56
	v_cvt_i32_f32_e32 v36, v36
	v_cvt_i32_f32_sdwa v54, v54 dst_sel:WORD_1 dst_unused:UNUSED_PAD src0_sel:DWORD
	v_cvt_i32_f32_e32 v55, v55
	v_mul_f32_e32 v58, v77, v87
	v_rndne_f32_e32 v56, v56
	v_mul_f32_e32 v59, v77, v88
	v_mul_f32_e32 v57, v77, v57
	v_rndne_f32_e32 v58, v58
	v_cvt_i32_f32_e32 v56, v56
	v_rndne_f32_e32 v59, v59
	v_rndne_f32_e32 v57, v57
	v_cvt_i32_f32_e32 v58, v58
	v_cvt_i32_f32_sdwa v59, v59 dst_sel:WORD_1 dst_unused:UNUSED_PAD src0_sel:DWORD
	v_cvt_i32_f32_e32 v57, v57
	v_lshlrev_b32_e32 v37, 8, v37
	v_and_b32_e32 v37, 0xff00, v37
	v_and_b32_e32 v54, 0xff0000, v54
	v_perm_b32 v36, v55, v36, s26
	v_or3_b32 v36, v36, v37, v54
	v_lshlrev_b32_e32 v37, 8, v56
	v_and_b32_e32 v37, 0xff00, v37
	v_and_b32_e32 v54, 0xff0000, v59
	v_perm_b32 v55, v57, v58, s26
	v_or3_b32 v37, v55, v37, v54
	global_store_dwordx2 v[66:67], v[36:37], off offset:1024 sc0 sc1
	v_mul_f32_e32 v37, v77, v50
	v_mul_f32_e32 v36, v77, v86
	v_rndne_f32_e32 v37, v37
	v_mul_f32_e32 v50, v77, v89
	v_mul_f32_e32 v51, v77, v51
	v_rndne_f32_e32 v36, v36
	v_cvt_i32_f32_e32 v37, v37
	v_rndne_f32_e32 v50, v50
	v_rndne_f32_e32 v51, v51
	v_mul_f32_e32 v52, v77, v52
	v_cvt_i32_f32_e32 v36, v36
	v_cvt_i32_f32_sdwa v50, v50 dst_sel:WORD_1 dst_unused:UNUSED_PAD src0_sel:DWORD
	v_cvt_i32_f32_e32 v51, v51
	v_mul_f32_e32 v54, v77, v91
	v_rndne_f32_e32 v52, v52
	v_mul_f32_e32 v55, v77, v92
	v_mul_f32_e32 v53, v77, v53
	v_rndne_f32_e32 v54, v54
	v_cvt_i32_f32_e32 v52, v52
	v_rndne_f32_e32 v55, v55
	v_rndne_f32_e32 v53, v53
	v_cvt_i32_f32_e32 v54, v54
	v_cvt_i32_f32_sdwa v55, v55 dst_sel:WORD_1 dst_unused:UNUSED_PAD src0_sel:DWORD
	v_cvt_i32_f32_e32 v53, v53
	v_lshlrev_b32_e32 v37, 8, v37
	v_and_b32_e32 v37, 0xff00, v37
	v_and_b32_e32 v50, 0xff0000, v50
	v_perm_b32 v36, v51, v36, s26
	v_or3_b32 v36, v36, v37, v50
	v_lshlrev_b32_e32 v37, 8, v52
	v_and_b32_e32 v37, 0xff00, v37
	v_and_b32_e32 v50, 0xff0000, v55
	v_perm_b32 v51, v53, v54, s26
	v_or3_b32 v37, v51, v37, v50
	global_store_dwordx2 v[66:67], v[36:37], off offset:1536 sc0 sc1
	v_mul_f32_e32 v37, v77, v46
	v_mul_f32_e32 v36, v77, v90
	v_rndne_f32_e32 v37, v37
	v_mul_f32_e32 v46, v77, v93
	v_mul_f32_e32 v47, v77, v47
	v_rndne_f32_e32 v36, v36
	v_cvt_i32_f32_e32 v37, v37
	v_rndne_f32_e32 v46, v46
	v_rndne_f32_e32 v47, v47
	v_mul_f32_e32 v48, v77, v48
	v_cvt_i32_f32_e32 v36, v36
	v_cvt_i32_f32_sdwa v46, v46 dst_sel:WORD_1 dst_unused:UNUSED_PAD src0_sel:DWORD
	v_cvt_i32_f32_e32 v47, v47
	v_mul_f32_e32 v50, v77, v95
	v_rndne_f32_e32 v48, v48
	v_mul_f32_e32 v51, v77, v96
	v_mul_f32_e32 v49, v77, v49
	v_rndne_f32_e32 v50, v50
	v_cvt_i32_f32_e32 v48, v48
	v_rndne_f32_e32 v51, v51
	v_rndne_f32_e32 v49, v49
	v_cvt_i32_f32_e32 v50, v50
	v_cvt_i32_f32_sdwa v51, v51 dst_sel:WORD_1 dst_unused:UNUSED_PAD src0_sel:DWORD
	v_cvt_i32_f32_e32 v49, v49
	v_lshlrev_b32_e32 v37, 8, v37
	v_and_b32_e32 v37, 0xff00, v37
	v_and_b32_e32 v46, 0xff0000, v46
	v_perm_b32 v36, v47, v36, s26
	v_or3_b32 v36, v36, v37, v46
	v_lshlrev_b32_e32 v37, 8, v48
	v_and_b32_e32 v37, 0xff00, v37
	v_and_b32_e32 v46, 0xff0000, v51
	v_perm_b32 v47, v49, v50, s26
	v_or3_b32 v37, v47, v37, v46
	global_store_dwordx2 v[66:67], v[36:37], off offset:2048 sc0 sc1
	v_mul_f32_e32 v37, v77, v42
	v_mul_f32_e32 v36, v77, v94
	v_rndne_f32_e32 v37, v37
	v_mul_f32_e32 v42, v77, v97
	v_mul_f32_e32 v43, v77, v43
	v_rndne_f32_e32 v36, v36
	v_cvt_i32_f32_e32 v37, v37
	v_rndne_f32_e32 v42, v42
	v_rndne_f32_e32 v43, v43
	v_mul_f32_e32 v44, v77, v44
	v_cvt_i32_f32_e32 v36, v36
	v_cvt_i32_f32_sdwa v42, v42 dst_sel:WORD_1 dst_unused:UNUSED_PAD src0_sel:DWORD
	v_cvt_i32_f32_e32 v43, v43
	v_mul_f32_e32 v46, v77, v99
	v_rndne_f32_e32 v44, v44
	v_mul_f32_e32 v47, v77, v100
	v_mul_f32_e32 v45, v77, v45
	v_rndne_f32_e32 v46, v46
	v_cvt_i32_f32_e32 v44, v44
	v_rndne_f32_e32 v47, v47
	v_rndne_f32_e32 v45, v45
	v_cvt_i32_f32_e32 v46, v46
	v_cvt_i32_f32_sdwa v47, v47 dst_sel:WORD_1 dst_unused:UNUSED_PAD src0_sel:DWORD
	v_cvt_i32_f32_e32 v45, v45
	v_lshlrev_b32_e32 v37, 8, v37
	v_and_b32_e32 v37, 0xff00, v37
	v_and_b32_e32 v42, 0xff0000, v42
	v_perm_b32 v36, v43, v36, s26
	v_or3_b32 v36, v36, v37, v42
	v_lshlrev_b32_e32 v37, 8, v44
	v_and_b32_e32 v37, 0xff00, v37
	v_and_b32_e32 v42, 0xff0000, v47
	v_perm_b32 v43, v45, v46, s26
	v_or3_b32 v37, v43, v37, v42
	global_store_dwordx2 v[66:67], v[36:37], off offset:2560 sc0 sc1
	v_mul_f32_e32 v37, v77, v38
	v_mul_f32_e32 v36, v77, v98
	v_rndne_f32_e32 v37, v37
	v_mul_f32_e32 v38, v77, v101
	v_mul_f32_e32 v39, v77, v39
	v_rndne_f32_e32 v36, v36
	v_cvt_i32_f32_e32 v37, v37
	v_rndne_f32_e32 v38, v38
	v_rndne_f32_e32 v39, v39
	v_mul_f32_e32 v40, v77, v40
	v_cvt_i32_f32_e32 v36, v36
	v_cvt_i32_f32_sdwa v38, v38 dst_sel:WORD_1 dst_unused:UNUSED_PAD src0_sel:DWORD
	v_cvt_i32_f32_e32 v39, v39
	v_mul_f32_e32 v42, v77, v103
	v_rndne_f32_e32 v40, v40
	v_mul_f32_e32 v43, v77, v104
	v_mul_f32_e32 v41, v77, v41
	v_rndne_f32_e32 v42, v42
	v_cvt_i32_f32_e32 v40, v40
	v_rndne_f32_e32 v43, v43
	v_rndne_f32_e32 v41, v41
	v_cvt_i32_f32_e32 v42, v42
	v_cvt_i32_f32_sdwa v43, v43 dst_sel:WORD_1 dst_unused:UNUSED_PAD src0_sel:DWORD
	v_cvt_i32_f32_e32 v41, v41
	v_lshlrev_b32_e32 v37, 8, v37
	v_and_b32_e32 v37, 0xff00, v37
	v_and_b32_e32 v38, 0xff0000, v38
	v_perm_b32 v36, v39, v36, s26
	v_or3_b32 v36, v36, v37, v38
	v_lshlrev_b32_e32 v37, 8, v40
	v_and_b32_e32 v37, 0xff00, v37
	v_and_b32_e32 v38, 0xff0000, v43
	v_perm_b32 v39, v41, v42, s26
	v_or3_b32 v37, v39, v37, v38
	global_store_dwordx2 v[66:67], v[36:37], off offset:3072 sc0 sc1
	v_mul_f32_e32 v37, v77, v105
	v_mul_f32_e32 v36, v77, v102
	v_rndne_f32_e32 v37, v37
	v_mul_f32_e32 v38, v77, v106
	v_mul_f32_e32 v35, v77, v35
	v_rndne_f32_e32 v36, v36
	v_cvt_i32_f32_e32 v37, v37
	v_rndne_f32_e32 v38, v38
	v_rndne_f32_e32 v35, v35
	v_mul_f32_e32 v40, v77, v108
	v_cvt_i32_f32_e32 v36, v36
	v_cvt_i32_f32_sdwa v38, v38 dst_sel:WORD_1 dst_unused:UNUSED_PAD src0_sel:DWORD
	v_cvt_i32_f32_e32 v35, v35
	v_mul_f32_e32 v39, v77, v107
	v_rndne_f32_e32 v40, v40
	v_mul_f32_e32 v41, v77, v109
	v_mul_f32_e32 v42, v77, v110
	v_rndne_f32_e32 v39, v39
	v_cvt_i32_f32_e32 v40, v40
	v_rndne_f32_e32 v41, v41
	v_rndne_f32_e32 v42, v42
	v_cvt_i32_f32_e32 v39, v39
	v_cvt_i32_f32_sdwa v41, v41 dst_sel:WORD_1 dst_unused:UNUSED_PAD src0_sel:DWORD
	v_cvt_i32_f32_e32 v42, v42
	v_lshlrev_b32_e32 v37, 8, v37
	v_and_b32_e32 v37, 0xff00, v37
	v_and_b32_e32 v38, 0xff0000, v38
	v_perm_b32 v35, v35, v36, s26
	v_or3_b32 v36, v35, v37, v38
	v_lshlrev_b32_e32 v35, 8, v40
	v_and_b32_e32 v35, 0xff00, v35
	v_and_b32_e32 v37, 0xff0000, v41
	v_perm_b32 v38, v42, v39, s26
	v_or3_b32 v37, v38, v35, v37
	global_store_dwordx2 v[66:67], v[36:37], off offset:3584 sc0 sc1
	s_and_saveexec_b64 s[64:65], s[8:9]
	s_cbranch_execz .LBB0_1735
	s_add_u32 s6, s22, s46
	s_addc_u32 s7, s23, s47
	v_mul_f32_e32 v36, 0x3c010204, v34
	v_mov_b64_e32 v[34:35], s[6:7]
	flat_store_dword v[34:35], v36 sc0 sc1

.LBB0_1737:
	s_waitcnt vmcnt(0)
	s_waitcnt lgkmcnt(0)
	s_barrier
	s_and_saveexec_b64 s[8:9], s[4:5]
	s_cbranch_execz .LBB0_1754
	s_mov_b64 s[10:11], exec
	s_waitcnt vmcnt(0)
	s_waitcnt vmcnt(0)
	v_mbcnt_lo_u32_b32 v1, s10, 0
	v_mbcnt_hi_u32_b32 v1, s11, v1
	v_cmp_eq_u32_e32 vcc, 0, v1
	s_and_saveexec_b64 s[12:13], vcc
	s_cbranch_execz .LBB0_1740
	s_bcnt1_i32_b64 s6, s[10:11]
	v_mov_b32_e32 v1, 0
	v_mov_b32_e32 v2, s6
	global_atomic_add v1, v2, s[36:37]

.LBB0_1771:
	ds_read_b128 v[130:133], v185
	ds_read_b128 v[134:137], v185 offset:1024
	ds_read_b128 v[138:141], v185 offset:2048
	ds_read_b128 v[142:145], v185 offset:3072
	ds_read_b128 v[146:149], v188
	ds_read_b128 v[150:153], v188 offset:1024
	ds_read_b128 v[168:171], v188 offset:2048
	ds_read_b128 v[172:175], v188 offset:3072
	s_add_u32 s6, s8, 0xfff80080
	s_addc_u32 s7, s9, -1
	s_cmp_eq_u32 s71, 28
	s_cselect_b32 s81, s26, s7
	s_cselect_b32 s80, s27, s6
	s_cselect_b32 s79, s28, s41
	s_cselect_b32 s78, s29, s40
	s_add_i32 m0, s11, 0xc000
	ds_read_b128 v[192:195], v189
	ds_read_b128 v[196:199], v189 offset:1024
	ds_read_b128 v[200:203], v189 offset:2048
	ds_read_b128 v[204:207], v189 offset:3072
	ds_read_b128 v[208:211], v189 offset:4096
	ds_read_b128 v[212:215], v189 offset:5120
	ds_read_b128 v[216:219], v189 offset:6144
	ds_read_b128 v[220:223], v189 offset:7168
	global_load_lds_dwordx4 v162, s[8:9]
	s_add_i32 m0, s11, 0xe000
	s_nop 0
	global_load_lds_dwordx4 v166, s[8:9]
	s_waitcnt vmcnt(8)
	s_waitcnt lgkmcnt(0)
	s_barrier
	s_setprio 1
	s_waitcnt lgkmcnt(0)
	v_mfma_i32_16x16x64_i8 v[126:129], v[130:133], v[192:195], v[126:129]
	v_mfma_i32_16x16x64_i8 v[122:125], v[138:141], v[192:195], v[122:125]
	v_mfma_i32_16x16x64_i8 v[110:113], v[130:133], v[200:203], v[110:113]
	v_mfma_i32_16x16x64_i8 v[106:109], v[138:141], v[200:203], v[106:109]
	v_mfma_i32_16x16x64_i8 v[94:97], v[130:133], v[208:211], v[94:97]
	v_mfma_i32_16x16x64_i8 v[90:93], v[138:141], v[208:211], v[90:93]
	v_mfma_i32_16x16x64_i8 v[78:81], v[130:133], v[216:219], v[78:81]
	v_mfma_i32_16x16x64_i8 v[74:77], v[138:141], v[216:219], v[74:77]
	v_mfma_i32_16x16x64_i8 v[126:129], v[134:137], v[196:199], v[126:129]
	v_mfma_i32_16x16x64_i8 v[122:125], v[142:145], v[196:199], v[122:125]
	v_mfma_i32_16x16x64_i8 v[110:113], v[134:137], v[204:207], v[110:113]
	v_mfma_i32_16x16x64_i8 v[106:109], v[142:145], v[204:207], v[106:109]
	v_mfma_i32_16x16x64_i8 v[94:97], v[134:137], v[212:215], v[94:97]
	v_mfma_i32_16x16x64_i8 v[90:93], v[142:145], v[212:215], v[90:93]
	v_mfma_i32_16x16x64_i8 v[78:81], v[134:137], v[220:223], v[78:81]
	v_mfma_i32_16x16x64_i8 v[74:77], v[142:145], v[220:223], v[74:77]
	s_setprio 0
	s_setprio 1
	v_mfma_i32_16x16x64_i8 v[118:121], v[146:149], v[192:195], v[118:121]
	v_mfma_i32_16x16x64_i8 v[114:117], v[168:171], v[192:195], v[114:117]
	v_mfma_i32_16x16x64_i8 v[102:105], v[146:149], v[200:203], v[102:105]
	v_mfma_i32_16x16x64_i8 v[98:101], v[168:171], v[200:203], v[98:101]
	v_mfma_i32_16x16x64_i8 v[86:89], v[146:149], v[208:211], v[86:89]
	v_mfma_i32_16x16x64_i8 v[82:85], v[168:171], v[208:211], v[82:85]
	v_mfma_i32_16x16x64_i8 v[70:73], v[146:149], v[216:219], v[70:73]
	v_mfma_i32_16x16x64_i8 v[66:69], v[168:171], v[216:219], v[66:69]
	v_mfma_i32_16x16x64_i8 v[118:121], v[150:153], v[196:199], v[118:121]
	v_mfma_i32_16x16x64_i8 v[114:117], v[172:175], v[196:199], v[114:117]
	v_mfma_i32_16x16x64_i8 v[102:105], v[150:153], v[204:207], v[102:105]
	v_mfma_i32_16x16x64_i8 v[98:101], v[172:175], v[204:207], v[98:101]
	v_mfma_i32_16x16x64_i8 v[86:89], v[150:153], v[212:215], v[86:89]
	v_mfma_i32_16x16x64_i8 v[82:85], v[172:175], v[212:215], v[82:85]
	v_mfma_i32_16x16x64_i8 v[70:73], v[150:153], v[220:223], v[70:73]
	v_mfma_i32_16x16x64_i8 v[66:69], v[172:175], v[220:223], v[66:69]
	s_setprio 0
	s_barrier
	s_add_i32 s6, s87, s67
	v_lshl_add_u64 v[176:177], s[78:79], 0, v[156:157]
	s_mov_b32 m0, s6
	ds_read_b128 v[192:195], v189 offset:16384
	ds_read_b128 v[196:199], v189 offset:17408
	ds_read_b128 v[200:203], v189 offset:18432
	ds_read_b128 v[204:207], v189 offset:19456
	ds_read_b128 v[208:211], v189 offset:20480
	ds_read_b128 v[212:215], v189 offset:21504
	ds_read_b128 v[216:219], v189 offset:22528
	ds_read_b128 v[220:223], v189 offset:23552
	global_load_lds_dwordx4 v[176:177], off
	s_add_i32 m0, s6, 0x2000
	s_add_u32 s6, s78, 0x80000
	v_lshl_add_u64 v[182:183], s[78:79], 0, v[160:161]
	s_addc_u32 s7, s79, 0
	s_add_i32 s16, s88, s67
	global_load_lds_dwordx4 v[182:183], off
	s_mov_b32 m0, s16
	v_lshl_add_u64 v[226:227], s[80:81], 0, v[158:159]
	global_load_lds_dwordx4 v156, s[6:7]
	s_add_i32 m0, s16, 0x2000
	s_nop 0
	global_load_lds_dwordx4 v160, s[6:7]
	v_lshl_add_u64 v[224:225], s[80:81], 0, v[154:155]
	s_mov_b32 m0, s11
	s_nop 0
	global_load_lds_dwordx4 v[224:225], off
	s_mov_b32 m0, s56
	s_nop 0
	global_load_lds_dwordx4 v[226:227], off
	s_waitcnt vmcnt(8)
	s_waitcnt lgkmcnt(0)
	s_barrier
	s_setprio 1
	s_waitcnt lgkmcnt(0)
	v_mfma_i32_16x16x64_i8 v[62:65], v[130:133], v[192:195], v[62:65]
	v_mfma_i32_16x16x64_i8 v[58:61], v[138:141], v[192:195], v[58:61]
	v_mfma_i32_16x16x64_i8 v[46:49], v[130:133], v[200:203], v[46:49]
	v_mfma_i32_16x16x64_i8 v[42:45], v[138:141], v[200:203], v[42:45]
	v_mfma_i32_16x16x64_i8 v[30:33], v[130:133], v[208:211], v[30:33]
	v_mfma_i32_16x16x64_i8 v[26:29], v[138:141], v[208:211], v[26:29]
	v_mfma_i32_16x16x64_i8 v[14:17], v[130:133], v[216:219], v[14:17]
	v_mfma_i32_16x16x64_i8 v[10:13], v[138:141], v[216:219], v[10:13]
	v_mfma_i32_16x16x64_i8 v[62:65], v[134:137], v[196:199], v[62:65]
	v_mfma_i32_16x16x64_i8 v[58:61], v[142:145], v[196:199], v[58:61]
	v_mfma_i32_16x16x64_i8 v[46:49], v[134:137], v[204:207], v[46:49]
	v_mfma_i32_16x16x64_i8 v[42:45], v[142:145], v[204:207], v[42:45]
	v_mfma_i32_16x16x64_i8 v[30:33], v[134:137], v[212:215], v[30:33]
	v_mfma_i32_16x16x64_i8 v[26:29], v[142:145], v[212:215], v[26:29]
	v_mfma_i32_16x16x64_i8 v[14:17], v[134:137], v[220:223], v[14:17]
	v_mfma_i32_16x16x64_i8 v[10:13], v[142:145], v[220:223], v[10:13]
	s_setprio 0
	s_setprio 1
	v_mfma_i32_16x16x64_i8 v[54:57], v[146:149], v[192:195], v[54:57]
	v_mfma_i32_16x16x64_i8 v[50:53], v[168:171], v[192:195], v[50:53]
	v_mfma_i32_16x16x64_i8 v[38:41], v[146:149], v[200:203], v[38:41]
	v_mfma_i32_16x16x64_i8 v[34:37], v[168:171], v[200:203], v[34:37]
	v_mfma_i32_16x16x64_i8 v[22:25], v[146:149], v[208:211], v[22:25]
	v_mfma_i32_16x16x64_i8 v[18:21], v[168:171], v[208:211], v[18:21]
	v_mfma_i32_16x16x64_i8 v[6:9], v[146:149], v[216:219], v[6:9]
	v_mfma_i32_16x16x64_i8 v[2:5], v[168:171], v[216:219], v[2:5]
	v_mfma_i32_16x16x64_i8 v[54:57], v[150:153], v[196:199], v[54:57]
	v_mfma_i32_16x16x64_i8 v[50:53], v[172:175], v[196:199], v[50:53]
	v_mfma_i32_16x16x64_i8 v[38:41], v[150:153], v[204:207], v[38:41]
	v_mfma_i32_16x16x64_i8 v[34:37], v[172:175], v[204:207], v[34:37]
	v_mfma_i32_16x16x64_i8 v[22:25], v[150:153], v[212:215], v[22:25]
	v_mfma_i32_16x16x64_i8 v[18:21], v[172:175], v[212:215], v[18:21]
	v_mfma_i32_16x16x64_i8 v[6:9], v[150:153], v[220:223], v[6:9]
	v_mfma_i32_16x16x64_i8 v[2:5], v[172:175], v[220:223], v[2:5]
	s_setprio 0
	s_barrier
	s_add_i32 s16, 0, 0x18000
	s_add_i32 s17, 0, 0x1c000
	v_add_u32_e32 v142, s16, v179
	v_add_u32_e32 v172, s17, v179
	ds_read_b128 v[130:133], v142
	ds_read_b128 v[134:137], v142 offset:1024
	ds_read_b128 v[138:141], v142 offset:2048
	ds_read_b128 v[142:145], v142 offset:3072
	ds_read_b128 v[146:149], v172
	ds_read_b128 v[150:153], v172 offset:1024
	ds_read_b128 v[168:171], v172 offset:2048
	ds_read_b128 v[172:175], v172 offset:3072
	s_add_u32 s6, s80, 0x80000
	s_addc_u32 s7, s81, 0
	s_mov_b32 m0, s57
	ds_read_b128 v[192:195], v189 offset:32768
	ds_read_b128 v[196:199], v189 offset:33792
	ds_read_b128 v[200:203], v189 offset:34816
	ds_read_b128 v[204:207], v189 offset:35840
	ds_read_b128 v[208:211], v189 offset:36864
	ds_read_b128 v[212:215], v189 offset:37888
	ds_read_b128 v[216:219], v189 offset:38912
	ds_read_b128 v[220:223], v189 offset:39936
	global_load_lds_dwordx4 v154, s[6:7]
	s_mov_b32 m0, s82
	s_nop 0
	global_load_lds_dwordx4 v158, s[6:7]
	s_waitcnt vmcnt(8)
	s_waitcnt lgkmcnt(0)
	s_barrier
	s_setprio 1
	s_waitcnt lgkmcnt(0)
	v_mfma_i32_16x16x64_i8 v[126:129], v[130:133], v[192:195], v[126:129]
	v_mfma_i32_16x16x64_i8 v[122:125], v[138:141], v[192:195], v[122:125]
	v_mfma_i32_16x16x64_i8 v[110:113], v[130:133], v[200:203], v[110:113]
	v_mfma_i32_16x16x64_i8 v[106:109], v[138:141], v[200:203], v[106:109]
	v_mfma_i32_16x16x64_i8 v[94:97], v[130:133], v[208:211], v[94:97]
	v_mfma_i32_16x16x64_i8 v[90:93], v[138:141], v[208:211], v[90:93]
	v_mfma_i32_16x16x64_i8 v[78:81], v[130:133], v[216:219], v[78:81]
	v_mfma_i32_16x16x64_i8 v[74:77], v[138:141], v[216:219], v[74:77]
	v_mfma_i32_16x16x64_i8 v[126:129], v[134:137], v[196:199], v[126:129]
	v_mfma_i32_16x16x64_i8 v[122:125], v[142:145], v[196:199], v[122:125]
	v_mfma_i32_16x16x64_i8 v[110:113], v[134:137], v[204:207], v[110:113]
	v_mfma_i32_16x16x64_i8 v[106:109], v[142:145], v[204:207], v[106:109]
	v_mfma_i32_16x16x64_i8 v[94:97], v[134:137], v[212:215], v[94:97]
	v_mfma_i32_16x16x64_i8 v[90:93], v[142:145], v[212:215], v[90:93]
	v_mfma_i32_16x16x64_i8 v[78:81], v[134:137], v[220:223], v[78:81]
	v_mfma_i32_16x16x64_i8 v[74:77], v[142:145], v[220:223], v[74:77]
	s_setprio 0
	s_setprio 1
	v_mfma_i32_16x16x64_i8 v[118:121], v[146:149], v[192:195], v[118:121]
	v_mfma_i32_16x16x64_i8 v[114:117], v[168:171], v[192:195], v[114:117]
	v_mfma_i32_16x16x64_i8 v[102:105], v[146:149], v[200:203], v[102:105]
	v_mfma_i32_16x16x64_i8 v[98:101], v[168:171], v[200:203], v[98:101]
	v_mfma_i32_16x16x64_i8 v[86:89], v[146:149], v[208:211], v[86:89]
	v_mfma_i32_16x16x64_i8 v[82:85], v[168:171], v[208:211], v[82:85]
	v_mfma_i32_16x16x64_i8 v[70:73], v[146:149], v[216:219], v[70:73]
	v_mfma_i32_16x16x64_i8 v[66:69], v[168:171], v[216:219], v[66:69]
	v_mfma_i32_16x16x64_i8 v[118:121], v[150:153], v[196:199], v[118:121]
	v_mfma_i32_16x16x64_i8 v[114:117], v[172:175], v[196:199], v[114:117]
	v_mfma_i32_16x16x64_i8 v[102:105], v[150:153], v[204:207], v[102:105]
	v_mfma_i32_16x16x64_i8 v[98:101], v[172:175], v[204:207], v[98:101]
	v_mfma_i32_16x16x64_i8 v[86:89], v[150:153], v[212:215], v[86:89]
	v_mfma_i32_16x16x64_i8 v[82:85], v[172:175], v[212:215], v[82:85]
	v_mfma_i32_16x16x64_i8 v[70:73], v[150:153], v[220:223], v[70:73]
	v_mfma_i32_16x16x64_i8 v[66:69], v[172:175], v[220:223], v[66:69]
	s_setprio 0
	s_barrier
	s_add_i32 s6, s16, s67
	v_lshl_add_u64 v[176:177], v[176:177], 0, s[62:63]
	s_mov_b32 m0, s6
	ds_read_b128 v[192:195], v189 offset:49152
	ds_read_b128 v[196:199], v189 offset:50176
	ds_read_b128 v[200:203], v189 offset:51200
	ds_read_b128 v[204:207], v189 offset:52224
	ds_read_b128 v[208:211], v189 offset:53248
	ds_read_b128 v[212:215], v189 offset:54272
	ds_read_b128 v[216:219], v189 offset:55296
	ds_read_b128 v[220:223], v189 offset:56320
	global_load_lds_dwordx4 v[176:177], off
	s_add_i32 m0, s6, 0x2000
	s_add_u32 s6, s78, 0x80080
	v_lshl_add_u64 v[176:177], v[182:183], 0, s[62:63]
	s_addc_u32 s7, s79, 0
	s_add_i32 s16, s17, s67
	global_load_lds_dwordx4 v[176:177], off
	s_mov_b32 m0, s16
	s_nop 0
	global_load_lds_dwordx4 v156, s[6:7]
	s_add_i32 m0, s16, 0x2000
	s_nop 0
	global_load_lds_dwordx4 v160, s[6:7]
	v_lshl_add_u64 v[176:177], v[224:225], 0, s[62:63]
	s_mov_b32 m0, s84
	s_nop 0
	global_load_lds_dwordx4 v[176:177], off
	v_lshl_add_u64 v[176:177], v[226:227], 0, s[62:63]
	s_mov_b32 m0, s85
	s_nop 0
	global_load_lds_dwordx4 v[176:177], off
	s_waitcnt vmcnt(8)
	s_waitcnt lgkmcnt(0)
	s_barrier
	s_setprio 1
	s_waitcnt lgkmcnt(0)
	v_mfma_i32_16x16x64_i8 v[62:65], v[130:133], v[192:195], v[62:65]
	v_mfma_i32_16x16x64_i8 v[58:61], v[138:141], v[192:195], v[58:61]
	v_mfma_i32_16x16x64_i8 v[46:49], v[130:133], v[200:203], v[46:49]
	v_mfma_i32_16x16x64_i8 v[42:45], v[138:141], v[200:203], v[42:45]
	v_mfma_i32_16x16x64_i8 v[30:33], v[130:133], v[208:211], v[30:33]
	v_mfma_i32_16x16x64_i8 v[26:29], v[138:141], v[208:211], v[26:29]
	v_mfma_i32_16x16x64_i8 v[14:17], v[130:133], v[216:219], v[14:17]
	v_mfma_i32_16x16x64_i8 v[10:13], v[138:141], v[216:219], v[10:13]
	v_mfma_i32_16x16x64_i8 v[62:65], v[134:137], v[196:199], v[62:65]
	v_mfma_i32_16x16x64_i8 v[58:61], v[142:145], v[196:199], v[58:61]
	v_mfma_i32_16x16x64_i8 v[46:49], v[134:137], v[204:207], v[46:49]
	v_mfma_i32_16x16x64_i8 v[42:45], v[142:145], v[204:207], v[42:45]
	v_mfma_i32_16x16x64_i8 v[30:33], v[134:137], v[212:215], v[30:33]
	v_mfma_i32_16x16x64_i8 v[26:29], v[142:145], v[212:215], v[26:29]
	v_mfma_i32_16x16x64_i8 v[14:17], v[134:137], v[220:223], v[14:17]
	v_mfma_i32_16x16x64_i8 v[10:13], v[142:145], v[220:223], v[10:13]
	s_setprio 0
	s_setprio 1
	v_mfma_i32_16x16x64_i8 v[54:57], v[146:149], v[192:195], v[54:57]
	v_mfma_i32_16x16x64_i8 v[50:53], v[168:171], v[192:195], v[50:53]
	v_mfma_i32_16x16x64_i8 v[38:41], v[146:149], v[200:203], v[38:41]
	v_mfma_i32_16x16x64_i8 v[34:37], v[168:171], v[200:203], v[34:37]
	v_mfma_i32_16x16x64_i8 v[22:25], v[146:149], v[208:211], v[22:25]
	v_mfma_i32_16x16x64_i8 v[18:21], v[168:171], v[208:211], v[18:21]
	v_mfma_i32_16x16x64_i8 v[6:9], v[146:149], v[216:219], v[6:9]
	v_mfma_i32_16x16x64_i8 v[2:5], v[168:171], v[216:219], v[2:5]
	v_mfma_i32_16x16x64_i8 v[54:57], v[150:153], v[196:199], v[54:57]
	v_mfma_i32_16x16x64_i8 v[50:53], v[172:175], v[196:199], v[50:53]
	v_mfma_i32_16x16x64_i8 v[38:41], v[150:153], v[204:207], v[38:41]
	v_mfma_i32_16x16x64_i8 v[34:37], v[172:175], v[204:207], v[34:37]
	v_mfma_i32_16x16x64_i8 v[22:25], v[150:153], v[212:215], v[22:25]
	v_mfma_i32_16x16x64_i8 v[18:21], v[172:175], v[212:215], v[18:21]
	v_mfma_i32_16x16x64_i8 v[6:9], v[150:153], v[220:223], v[6:9]
	v_mfma_i32_16x16x64_i8 v[2:5], v[172:175], v[220:223], v[2:5]
	s_setprio 0
	s_barrier
	s_add_i32 s71, s71, 2
	s_add_u32 s8, s8, 0x100
	s_addc_u32 s9, s9, 0
	s_add_u32 s40, s40, 0x100
	s_addc_u32 s41, s41, 0
	s_cmp_gt_u32 s71, 29
	s_cbranch_scc0 .LBB0_1771
	s_and_b64 vcc, exec, s[64:65]
	s_cbranch_vccz .LBB0_1774
	s_barrier

.LBB0_1778:
	v_lshl_or_b32 v192, s92, 8, v181
	v_ashrrev_i32_e32 v193, 31, v192
	v_lshl_add_u64 v[134:135], v[192:193], 2, s[46:47]
	flat_load_dwordx4 v[146:149], v[134:135]
	flat_load_dwordx4 v[142:145], v[134:135] offset:16
	flat_load_dwordx4 v[138:141], v[134:135] offset:512
	s_nop 0
	flat_load_dwordx4 v[134:137], v[134:135] offset:528
	v_cvt_f32_i32_e32 v127, v127
	v_cvt_f32_i32_e32 v126, v126
	v_cvt_f32_i32_e32 v129, v129
	v_cvt_f32_i32_e32 v128, v128
	v_cvt_f32_i32_e32 v123, v123
	v_cvt_f32_i32_e32 v122, v122
	v_cvt_f32_i32_e32 v125, v125
	v_cvt_f32_i32_e32 v124, v124
	v_cvt_f32_i32_e32 v103, v103
	v_cvt_f32_i32_e32 v102, v102
	v_lshlrev_b64 v[176:177], 13, v[176:177]
	v_cvt_f32_i32_e32 v119, v119
	v_cvt_f32_i32_e32 v118, v118
	v_cvt_f32_i32_e32 v121, v121
	v_cvt_f32_i32_e32 v120, v120
	v_cvt_f32_i32_e32 v115, v115
	v_cvt_f32_i32_e32 v114, v114
	v_cvt_f32_i32_e32 v117, v117
	v_cvt_f32_i32_e32 v116, v116
	v_cvt_f32_i32_e32 v111, v111
	v_cvt_f32_i32_e32 v110, v110
	v_cvt_f32_i32_e32 v113, v113
	v_cvt_f32_i32_e32 v112, v112
	v_cvt_f32_i32_e32 v107, v107
	v_cvt_f32_i32_e32 v106, v106
	v_cvt_f32_i32_e32 v109, v109
	v_cvt_f32_i32_e32 v108, v108
	v_cvt_f32_i32_e32 v195, v99
	v_cvt_f32_i32_e32 v194, v98
	v_cvt_f32_i32_e32 v197, v101
	v_cvt_f32_i32_e32 v196, v100
	v_lshl_add_u64 v[100:101], s[44:45], 0, v[176:177]
	v_lshlrev_b64 v[98:99], 1, v[192:193]
	v_lshl_add_u64 v[176:177], v[100:101], 0, v[98:99]
	v_cvt_f32_i32_e32 v105, v105
	v_cvt_f32_i32_e32 v104, v104
	v_lshlrev_b64 v[174:175], 13, v[174:175]
	v_lshl_add_u64 v[174:175], s[44:45], 0, v[174:175]
	v_lshl_add_u64 v[174:175], v[174:175], 0, v[98:99]
	v_cvt_f32_i32_e32 v95, v95
	v_cvt_f32_i32_e32 v97, v97
	v_cvt_f32_i32_e32 v96, v96
	v_cvt_f32_i32_e32 v94, v94
	v_cvt_f32_i32_e32 v91, v91
	v_cvt_f32_i32_e32 v93, v93
	v_cvt_f32_i32_e32 v92, v92
	v_cvt_f32_i32_e32 v90, v90
	v_cvt_f32_i32_e32 v87, v87
	v_cvt_f32_i32_e32 v89, v89
	v_cvt_f32_i32_e32 v88, v88
	v_cvt_f32_i32_e32 v86, v86
	v_cvt_f32_i32_e32 v83, v83
	v_cvt_f32_i32_e32 v85, v85
	v_cvt_f32_i32_e32 v84, v84
	v_cvt_f32_i32_e32 v82, v82
	v_cvt_f32_i32_e32 v79, v79
	v_cvt_f32_i32_e32 v81, v81
	v_cvt_f32_i32_e32 v80, v80
	v_cvt_f32_i32_e32 v78, v78
	v_cvt_f32_i32_e32 v75, v75
	v_cvt_f32_i32_e32 v77, v77
	v_cvt_f32_i32_e32 v76, v76
	v_cvt_f32_i32_e32 v74, v74
	v_cvt_f32_i32_e32 v71, v71
	v_cvt_f32_i32_e32 v73, v73
	v_cvt_f32_i32_e32 v72, v72
	v_cvt_f32_i32_e32 v70, v70
	v_cvt_f32_i32_e32 v67, v67
	v_cvt_f32_i32_e32 v69, v69
	v_cvt_f32_i32_e32 v68, v68
	v_cvt_f32_i32_e32 v66, v66
	v_cvt_f32_i32_e32 v63, v63
	v_cvt_f32_i32_e32 v65, v65
	v_cvt_f32_i32_e32 v64, v64
	v_cvt_f32_i32_e32 v62, v62
	v_cvt_f32_i32_e32 v59, v59
	s_waitcnt vmcnt(0) lgkmcnt(0)
	v_pk_mul_f32 v[100:101], v[148:149], v[128:129]
	v_pk_mul_f32 v[126:127], v[146:147], v[126:127]
	v_pk_mul_f32 v[124:125], v[144:145], v[124:125]
	v_pk_mul_f32 v[122:123], v[142:143], v[122:123]
	v_pk_mul_f32 v[102:103], v[138:139], v[102:103]
	v_pk_mul_f32 v[128:129], v[150:151], v[100:101] op_sel_hi:[0,1]
	v_pk_mul_f32 v[100:101], v[150:151], v[126:127] op_sel_hi:[0,1]
	v_pk_mul_f32 v[120:121], v[140:141], v[120:121]
	v_pk_mul_f32 v[118:119], v[138:139], v[118:119]
	v_pk_mul_f32 v[116:117], v[136:137], v[116:117]
	v_pk_mul_f32 v[114:115], v[134:135], v[114:115]
	v_pk_mul_f32 v[124:125], v[150:151], v[124:125] op_sel_hi:[0,1]
	v_pk_mul_f32 v[122:123], v[150:151], v[122:123] op_sel_hi:[0,1]
	v_pk_mul_f32 v[126:127], v[186:187], v[102:103] op_sel_hi:[0,1]
	s_nop 0
	v_cvt_pk_bf16_f32 v100, v100, v101
	s_nop 0
	v_cvt_pk_bf16_f32 v101, v128, v129
	s_nop 0
	v_cvt_pk_bf16_f32 v102, v122, v123
	s_nop 0
	v_cvt_pk_bf16_f32 v103, v124, v125
	v_pk_mul_f32 v[112:113], v[148:149], v[112:113]
	v_pk_mul_f32 v[110:111], v[146:147], v[110:111]
	v_pk_mul_f32 v[108:109], v[144:145], v[108:109]
	v_pk_mul_f32 v[106:107], v[142:143], v[106:107]
	v_pk_mul_f32 v[120:121], v[150:151], v[120:121] op_sel_hi:[0,1]
	v_pk_mul_f32 v[118:119], v[150:151], v[118:119] op_sel_hi:[0,1]
	v_pk_mul_f32 v[116:117], v[150:151], v[116:117] op_sel_hi:[0,1]
	v_pk_mul_f32 v[114:115], v[150:151], v[114:115] op_sel_hi:[0,1]
	flat_store_dwordx4 v[176:177], v[100:103] sc0 sc1
	v_pk_mul_f32 v[112:113], v[186:187], v[112:113] op_sel_hi:[0,1]
	v_pk_mul_f32 v[110:111], v[186:187], v[110:111] op_sel_hi:[0,1]
	s_nop 0
	v_cvt_pk_bf16_f32 v100, v118, v119
	s_nop 0
	v_cvt_pk_bf16_f32 v101, v120, v121
	s_nop 0
	v_cvt_pk_bf16_f32 v102, v114, v115
	s_nop 0
	v_cvt_pk_bf16_f32 v103, v116, v117
	v_pk_mul_f32 v[108:109], v[186:187], v[108:109] op_sel_hi:[0,1]
	v_pk_mul_f32 v[106:107], v[186:187], v[106:107] op_sel_hi:[0,1]
	flat_store_dwordx4 v[176:177], v[100:103] offset:256 sc0 sc1
	v_pk_mul_f32 v[104:105], v[140:141], v[104:105]
	v_pk_mul_f32 v[96:97], v[148:149], v[96:97]
	s_nop 0
	v_cvt_pk_bf16_f32 v100, v110, v111
	s_nop 0
	v_cvt_pk_bf16_f32 v101, v112, v113
	s_nop 0
	v_cvt_pk_bf16_f32 v102, v106, v107
	s_nop 0
	v_cvt_pk_bf16_f32 v103, v108, v109
	flat_store_dwordx4 v[174:175], v[100:103] sc0 sc1
	v_pk_mul_f32 v[104:105], v[186:187], v[104:105] op_sel_hi:[0,1]
	v_pk_mul_f32 v[94:95], v[146:147], v[94:95]
	v_pk_mul_f32 v[100:101], v[136:137], v[196:197]
	v_pk_mul_f32 v[102:103], v[134:135], v[194:195]
	v_pk_mul_f32 v[106:107], v[186:187], v[100:101] op_sel_hi:[0,1]
	v_pk_mul_f32 v[102:103], v[186:187], v[102:103] op_sel_hi:[0,1]
	s_nop 0
	v_cvt_pk_bf16_f32 v100, v126, v127
	s_nop 0
	v_cvt_pk_bf16_f32 v101, v104, v105
	s_nop 0
	v_cvt_pk_bf16_f32 v102, v102, v103
	s_nop 0
	v_cvt_pk_bf16_f32 v103, v106, v107
	flat_store_dwordx4 v[174:175], v[100:103] offset:256 sc0 sc1
	v_pk_mul_f32 v[92:93], v[144:145], v[92:93]
	v_pk_mul_f32 v[90:91], v[142:143], v[90:91]
	v_lshlrev_b64 v[100:101], 13, v[170:171]
	v_lshl_add_u64 v[100:101], s[44:45], 0, v[100:101]
	v_lshl_add_u64 v[100:101], v[100:101], 0, v[98:99]
	v_pk_mul_f32 v[96:97], v[152:153], v[96:97] op_sel_hi:[0,1]
	v_pk_mul_f32 v[94:95], v[152:153], v[94:95] op_sel_hi:[0,1]
	v_pk_mul_f32 v[102:103], v[152:153], v[92:93] op_sel_hi:[0,1]
	v_pk_mul_f32 v[92:93], v[152:153], v[90:91] op_sel_hi:[0,1]
	s_nop 0
	v_cvt_pk_bf16_f32 v90, v94, v95
	s_nop 0
	v_cvt_pk_bf16_f32 v91, v96, v97
	v_pk_mul_f32 v[88:89], v[140:141], v[88:89]
	v_pk_mul_f32 v[86:87], v[138:139], v[86:87]
	v_pk_mul_f32 v[84:85], v[136:137], v[84:85]
	v_pk_mul_f32 v[82:83], v[134:135], v[82:83]
	s_nop 0
	v_cvt_pk_bf16_f32 v92, v92, v93
	s_nop 0
	v_cvt_pk_bf16_f32 v93, v102, v103
	flat_store_dwordx4 v[100:101], v[90:93] sc0 sc1
	v_pk_mul_f32 v[88:89], v[152:153], v[88:89] op_sel_hi:[0,1]
	v_pk_mul_f32 v[86:87], v[152:153], v[86:87] op_sel_hi:[0,1]
	v_pk_mul_f32 v[90:91], v[152:153], v[84:85] op_sel_hi:[0,1]
	v_pk_mul_f32 v[84:85], v[152:153], v[82:83] op_sel_hi:[0,1]
	s_nop 0
	v_cvt_pk_bf16_f32 v82, v86, v87
	s_nop 0
	v_cvt_pk_bf16_f32 v83, v88, v89
	s_nop 0
	v_cvt_pk_bf16_f32 v84, v84, v85
	s_nop 0
	v_cvt_pk_bf16_f32 v85, v90, v91
	flat_store_dwordx4 v[100:101], v[82:85] offset:256 sc0 sc1
	v_pk_mul_f32 v[80:81], v[148:149], v[80:81]
	v_pk_mul_f32 v[78:79], v[146:147], v[78:79]
	v_lshlrev_b64 v[82:83], 13, v[168:169]
	v_lshl_add_u64 v[82:83], s[44:45], 0, v[82:83]
	v_pk_mul_f32 v[76:77], v[144:145], v[76:77]
	v_pk_mul_f32 v[74:75], v[142:143], v[74:75]
	v_cvt_f32_i32_e32 v61, v61
	v_cvt_f32_i32_e32 v60, v60
	v_cvt_f32_i32_e32 v58, v58
	v_lshl_add_u64 v[82:83], v[82:83], 0, v[98:99]
	v_pk_mul_f32 v[80:81], v[184:185], v[80:81] op_sel_hi:[0,1]
	v_pk_mul_f32 v[78:79], v[184:185], v[78:79] op_sel_hi:[0,1]
	v_pk_mul_f32 v[84:85], v[184:185], v[76:77] op_sel_hi:[0,1]
	v_pk_mul_f32 v[76:77], v[184:185], v[74:75] op_sel_hi:[0,1]
	s_nop 0
	v_cvt_pk_bf16_f32 v74, v78, v79
	s_nop 0
	v_cvt_pk_bf16_f32 v75, v80, v81
	v_pk_mul_f32 v[72:73], v[140:141], v[72:73]
	v_pk_mul_f32 v[70:71], v[138:139], v[70:71]
	v_pk_mul_f32 v[68:69], v[136:137], v[68:69]
	v_pk_mul_f32 v[66:67], v[134:135], v[66:67]
	v_cvt_f32_i32_e32 v51, v51
	v_cvt_f32_i32_e32 v53, v53
	v_cvt_f32_i32_e32 v52, v52
	v_cvt_f32_i32_e32 v50, v50
	s_nop 0
	v_cvt_pk_bf16_f32 v76, v76, v77
	s_nop 0
	v_cvt_pk_bf16_f32 v77, v84, v85
	flat_store_dwordx4 v[82:83], v[74:77] sc0 sc1
	v_pk_mul_f32 v[72:73], v[184:185], v[72:73] op_sel_hi:[0,1]
	v_pk_mul_f32 v[70:71], v[184:185], v[70:71] op_sel_hi:[0,1]
	v_pk_mul_f32 v[74:75], v[184:185], v[68:69] op_sel_hi:[0,1]
	v_pk_mul_f32 v[68:69], v[184:185], v[66:67] op_sel_hi:[0,1]
	s_nop 0
	v_cvt_pk_bf16_f32 v66, v70, v71
	s_nop 0
	v_cvt_pk_bf16_f32 v67, v72, v73
	v_cvt_f32_i32_e32 v55, v55
	v_cvt_f32_i32_e32 v57, v57
	v_cvt_f32_i32_e32 v56, v56
	v_cvt_f32_i32_e32 v54, v54
	s_nop 0
	v_cvt_pk_bf16_f32 v68, v68, v69
	s_nop 0
	v_cvt_pk_bf16_f32 v69, v74, v75
	flat_store_dwordx4 v[82:83], v[66:69] offset:256 sc0 sc1
	v_pk_mul_f32 v[64:65], v[148:149], v[64:65]
	v_pk_mul_f32 v[62:63], v[146:147], v[62:63]
	v_lshlrev_b64 v[66:67], 13, v[182:183]
	v_lshl_add_u64 v[66:67], s[44:45], 0, v[66:67]
	v_pk_mul_f32 v[60:61], v[144:145], v[60:61]
	v_pk_mul_f32 v[58:59], v[142:143], v[58:59]
	v_lshl_add_u64 v[66:67], v[66:67], 0, v[98:99]
	v_pk_mul_f32 v[64:65], v[130:131], v[64:65] op_sel_hi:[0,1]
	v_pk_mul_f32 v[62:63], v[130:131], v[62:63] op_sel_hi:[0,1]
	v_pk_mul_f32 v[68:69], v[130:131], v[60:61] op_sel_hi:[0,1]
	v_pk_mul_f32 v[60:61], v[130:131], v[58:59] op_sel_hi:[0,1]
	s_nop 0
	v_cvt_pk_bf16_f32 v58, v62, v63
	s_nop 0
	v_cvt_pk_bf16_f32 v59, v64, v65
	v_pk_mul_f32 v[52:53], v[136:137], v[52:53]
	v_pk_mul_f32 v[50:51], v[134:135], v[50:51]
	s_nop 0
	v_cvt_pk_bf16_f32 v60, v60, v61
	s_nop 0
	v_cvt_pk_bf16_f32 v61, v68, v69
	flat_store_dwordx4 v[66:67], v[58:61] sc0 sc1
	v_pk_mul_f32 v[56:57], v[140:141], v[56:57]
	v_pk_mul_f32 v[54:55], v[138:139], v[54:55]
	v_pk_mul_f32 v[58:59], v[130:131], v[52:53] op_sel_hi:[0,1]
	v_pk_mul_f32 v[52:53], v[130:131], v[50:51] op_sel_hi:[0,1]
	v_pk_mul_f32 v[56:57], v[130:131], v[56:57] op_sel_hi:[0,1]
	v_pk_mul_f32 v[54:55], v[130:131], v[54:55] op_sel_hi:[0,1]
	s_nop 0
	v_cvt_pk_bf16_f32 v50, v54, v55
	s_nop 0
	v_cvt_pk_bf16_f32 v51, v56, v57
	s_nop 0
	v_cvt_pk_bf16_f32 v52, v52, v53
	s_nop 0
	v_cvt_pk_bf16_f32 v53, v58, v59
	v_cvt_f32_i32_e32 v49, v49
	v_cvt_f32_i32_e32 v48, v48
	flat_store_dwordx4 v[66:67], v[50:53] offset:256 sc0 sc1
	v_ashrrev_i32_e32 v173, 31, v172
	v_cvt_f32_i32_e32 v43, v43
	v_cvt_f32_i32_e32 v53, v47
	v_cvt_f32_i32_e32 v52, v46
	v_cvt_f32_i32_e32 v45, v45
	v_cvt_f32_i32_e32 v44, v44
	v_cvt_f32_i32_e32 v42, v42
	v_lshlrev_b64 v[50:51], 13, v[172:173]
	v_lshl_add_u64 v[50:51], s[44:45], 0, v[50:51]
	v_cvt_f32_i32_e32 v39, v39
	v_cvt_f32_i32_e32 v38, v38
	v_cvt_f32_i32_e32 v41, v41
	v_cvt_f32_i32_e32 v40, v40
	v_cvt_f32_i32_e32 v35, v35
	v_cvt_f32_i32_e32 v37, v37
	v_cvt_f32_i32_e32 v36, v36
	v_cvt_f32_i32_e32 v34, v34
	v_lshl_add_u64 v[46:47], v[50:51], 0, v[98:99]
	s_mov_b64 s[6:7], 0x20000
	v_pk_mul_f32 v[48:49], v[148:149], v[48:49]
	v_cvt_f32_i32_e32 v31, v31
	v_cvt_f32_i32_e32 v30, v30
	v_lshl_add_u64 v[50:51], v[46:47], 0, s[6:7]
	v_pk_mul_f32 v[52:53], v[146:147], v[52:53]
	v_pk_mul_f32 v[48:49], v[180:181], v[48:49] op_sel_hi:[0,1]
	v_pk_mul_f32 v[44:45], v[144:145], v[44:45]
	v_pk_mul_f32 v[42:43], v[142:143], v[42:43]
	s_mov_b32 s6, 0x20000
	v_cvt_f32_i32_e32 v27, v27
	v_cvt_f32_i32_e32 v29, v29
	v_cvt_f32_i32_e32 v28, v28
	v_cvt_f32_i32_e32 v26, v26
	v_pk_mul_f32 v[52:53], v[180:181], v[52:53] op_sel_hi:[0,1]
	v_pk_mul_f32 v[54:55], v[180:181], v[44:45] op_sel_hi:[0,1]
	v_pk_mul_f32 v[44:45], v[180:181], v[42:43] op_sel_hi:[0,1]
	s_nop 0
	v_cvt_pk_bf16_f32 v42, v52, v53
	s_nop 0
	v_cvt_pk_bf16_f32 v43, v48, v49
	v_add_co_u32_e32 v48, vcc, s6, v46
	v_cvt_f32_i32_e32 v33, v33
	v_cvt_f32_i32_e32 v32, v32
	v_addc_co_u32_e32 v49, vcc, 0, v47, vcc
	v_pk_mul_f32 v[40:41], v[140:141], v[40:41]
	v_pk_mul_f32 v[38:39], v[138:139], v[38:39]
	v_pk_mul_f32 v[36:37], v[136:137], v[36:37]
	v_pk_mul_f32 v[34:35], v[134:135], v[34:35]
	v_cvt_f32_i32_e32 v23, v23
	v_cvt_f32_i32_e32 v22, v22
	v_cvt_f32_i32_e32 v25, v25
	v_cvt_f32_i32_e32 v24, v24
	v_cvt_f32_i32_e32 v19, v19
	v_cvt_f32_i32_e32 v21, v21
	v_cvt_f32_i32_e32 v20, v20
	v_cvt_f32_i32_e32 v18, v18
	s_nop 0
	v_cvt_pk_bf16_f32 v44, v44, v45
	s_nop 0
	v_cvt_pk_bf16_f32 v45, v54, v55
	flat_store_dwordx4 v[48:49], v[42:45] sc0 sc1
	v_pk_mul_f32 v[40:41], v[180:181], v[40:41] op_sel_hi:[0,1]
	v_pk_mul_f32 v[38:39], v[180:181], v[38:39] op_sel_hi:[0,1]
	v_pk_mul_f32 v[42:43], v[180:181], v[36:37] op_sel_hi:[0,1]
	v_pk_mul_f32 v[36:37], v[180:181], v[34:35] op_sel_hi:[0,1]
	s_nop 0
	v_cvt_pk_bf16_f32 v34, v38, v39
	s_nop 0
	v_cvt_pk_bf16_f32 v35, v40, v41
	s_mov_b64 s[6:7], 0x40000
	v_pk_mul_f32 v[30:31], v[146:147], v[30:31]
	v_cvt_f32_i32_e32 v15, v15
	v_cvt_f32_i32_e32 v14, v14
	s_nop 0
	v_cvt_pk_bf16_f32 v36, v36, v37
	s_nop 0
	v_cvt_pk_bf16_f32 v37, v42, v43
	flat_store_dwordx4 v[50:51], v[34:37] offset:256 sc0 sc1
	v_pk_mul_f32 v[30:31], v[132:133], v[30:31] op_sel_hi:[0,1]
	v_pk_mul_f32 v[28:29], v[144:145], v[28:29]
	v_lshl_add_u64 v[34:35], v[46:47], 0, s[6:7]
	v_pk_mul_f32 v[26:27], v[142:143], v[26:27]
	s_mov_b32 s6, 0x40000
	v_cvt_f32_i32_e32 v11, v11
	v_cvt_f32_i32_e32 v13, v13
	v_cvt_f32_i32_e32 v12, v12
	v_cvt_f32_i32_e32 v10, v10
	v_pk_mul_f32 v[32:33], v[148:149], v[32:33]
	v_pk_mul_f32 v[36:37], v[132:133], v[28:29] op_sel_hi:[0,1]
	v_pk_mul_f32 v[28:29], v[132:133], v[26:27] op_sel_hi:[0,1]
	s_nop 0
	v_cvt_pk_bf16_f32 v26, v30, v31
	v_add_co_u32_e32 v30, vcc, s6, v46
	v_cvt_f32_i32_e32 v17, v17
	v_cvt_f32_i32_e32 v16, v16
	v_pk_mul_f32 v[32:33], v[132:133], v[32:33] op_sel_hi:[0,1]
	s_nop 0
	v_cvt_pk_bf16_f32 v27, v32, v33
	v_addc_co_u32_e32 v31, vcc, 0, v47, vcc
	v_pk_mul_f32 v[24:25], v[140:141], v[24:25]
	v_pk_mul_f32 v[22:23], v[138:139], v[22:23]
	v_pk_mul_f32 v[20:21], v[136:137], v[20:21]
	v_pk_mul_f32 v[18:19], v[134:135], v[18:19]
	v_cvt_f32_i32_e32 v3, v3
	v_cvt_f32_i32_e32 v5, v5
	v_cvt_f32_i32_e32 v4, v4
	v_cvt_f32_i32_e32 v2, v2
	s_nop 0
	v_cvt_pk_bf16_f32 v28, v28, v29
	s_nop 0
	v_cvt_pk_bf16_f32 v29, v36, v37
	flat_store_dwordx4 v[30:31], v[26:29] sc0 sc1
	v_pk_mul_f32 v[24:25], v[132:133], v[24:25] op_sel_hi:[0,1]
	v_pk_mul_f32 v[22:23], v[132:133], v[22:23] op_sel_hi:[0,1]
	v_pk_mul_f32 v[26:27], v[132:133], v[20:21] op_sel_hi:[0,1]
	v_pk_mul_f32 v[20:21], v[132:133], v[18:19] op_sel_hi:[0,1]
	s_nop 0
	v_cvt_pk_bf16_f32 v18, v22, v23
	s_nop 0
	v_cvt_pk_bf16_f32 v19, v24, v25
	s_mov_b64 s[6:7], 0x60000
	v_pk_mul_f32 v[14:15], v[146:147], v[14:15]
	v_cvt_f32_i32_e32 v7, v7
	v_cvt_f32_i32_e32 v6, v6
	v_cvt_f32_i32_e32 v9, v9
	v_cvt_f32_i32_e32 v8, v8
	s_nop 0
	v_cvt_pk_bf16_f32 v20, v20, v21
	s_nop 0
	v_cvt_pk_bf16_f32 v21, v26, v27
	flat_store_dwordx4 v[34:35], v[18:21] offset:256 sc0 sc1
	v_pk_mul_f32 v[14:15], v[178:179], v[14:15] op_sel_hi:[0,1]
	v_pk_mul_f32 v[12:13], v[144:145], v[12:13]
	v_lshl_add_u64 v[18:19], v[46:47], 0, s[6:7]
	v_pk_mul_f32 v[10:11], v[142:143], v[10:11]
	s_mov_b32 s6, 0x60000
	v_pk_mul_f32 v[16:17], v[148:149], v[16:17]
	v_pk_mul_f32 v[20:21], v[178:179], v[12:13] op_sel_hi:[0,1]
	v_pk_mul_f32 v[12:13], v[178:179], v[10:11] op_sel_hi:[0,1]
	s_nop 0
	v_cvt_pk_bf16_f32 v10, v14, v15
	v_add_co_u32_e32 v14, vcc, s6, v46
	v_pk_mul_f32 v[16:17], v[178:179], v[16:17] op_sel_hi:[0,1]
	s_nop 0
	v_cvt_pk_bf16_f32 v11, v16, v17
	s_nop 0
	v_addc_co_u32_e32 v15, vcc, 0, v47, vcc
	v_pk_mul_f32 v[4:5], v[136:137], v[4:5]
	v_pk_mul_f32 v[2:3], v[134:135], v[2:3]
	s_nop 0
	v_cvt_pk_bf16_f32 v12, v12, v13
	s_nop 0
	v_cvt_pk_bf16_f32 v13, v20, v21
	flat_store_dwordx4 v[14:15], v[10:13] sc0 sc1
	v_pk_mul_f32 v[8:9], v[140:141], v[8:9]
	v_pk_mul_f32 v[6:7], v[138:139], v[6:7]
	v_pk_mul_f32 v[10:11], v[178:179], v[4:5] op_sel_hi:[0,1]
	v_pk_mul_f32 v[4:5], v[178:179], v[2:3] op_sel_hi:[0,1]
	s_andn2_b64 vcc, exec, s[68:69]
	s_mov_b64 s[8:9], -1
	v_pk_mul_f32 v[8:9], v[178:179], v[8:9] op_sel_hi:[0,1]
	v_pk_mul_f32 v[6:7], v[178:179], v[6:7] op_sel_hi:[0,1]
	s_nop 0
	v_cvt_pk_bf16_f32 v2, v6, v7
	s_nop 0
	v_cvt_pk_bf16_f32 v3, v8, v9
	s_nop 0
	v_cvt_pk_bf16_f32 v4, v4, v5
	s_nop 0
	v_cvt_pk_bf16_f32 v5, v10, v11
	flat_store_dwordx4 v[18:19], v[2:5] offset:256 sc0 sc1
	s_cbranch_vccnz .LBB0_1763
	s_andn2_b64 vcc, exec, s[12:13]
	s_cbranch_vccnz .LBB0_1762
	s_barrier
	s_branch .LBB0_1762

.LBB0_1782:
	s_waitcnt vmcnt(0)
	s_waitcnt lgkmcnt(0)
	s_barrier
	s_and_saveexec_b64 s[8:9], s[4:5]
	s_cbranch_execz .LBB0_1799
	s_mov_b64 s[10:11], exec
	s_waitcnt vmcnt(0)
	s_waitcnt vmcnt(0)
	v_mbcnt_lo_u32_b32 v2, s10, 0
	v_mbcnt_hi_u32_b32 v2, s11, v2
	v_cmp_eq_u32_e32 vcc, 0, v2
	s_and_saveexec_b64 s[12:13], vcc
	s_cbranch_execz .LBB0_1785
	s_bcnt1_i32_b64 s6, s[10:11]
	v_mov_b32_e32 v2, 0
	v_mov_b32_e32 v3, s6
	global_atomic_add v2, v3, s[36:37]

.LBB0_1814:
	ds_read_b128 v[122:125], v195
	ds_read_b128 v[134:137], v195 offset:1024
	ds_read_b128 v[138:141], v195 offset:2048
	ds_read_b128 v[142:145], v195 offset:3072
	ds_read_b128 v[146:149], v196
	ds_read_b128 v[150:153], v196 offset:1024
	ds_read_b128 v[154:157], v196 offset:2048
	ds_read_b128 v[200:203], v196 offset:3072
	s_add_u32 s6, s78, 0xfff00080
	s_addc_u32 s7, s79, -1
	s_cmp_eq_u32 s61, 12
	s_cselect_b32 s83, s75, s7
	s_cselect_b32 s82, s74, s6
	s_cselect_b32 s81, s77, s27
	s_cselect_b32 s80, s76, s13
	s_add_i32 m0, s85, 0xc000
	ds_read_b128 v[204:207], v197
	ds_read_b128 v[208:211], v197 offset:1024
	ds_read_b128 v[212:215], v197 offset:2048
	ds_read_b128 v[216:219], v197 offset:3072
	ds_read_b128 v[220:223], v197 offset:4096
	ds_read_b128 v[224:227], v197 offset:5120
	ds_read_b128 v[228:231], v197 offset:6144
	ds_read_b128 v[232:235], v197 offset:7168
	global_load_lds_dwordx4 v174, s[78:79]
	s_add_i32 m0, s85, 0xe000
	s_nop 0
	global_load_lds_dwordx4 v172, s[78:79]
	s_waitcnt vmcnt(8)
	s_waitcnt lgkmcnt(0)
	s_barrier
	s_setprio 1
	s_waitcnt lgkmcnt(0)
	v_mfma_f32_16x16x32_bf16 v[130:133], v[122:125], v[204:207], v[130:133]
	v_mfma_f32_16x16x32_bf16 v[126:129], v[138:141], v[204:207], v[126:129]
	v_mfma_f32_16x16x32_bf16 v[110:113], v[122:125], v[212:215], v[110:113]
	v_mfma_f32_16x16x32_bf16 v[106:109], v[138:141], v[212:215], v[106:109]
	v_mfma_f32_16x16x32_bf16 v[94:97], v[122:125], v[220:223], v[94:97]
	v_mfma_f32_16x16x32_bf16 v[90:93], v[138:141], v[220:223], v[90:93]
	v_mfma_f32_16x16x32_bf16 v[78:81], v[122:125], v[228:231], v[78:81]
	v_mfma_f32_16x16x32_bf16 v[74:77], v[138:141], v[228:231], v[74:77]
	v_mfma_f32_16x16x32_bf16 v[130:133], v[134:137], v[208:211], v[130:133]
	v_mfma_f32_16x16x32_bf16 v[126:129], v[142:145], v[208:211], v[126:129]
	v_mfma_f32_16x16x32_bf16 v[110:113], v[134:137], v[216:219], v[110:113]
	v_mfma_f32_16x16x32_bf16 v[106:109], v[142:145], v[216:219], v[106:109]
	v_mfma_f32_16x16x32_bf16 v[94:97], v[134:137], v[224:227], v[94:97]
	v_mfma_f32_16x16x32_bf16 v[90:93], v[142:145], v[224:227], v[90:93]
	v_mfma_f32_16x16x32_bf16 v[78:81], v[134:137], v[232:235], v[78:81]
	v_mfma_f32_16x16x32_bf16 v[74:77], v[142:145], v[232:235], v[74:77]
	s_setprio 0
	s_setprio 1
	v_mfma_f32_16x16x32_bf16 v[118:121], v[146:149], v[204:207], v[118:121]
	v_mfma_f32_16x16x32_bf16 v[114:117], v[154:157], v[204:207], v[114:117]
	v_mfma_f32_16x16x32_bf16 v[102:105], v[146:149], v[212:215], v[102:105]
	v_mfma_f32_16x16x32_bf16 v[98:101], v[154:157], v[212:215], v[98:101]
	v_mfma_f32_16x16x32_bf16 v[86:89], v[146:149], v[220:223], v[86:89]
	v_mfma_f32_16x16x32_bf16 v[82:85], v[154:157], v[220:223], v[82:85]
	v_mfma_f32_16x16x32_bf16 v[70:73], v[146:149], v[228:231], v[70:73]
	v_mfma_f32_16x16x32_bf16 v[66:69], v[154:157], v[228:231], v[66:69]
	v_mfma_f32_16x16x32_bf16 v[118:121], v[150:153], v[208:211], v[118:121]
	v_mfma_f32_16x16x32_bf16 v[114:117], v[200:203], v[208:211], v[114:117]
	v_mfma_f32_16x16x32_bf16 v[102:105], v[150:153], v[216:219], v[102:105]
	v_mfma_f32_16x16x32_bf16 v[98:101], v[200:203], v[216:219], v[98:101]
	v_mfma_f32_16x16x32_bf16 v[86:89], v[150:153], v[224:227], v[86:89]
	v_mfma_f32_16x16x32_bf16 v[82:85], v[200:203], v[224:227], v[82:85]
	v_mfma_f32_16x16x32_bf16 v[70:73], v[150:153], v[232:235], v[70:73]
	v_mfma_f32_16x16x32_bf16 v[66:69], v[200:203], v[232:235], v[66:69]
	s_setprio 0
	s_barrier
	s_add_i32 s6, s28, s84
	v_lshl_add_u64 v[176:177], s[80:81], 0, v[160:161]
	s_mov_b32 m0, s6
	ds_read_b128 v[204:207], v197 offset:16384
	ds_read_b128 v[208:211], v197 offset:17408
	ds_read_b128 v[212:215], v197 offset:18432
	ds_read_b128 v[216:219], v197 offset:19456
	ds_read_b128 v[220:223], v197 offset:20480
	ds_read_b128 v[224:227], v197 offset:21504
	ds_read_b128 v[228:231], v197 offset:22528
	ds_read_b128 v[232:235], v197 offset:23552
	global_load_lds_dwordx4 v[176:177], off
	s_add_i32 m0, s6, 0x2000
	s_add_u32 s6, s80, 0x100000
	v_lshl_add_u64 v[236:237], s[80:81], 0, v[166:167]
	s_addc_u32 s7, s81, 0
	s_add_i32 s16, s29, s84
	global_load_lds_dwordx4 v[236:237], off
	s_mov_b32 m0, s16
	v_lshl_add_u64 v[240:241], s[82:83], 0, v[162:163]
	global_load_lds_dwordx4 v160, s[6:7]
	s_add_i32 m0, s16, 0x2000
	s_nop 0
	global_load_lds_dwordx4 v166, s[6:7]
	v_lshl_add_u64 v[238:239], s[82:83], 0, v[158:159]
	s_mov_b32 m0, s85
	s_nop 0
	global_load_lds_dwordx4 v[238:239], off
	s_mov_b32 m0, s86
	s_nop 0
	global_load_lds_dwordx4 v[240:241], off
	s_waitcnt vmcnt(8)
	s_waitcnt lgkmcnt(0)
	s_barrier
	s_setprio 1
	s_waitcnt lgkmcnt(0)
	v_mfma_f32_16x16x32_bf16 v[62:65], v[122:125], v[204:207], v[62:65]
	v_mfma_f32_16x16x32_bf16 v[58:61], v[138:141], v[204:207], v[58:61]
	v_mfma_f32_16x16x32_bf16 v[46:49], v[122:125], v[212:215], v[46:49]
	v_mfma_f32_16x16x32_bf16 v[42:45], v[138:141], v[212:215], v[42:45]
	v_mfma_f32_16x16x32_bf16 v[30:33], v[122:125], v[220:223], v[30:33]
	v_mfma_f32_16x16x32_bf16 v[26:29], v[138:141], v[220:223], v[26:29]
	v_mfma_f32_16x16x32_bf16 v[14:17], v[122:125], v[228:231], v[14:17]
	v_mfma_f32_16x16x32_bf16 v[10:13], v[138:141], v[228:231], v[10:13]
	v_mfma_f32_16x16x32_bf16 v[62:65], v[134:137], v[208:211], v[62:65]
	v_mfma_f32_16x16x32_bf16 v[58:61], v[142:145], v[208:211], v[58:61]
	v_mfma_f32_16x16x32_bf16 v[46:49], v[134:137], v[216:219], v[46:49]
	v_mfma_f32_16x16x32_bf16 v[42:45], v[142:145], v[216:219], v[42:45]
	v_mfma_f32_16x16x32_bf16 v[30:33], v[134:137], v[224:227], v[30:33]
	v_mfma_f32_16x16x32_bf16 v[26:29], v[142:145], v[224:227], v[26:29]
	v_mfma_f32_16x16x32_bf16 v[14:17], v[134:137], v[232:235], v[14:17]
	v_mfma_f32_16x16x32_bf16 v[10:13], v[142:145], v[232:235], v[10:13]
	s_setprio 0
	s_setprio 1
	v_mfma_f32_16x16x32_bf16 v[54:57], v[146:149], v[204:207], v[54:57]
	v_mfma_f32_16x16x32_bf16 v[50:53], v[154:157], v[204:207], v[50:53]
	v_mfma_f32_16x16x32_bf16 v[38:41], v[146:149], v[212:215], v[38:41]
	v_mfma_f32_16x16x32_bf16 v[34:37], v[154:157], v[212:215], v[34:37]
	v_mfma_f32_16x16x32_bf16 v[22:25], v[146:149], v[220:223], v[22:25]
	v_mfma_f32_16x16x32_bf16 v[18:21], v[154:157], v[220:223], v[18:21]
	v_mfma_f32_16x16x32_bf16 v[6:9], v[146:149], v[228:231], v[6:9]
	v_mfma_f32_16x16x32_bf16 v[2:5], v[154:157], v[228:231], v[2:5]
	v_mfma_f32_16x16x32_bf16 v[54:57], v[150:153], v[208:211], v[54:57]
	v_mfma_f32_16x16x32_bf16 v[50:53], v[200:203], v[208:211], v[50:53]
	v_mfma_f32_16x16x32_bf16 v[38:41], v[150:153], v[216:219], v[38:41]
	v_mfma_f32_16x16x32_bf16 v[34:37], v[200:203], v[216:219], v[34:37]
	v_mfma_f32_16x16x32_bf16 v[22:25], v[150:153], v[224:227], v[22:25]
	v_mfma_f32_16x16x32_bf16 v[18:21], v[200:203], v[224:227], v[18:21]
	v_mfma_f32_16x16x32_bf16 v[6:9], v[150:153], v[232:235], v[6:9]
	v_mfma_f32_16x16x32_bf16 v[2:5], v[200:203], v[232:235], v[2:5]
	s_setprio 0
	s_barrier
	s_add_i32 s16, 0, 0x18000
	s_add_i32 s17, 0, 0x1c000
	v_add_u32_e32 v142, s16, v171
	v_add_u32_e32 v168, s17, v171
	ds_read_b128 v[122:125], v142
	ds_read_b128 v[134:137], v142 offset:1024
	ds_read_b128 v[138:141], v142 offset:2048
	ds_read_b128 v[142:145], v142 offset:3072
	ds_read_b128 v[146:149], v168
	ds_read_b128 v[150:153], v168 offset:1024
	ds_read_b128 v[154:157], v168 offset:2048
	ds_read_b128 v[200:203], v168 offset:3072
	s_add_u32 s6, s82, 0x100000
	s_addc_u32 s7, s83, 0
	s_mov_b32 m0, s87
	ds_read_b128 v[204:207], v197 offset:32768
	ds_read_b128 v[208:211], v197 offset:33792
	ds_read_b128 v[212:215], v197 offset:34816
	ds_read_b128 v[216:219], v197 offset:35840
	ds_read_b128 v[220:223], v197 offset:36864
	ds_read_b128 v[224:227], v197 offset:37888
	ds_read_b128 v[228:231], v197 offset:38912
	ds_read_b128 v[232:235], v197 offset:39936
	global_load_lds_dwordx4 v158, s[6:7]
	s_mov_b32 m0, s88
	s_nop 0
	global_load_lds_dwordx4 v162, s[6:7]
	s_waitcnt vmcnt(8)
	s_waitcnt lgkmcnt(0)
	s_barrier
	s_setprio 1
	s_waitcnt lgkmcnt(0)
	v_mfma_f32_16x16x32_bf16 v[130:133], v[122:125], v[204:207], v[130:133]
	v_mfma_f32_16x16x32_bf16 v[126:129], v[138:141], v[204:207], v[126:129]
	v_mfma_f32_16x16x32_bf16 v[110:113], v[122:125], v[212:215], v[110:113]
	v_mfma_f32_16x16x32_bf16 v[106:109], v[138:141], v[212:215], v[106:109]
	v_mfma_f32_16x16x32_bf16 v[94:97], v[122:125], v[220:223], v[94:97]
	v_mfma_f32_16x16x32_bf16 v[90:93], v[138:141], v[220:223], v[90:93]
	v_mfma_f32_16x16x32_bf16 v[78:81], v[122:125], v[228:231], v[78:81]
	v_mfma_f32_16x16x32_bf16 v[74:77], v[138:141], v[228:231], v[74:77]
	v_mfma_f32_16x16x32_bf16 v[130:133], v[134:137], v[208:211], v[130:133]
	v_mfma_f32_16x16x32_bf16 v[126:129], v[142:145], v[208:211], v[126:129]
	v_mfma_f32_16x16x32_bf16 v[110:113], v[134:137], v[216:219], v[110:113]
	v_mfma_f32_16x16x32_bf16 v[106:109], v[142:145], v[216:219], v[106:109]
	v_mfma_f32_16x16x32_bf16 v[94:97], v[134:137], v[224:227], v[94:97]
	v_mfma_f32_16x16x32_bf16 v[90:93], v[142:145], v[224:227], v[90:93]
	v_mfma_f32_16x16x32_bf16 v[78:81], v[134:137], v[232:235], v[78:81]
	v_mfma_f32_16x16x32_bf16 v[74:77], v[142:145], v[232:235], v[74:77]
	s_setprio 0
	s_setprio 1
	v_mfma_f32_16x16x32_bf16 v[118:121], v[146:149], v[204:207], v[118:121]
	v_mfma_f32_16x16x32_bf16 v[114:117], v[154:157], v[204:207], v[114:117]
	v_mfma_f32_16x16x32_bf16 v[102:105], v[146:149], v[212:215], v[102:105]
	v_mfma_f32_16x16x32_bf16 v[98:101], v[154:157], v[212:215], v[98:101]
	v_mfma_f32_16x16x32_bf16 v[86:89], v[146:149], v[220:223], v[86:89]
	v_mfma_f32_16x16x32_bf16 v[82:85], v[154:157], v[220:223], v[82:85]
	v_mfma_f32_16x16x32_bf16 v[70:73], v[146:149], v[228:231], v[70:73]
	v_mfma_f32_16x16x32_bf16 v[66:69], v[154:157], v[228:231], v[66:69]
	v_mfma_f32_16x16x32_bf16 v[118:121], v[150:153], v[208:211], v[118:121]
	v_mfma_f32_16x16x32_bf16 v[114:117], v[200:203], v[208:211], v[114:117]
	v_mfma_f32_16x16x32_bf16 v[102:105], v[150:153], v[216:219], v[102:105]
	v_mfma_f32_16x16x32_bf16 v[98:101], v[200:203], v[216:219], v[98:101]
	v_mfma_f32_16x16x32_bf16 v[86:89], v[150:153], v[224:227], v[86:89]
	v_mfma_f32_16x16x32_bf16 v[82:85], v[200:203], v[224:227], v[82:85]
	v_mfma_f32_16x16x32_bf16 v[70:73], v[150:153], v[232:235], v[70:73]
	v_mfma_f32_16x16x32_bf16 v[66:69], v[200:203], v[232:235], v[66:69]
	s_setprio 0
	s_barrier
	s_add_i32 s6, s16, s84
	v_lshl_add_u64 v[176:177], v[176:177], 0, s[66:67]
	s_mov_b32 m0, s6
	ds_read_b128 v[204:207], v197 offset:49152
	ds_read_b128 v[208:211], v197 offset:50176
	ds_read_b128 v[212:215], v197 offset:51200
	ds_read_b128 v[216:219], v197 offset:52224
	ds_read_b128 v[220:223], v197 offset:53248
	ds_read_b128 v[224:227], v197 offset:54272
	ds_read_b128 v[228:231], v197 offset:55296
	ds_read_b128 v[232:235], v197 offset:56320
	global_load_lds_dwordx4 v[176:177], off
	s_add_i32 m0, s6, 0x2000
	s_add_u32 s6, s80, 0x100080
	v_lshl_add_u64 v[176:177], v[236:237], 0, s[66:67]
	s_addc_u32 s7, s81, 0
	s_add_i32 s16, s17, s84
	global_load_lds_dwordx4 v[176:177], off
	s_mov_b32 m0, s16
	s_nop 0
	global_load_lds_dwordx4 v160, s[6:7]
	s_add_i32 m0, s16, 0x2000
	s_nop 0
	global_load_lds_dwordx4 v166, s[6:7]
	v_lshl_add_u64 v[176:177], v[238:239], 0, s[66:67]
	s_mov_b32 m0, s94
	s_nop 0
	global_load_lds_dwordx4 v[176:177], off
	v_lshl_add_u64 v[176:177], v[240:241], 0, s[66:67]
	s_mov_b32 m0, s95
	s_nop 0
	global_load_lds_dwordx4 v[176:177], off
	s_waitcnt vmcnt(8)
	s_waitcnt lgkmcnt(0)
	s_barrier
	s_setprio 1
	s_waitcnt lgkmcnt(0)
	v_mfma_f32_16x16x32_bf16 v[62:65], v[122:125], v[204:207], v[62:65]
	v_mfma_f32_16x16x32_bf16 v[58:61], v[138:141], v[204:207], v[58:61]
	v_mfma_f32_16x16x32_bf16 v[46:49], v[122:125], v[212:215], v[46:49]
	v_mfma_f32_16x16x32_bf16 v[42:45], v[138:141], v[212:215], v[42:45]
	v_mfma_f32_16x16x32_bf16 v[30:33], v[122:125], v[220:223], v[30:33]
	v_mfma_f32_16x16x32_bf16 v[26:29], v[138:141], v[220:223], v[26:29]
	v_mfma_f32_16x16x32_bf16 v[14:17], v[122:125], v[228:231], v[14:17]
	v_mfma_f32_16x16x32_bf16 v[10:13], v[138:141], v[228:231], v[10:13]
	v_mfma_f32_16x16x32_bf16 v[62:65], v[134:137], v[208:211], v[62:65]
	v_mfma_f32_16x16x32_bf16 v[58:61], v[142:145], v[208:211], v[58:61]
	v_mfma_f32_16x16x32_bf16 v[46:49], v[134:137], v[216:219], v[46:49]
	v_mfma_f32_16x16x32_bf16 v[42:45], v[142:145], v[216:219], v[42:45]
	v_mfma_f32_16x16x32_bf16 v[30:33], v[134:137], v[224:227], v[30:33]
	v_mfma_f32_16x16x32_bf16 v[26:29], v[142:145], v[224:227], v[26:29]
	v_mfma_f32_16x16x32_bf16 v[14:17], v[134:137], v[232:235], v[14:17]
	v_mfma_f32_16x16x32_bf16 v[10:13], v[142:145], v[232:235], v[10:13]
	s_setprio 0
	s_setprio 1
	v_mfma_f32_16x16x32_bf16 v[54:57], v[146:149], v[204:207], v[54:57]
	v_mfma_f32_16x16x32_bf16 v[50:53], v[154:157], v[204:207], v[50:53]
	v_mfma_f32_16x16x32_bf16 v[38:41], v[146:149], v[212:215], v[38:41]
	v_mfma_f32_16x16x32_bf16 v[34:37], v[154:157], v[212:215], v[34:37]
	v_mfma_f32_16x16x32_bf16 v[22:25], v[146:149], v[220:223], v[22:25]
	v_mfma_f32_16x16x32_bf16 v[18:21], v[154:157], v[220:223], v[18:21]
	v_mfma_f32_16x16x32_bf16 v[6:9], v[146:149], v[228:231], v[6:9]
	v_mfma_f32_16x16x32_bf16 v[2:5], v[154:157], v[228:231], v[2:5]
	v_mfma_f32_16x16x32_bf16 v[54:57], v[150:153], v[208:211], v[54:57]
	v_mfma_f32_16x16x32_bf16 v[50:53], v[200:203], v[208:211], v[50:53]
	v_mfma_f32_16x16x32_bf16 v[38:41], v[150:153], v[216:219], v[38:41]
	v_mfma_f32_16x16x32_bf16 v[34:37], v[200:203], v[216:219], v[34:37]
	v_mfma_f32_16x16x32_bf16 v[22:25], v[150:153], v[224:227], v[22:25]
	v_mfma_f32_16x16x32_bf16 v[18:21], v[200:203], v[224:227], v[18:21]
	v_mfma_f32_16x16x32_bf16 v[6:9], v[150:153], v[232:235], v[6:9]
	v_mfma_f32_16x16x32_bf16 v[2:5], v[200:203], v[232:235], v[2:5]
	s_setprio 0
	s_barrier
	s_add_i32 s61, s61, 2
	s_add_u32 s13, s13, 0x100
	s_addc_u32 s27, s27, 0
	s_add_u32 s78, s78, 0x100
	s_addc_u32 s79, s79, 0
	s_cmp_gt_u32 s61, 13
	s_cbranch_scc0 .LBB0_1814
	s_and_b64 vcc, exec, s[68:69]
	s_cbranch_vccz .LBB0_1817
	s_barrier

.LBB0_1833:
	s_or_b64 exec, exec, s[78:79]
	s_waitcnt lgkmcnt(0)
	s_barrier
	s_waitcnt lgkmcnt(0)
	ds_read_b128 v[122:125], v192
	ds_read_b128 v[154:157], v192 offset:256
	s_lshl_b32 s27, s12, 8
	s_cmp_lt_i32 s89, 0
	s_cselect_b64 s[78:79], -1, 0
	s_waitcnt lgkmcnt(0)
	v_max_f32_e32 v125, v125, v125
	v_max_f32_e32 v124, v124, v124
	v_max_f32_e32 v124, v124, v125
	v_max3_f32 v203, v122, v123, v124
	v_sub_f32_e32 v130, v130, v203
	v_sub_f32_e32 v126, v126, v203
	v_exp_f32_e32 v201, v130
	v_exp_f32_e32 v130, v126
	v_sub_f32_e32 v126, v131, v203
	ds_read_b128 v[150:153], v192 offset:512
	ds_read_b128 v[146:149], v192 offset:768
	ds_read_b128 v[142:145], v192 offset:2048
	ds_read_b128 v[138:141], v192 offset:2304
	ds_read_b128 v[134:137], v192 offset:2560
	ds_read_b128 v[122:125], v192 offset:2816
	v_exp_f32_e32 v202, v126
	v_sub_f32_e32 v126, v127, v203
	v_exp_f32_e32 v131, v126
	v_sub_f32_e32 v126, v132, v203
	v_exp_f32_e32 v132, v126
	v_sub_f32_e32 v126, v128, v203
	v_exp_f32_e32 v128, v126
	v_sub_f32_e32 v126, v133, v203
	s_cmp_eq_u32 s96, s89
	v_exp_f32_e32 v133, v126
	v_sub_f32_e32 v126, v129, v203
	v_add_u32_e32 v176, s27, v165
	s_cselect_b64 s[6:7], -1, 0
	v_exp_f32_e32 v129, v126
	s_waitcnt lgkmcnt(0)
	s_barrier
	v_ashrrev_i32_e32 v177, 31, v176
	s_or_b64 s[80:81], s[78:79], s[6:7]
	v_lshlrev_b64 v[204:205], 11, v[176:177]
	v_cndmask_b32_e64 v126, 0, 1, s[80:81]
	v_cmp_ne_u32_e64 s[12:13], 1, v126
	s_andn2_b64 vcc, exec, s[80:81]
	v_lshl_add_u64 v[126:127], s[42:43], 0, v[204:205]
	v_lshlrev_b32_e32 v168, 1, v170
	s_cbranch_vccnz .LBB0_1835
	s_lshl_b32 s6, s60, 8
	s_ashr_i32 s7, s6, 31
	v_lshl_add_u64 v[204:205], s[6:7], 1, v[126:127]
	s_lshl_b32 s62, s93, 1
	v_lshl_add_u64 v[204:205], v[204:205], 0, s[62:63]
	v_lshl_add_u64 v[208:209], v[204:205], 0, v[168:169]
	s_nop 0
	v_cvt_pk_bf16_f32 v204, v201, v202
	s_nop 0
	v_cvt_pk_bf16_f32 v205, v132, v133
	s_nop 0
	v_cvt_pk_bf16_f32 v206, v130, v131
	s_nop 0
	v_cvt_pk_bf16_f32 v207, v128, v129
	flat_store_dwordx4 v[208:209], v[204:207] sc0 sc1
.LBB0_1835:
	v_sub_f32_e32 v118, v118, v203
	v_sub_f32_e32 v114, v114, v203
	v_sub_f32_e32 v119, v119, v203
	v_sub_f32_e32 v115, v115, v203
	v_sub_f32_e32 v120, v120, v203
	v_sub_f32_e32 v116, v116, v203
	v_sub_f32_e32 v121, v121, v203
	v_sub_f32_e32 v117, v117, v203
	v_exp_f32_e32 v118, v118
	v_exp_f32_e32 v114, v114
	v_exp_f32_e32 v119, v119
	v_exp_f32_e32 v115, v115
	v_exp_f32_e32 v120, v120
	v_exp_f32_e32 v116, v116
	v_exp_f32_e32 v121, v121
	v_exp_f32_e32 v117, v117
	s_and_b64 vcc, exec, s[12:13]
	s_cbranch_vccnz .LBB0_1837
	s_lshl_b32 s6, s60, 8
	s_ashr_i32 s7, s6, 31
	v_lshl_add_u64 v[126:127], s[6:7], 1, v[126:127]
	s_lshl_b32 s62, s93, 1
	v_lshl_add_u64 v[126:127], v[126:127], 0, s[62:63]
	v_lshl_add_u64 v[126:127], v[126:127], 0, v[168:169]
	s_nop 0
	v_cvt_pk_bf16_f32 v204, v118, v119
	s_nop 0
	v_cvt_pk_bf16_f32 v205, v120, v121
	s_nop 0
	v_cvt_pk_bf16_f32 v206, v114, v115
	s_nop 0
	v_cvt_pk_bf16_f32 v207, v116, v117
	flat_store_dwordx4 v[126:127], v[204:207] offset:256 sc0 sc1
.LBB0_1837:
	v_add_f32_e32 v126, v201, v202
	v_add_f32_e32 v127, v132, v133
	v_add_f32_e32 v126, v126, v127
	v_add_f32_e32 v127, v130, v131
	v_add_f32_e32 v118, v118, v119
	v_add_f32_e32 v119, v120, v121
	v_add_f32_e32 v126, v127, v126
	v_add_f32_e32 v127, v128, v129
	v_add_f32_e32 v118, v118, v119
	v_add_f32_e32 v114, v114, v115
	v_add_f32_e32 v126, v127, v126
	v_add_f32_e32 v114, v114, v118
	v_add_f32_e32 v115, v116, v117
	v_add_f32_e32 v126, 0, v126
	v_add_f32_e32 v114, v115, v114
	v_add_f32_e32 v114, v114, v126
	ds_bpermute_b32 v115, v199, v114
	s_and_b64 s[80:81], s[8:9], s[80:81]
	s_waitcnt lgkmcnt(0)
	v_add_f32_e32 v114, v114, v115
	ds_bpermute_b32 v115, v200, v114
	s_and_saveexec_b64 s[82:83], s[80:81]
	s_cbranch_execz .LBB0_1839
	s_waitcnt lgkmcnt(0)
	v_add_f32_e32 v116, v114, v115
	v_lshlrev_b64 v[114:115], 6, v[176:177]
	s_ashr_i32 s61, s60, 31
	v_lshl_add_u64 v[114:115], s[46:47], 0, v[114:115]
	v_lshl_add_u64 v[114:115], s[60:61], 4, v[114:115]
	s_lshl_b32 s62, s92, 2
	v_lshl_add_u64 v[114:115], v[114:115], 0, s[62:63]
	flat_store_dword v[114:115], v116 sc0 sc1
.LBB0_1839:
	s_or_b64 exec, exec, s[82:83]
	v_max_f32_e32 v114, v157, v157
	s_waitcnt lgkmcnt(0)
	v_max_f32_e32 v115, v156, v156
	v_max_f32_e32 v114, v115, v114
	v_max3_f32 v118, v154, v155, v114
	v_sub_f32_e32 v110, v110, v118
	v_sub_f32_e32 v106, v106, v118
	v_exp_f32_e32 v116, v110
	v_exp_f32_e32 v110, v106
	v_sub_f32_e32 v106, v111, v118
	v_exp_f32_e32 v117, v106
	v_sub_f32_e32 v106, v107, v118
	v_exp_f32_e32 v111, v106
	v_sub_f32_e32 v106, v112, v118
	v_exp_f32_e32 v112, v106
	v_sub_f32_e32 v106, v108, v118
	v_exp_f32_e32 v108, v106
	v_sub_f32_e32 v106, v113, v118
	v_exp_f32_e32 v113, v106
	v_sub_f32_e32 v106, v109, v118
	v_add_u32_e32 v114, s27, v178
	v_exp_f32_e32 v109, v106
	v_ashrrev_i32_e32 v115, 31, v114
	v_lshlrev_b64 v[106:107], 11, v[114:115]
	s_and_b64 vcc, exec, s[12:13]
	v_lshl_add_u64 v[106:107], s[42:43], 0, v[106:107]
	s_cbranch_vccnz .LBB0_1841
	s_lshl_b32 s6, s60, 8
	s_ashr_i32 s7, s6, 31
	v_lshl_add_u64 v[120:121], s[6:7], 1, v[106:107]
	s_lshl_b32 s62, s93, 1
	v_lshl_add_u64 v[120:121], v[120:121], 0, s[62:63]
	v_lshl_add_u64 v[120:121], v[120:121], 0, v[168:169]
	s_nop 0
	v_cvt_pk_bf16_f32 v126, v116, v117
	s_nop 0
	v_cvt_pk_bf16_f32 v127, v112, v113
	s_nop 0
	v_cvt_pk_bf16_f32 v128, v110, v111
	s_nop 0
	v_cvt_pk_bf16_f32 v129, v108, v109
	flat_store_dwordx4 v[120:121], v[126:129] sc0 sc1
.LBB0_1841:
	v_sub_f32_e32 v102, v102, v118
	v_sub_f32_e32 v98, v98, v118
	v_sub_f32_e32 v103, v103, v118
	v_sub_f32_e32 v99, v99, v118
	v_sub_f32_e32 v104, v104, v118
	v_sub_f32_e32 v100, v100, v118
	v_sub_f32_e32 v105, v105, v118
	v_sub_f32_e32 v101, v101, v118
	v_exp_f32_e32 v102, v102
	v_exp_f32_e32 v98, v98
	v_exp_f32_e32 v103, v103
	v_exp_f32_e32 v99, v99
	v_exp_f32_e32 v104, v104
	v_exp_f32_e32 v100, v100
	v_exp_f32_e32 v105, v105
	v_exp_f32_e32 v101, v101
	s_and_b64 vcc, exec, s[12:13]
	s_cbranch_vccnz .LBB0_1843
	s_lshl_b32 s6, s60, 8
	s_ashr_i32 s7, s6, 31
	v_lshl_add_u64 v[106:107], s[6:7], 1, v[106:107]
	s_lshl_b32 s62, s93, 1
	v_lshl_add_u64 v[106:107], v[106:107], 0, s[62:63]
	v_lshl_add_u64 v[106:107], v[106:107], 0, v[168:169]
	s_nop 0
	v_cvt_pk_bf16_f32 v118, v102, v103
	s_nop 0
	v_cvt_pk_bf16_f32 v119, v104, v105
	s_nop 0
	v_cvt_pk_bf16_f32 v120, v98, v99
	s_nop 0
	v_cvt_pk_bf16_f32 v121, v100, v101
	flat_store_dwordx4 v[106:107], v[118:121] offset:256 sc0 sc1
.LBB0_1843:
	v_add_f32_e32 v106, v116, v117
	v_add_f32_e32 v107, v112, v113
	v_add_f32_e32 v106, v106, v107
	v_add_f32_e32 v107, v110, v111
	v_add_f32_e32 v102, v102, v103
	v_add_f32_e32 v103, v104, v105
	v_add_f32_e32 v106, v107, v106
	v_add_f32_e32 v107, v108, v109
	v_add_f32_e32 v102, v102, v103
	v_add_f32_e32 v98, v98, v99
	v_add_f32_e32 v106, v107, v106
	v_add_f32_e32 v98, v98, v102
	v_add_f32_e32 v99, v100, v101
	v_add_f32_e32 v106, 0, v106
	v_add_f32_e32 v98, v99, v98
	v_add_f32_e32 v98, v98, v106
	ds_bpermute_b32 v99, v199, v98
	s_waitcnt lgkmcnt(0)
	v_add_f32_e32 v98, v98, v99
	ds_bpermute_b32 v99, v200, v98
	s_and_saveexec_b64 s[12:13], s[80:81]
	s_cbranch_execz .LBB0_1845
	s_waitcnt lgkmcnt(0)
	v_add_f32_e32 v100, v98, v99
	v_lshlrev_b64 v[98:99], 6, v[114:115]
	s_ashr_i32 s61, s60, 31
	v_lshl_add_u64 v[98:99], s[46:47], 0, v[98:99]
	v_lshl_add_u64 v[98:99], s[60:61], 4, v[98:99]
	s_lshl_b32 s62, s92, 2
	v_lshl_add_u64 v[98:99], v[98:99], 0, s[62:63]
	flat_store_dword v[98:99], v100 sc0 sc1
.LBB0_1845:
	s_or_b64 exec, exec, s[12:13]
	v_max_f32_e32 v98, v153, v153
	s_waitcnt lgkmcnt(0)
	v_max_f32_e32 v99, v152, v152
	v_max_f32_e32 v98, v99, v98
	v_max3_f32 v102, v150, v151, v98
	v_sub_f32_e32 v94, v94, v102
	v_sub_f32_e32 v90, v90, v102
	v_exp_f32_e32 v100, v94
	v_exp_f32_e32 v94, v90
	v_sub_f32_e32 v90, v95, v102
	v_exp_f32_e32 v101, v90
	v_sub_f32_e32 v90, v91, v102
	v_exp_f32_e32 v95, v90
	v_sub_f32_e32 v90, v96, v102
	v_exp_f32_e32 v96, v90
	v_sub_f32_e32 v90, v92, v102
	v_exp_f32_e32 v92, v90
	v_sub_f32_e32 v90, v97, v102
	v_exp_f32_e32 v97, v90
	v_sub_f32_e32 v90, v93, v102
	v_add_u32_e32 v98, s27, v179
	v_exp_f32_e32 v93, v90
	v_ashrrev_i32_e32 v99, 31, v98
	v_cmp_eq_u32_e32 vcc, s89, v180
	v_lshlrev_b64 v[90:91], 11, v[98:99]
	s_or_b64 s[12:13], s[78:79], vcc
	v_lshl_add_u64 v[90:91], s[42:43], 0, v[90:91]
	s_and_saveexec_b64 s[80:81], s[12:13]
	s_cbranch_execz .LBB0_1847
	s_lshl_b32 s6, s60, 8
	s_ashr_i32 s7, s6, 31
	v_lshl_add_u64 v[104:105], s[6:7], 1, v[90:91]
	s_lshl_b32 s62, s93, 1
	v_lshl_add_u64 v[104:105], v[104:105], 0, s[62:63]
	v_lshl_add_u64 v[108:109], v[104:105], 0, v[168:169]
	s_nop 0
	v_cvt_pk_bf16_f32 v104, v100, v101
	s_nop 0
	v_cvt_pk_bf16_f32 v105, v96, v97
	s_nop 0
	v_cvt_pk_bf16_f32 v106, v94, v95
	s_nop 0
	v_cvt_pk_bf16_f32 v107, v92, v93
	flat_store_dwordx4 v[108:109], v[104:107] sc0 sc1
.LBB0_1847:
	s_or_b64 exec, exec, s[80:81]
	v_sub_f32_e32 v86, v86, v102
	v_sub_f32_e32 v82, v82, v102
	v_sub_f32_e32 v87, v87, v102
	v_sub_f32_e32 v83, v83, v102
	v_sub_f32_e32 v88, v88, v102
	v_sub_f32_e32 v84, v84, v102
	v_sub_f32_e32 v89, v89, v102
	v_sub_f32_e32 v85, v85, v102
	v_exp_f32_e32 v86, v86
	v_exp_f32_e32 v82, v82
	v_exp_f32_e32 v87, v87
	v_exp_f32_e32 v83, v83
	v_exp_f32_e32 v88, v88
	v_exp_f32_e32 v84, v84
	v_exp_f32_e32 v89, v89
	v_exp_f32_e32 v85, v85
	s_and_saveexec_b64 s[80:81], s[12:13]
	s_cbranch_execz .LBB0_1849
	s_lshl_b32 s6, s60, 8
	s_ashr_i32 s7, s6, 31
	v_lshl_add_u64 v[90:91], s[6:7], 1, v[90:91]
	s_lshl_b32 s62, s93, 1
	v_lshl_add_u64 v[90:91], v[90:91], 0, s[62:63]
	v_lshl_add_u64 v[90:91], v[90:91], 0, v[168:169]
	s_nop 0
	v_cvt_pk_bf16_f32 v102, v86, v87
	s_nop 0
	v_cvt_pk_bf16_f32 v103, v88, v89
	s_nop 0
	v_cvt_pk_bf16_f32 v104, v82, v83
	s_nop 0
	v_cvt_pk_bf16_f32 v105, v84, v85
	flat_store_dwordx4 v[90:91], v[102:105] offset:256 sc0 sc1
.LBB0_1849:
	s_or_b64 exec, exec, s[80:81]
	v_add_f32_e32 v90, v100, v101
	v_add_f32_e32 v91, v96, v97
	v_add_f32_e32 v90, v90, v91
	v_add_f32_e32 v91, v94, v95
	v_add_f32_e32 v86, v86, v87
	v_add_f32_e32 v87, v88, v89
	v_add_f32_e32 v90, v91, v90
	v_add_f32_e32 v91, v92, v93
	v_add_f32_e32 v86, v86, v87
	v_add_f32_e32 v82, v82, v83
	v_add_f32_e32 v90, v91, v90
	v_add_f32_e32 v82, v82, v86
	v_add_f32_e32 v83, v84, v85
	v_add_f32_e32 v90, 0, v90
	v_add_f32_e32 v82, v83, v82
	v_add_f32_e32 v82, v82, v90
	ds_bpermute_b32 v83, v199, v82
	s_and_b64 s[6:7], s[8:9], s[12:13]
	s_waitcnt lgkmcnt(0)
	v_add_f32_e32 v82, v82, v83
	ds_bpermute_b32 v83, v200, v82
	s_and_saveexec_b64 s[12:13], s[6:7]
	s_cbranch_execz .LBB0_1851
	s_waitcnt lgkmcnt(0)
	v_add_f32_e32 v84, v82, v83
	v_lshlrev_b64 v[82:83], 6, v[98:99]
	s_ashr_i32 s61, s60, 31
	v_lshl_add_u64 v[82:83], s[46:47], 0, v[82:83]
	v_lshl_add_u64 v[82:83], s[60:61], 4, v[82:83]
	s_lshl_b32 s62, s92, 2
	v_lshl_add_u64 v[82:83], v[82:83], 0, s[62:63]
	flat_store_dword v[82:83], v84 sc0 sc1
.LBB0_1851:
	s_or_b64 exec, exec, s[12:13]
	v_max_f32_e32 v82, v149, v149
	s_waitcnt lgkmcnt(0)
	v_max_f32_e32 v83, v148, v148
	v_max_f32_e32 v82, v83, v82
	v_max3_f32 v86, v146, v147, v82
	v_sub_f32_e32 v78, v78, v86
	v_sub_f32_e32 v74, v74, v86
	v_exp_f32_e32 v84, v78
	v_exp_f32_e32 v78, v74
	v_sub_f32_e32 v74, v79, v86
	v_exp_f32_e32 v85, v74
	v_sub_f32_e32 v74, v75, v86
	v_exp_f32_e32 v79, v74
	v_sub_f32_e32 v74, v80, v86
	v_exp_f32_e32 v80, v74
	v_sub_f32_e32 v74, v76, v86
	v_exp_f32_e32 v76, v74
	v_sub_f32_e32 v74, v81, v86
	v_exp_f32_e32 v81, v74
	v_sub_f32_e32 v74, v77, v86
	v_add_u32_e32 v82, s27, v181
	v_exp_f32_e32 v77, v74
	v_ashrrev_i32_e32 v83, 31, v82
	v_cmp_eq_u32_e32 vcc, s89, v182
	v_lshlrev_b64 v[74:75], 11, v[82:83]
	s_or_b64 s[12:13], s[78:79], vcc
	v_lshl_add_u64 v[74:75], s[42:43], 0, v[74:75]
	s_and_saveexec_b64 s[80:81], s[12:13]
	s_cbranch_execz .LBB0_1853
	s_lshl_b32 s6, s60, 8
	s_ashr_i32 s7, s6, 31
	v_lshl_add_u64 v[88:89], s[6:7], 1, v[74:75]
	s_lshl_b32 s62, s93, 1
	v_lshl_add_u64 v[88:89], v[88:89], 0, s[62:63]
	v_lshl_add_u64 v[92:93], v[88:89], 0, v[168:169]
	s_nop 0
	v_cvt_pk_bf16_f32 v88, v84, v85
	s_nop 0
	v_cvt_pk_bf16_f32 v89, v80, v81
	s_nop 0
	v_cvt_pk_bf16_f32 v90, v78, v79
	s_nop 0
	v_cvt_pk_bf16_f32 v91, v76, v77
	flat_store_dwordx4 v[92:93], v[88:91] sc0 sc1
.LBB0_1853:
	s_or_b64 exec, exec, s[80:81]
	v_sub_f32_e32 v70, v70, v86
	v_sub_f32_e32 v66, v66, v86
	v_sub_f32_e32 v71, v71, v86
	v_sub_f32_e32 v67, v67, v86
	v_sub_f32_e32 v72, v72, v86
	v_sub_f32_e32 v68, v68, v86
	v_sub_f32_e32 v73, v73, v86
	v_sub_f32_e32 v69, v69, v86
	v_exp_f32_e32 v70, v70
	v_exp_f32_e32 v66, v66
	v_exp_f32_e32 v71, v71
	v_exp_f32_e32 v67, v67
	v_exp_f32_e32 v72, v72
	v_exp_f32_e32 v68, v68
	v_exp_f32_e32 v73, v73
	v_exp_f32_e32 v69, v69
	s_and_saveexec_b64 s[80:81], s[12:13]
	s_cbranch_execz .LBB0_1855
	s_lshl_b32 s6, s60, 8
	s_ashr_i32 s7, s6, 31
	v_lshl_add_u64 v[74:75], s[6:7], 1, v[74:75]
	s_lshl_b32 s62, s93, 1
	v_lshl_add_u64 v[74:75], v[74:75], 0, s[62:63]
	v_lshl_add_u64 v[74:75], v[74:75], 0, v[168:169]
	s_nop 0
	v_cvt_pk_bf16_f32 v86, v70, v71
	s_nop 0
	v_cvt_pk_bf16_f32 v87, v72, v73
	s_nop 0
	v_cvt_pk_bf16_f32 v88, v66, v67
	s_nop 0
	v_cvt_pk_bf16_f32 v89, v68, v69
	flat_store_dwordx4 v[74:75], v[86:89] offset:256 sc0 sc1
.LBB0_1855:
	s_or_b64 exec, exec, s[80:81]
	v_add_f32_e32 v74, v84, v85
	v_add_f32_e32 v75, v80, v81
	v_add_f32_e32 v74, v74, v75
	v_add_f32_e32 v75, v78, v79
	v_add_f32_e32 v70, v70, v71
	v_add_f32_e32 v71, v72, v73
	v_add_f32_e32 v74, v75, v74
	v_add_f32_e32 v75, v76, v77
	v_add_f32_e32 v70, v70, v71
	v_add_f32_e32 v66, v66, v67
	v_add_f32_e32 v74, v75, v74
	v_add_f32_e32 v66, v66, v70
	v_add_f32_e32 v67, v68, v69
	v_add_f32_e32 v74, 0, v74
	v_add_f32_e32 v66, v67, v66
	v_add_f32_e32 v66, v66, v74
	ds_bpermute_b32 v67, v199, v66
	s_and_b64 s[6:7], s[8:9], s[12:13]
	s_waitcnt lgkmcnt(0)
	v_add_f32_e32 v66, v66, v67
	ds_bpermute_b32 v67, v200, v66
	s_and_saveexec_b64 s[12:13], s[6:7]
	s_cbranch_execz .LBB0_1857
	s_waitcnt lgkmcnt(0)
	v_add_f32_e32 v68, v66, v67
	v_lshlrev_b64 v[66:67], 6, v[82:83]
	s_ashr_i32 s61, s60, 31
	v_lshl_add_u64 v[66:67], s[46:47], 0, v[66:67]
	v_lshl_add_u64 v[66:67], s[60:61], 4, v[66:67]
	s_lshl_b32 s62, s92, 2
	v_lshl_add_u64 v[66:67], v[66:67], 0, s[62:63]
	flat_store_dword v[66:67], v68 sc0 sc1
.LBB0_1857:
	s_or_b64 exec, exec, s[12:13]
	v_max_f32_e32 v66, v145, v145
	s_waitcnt lgkmcnt(0)
	v_max_f32_e32 v67, v144, v144
	v_max_f32_e32 v66, v67, v66
	v_max3_f32 v70, v142, v143, v66
	v_sub_f32_e32 v62, v62, v70
	v_sub_f32_e32 v58, v58, v70
	v_exp_f32_e32 v68, v62
	v_exp_f32_e32 v62, v58
	v_sub_f32_e32 v58, v63, v70
	v_exp_f32_e32 v69, v58
	v_sub_f32_e32 v58, v59, v70
	v_exp_f32_e32 v63, v58
	v_sub_f32_e32 v58, v64, v70
	v_exp_f32_e32 v64, v58
	v_sub_f32_e32 v58, v60, v70
	v_exp_f32_e32 v60, v58
	v_sub_f32_e32 v58, v65, v70
	v_exp_f32_e32 v65, v58
	v_sub_f32_e32 v58, v61, v70
	v_add_u32_e32 v66, s27, v183
	v_exp_f32_e32 v61, v58
	v_ashrrev_i32_e32 v67, 31, v66
	v_cmp_eq_u32_e32 vcc, s89, v184
	v_lshlrev_b64 v[58:59], 11, v[66:67]
	s_or_b64 s[12:13], s[78:79], vcc
	v_lshl_add_u64 v[58:59], s[42:43], 0, v[58:59]
	s_and_saveexec_b64 s[80:81], s[12:13]
	s_cbranch_execz .LBB0_1859
	s_lshl_b32 s6, s60, 8
	s_ashr_i32 s7, s6, 31
	v_lshl_add_u64 v[72:73], s[6:7], 1, v[58:59]
	s_lshl_b32 s62, s93, 1
	v_lshl_add_u64 v[72:73], v[72:73], 0, s[62:63]
	v_lshl_add_u64 v[76:77], v[72:73], 0, v[168:169]
	s_nop 0
	v_cvt_pk_bf16_f32 v72, v68, v69
	s_nop 0
	v_cvt_pk_bf16_f32 v73, v64, v65
	s_nop 0
	v_cvt_pk_bf16_f32 v74, v62, v63
	s_nop 0
	v_cvt_pk_bf16_f32 v75, v60, v61
	flat_store_dwordx4 v[76:77], v[72:75] sc0 sc1
.LBB0_1859:
	s_or_b64 exec, exec, s[80:81]
	v_sub_f32_e32 v54, v54, v70
	v_sub_f32_e32 v50, v50, v70
	v_sub_f32_e32 v55, v55, v70
	v_sub_f32_e32 v51, v51, v70
	v_sub_f32_e32 v56, v56, v70
	v_sub_f32_e32 v52, v52, v70
	v_sub_f32_e32 v57, v57, v70
	v_sub_f32_e32 v53, v53, v70
	v_exp_f32_e32 v54, v54
	v_exp_f32_e32 v50, v50
	v_exp_f32_e32 v55, v55
	v_exp_f32_e32 v51, v51
	v_exp_f32_e32 v56, v56
	v_exp_f32_e32 v52, v52
	v_exp_f32_e32 v57, v57
	v_exp_f32_e32 v53, v53
	s_and_saveexec_b64 s[80:81], s[12:13]
	s_cbranch_execz .LBB0_1861
	s_lshl_b32 s6, s60, 8
	s_ashr_i32 s7, s6, 31
	v_lshl_add_u64 v[58:59], s[6:7], 1, v[58:59]
	s_lshl_b32 s62, s93, 1
	v_lshl_add_u64 v[58:59], v[58:59], 0, s[62:63]
	v_lshl_add_u64 v[58:59], v[58:59], 0, v[168:169]
	s_nop 0
	v_cvt_pk_bf16_f32 v70, v54, v55
	s_nop 0
	v_cvt_pk_bf16_f32 v71, v56, v57
	s_nop 0
	v_cvt_pk_bf16_f32 v72, v50, v51
	s_nop 0
	v_cvt_pk_bf16_f32 v73, v52, v53
	flat_store_dwordx4 v[58:59], v[70:73] offset:256 sc0 sc1
.LBB0_1861:
	s_or_b64 exec, exec, s[80:81]
	v_add_f32_e32 v58, v68, v69
	v_add_f32_e32 v59, v64, v65
	v_add_f32_e32 v58, v58, v59
	v_add_f32_e32 v59, v62, v63
	v_add_f32_e32 v54, v54, v55
	v_add_f32_e32 v55, v56, v57
	v_add_f32_e32 v58, v59, v58
	v_add_f32_e32 v59, v60, v61
	v_add_f32_e32 v54, v54, v55
	v_add_f32_e32 v50, v50, v51
	v_add_f32_e32 v58, v59, v58
	v_add_f32_e32 v50, v50, v54
	v_add_f32_e32 v51, v52, v53
	v_add_f32_e32 v58, 0, v58
	v_add_f32_e32 v50, v51, v50
	v_add_f32_e32 v50, v50, v58
	ds_bpermute_b32 v51, v199, v50
	s_and_b64 s[6:7], s[8:9], s[12:13]
	s_waitcnt lgkmcnt(0)
	v_add_f32_e32 v50, v50, v51
	ds_bpermute_b32 v51, v200, v50
	s_and_saveexec_b64 s[12:13], s[6:7]
	s_cbranch_execz .LBB0_1863
	s_waitcnt lgkmcnt(0)
	v_add_f32_e32 v52, v50, v51
	v_lshlrev_b64 v[50:51], 6, v[66:67]
	s_ashr_i32 s61, s60, 31
	v_lshl_add_u64 v[50:51], s[46:47], 0, v[50:51]
	v_lshl_add_u64 v[50:51], s[60:61], 4, v[50:51]
	s_lshl_b32 s62, s92, 2
	v_lshl_add_u64 v[50:51], v[50:51], 0, s[62:63]
	flat_store_dword v[50:51], v52 sc0 sc1
.LBB0_1863:
	s_or_b64 exec, exec, s[12:13]
	v_max_f32_e32 v50, v141, v141
	s_waitcnt lgkmcnt(0)
	v_max_f32_e32 v51, v140, v140
	v_max_f32_e32 v50, v51, v50
	v_max3_f32 v54, v138, v139, v50
	v_sub_f32_e32 v46, v46, v54
	v_sub_f32_e32 v42, v42, v54
	v_exp_f32_e32 v52, v46
	v_exp_f32_e32 v46, v42
	v_sub_f32_e32 v42, v47, v54
	v_exp_f32_e32 v53, v42
	v_sub_f32_e32 v42, v43, v54
	v_exp_f32_e32 v47, v42
	v_sub_f32_e32 v42, v48, v54
	v_exp_f32_e32 v48, v42
	v_sub_f32_e32 v42, v44, v54
	v_exp_f32_e32 v44, v42
	v_sub_f32_e32 v42, v49, v54
	v_exp_f32_e32 v49, v42
	v_sub_f32_e32 v42, v45, v54
	v_add_u32_e32 v50, s27, v185
	v_exp_f32_e32 v45, v42
	v_ashrrev_i32_e32 v51, 31, v50
	v_cmp_eq_u32_e32 vcc, s89, v186
	v_lshlrev_b64 v[42:43], 11, v[50:51]
	s_or_b64 s[12:13], s[78:79], vcc
	v_lshl_add_u64 v[42:43], s[42:43], 0, v[42:43]
	s_and_saveexec_b64 s[80:81], s[12:13]
	s_cbranch_execz .LBB0_1865
	s_lshl_b32 s6, s60, 8
	s_ashr_i32 s7, s6, 31
	v_lshl_add_u64 v[56:57], s[6:7], 1, v[42:43]
	s_lshl_b32 s62, s93, 1
	v_lshl_add_u64 v[56:57], v[56:57], 0, s[62:63]
	v_lshl_add_u64 v[60:61], v[56:57], 0, v[168:169]
	s_nop 0
	v_cvt_pk_bf16_f32 v56, v52, v53
	s_nop 0
	v_cvt_pk_bf16_f32 v57, v48, v49
	s_nop 0
	v_cvt_pk_bf16_f32 v58, v46, v47
	s_nop 0
	v_cvt_pk_bf16_f32 v59, v44, v45
	flat_store_dwordx4 v[60:61], v[56:59] sc0 sc1
.LBB0_1865:
	s_or_b64 exec, exec, s[80:81]
	v_sub_f32_e32 v38, v38, v54
	v_sub_f32_e32 v34, v34, v54
	v_sub_f32_e32 v39, v39, v54
	v_sub_f32_e32 v35, v35, v54
	v_sub_f32_e32 v40, v40, v54
	v_sub_f32_e32 v36, v36, v54
	v_sub_f32_e32 v41, v41, v54
	v_sub_f32_e32 v37, v37, v54
	v_exp_f32_e32 v38, v38
	v_exp_f32_e32 v34, v34
	v_exp_f32_e32 v39, v39
	v_exp_f32_e32 v35, v35
	v_exp_f32_e32 v40, v40
	v_exp_f32_e32 v36, v36
	v_exp_f32_e32 v41, v41
	v_exp_f32_e32 v37, v37
	s_and_saveexec_b64 s[80:81], s[12:13]
	s_cbranch_execz .LBB0_1867
	s_lshl_b32 s6, s60, 8
	s_ashr_i32 s7, s6, 31
	v_lshl_add_u64 v[42:43], s[6:7], 1, v[42:43]
	s_lshl_b32 s62, s93, 1
	v_lshl_add_u64 v[42:43], v[42:43], 0, s[62:63]
	v_lshl_add_u64 v[42:43], v[42:43], 0, v[168:169]
	s_nop 0
	v_cvt_pk_bf16_f32 v54, v38, v39
	s_nop 0
	v_cvt_pk_bf16_f32 v55, v40, v41
	s_nop 0
	v_cvt_pk_bf16_f32 v56, v34, v35
	s_nop 0
	v_cvt_pk_bf16_f32 v57, v36, v37
	flat_store_dwordx4 v[42:43], v[54:57] offset:256 sc0 sc1
.LBB0_1867:
	s_or_b64 exec, exec, s[80:81]
	v_add_f32_e32 v42, v52, v53
	v_add_f32_e32 v43, v48, v49
	v_add_f32_e32 v42, v42, v43
	v_add_f32_e32 v43, v46, v47
	v_add_f32_e32 v38, v38, v39
	v_add_f32_e32 v39, v40, v41
	v_add_f32_e32 v42, v43, v42
	v_add_f32_e32 v43, v44, v45
	v_add_f32_e32 v38, v38, v39
	v_add_f32_e32 v34, v34, v35
	v_add_f32_e32 v42, v43, v42
	v_add_f32_e32 v34, v34, v38
	v_add_f32_e32 v35, v36, v37
	v_add_f32_e32 v42, 0, v42
	v_add_f32_e32 v34, v35, v34
	v_add_f32_e32 v34, v34, v42
	ds_bpermute_b32 v35, v199, v34
	s_and_b64 s[6:7], s[8:9], s[12:13]
	s_waitcnt lgkmcnt(0)
	v_add_f32_e32 v34, v34, v35
	ds_bpermute_b32 v35, v200, v34
	s_and_saveexec_b64 s[12:13], s[6:7]
	s_cbranch_execz .LBB0_1869
	s_waitcnt lgkmcnt(0)
	v_add_f32_e32 v36, v34, v35
	v_lshlrev_b64 v[34:35], 6, v[50:51]
	s_ashr_i32 s61, s60, 31
	v_lshl_add_u64 v[34:35], s[46:47], 0, v[34:35]
	v_lshl_add_u64 v[34:35], s[60:61], 4, v[34:35]
	s_lshl_b32 s62, s92, 2
	v_lshl_add_u64 v[34:35], v[34:35], 0, s[62:63]
	flat_store_dword v[34:35], v36 sc0 sc1
.LBB0_1869:
	s_or_b64 exec, exec, s[12:13]
	v_max_f32_e32 v34, v137, v137
	s_waitcnt lgkmcnt(0)
	v_max_f32_e32 v35, v136, v136
	v_max_f32_e32 v34, v35, v34
	v_max3_f32 v38, v134, v135, v34
	v_sub_f32_e32 v30, v30, v38
	v_sub_f32_e32 v26, v26, v38
	v_exp_f32_e32 v36, v30
	v_exp_f32_e32 v30, v26
	v_sub_f32_e32 v26, v31, v38
	v_exp_f32_e32 v37, v26
	v_sub_f32_e32 v26, v27, v38
	v_exp_f32_e32 v31, v26
	v_sub_f32_e32 v26, v32, v38
	v_exp_f32_e32 v32, v26
	v_sub_f32_e32 v26, v28, v38
	v_exp_f32_e32 v28, v26
	v_sub_f32_e32 v26, v33, v38
	v_exp_f32_e32 v33, v26
	v_sub_f32_e32 v26, v29, v38
	v_add_u32_e32 v34, s27, v188
	v_exp_f32_e32 v29, v26
	v_ashrrev_i32_e32 v35, 31, v34
	v_cmp_eq_u32_e32 vcc, s89, v189
	v_lshlrev_b64 v[26:27], 11, v[34:35]
	s_or_b64 s[12:13], s[78:79], vcc
	v_lshl_add_u64 v[26:27], s[42:43], 0, v[26:27]
	s_and_saveexec_b64 s[80:81], s[12:13]
	s_cbranch_execz .LBB0_1871
	s_lshl_b32 s6, s60, 8
	s_ashr_i32 s7, s6, 31
	v_lshl_add_u64 v[40:41], s[6:7], 1, v[26:27]
	s_lshl_b32 s62, s93, 1
	v_lshl_add_u64 v[40:41], v[40:41], 0, s[62:63]
	v_lshl_add_u64 v[44:45], v[40:41], 0, v[168:169]
	s_nop 0
	v_cvt_pk_bf16_f32 v40, v36, v37
	s_nop 0
	v_cvt_pk_bf16_f32 v41, v32, v33
	s_nop 0
	v_cvt_pk_bf16_f32 v42, v30, v31
	s_nop 0
	v_cvt_pk_bf16_f32 v43, v28, v29
	flat_store_dwordx4 v[44:45], v[40:43] sc0 sc1
.LBB0_1871:
	s_or_b64 exec, exec, s[80:81]
	v_sub_f32_e32 v22, v22, v38
	v_sub_f32_e32 v18, v18, v38
	v_sub_f32_e32 v23, v23, v38
	v_sub_f32_e32 v19, v19, v38
	v_sub_f32_e32 v24, v24, v38
	v_sub_f32_e32 v20, v20, v38
	v_sub_f32_e32 v25, v25, v38
	v_sub_f32_e32 v21, v21, v38
	v_exp_f32_e32 v22, v22
	v_exp_f32_e32 v18, v18
	v_exp_f32_e32 v23, v23
	v_exp_f32_e32 v19, v19
	v_exp_f32_e32 v24, v24
	v_exp_f32_e32 v20, v20
	v_exp_f32_e32 v25, v25
	v_exp_f32_e32 v21, v21
	s_and_saveexec_b64 s[80:81], s[12:13]
	s_cbranch_execz .LBB0_1873
	s_lshl_b32 s6, s60, 8
	s_ashr_i32 s7, s6, 31
	v_lshl_add_u64 v[26:27], s[6:7], 1, v[26:27]
	s_lshl_b32 s62, s93, 1
	v_lshl_add_u64 v[26:27], v[26:27], 0, s[62:63]
	v_lshl_add_u64 v[26:27], v[26:27], 0, v[168:169]
	s_nop 0
	v_cvt_pk_bf16_f32 v38, v22, v23
	s_nop 0
	v_cvt_pk_bf16_f32 v39, v24, v25
	s_nop 0
	v_cvt_pk_bf16_f32 v40, v18, v19
	s_nop 0
	v_cvt_pk_bf16_f32 v41, v20, v21
	flat_store_dwordx4 v[26:27], v[38:41] offset:256 sc0 sc1
.LBB0_1873:
	s_or_b64 exec, exec, s[80:81]
	v_add_f32_e32 v26, v36, v37
	v_add_f32_e32 v27, v32, v33
	v_add_f32_e32 v26, v26, v27
	v_add_f32_e32 v27, v30, v31
	v_add_f32_e32 v22, v22, v23
	v_add_f32_e32 v23, v24, v25
	v_add_f32_e32 v26, v27, v26
	v_add_f32_e32 v27, v28, v29
	v_add_f32_e32 v22, v22, v23
	v_add_f32_e32 v18, v18, v19
	v_add_f32_e32 v26, v27, v26
	v_add_f32_e32 v18, v18, v22
	v_add_f32_e32 v19, v20, v21
	v_add_f32_e32 v26, 0, v26
	v_add_f32_e32 v18, v19, v18
	v_add_f32_e32 v18, v18, v26
	ds_bpermute_b32 v19, v199, v18
	s_and_b64 s[6:7], s[8:9], s[12:13]
	s_waitcnt lgkmcnt(0)
	v_add_f32_e32 v18, v18, v19
	ds_bpermute_b32 v19, v200, v18
	s_and_saveexec_b64 s[12:13], s[6:7]
	s_cbranch_execz .LBB0_1875
	s_waitcnt lgkmcnt(0)
	v_add_f32_e32 v20, v18, v19
	v_lshlrev_b64 v[18:19], 6, v[34:35]
	s_ashr_i32 s61, s60, 31
	v_lshl_add_u64 v[18:19], s[46:47], 0, v[18:19]
	v_lshl_add_u64 v[18:19], s[60:61], 4, v[18:19]
	s_lshl_b32 s62, s92, 2
	v_lshl_add_u64 v[18:19], v[18:19], 0, s[62:63]
	flat_store_dword v[18:19], v20 sc0 sc1
.LBB0_1875:
	s_or_b64 exec, exec, s[12:13]
	v_max_f32_e32 v18, v125, v125
	s_waitcnt lgkmcnt(0)
	v_max_f32_e32 v19, v124, v124
	v_max_f32_e32 v18, v19, v18
	v_max3_f32 v22, v122, v123, v18
	v_sub_f32_e32 v14, v14, v22
	v_sub_f32_e32 v10, v10, v22
	v_exp_f32_e32 v20, v14
	v_exp_f32_e32 v14, v10
	v_sub_f32_e32 v10, v15, v22
	v_exp_f32_e32 v21, v10
	v_sub_f32_e32 v10, v11, v22
	v_exp_f32_e32 v15, v10
	v_sub_f32_e32 v10, v16, v22
	v_exp_f32_e32 v16, v10
	v_sub_f32_e32 v10, v12, v22
	v_exp_f32_e32 v12, v10
	v_sub_f32_e32 v10, v17, v22
	v_exp_f32_e32 v17, v10
	v_sub_f32_e32 v10, v13, v22
	v_add_u32_e32 v18, s27, v190
	v_exp_f32_e32 v13, v10
	v_ashrrev_i32_e32 v19, 31, v18
	v_cmp_eq_u32_e32 vcc, s89, v191
	v_lshlrev_b64 v[10:11], 11, v[18:19]
	s_or_b64 s[12:13], s[78:79], vcc
	v_lshl_add_u64 v[10:11], s[42:43], 0, v[10:11]
	s_and_saveexec_b64 s[78:79], s[12:13]
	s_cbranch_execz .LBB0_1877
	s_lshl_b32 s6, s60, 8
	s_ashr_i32 s7, s6, 31
	v_lshl_add_u64 v[24:25], s[6:7], 1, v[10:11]
	s_lshl_b32 s62, s93, 1
	v_lshl_add_u64 v[24:25], v[24:25], 0, s[62:63]
	v_lshl_add_u64 v[28:29], v[24:25], 0, v[168:169]
	s_nop 0
	v_cvt_pk_bf16_f32 v24, v20, v21
	s_nop 0
	v_cvt_pk_bf16_f32 v25, v16, v17
	s_nop 0
	v_cvt_pk_bf16_f32 v26, v14, v15
	s_nop 0
	v_cvt_pk_bf16_f32 v27, v12, v13
	flat_store_dwordx4 v[28:29], v[24:27] sc0 sc1
.LBB0_1877:
	s_or_b64 exec, exec, s[78:79]
	v_sub_f32_e32 v6, v6, v22
	v_sub_f32_e32 v2, v2, v22
	v_sub_f32_e32 v7, v7, v22
	v_sub_f32_e32 v3, v3, v22
	v_sub_f32_e32 v8, v8, v22
	v_sub_f32_e32 v4, v4, v22
	v_sub_f32_e32 v9, v9, v22
	v_sub_f32_e32 v5, v5, v22
	v_exp_f32_e32 v6, v6
	v_exp_f32_e32 v2, v2
	v_exp_f32_e32 v7, v7
	v_exp_f32_e32 v3, v3
	v_exp_f32_e32 v8, v8
	v_exp_f32_e32 v4, v4
	v_exp_f32_e32 v9, v9
	v_exp_f32_e32 v5, v5
	s_and_saveexec_b64 s[78:79], s[12:13]
	s_cbranch_execz .LBB0_1879
	s_lshl_b32 s6, s60, 8
	s_ashr_i32 s7, s6, 31
	v_lshl_add_u64 v[10:11], s[6:7], 1, v[10:11]
	s_lshl_b32 s62, s93, 1
	v_lshl_add_u64 v[10:11], v[10:11], 0, s[62:63]
	v_lshl_add_u64 v[10:11], v[10:11], 0, v[168:169]
	s_nop 0
	v_cvt_pk_bf16_f32 v22, v6, v7
	s_nop 0
	v_cvt_pk_bf16_f32 v23, v8, v9
	s_nop 0
	v_cvt_pk_bf16_f32 v24, v2, v3
	s_nop 0
	v_cvt_pk_bf16_f32 v25, v4, v5
	flat_store_dwordx4 v[10:11], v[22:25] offset:256 sc0 sc1
.LBB0_1879:
	s_or_b64 exec, exec, s[78:79]
	v_add_f32_e32 v10, v20, v21
	v_add_f32_e32 v11, v16, v17
	v_add_f32_e32 v10, v10, v11
	v_add_f32_e32 v11, v14, v15
	v_add_f32_e32 v6, v6, v7
	v_add_f32_e32 v7, v8, v9
	v_add_f32_e32 v10, v11, v10
	v_add_f32_e32 v11, v12, v13
	v_add_f32_e32 v6, v6, v7
	v_add_f32_e32 v2, v2, v3
	v_add_f32_e32 v10, v11, v10
	v_add_f32_e32 v2, v2, v6
	v_add_f32_e32 v3, v4, v5
	v_add_f32_e32 v10, 0, v10
	v_add_f32_e32 v2, v3, v2
	v_add_f32_e32 v2, v2, v10
	ds_bpermute_b32 v3, v199, v2
	s_and_b64 s[6:7], s[8:9], s[12:13]
	s_waitcnt lgkmcnt(0)
	v_add_f32_e32 v2, v2, v3
	ds_bpermute_b32 v3, v200, v2
	s_and_saveexec_b64 s[12:13], s[6:7]
	s_cbranch_execz .LBB0_1881
	s_waitcnt lgkmcnt(0)
	v_add_f32_e32 v4, v2, v3
	v_lshlrev_b64 v[2:3], 6, v[18:19]
	s_ashr_i32 s61, s60, 31
	v_lshl_add_u64 v[2:3], s[46:47], 0, v[2:3]
	v_lshl_add_u64 v[2:3], s[60:61], 4, v[2:3]
	s_lshl_b32 s62, s92, 2
	v_lshl_add_u64 v[2:3], v[2:3], 0, s[62:63]
	flat_store_dword v[2:3], v4 sc0 sc1

.LBB0_1885:
	s_waitcnt vmcnt(0)
	s_waitcnt vmcnt(0) lgkmcnt(0)
	s_barrier
	s_and_saveexec_b64 s[8:9], s[4:5]
	s_cbranch_execz .LBB0_1902
	s_mov_b64 s[10:11], exec
	s_waitcnt vmcnt(0)
	v_mbcnt_lo_u32_b32 v2, s10, 0
	v_mbcnt_hi_u32_b32 v2, s11, v2
	v_cmp_eq_u32_e32 vcc, 0, v2
	s_and_saveexec_b64 s[12:13], vcc
	s_cbranch_execz .LBB0_1888
	s_bcnt1_i32_b64 s6, s[10:11]
	v_mov_b32_e32 v2, 0
	v_mov_b32_e32 v3, s6
	global_atomic_add v2, v3, s[36:37]

.LBB0_1923:
	s_add_u32 s16, s76, s65
	s_addc_u32 s17, s77, 0
	s_add_u32 s67, s16, 0x100
	s_addc_u32 s80, s17, 0
	s_and_b64 s[6:7], s[78:79], exec
	s_cselect_b32 s83, s69, s80
	s_cselect_b32 s82, s68, s67
	s_add_u32 s6, s74, s65
	s_addc_u32 s7, s75, 0
	s_add_u32 s65, s6, 0x100
	s_addc_u32 s67, s7, 0
	s_and_b64 s[6:7], s[78:79], exec
	s_cselect_b32 s85, s71, s67
	s_cselect_b32 s84, s70, s65
	s_add_u32 s88, s16, 0x40080
	s_addc_u32 s89, s17, 0
	s_add_i32 s90, s94, s28
	s_waitcnt lgkmcnt(0)
	ds_read_b128 v[130:133], v169
	ds_read_b128 v[134:137], v169 offset:1024
	ds_read_b128 v[172:175], v169 offset:2048
	ds_read_b128 v[176:179], v169 offset:3072
	ds_read_b128 v[180:183], v170
	ds_read_b128 v[188:191], v170 offset:1024
	ds_read_b128 v[192:195], v170 offset:2048
	ds_read_b128 v[196:199], v170 offset:3072
	s_add_i32 m0, s13, 0xc000
	s_add_i32 s17, s13, 0xe000
	s_add_i32 s16, s90, 0x2000
	s_add_u32 s86, s84, 0x10000
	s_addc_u32 s87, s85, 0
	s_add_i32 s7, s95, s28
	s_add_i32 s6, s7, 0x2000
	s_add_i32 vcc_lo, 0, 0x18000
	s_add_i32 vcc_hi, 0, 0x1c000
	s_add_u32 s80, s82, 0x40000
	s_addc_u32 s81, s83, 0
	s_add_i32 s67, vcc_lo, s28
	s_add_i32 s91, s67, 0x2000
	s_add_u32 s78, s84, 0x10080
	s_addc_u32 s79, s85, 0
	s_add_i32 s97, vcc_hi, s28
	s_add_i32 s65, s97, 0x2000
	ds_read_b128 v[200:203], v171
	ds_read_b128 v[204:207], v171 offset:1024
	ds_read_b128 v[208:211], v171 offset:2048
	ds_read_b128 v[212:215], v171 offset:3072
	ds_read_b128 v[216:219], v171 offset:4096
	ds_read_b128 v[220:223], v171 offset:5120
	ds_read_b128 v[224:227], v171 offset:6144
	ds_read_b128 v[228:231], v171 offset:7168
	global_load_lds_dwordx4 v138, s[88:89]
	s_mov_b32 m0, s17
	s_nop 0
	global_load_lds_dwordx4 v142, s[88:89]
	s_waitcnt vmcnt(8)
	s_waitcnt lgkmcnt(0)
	s_barrier
	s_setprio 1
	s_waitcnt lgkmcnt(0)
	v_mfma_f32_16x16x32_bf16 v[126:129], v[130:133], v[200:203], v[126:129]
	v_mfma_f32_16x16x32_bf16 v[122:125], v[172:175], v[200:203], v[122:125]
	v_mfma_f32_16x16x32_bf16 v[114:117], v[130:133], v[208:211], v[114:117]
	v_mfma_f32_16x16x32_bf16 v[106:109], v[172:175], v[208:211], v[106:109]
	v_mfma_f32_16x16x32_bf16 v[94:97], v[130:133], v[216:219], v[94:97]
	v_mfma_f32_16x16x32_bf16 v[90:93], v[172:175], v[216:219], v[90:93]
	v_mfma_f32_16x16x32_bf16 v[78:81], v[130:133], v[224:227], v[78:81]
	v_mfma_f32_16x16x32_bf16 v[74:77], v[172:175], v[224:227], v[74:77]
	v_mfma_f32_16x16x32_bf16 v[126:129], v[134:137], v[204:207], v[126:129]
	v_mfma_f32_16x16x32_bf16 v[122:125], v[176:179], v[204:207], v[122:125]
	v_mfma_f32_16x16x32_bf16 v[114:117], v[134:137], v[212:215], v[114:117]
	v_mfma_f32_16x16x32_bf16 v[106:109], v[176:179], v[212:215], v[106:109]
	v_mfma_f32_16x16x32_bf16 v[94:97], v[134:137], v[220:223], v[94:97]
	v_mfma_f32_16x16x32_bf16 v[90:93], v[176:179], v[220:223], v[90:93]
	v_mfma_f32_16x16x32_bf16 v[78:81], v[134:137], v[228:231], v[78:81]
	v_mfma_f32_16x16x32_bf16 v[74:77], v[176:179], v[228:231], v[74:77]
	s_setprio 0
	s_setprio 1
	v_mfma_f32_16x16x32_bf16 v[118:121], v[180:183], v[200:203], v[118:121]
	v_mfma_f32_16x16x32_bf16 v[110:113], v[192:195], v[200:203], v[110:113]
	v_mfma_f32_16x16x32_bf16 v[102:105], v[180:183], v[208:211], v[102:105]
	v_mfma_f32_16x16x32_bf16 v[98:101], v[192:195], v[208:211], v[98:101]
	v_mfma_f32_16x16x32_bf16 v[86:89], v[180:183], v[216:219], v[86:89]
	v_mfma_f32_16x16x32_bf16 v[82:85], v[192:195], v[216:219], v[82:85]
	v_mfma_f32_16x16x32_bf16 v[70:73], v[180:183], v[224:227], v[70:73]
	v_mfma_f32_16x16x32_bf16 v[66:69], v[192:195], v[224:227], v[66:69]
	v_mfma_f32_16x16x32_bf16 v[118:121], v[188:191], v[204:207], v[118:121]
	v_mfma_f32_16x16x32_bf16 v[110:113], v[196:199], v[204:207], v[110:113]
	v_mfma_f32_16x16x32_bf16 v[102:105], v[188:191], v[212:215], v[102:105]
	v_mfma_f32_16x16x32_bf16 v[98:101], v[196:199], v[212:215], v[98:101]
	v_mfma_f32_16x16x32_bf16 v[86:89], v[188:191], v[220:223], v[86:89]
	v_mfma_f32_16x16x32_bf16 v[82:85], v[196:199], v[220:223], v[82:85]
	v_mfma_f32_16x16x32_bf16 v[70:73], v[188:191], v[228:231], v[70:73]
	v_mfma_f32_16x16x32_bf16 v[66:69], v[196:199], v[228:231], v[66:69]
	s_setprio 0
	s_barrier
	s_mov_b32 m0, s90
	v_lshl_add_u64 v[150:151], s[84:85], 0, v[140:141]
	ds_read_b128 v[200:203], v171 offset:16384
	ds_read_b128 v[204:207], v171 offset:17408
	ds_read_b128 v[208:211], v171 offset:18432
	ds_read_b128 v[212:215], v171 offset:19456
	ds_read_b128 v[216:219], v171 offset:20480
	ds_read_b128 v[220:223], v171 offset:21504
	ds_read_b128 v[224:227], v171 offset:22528
	ds_read_b128 v[228:231], v171 offset:23552
	global_load_lds_dwordx4 v[150:151], off
	v_lshl_add_u64 v[184:185], s[84:85], 0, v[144:145]
	s_mov_b32 m0, s16
	s_nop 0
	global_load_lds_dwordx4 v[184:185], off
	s_mov_b32 m0, s7
	v_lshl_add_u64 v[234:235], s[82:83], 0, v[142:143]
	global_load_lds_dwordx4 v140, s[86:87]
	s_mov_b32 m0, s6
	s_nop 0
	global_load_lds_dwordx4 v144, s[86:87]
	v_lshl_add_u64 v[232:233], s[82:83], 0, v[138:139]
	s_mov_b32 m0, s13
	s_nop 0
	global_load_lds_dwordx4 v[232:233], off
	s_mov_b32 m0, s29
	s_nop 0
	global_load_lds_dwordx4 v[234:235], off
	s_waitcnt vmcnt(8)
	s_waitcnt lgkmcnt(0)
	s_barrier
	s_setprio 1
	s_waitcnt lgkmcnt(0)
	v_mfma_f32_16x16x32_bf16 v[62:65], v[130:133], v[200:203], v[62:65]
	v_mfma_f32_16x16x32_bf16 v[58:61], v[172:175], v[200:203], v[58:61]
	v_mfma_f32_16x16x32_bf16 v[46:49], v[130:133], v[208:211], v[46:49]
	v_mfma_f32_16x16x32_bf16 v[42:45], v[172:175], v[208:211], v[42:45]
	v_mfma_f32_16x16x32_bf16 v[30:33], v[130:133], v[216:219], v[30:33]
	v_mfma_f32_16x16x32_bf16 v[26:29], v[172:175], v[216:219], v[26:29]
	v_mfma_f32_16x16x32_bf16 v[14:17], v[130:133], v[224:227], v[14:17]
	v_mfma_f32_16x16x32_bf16 v[10:13], v[172:175], v[224:227], v[10:13]
	v_mfma_f32_16x16x32_bf16 v[62:65], v[134:137], v[204:207], v[62:65]
	v_mfma_f32_16x16x32_bf16 v[58:61], v[176:179], v[204:207], v[58:61]
	v_mfma_f32_16x16x32_bf16 v[46:49], v[134:137], v[212:215], v[46:49]
	v_mfma_f32_16x16x32_bf16 v[42:45], v[176:179], v[212:215], v[42:45]
	v_mfma_f32_16x16x32_bf16 v[30:33], v[134:137], v[220:223], v[30:33]
	v_mfma_f32_16x16x32_bf16 v[26:29], v[176:179], v[220:223], v[26:29]
	v_mfma_f32_16x16x32_bf16 v[14:17], v[134:137], v[228:231], v[14:17]
	v_mfma_f32_16x16x32_bf16 v[10:13], v[176:179], v[228:231], v[10:13]
	s_setprio 0
	s_setprio 1
	v_mfma_f32_16x16x32_bf16 v[54:57], v[180:183], v[200:203], v[54:57]
	v_mfma_f32_16x16x32_bf16 v[50:53], v[192:195], v[200:203], v[50:53]
	v_mfma_f32_16x16x32_bf16 v[38:41], v[180:183], v[208:211], v[38:41]
	v_mfma_f32_16x16x32_bf16 v[34:37], v[192:195], v[208:211], v[34:37]
	v_mfma_f32_16x16x32_bf16 v[22:25], v[180:183], v[216:219], v[22:25]
	v_mfma_f32_16x16x32_bf16 v[18:21], v[192:195], v[216:219], v[18:21]
	v_mfma_f32_16x16x32_bf16 v[6:9], v[180:183], v[224:227], v[6:9]
	v_mfma_f32_16x16x32_bf16 v[2:5], v[192:195], v[224:227], v[2:5]
	v_mfma_f32_16x16x32_bf16 v[54:57], v[188:191], v[204:207], v[54:57]
	v_mfma_f32_16x16x32_bf16 v[50:53], v[196:199], v[204:207], v[50:53]
	v_mfma_f32_16x16x32_bf16 v[38:41], v[188:191], v[212:215], v[38:41]
	v_mfma_f32_16x16x32_bf16 v[34:37], v[196:199], v[212:215], v[34:37]
	v_mfma_f32_16x16x32_bf16 v[22:25], v[188:191], v[220:223], v[22:25]
	v_mfma_f32_16x16x32_bf16 v[18:21], v[196:199], v[220:223], v[18:21]
	v_mfma_f32_16x16x32_bf16 v[6:9], v[188:191], v[228:231], v[6:9]
	v_mfma_f32_16x16x32_bf16 v[2:5], v[196:199], v[228:231], v[2:5]
	s_setprio 0
	s_barrier
	v_add_u32_e32 v176, vcc_lo, v153
	v_add_u32_e32 v186, vcc_hi, v153
	ds_read_b128 v[130:133], v176
	ds_read_b128 v[134:137], v176 offset:1024
	ds_read_b128 v[172:175], v176 offset:2048
	ds_read_b128 v[176:179], v176 offset:3072
	ds_read_b128 v[180:183], v186
	ds_read_b128 v[188:191], v186 offset:1024
	ds_read_b128 v[192:195], v186 offset:2048
	ds_read_b128 v[196:199], v186 offset:3072
	s_mov_b32 m0, s39
	ds_read_b128 v[200:203], v171 offset:32768
	ds_read_b128 v[204:207], v171 offset:33792
	ds_read_b128 v[208:211], v171 offset:34816
	ds_read_b128 v[212:215], v171 offset:35840
	ds_read_b128 v[216:219], v171 offset:36864
	ds_read_b128 v[220:223], v171 offset:37888
	ds_read_b128 v[224:227], v171 offset:38912
	ds_read_b128 v[228:231], v171 offset:39936
	global_load_lds_dwordx4 v138, s[80:81]
	s_mov_b32 m0, s40
	s_nop 0
	global_load_lds_dwordx4 v142, s[80:81]
	s_waitcnt vmcnt(8)
	s_waitcnt lgkmcnt(0)
	s_barrier
	s_setprio 1
	s_waitcnt lgkmcnt(0)
	v_mfma_f32_16x16x32_bf16 v[126:129], v[130:133], v[200:203], v[126:129]
	v_mfma_f32_16x16x32_bf16 v[122:125], v[172:175], v[200:203], v[122:125]
	v_mfma_f32_16x16x32_bf16 v[114:117], v[130:133], v[208:211], v[114:117]
	v_mfma_f32_16x16x32_bf16 v[106:109], v[172:175], v[208:211], v[106:109]
	v_mfma_f32_16x16x32_bf16 v[94:97], v[130:133], v[216:219], v[94:97]
	v_mfma_f32_16x16x32_bf16 v[90:93], v[172:175], v[216:219], v[90:93]
	v_mfma_f32_16x16x32_bf16 v[78:81], v[130:133], v[224:227], v[78:81]
	v_mfma_f32_16x16x32_bf16 v[74:77], v[172:175], v[224:227], v[74:77]
	v_mfma_f32_16x16x32_bf16 v[126:129], v[134:137], v[204:207], v[126:129]
	v_mfma_f32_16x16x32_bf16 v[122:125], v[176:179], v[204:207], v[122:125]
	v_mfma_f32_16x16x32_bf16 v[114:117], v[134:137], v[212:215], v[114:117]
	v_mfma_f32_16x16x32_bf16 v[106:109], v[176:179], v[212:215], v[106:109]
	v_mfma_f32_16x16x32_bf16 v[94:97], v[134:137], v[220:223], v[94:97]
	v_mfma_f32_16x16x32_bf16 v[90:93], v[176:179], v[220:223], v[90:93]
	v_mfma_f32_16x16x32_bf16 v[78:81], v[134:137], v[228:231], v[78:81]
	v_mfma_f32_16x16x32_bf16 v[74:77], v[176:179], v[228:231], v[74:77]
	s_setprio 0
	s_setprio 1
	v_mfma_f32_16x16x32_bf16 v[118:121], v[180:183], v[200:203], v[118:121]
	v_mfma_f32_16x16x32_bf16 v[110:113], v[192:195], v[200:203], v[110:113]
	v_mfma_f32_16x16x32_bf16 v[102:105], v[180:183], v[208:211], v[102:105]
	v_mfma_f32_16x16x32_bf16 v[98:101], v[192:195], v[208:211], v[98:101]
	v_mfma_f32_16x16x32_bf16 v[86:89], v[180:183], v[216:219], v[86:89]
	v_mfma_f32_16x16x32_bf16 v[82:85], v[192:195], v[216:219], v[82:85]
	v_mfma_f32_16x16x32_bf16 v[70:73], v[180:183], v[224:227], v[70:73]
	v_mfma_f32_16x16x32_bf16 v[66:69], v[192:195], v[224:227], v[66:69]
	v_mfma_f32_16x16x32_bf16 v[118:121], v[188:191], v[204:207], v[118:121]
	v_mfma_f32_16x16x32_bf16 v[110:113], v[196:199], v[204:207], v[110:113]
	v_mfma_f32_16x16x32_bf16 v[102:105], v[188:191], v[212:215], v[102:105]
	v_mfma_f32_16x16x32_bf16 v[98:101], v[196:199], v[212:215], v[98:101]
	v_mfma_f32_16x16x32_bf16 v[86:89], v[188:191], v[220:223], v[86:89]
	v_mfma_f32_16x16x32_bf16 v[82:85], v[196:199], v[220:223], v[82:85]
	v_mfma_f32_16x16x32_bf16 v[70:73], v[188:191], v[228:231], v[70:73]
	v_mfma_f32_16x16x32_bf16 v[66:69], v[196:199], v[228:231], v[66:69]
	s_setprio 0
	s_barrier
	s_mov_b32 m0, s67
	v_lshl_add_u64 v[150:151], v[150:151], 0, s[60:61]
	ds_read_b128 v[200:203], v171 offset:49152
	ds_read_b128 v[204:207], v171 offset:50176
	ds_read_b128 v[208:211], v171 offset:51200
	ds_read_b128 v[212:215], v171 offset:52224
	ds_read_b128 v[216:219], v171 offset:53248
	ds_read_b128 v[220:223], v171 offset:54272
	ds_read_b128 v[224:227], v171 offset:55296
	ds_read_b128 v[228:231], v171 offset:56320
	global_load_lds_dwordx4 v[150:151], off
	v_lshl_add_u64 v[150:151], v[184:185], 0, s[60:61]
	s_mov_b32 m0, s91
	s_nop 0
	global_load_lds_dwordx4 v[150:151], off
	s_mov_b32 m0, s97
	s_nop 0
	global_load_lds_dwordx4 v140, s[78:79]
	s_mov_b32 m0, s65
	s_nop 0
	global_load_lds_dwordx4 v144, s[78:79]
	v_lshl_add_u64 v[150:151], v[232:233], 0, s[60:61]
	s_mov_b32 m0, s56
	s_nop 0
	global_load_lds_dwordx4 v[150:151], off
	v_lshl_add_u64 v[150:151], v[234:235], 0, s[60:61]
	s_mov_b32 m0, s57
	s_nop 0
	global_load_lds_dwordx4 v[150:151], off
	s_waitcnt vmcnt(8)
	s_waitcnt lgkmcnt(0)
	s_barrier
	s_setprio 1
	s_waitcnt lgkmcnt(0)
	v_mfma_f32_16x16x32_bf16 v[62:65], v[130:133], v[200:203], v[62:65]
	v_mfma_f32_16x16x32_bf16 v[58:61], v[172:175], v[200:203], v[58:61]
	v_mfma_f32_16x16x32_bf16 v[46:49], v[130:133], v[208:211], v[46:49]
	v_mfma_f32_16x16x32_bf16 v[42:45], v[172:175], v[208:211], v[42:45]
	v_mfma_f32_16x16x32_bf16 v[30:33], v[130:133], v[216:219], v[30:33]
	v_mfma_f32_16x16x32_bf16 v[26:29], v[172:175], v[216:219], v[26:29]
	v_mfma_f32_16x16x32_bf16 v[14:17], v[130:133], v[224:227], v[14:17]
	v_mfma_f32_16x16x32_bf16 v[10:13], v[172:175], v[224:227], v[10:13]
	v_mfma_f32_16x16x32_bf16 v[62:65], v[134:137], v[204:207], v[62:65]
	v_mfma_f32_16x16x32_bf16 v[58:61], v[176:179], v[204:207], v[58:61]
	v_mfma_f32_16x16x32_bf16 v[46:49], v[134:137], v[212:215], v[46:49]
	v_mfma_f32_16x16x32_bf16 v[42:45], v[176:179], v[212:215], v[42:45]
	v_mfma_f32_16x16x32_bf16 v[30:33], v[134:137], v[220:223], v[30:33]
	v_mfma_f32_16x16x32_bf16 v[26:29], v[176:179], v[220:223], v[26:29]
	v_mfma_f32_16x16x32_bf16 v[14:17], v[134:137], v[228:231], v[14:17]
	v_mfma_f32_16x16x32_bf16 v[10:13], v[176:179], v[228:231], v[10:13]
	s_setprio 0
	s_setprio 1
	v_mfma_f32_16x16x32_bf16 v[54:57], v[180:183], v[200:203], v[54:57]
	v_mfma_f32_16x16x32_bf16 v[50:53], v[192:195], v[200:203], v[50:53]
	v_mfma_f32_16x16x32_bf16 v[38:41], v[180:183], v[208:211], v[38:41]
	v_mfma_f32_16x16x32_bf16 v[34:37], v[192:195], v[208:211], v[34:37]
	v_mfma_f32_16x16x32_bf16 v[22:25], v[180:183], v[216:219], v[22:25]
	v_mfma_f32_16x16x32_bf16 v[18:21], v[192:195], v[216:219], v[18:21]
	v_mfma_f32_16x16x32_bf16 v[6:9], v[180:183], v[224:227], v[6:9]
	v_mfma_f32_16x16x32_bf16 v[2:5], v[192:195], v[224:227], v[2:5]
	v_mfma_f32_16x16x32_bf16 v[54:57], v[188:191], v[204:207], v[54:57]
	v_mfma_f32_16x16x32_bf16 v[50:53], v[196:199], v[204:207], v[50:53]
	v_mfma_f32_16x16x32_bf16 v[38:41], v[188:191], v[212:215], v[38:41]
	v_mfma_f32_16x16x32_bf16 v[34:37], v[196:199], v[212:215], v[34:37]
	v_mfma_f32_16x16x32_bf16 v[22:25], v[188:191], v[220:223], v[22:25]
	v_mfma_f32_16x16x32_bf16 v[18:21], v[196:199], v[220:223], v[18:21]
	v_mfma_f32_16x16x32_bf16 v[6:9], v[188:191], v[228:231], v[6:9]
	v_mfma_f32_16x16x32_bf16 v[2:5], v[196:199], v[228:231], v[2:5]
	s_setprio 0
	s_barrier
	s_movk_i32 s65, 0x100
	s_andn2_b64 vcc, exec, s[10:11]
	s_mov_b64 s[78:79], -1
	s_mov_b64 s[10:11], 0
	s_cbranch_vccz .LBB0_1923
	s_and_b64 vcc, exec, s[62:63]
	s_cbranch_vccz .LBB0_1926
	s_barrier

.LBB0_1930:
	s_cmp_lt_i32 s27, 0
	s_cselect_b64 s[10:11], -1, 0
	s_cmp_eq_u32 s92, s27
	s_cselect_b64 s[6:7], -1, 0
	v_lshl_or_b32 v150, s72, 8, v168
	s_or_b64 s[6:7], s[10:11], s[6:7]
	s_andn2_b64 vcc, exec, s[6:7]
	v_ashrrev_i32_e32 v151, 31, v150
	s_cbranch_vccnz .LBB0_1932
	s_lshl_b32 s6, s12, 8
	v_add_u32_e32 v172, s6, v152
	v_ashrrev_i32_e32 v173, 31, v172
	v_lshlrev_b64 v[172:173], 13, v[172:173]
	v_lshl_add_u64 v[172:173], s[18:19], 0, v[172:173]
	v_lshlrev_b64 v[174:175], 1, v[150:151]
	v_lshl_add_u64 v[172:173], v[172:173], 0, v[174:175]
	s_waitcnt lgkmcnt(0)
	v_pk_mul_f32 v[128:129], v[128:129], v[134:135] op_sel_hi:[1,0]
	v_pk_mul_f32 v[126:127], v[126:127], v[134:135] op_sel_hi:[1,0]
	v_pk_mul_f32 v[176:177], v[124:125], v[134:135] op_sel_hi:[1,0]
	v_pk_mul_f32 v[124:125], v[122:123], v[134:135] op_sel_hi:[1,0]
	s_nop 0
	v_cvt_pk_bf16_f32 v122, v126, v127
	s_nop 0
	v_cvt_pk_bf16_f32 v123, v128, v129
	v_pk_mul_f32 v[118:119], v[118:119], v[134:135] op_sel_hi:[1,0]
	s_nop 0
	v_cvt_pk_bf16_f32 v124, v124, v125
	s_nop 0
	v_cvt_pk_bf16_f32 v125, v176, v177
	flat_store_dwordx4 v[172:173], v[122:125] sc0 sc1
	v_pk_mul_f32 v[120:121], v[120:121], v[134:135] op_sel_hi:[1,0]
	v_pk_mul_f32 v[114:115], v[114:115], v[134:135] op_sel:[0,1]
	v_pk_mul_f32 v[122:123], v[112:113], v[134:135] op_sel_hi:[1,0]
	v_pk_mul_f32 v[112:113], v[110:111], v[134:135] op_sel_hi:[1,0]
	s_nop 0
	v_cvt_pk_bf16_f32 v110, v118, v119
	s_nop 0
	v_cvt_pk_bf16_f32 v111, v120, v121
	v_pk_mul_f32 v[104:105], v[104:105], v[134:135] op_sel:[0,1]
	s_nop 0
	v_cvt_pk_bf16_f32 v112, v112, v113
	s_nop 0
	v_cvt_pk_bf16_f32 v113, v122, v123
	flat_store_dwordx4 v[172:173], v[110:113] offset:256 sc0 sc1
	v_pk_mul_f32 v[102:103], v[102:103], v[134:135] op_sel:[0,1]
	s_nop 0
	v_add_u32_e32 v110, s6, v154
	v_ashrrev_i32_e32 v111, 31, v110
	v_lshlrev_b64 v[110:111], 13, v[110:111]
	v_lshl_add_u64 v[110:111], s[18:19], 0, v[110:111]
	v_lshl_add_u64 v[110:111], v[110:111], 0, v[174:175]
	v_pk_mul_f32 v[112:113], v[116:117], v[134:135] op_sel:[0,1]
	v_pk_mul_f32 v[116:117], v[108:109], v[134:135] op_sel:[0,1]
	v_pk_mul_f32 v[108:109], v[106:107], v[134:135] op_sel:[0,1]
	s_nop 0
	v_cvt_pk_bf16_f32 v106, v114, v115
	s_nop 0
	v_cvt_pk_bf16_f32 v107, v112, v113
	s_nop 0
	s_nop 0
	v_cvt_pk_bf16_f32 v108, v108, v109
	s_nop 0
	v_cvt_pk_bf16_f32 v109, v116, v117
	flat_store_dwordx4 v[110:111], v[106:109] sc0 sc1
	s_nop 1
	v_pk_mul_f32 v[106:107], v[100:101], v[134:135] op_sel:[0,1]
	v_pk_mul_f32 v[100:101], v[98:99], v[134:135] op_sel:[0,1]
	s_nop 0
	v_cvt_pk_bf16_f32 v98, v102, v103
	s_nop 0
	v_cvt_pk_bf16_f32 v99, v104, v105
	s_nop 0
	s_nop 0
	v_cvt_pk_bf16_f32 v100, v100, v101
	s_nop 0
	v_cvt_pk_bf16_f32 v101, v106, v107
	flat_store_dwordx4 v[110:111], v[98:101] offset:256 sc0 sc1
.LBB0_1932:
	v_cmp_eq_u32_e32 vcc, s27, v156
	s_or_b64 s[6:7], s[10:11], vcc
	s_and_saveexec_b64 s[72:73], s[6:7]
	s_cbranch_execz .LBB0_1934
	v_lshl_add_u32 v98, s12, 8, v155
	v_ashrrev_i32_e32 v99, 31, v98
	v_lshlrev_b64 v[98:99], 13, v[98:99]
	v_lshl_add_u64 v[98:99], s[18:19], 0, v[98:99]
	v_lshl_add_u64 v[98:99], v[150:151], 1, v[98:99]
	s_waitcnt lgkmcnt(0)
	v_pk_mul_f32 v[96:97], v[96:97], v[136:137] op_sel_hi:[1,0]
	v_pk_mul_f32 v[94:95], v[94:95], v[136:137] op_sel_hi:[1,0]
	v_pk_mul_f32 v[100:101], v[92:93], v[136:137] op_sel_hi:[1,0]
	v_pk_mul_f32 v[92:93], v[90:91], v[136:137] op_sel_hi:[1,0]
	s_nop 0
	v_cvt_pk_bf16_f32 v90, v94, v95
	s_nop 0
	v_cvt_pk_bf16_f32 v91, v96, v97
	v_pk_mul_f32 v[88:89], v[88:89], v[136:137] op_sel_hi:[1,0]
	s_nop 0
	v_cvt_pk_bf16_f32 v92, v92, v93
	s_nop 0
	v_cvt_pk_bf16_f32 v93, v100, v101
	flat_store_dwordx4 v[98:99], v[90:93] sc0 sc1
	v_pk_mul_f32 v[86:87], v[86:87], v[136:137] op_sel_hi:[1,0]
	s_nop 0
	v_pk_mul_f32 v[90:91], v[84:85], v[136:137] op_sel_hi:[1,0]
	v_pk_mul_f32 v[84:85], v[82:83], v[136:137] op_sel_hi:[1,0]
	s_nop 0
	v_cvt_pk_bf16_f32 v82, v86, v87
	s_nop 0
	v_cvt_pk_bf16_f32 v83, v88, v89
	s_nop 0
	s_nop 0
	v_cvt_pk_bf16_f32 v84, v84, v85
	s_nop 0
	v_cvt_pk_bf16_f32 v85, v90, v91
	flat_store_dwordx4 v[98:99], v[82:85] offset:256 sc0 sc1
.LBB0_1934:
	s_or_b64 exec, exec, s[72:73]
	v_cmp_eq_u32_e32 vcc, s27, v158
	s_or_b64 s[6:7], s[10:11], vcc
	s_and_saveexec_b64 s[72:73], s[6:7]
	s_cbranch_execz .LBB0_1936
	v_lshl_add_u32 v82, s12, 8, v157
	v_ashrrev_i32_e32 v83, 31, v82
	v_lshlrev_b64 v[82:83], 13, v[82:83]
	v_lshl_add_u64 v[82:83], s[18:19], 0, v[82:83]
	s_waitcnt lgkmcnt(0)
	v_mov_b32_e32 v84, v137
	v_lshl_add_u64 v[82:83], v[150:151], 1, v[82:83]
	v_pk_mul_f32 v[80:81], v[80:81], v[84:85] op_sel_hi:[1,0]
	v_pk_mul_f32 v[78:79], v[78:79], v[84:85] op_sel_hi:[1,0]
	v_pk_mul_f32 v[86:87], v[76:77], v[84:85] op_sel_hi:[1,0]
	v_pk_mul_f32 v[76:77], v[74:75], v[84:85] op_sel_hi:[1,0]
	s_nop 0
	v_cvt_pk_bf16_f32 v74, v78, v79
	s_nop 0
	v_cvt_pk_bf16_f32 v75, v80, v81
	v_pk_mul_f32 v[72:73], v[72:73], v[84:85] op_sel_hi:[1,0]
	s_nop 0
	v_cvt_pk_bf16_f32 v76, v76, v77
	s_nop 0
	v_cvt_pk_bf16_f32 v77, v86, v87
	flat_store_dwordx4 v[82:83], v[74:77] sc0 sc1
	v_pk_mul_f32 v[70:71], v[70:71], v[84:85] op_sel_hi:[1,0]
	s_nop 0
	v_pk_mul_f32 v[74:75], v[68:69], v[84:85] op_sel_hi:[1,0]
	v_pk_mul_f32 v[68:69], v[66:67], v[84:85] op_sel_hi:[1,0]
	s_nop 0
	v_cvt_pk_bf16_f32 v66, v70, v71
	s_nop 0
	v_cvt_pk_bf16_f32 v67, v72, v73
	s_nop 0
	s_nop 0
	v_cvt_pk_bf16_f32 v68, v68, v69
	s_nop 0
	v_cvt_pk_bf16_f32 v69, v74, v75
	flat_store_dwordx4 v[82:83], v[66:69] offset:256 sc0 sc1
.LBB0_1936:
	s_or_b64 exec, exec, s[72:73]
	v_cmp_eq_u32_e32 vcc, s27, v160
	s_or_b64 s[6:7], s[10:11], vcc
	s_and_saveexec_b64 s[72:73], s[6:7]
	s_cbranch_execz .LBB0_1938
	v_lshl_add_u32 v66, s12, 8, v159
	v_ashrrev_i32_e32 v67, 31, v66
	v_lshlrev_b64 v[66:67], 13, v[66:67]
	v_lshl_add_u64 v[66:67], s[18:19], 0, v[66:67]
	v_lshl_add_u64 v[66:67], v[150:151], 1, v[66:67]
	s_waitcnt lgkmcnt(0)
	v_pk_mul_f32 v[64:65], v[64:65], v[130:131] op_sel_hi:[1,0]
	v_pk_mul_f32 v[62:63], v[62:63], v[130:131] op_sel_hi:[1,0]
	v_pk_mul_f32 v[68:69], v[60:61], v[130:131] op_sel_hi:[1,0]
	v_pk_mul_f32 v[60:61], v[58:59], v[130:131] op_sel_hi:[1,0]
	s_nop 0
	v_cvt_pk_bf16_f32 v58, v62, v63
	s_nop 0
	v_cvt_pk_bf16_f32 v59, v64, v65
	v_pk_mul_f32 v[56:57], v[56:57], v[130:131] op_sel_hi:[1,0]
	s_nop 0
	v_cvt_pk_bf16_f32 v60, v60, v61
	s_nop 0
	v_cvt_pk_bf16_f32 v61, v68, v69
	flat_store_dwordx4 v[66:67], v[58:61] sc0 sc1
	v_pk_mul_f32 v[54:55], v[54:55], v[130:131] op_sel_hi:[1,0]
	s_nop 0
	v_pk_mul_f32 v[58:59], v[52:53], v[130:131] op_sel_hi:[1,0]
	v_pk_mul_f32 v[52:53], v[50:51], v[130:131] op_sel_hi:[1,0]
	s_nop 0
	v_cvt_pk_bf16_f32 v50, v54, v55
	s_nop 0
	v_cvt_pk_bf16_f32 v51, v56, v57
	s_nop 0
	s_nop 0
	v_cvt_pk_bf16_f32 v52, v52, v53
	s_nop 0
	v_cvt_pk_bf16_f32 v53, v58, v59
	flat_store_dwordx4 v[66:67], v[50:53] offset:256 sc0 sc1
.LBB0_1938:
	s_or_b64 exec, exec, s[72:73]
	v_cmp_eq_u32_e32 vcc, s27, v162
	s_or_b64 s[6:7], s[10:11], vcc
	s_and_saveexec_b64 s[72:73], s[6:7]
	s_cbranch_execz .LBB0_1940
	v_lshl_add_u32 v50, s12, 8, v161
	v_ashrrev_i32_e32 v51, 31, v50
	v_lshlrev_b64 v[50:51], 13, v[50:51]
	v_lshl_add_u64 v[50:51], s[18:19], 0, v[50:51]
	s_waitcnt lgkmcnt(0)
	v_mov_b32_e32 v52, v131
	v_lshl_add_u64 v[50:51], v[150:151], 1, v[50:51]
	v_pk_mul_f32 v[48:49], v[48:49], v[52:53] op_sel_hi:[1,0]
	v_pk_mul_f32 v[46:47], v[46:47], v[52:53] op_sel_hi:[1,0]
	v_pk_mul_f32 v[54:55], v[44:45], v[52:53] op_sel_hi:[1,0]
	v_pk_mul_f32 v[44:45], v[42:43], v[52:53] op_sel_hi:[1,0]
	s_nop 0
	v_cvt_pk_bf16_f32 v42, v46, v47
	s_nop 0
	v_cvt_pk_bf16_f32 v43, v48, v49
	v_pk_mul_f32 v[40:41], v[40:41], v[52:53] op_sel_hi:[1,0]
	s_nop 0
	v_cvt_pk_bf16_f32 v44, v44, v45
	s_nop 0
	v_cvt_pk_bf16_f32 v45, v54, v55
	flat_store_dwordx4 v[50:51], v[42:45] sc0 sc1
	v_pk_mul_f32 v[38:39], v[38:39], v[52:53] op_sel_hi:[1,0]
	s_nop 0
	v_pk_mul_f32 v[42:43], v[36:37], v[52:53] op_sel_hi:[1,0]
	v_pk_mul_f32 v[36:37], v[34:35], v[52:53] op_sel_hi:[1,0]
	s_nop 0
	v_cvt_pk_bf16_f32 v34, v38, v39
	s_nop 0
	v_cvt_pk_bf16_f32 v35, v40, v41
	s_nop 0
	s_nop 0
	v_cvt_pk_bf16_f32 v36, v36, v37
	s_nop 0
	v_cvt_pk_bf16_f32 v37, v42, v43
	flat_store_dwordx4 v[50:51], v[34:37] offset:256 sc0 sc1
.LBB0_1940:
	s_or_b64 exec, exec, s[72:73]
	v_cmp_eq_u32_e32 vcc, s27, v165
	s_or_b64 s[6:7], s[10:11], vcc
	s_and_saveexec_b64 s[72:73], s[6:7]
	s_cbranch_execz .LBB0_1942
	v_lshl_add_u32 v34, s12, 8, v163
	v_ashrrev_i32_e32 v35, 31, v34
	v_lshlrev_b64 v[34:35], 13, v[34:35]
	v_lshl_add_u64 v[34:35], s[18:19], 0, v[34:35]
	v_lshl_add_u64 v[34:35], v[150:151], 1, v[34:35]
	s_waitcnt lgkmcnt(0)
	v_pk_mul_f32 v[32:33], v[32:33], v[132:133] op_sel_hi:[1,0]
	v_pk_mul_f32 v[30:31], v[30:31], v[132:133] op_sel_hi:[1,0]
	v_pk_mul_f32 v[36:37], v[28:29], v[132:133] op_sel_hi:[1,0]
	v_pk_mul_f32 v[28:29], v[26:27], v[132:133] op_sel_hi:[1,0]
	s_nop 0
	v_cvt_pk_bf16_f32 v26, v30, v31
	s_nop 0
	v_cvt_pk_bf16_f32 v27, v32, v33
	v_pk_mul_f32 v[24:25], v[24:25], v[132:133] op_sel_hi:[1,0]
	s_nop 0
	v_cvt_pk_bf16_f32 v28, v28, v29
	s_nop 0
	v_cvt_pk_bf16_f32 v29, v36, v37
	flat_store_dwordx4 v[34:35], v[26:29] sc0 sc1
	v_pk_mul_f32 v[22:23], v[22:23], v[132:133] op_sel_hi:[1,0]
	s_nop 0
	v_pk_mul_f32 v[26:27], v[20:21], v[132:133] op_sel_hi:[1,0]
	v_pk_mul_f32 v[20:21], v[18:19], v[132:133] op_sel_hi:[1,0]
	s_nop 0
	v_cvt_pk_bf16_f32 v18, v22, v23
	s_nop 0
	v_cvt_pk_bf16_f32 v19, v24, v25
	s_nop 0
	s_nop 0
	v_cvt_pk_bf16_f32 v20, v20, v21
	s_nop 0
	v_cvt_pk_bf16_f32 v21, v26, v27
	flat_store_dwordx4 v[34:35], v[18:21] offset:256 sc0 sc1
.LBB0_1942:
	s_or_b64 exec, exec, s[72:73]
	v_cmp_eq_u32_e32 vcc, s27, v167
	s_or_b64 s[6:7], s[10:11], vcc
	s_and_saveexec_b64 s[10:11], s[6:7]
	s_cbranch_execz .LBB0_1944
	v_lshl_add_u32 v18, s12, 8, v166
	v_ashrrev_i32_e32 v19, 31, v18
	v_lshlrev_b64 v[18:19], 13, v[18:19]
	v_lshl_add_u64 v[18:19], s[18:19], 0, v[18:19]
	s_waitcnt lgkmcnt(0)
	v_mov_b32_e32 v20, v133
	v_lshl_add_u64 v[18:19], v[150:151], 1, v[18:19]
	v_pk_mul_f32 v[16:17], v[16:17], v[20:21] op_sel_hi:[1,0]
	v_pk_mul_f32 v[14:15], v[14:15], v[20:21] op_sel_hi:[1,0]
	v_pk_mul_f32 v[22:23], v[12:13], v[20:21] op_sel_hi:[1,0]
	v_pk_mul_f32 v[12:13], v[10:11], v[20:21] op_sel_hi:[1,0]
	s_nop 0
	v_cvt_pk_bf16_f32 v10, v14, v15
	s_nop 0
	v_cvt_pk_bf16_f32 v11, v16, v17
	v_pk_mul_f32 v[8:9], v[8:9], v[20:21] op_sel_hi:[1,0]
	s_nop 0
	v_cvt_pk_bf16_f32 v12, v12, v13
	s_nop 0
	v_cvt_pk_bf16_f32 v13, v22, v23
	flat_store_dwordx4 v[18:19], v[10:13] sc0 sc1
	v_pk_mul_f32 v[6:7], v[6:7], v[20:21] op_sel_hi:[1,0]
	s_nop 0
	v_pk_mul_f32 v[10:11], v[4:5], v[20:21] op_sel_hi:[1,0]
	v_pk_mul_f32 v[4:5], v[2:3], v[20:21] op_sel_hi:[1,0]
	s_nop 0
	v_cvt_pk_bf16_f32 v2, v6, v7
	s_nop 0
	v_cvt_pk_bf16_f32 v3, v8, v9
	s_nop 0
	s_nop 0
	v_cvt_pk_bf16_f32 v4, v4, v5
	s_nop 0
	v_cvt_pk_bf16_f32 v5, v10, v11
	flat_store_dwordx4 v[18:19], v[2:5] offset:256 sc0 sc1

.LBB0_1984:
	ds_read_b128 v[142:145], v149
	ds_read_b128 v[154:157], v149 offset:1024
	ds_read_b128 v[158:161], v149 offset:2048
	ds_read_b128 v[166:169], v149 offset:3072
	ds_read_b128 v[170:173], v150
	ds_read_b128 v[174:177], v150 offset:1024
	ds_read_b128 v[178:181], v150 offset:2048
	ds_read_b128 v[182:185], v150 offset:3072
	s_add_u32 s6, s72, 0xfff00080
	s_addc_u32 s7, s73, -1
	s_cmp_eq_u32 s83, 60
	s_cselect_b32 s77, s63, s7
	s_cselect_b32 s76, s69, s6
	s_cselect_b32 s75, s61, s82
	s_cselect_b32 s74, s80, s81
	s_add_i32 m0, s27, 0xc000
	ds_read_b128 v[188:191], v151
	ds_read_b128 v[192:195], v151 offset:1024
	ds_read_b128 v[196:199], v151 offset:2048
	ds_read_b128 v[200:203], v151 offset:3072
	ds_read_b128 v[204:207], v151 offset:4096
	ds_read_b128 v[208:211], v151 offset:5120
	ds_read_b128 v[212:215], v151 offset:6144
	ds_read_b128 v[216:219], v151 offset:7168
	global_load_lds_dwordx4 v140, s[72:73]
	s_add_i32 m0, s27, 0xe000
	s_nop 0
	global_load_lds_dwordx4 v138, s[72:73]
	s_waitcnt vmcnt(8)
	s_waitcnt lgkmcnt(0)
	s_barrier
	s_setprio 1
	s_waitcnt lgkmcnt(0)
	v_mfma_f32_16x16x32_bf16 v[126:129], v[142:145], v[188:191], v[126:129]
	v_mfma_f32_16x16x32_bf16 v[122:125], v[158:161], v[188:191], v[122:125]
	v_mfma_f32_16x16x32_bf16 v[110:113], v[142:145], v[196:199], v[110:113]
	v_mfma_f32_16x16x32_bf16 v[106:109], v[158:161], v[196:199], v[106:109]
	v_mfma_f32_16x16x32_bf16 v[94:97], v[142:145], v[204:207], v[94:97]
	v_mfma_f32_16x16x32_bf16 v[90:93], v[158:161], v[204:207], v[90:93]
	v_mfma_f32_16x16x32_bf16 v[78:81], v[142:145], v[212:215], v[78:81]
	v_mfma_f32_16x16x32_bf16 v[74:77], v[158:161], v[212:215], v[74:77]
	v_mfma_f32_16x16x32_bf16 v[126:129], v[154:157], v[192:195], v[126:129]
	v_mfma_f32_16x16x32_bf16 v[122:125], v[166:169], v[192:195], v[122:125]
	v_mfma_f32_16x16x32_bf16 v[110:113], v[154:157], v[200:203], v[110:113]
	v_mfma_f32_16x16x32_bf16 v[106:109], v[166:169], v[200:203], v[106:109]
	v_mfma_f32_16x16x32_bf16 v[94:97], v[154:157], v[208:211], v[94:97]
	v_mfma_f32_16x16x32_bf16 v[90:93], v[166:169], v[208:211], v[90:93]
	v_mfma_f32_16x16x32_bf16 v[78:81], v[154:157], v[216:219], v[78:81]
	v_mfma_f32_16x16x32_bf16 v[74:77], v[166:169], v[216:219], v[74:77]
	s_setprio 0
	s_setprio 1
	v_mfma_f32_16x16x32_bf16 v[118:121], v[170:173], v[188:191], v[118:121]
	v_mfma_f32_16x16x32_bf16 v[114:117], v[178:181], v[188:191], v[114:117]
	v_mfma_f32_16x16x32_bf16 v[102:105], v[170:173], v[196:199], v[102:105]
	v_mfma_f32_16x16x32_bf16 v[98:101], v[178:181], v[196:199], v[98:101]
	v_mfma_f32_16x16x32_bf16 v[86:89], v[170:173], v[204:207], v[86:89]
	v_mfma_f32_16x16x32_bf16 v[82:85], v[178:181], v[204:207], v[82:85]
	v_mfma_f32_16x16x32_bf16 v[70:73], v[170:173], v[212:215], v[70:73]
	v_mfma_f32_16x16x32_bf16 v[66:69], v[178:181], v[212:215], v[66:69]
	v_mfma_f32_16x16x32_bf16 v[118:121], v[174:177], v[192:195], v[118:121]
	v_mfma_f32_16x16x32_bf16 v[114:117], v[182:185], v[192:195], v[114:117]
	v_mfma_f32_16x16x32_bf16 v[102:105], v[174:177], v[200:203], v[102:105]
	v_mfma_f32_16x16x32_bf16 v[98:101], v[182:185], v[200:203], v[98:101]
	v_mfma_f32_16x16x32_bf16 v[86:89], v[174:177], v[208:211], v[86:89]
	v_mfma_f32_16x16x32_bf16 v[82:85], v[182:185], v[208:211], v[82:85]
	v_mfma_f32_16x16x32_bf16 v[70:73], v[174:177], v[216:219], v[70:73]
	v_mfma_f32_16x16x32_bf16 v[66:69], v[182:185], v[216:219], v[66:69]
	s_setprio 0
	s_barrier
	s_add_i32 s6, s78, s26
	v_lshl_add_u64 v[162:163], s[74:75], 0, v[132:133]
	s_mov_b32 m0, s6
	ds_read_b128 v[188:191], v151 offset:16384
	ds_read_b128 v[192:195], v151 offset:17408
	ds_read_b128 v[196:199], v151 offset:18432
	ds_read_b128 v[200:203], v151 offset:19456
	ds_read_b128 v[204:207], v151 offset:20480
	ds_read_b128 v[208:211], v151 offset:21504
	ds_read_b128 v[212:215], v151 offset:22528
	ds_read_b128 v[216:219], v151 offset:23552
	global_load_lds_dwordx4 v[162:163], off
	s_add_i32 m0, s6, 0x2000
	s_add_u32 s6, s74, 0x100000
	v_lshl_add_u64 v[220:221], s[74:75], 0, v[136:137]
	s_addc_u32 s7, s75, 0
	s_add_i32 s16, s79, s26
	global_load_lds_dwordx4 v[220:221], off
	s_mov_b32 m0, s16
	v_lshl_add_u64 v[224:225], s[76:77], 0, v[134:135]
	global_load_lds_dwordx4 v132, s[6:7]
	s_add_i32 m0, s16, 0x2000
	s_nop 0
	global_load_lds_dwordx4 v136, s[6:7]
	v_lshl_add_u64 v[222:223], s[76:77], 0, v[130:131]
	s_mov_b32 m0, s27
	s_nop 0
	global_load_lds_dwordx4 v[222:223], off
	s_mov_b32 m0, s28
	s_nop 0
	global_load_lds_dwordx4 v[224:225], off
	s_waitcnt vmcnt(8)
	s_waitcnt lgkmcnt(0)
	s_barrier
	s_setprio 1
	s_waitcnt lgkmcnt(0)
	v_mfma_f32_16x16x32_bf16 v[62:65], v[142:145], v[188:191], v[62:65]
	v_mfma_f32_16x16x32_bf16 v[58:61], v[158:161], v[188:191], v[58:61]
	v_mfma_f32_16x16x32_bf16 v[46:49], v[142:145], v[196:199], v[46:49]
	v_mfma_f32_16x16x32_bf16 v[42:45], v[158:161], v[196:199], v[42:45]
	v_mfma_f32_16x16x32_bf16 v[30:33], v[142:145], v[204:207], v[30:33]
	v_mfma_f32_16x16x32_bf16 v[26:29], v[158:161], v[204:207], v[26:29]
	v_mfma_f32_16x16x32_bf16 v[14:17], v[142:145], v[212:215], v[14:17]
	v_mfma_f32_16x16x32_bf16 v[10:13], v[158:161], v[212:215], v[10:13]
	v_mfma_f32_16x16x32_bf16 v[62:65], v[154:157], v[192:195], v[62:65]
	v_mfma_f32_16x16x32_bf16 v[58:61], v[166:169], v[192:195], v[58:61]
	v_mfma_f32_16x16x32_bf16 v[46:49], v[154:157], v[200:203], v[46:49]
	v_mfma_f32_16x16x32_bf16 v[42:45], v[166:169], v[200:203], v[42:45]
	v_mfma_f32_16x16x32_bf16 v[30:33], v[154:157], v[208:211], v[30:33]
	v_mfma_f32_16x16x32_bf16 v[26:29], v[166:169], v[208:211], v[26:29]
	v_mfma_f32_16x16x32_bf16 v[14:17], v[154:157], v[216:219], v[14:17]
	v_mfma_f32_16x16x32_bf16 v[10:13], v[166:169], v[216:219], v[10:13]
	s_setprio 0
	s_setprio 1
	v_mfma_f32_16x16x32_bf16 v[54:57], v[170:173], v[188:191], v[54:57]
	v_mfma_f32_16x16x32_bf16 v[50:53], v[178:181], v[188:191], v[50:53]
	v_mfma_f32_16x16x32_bf16 v[38:41], v[170:173], v[196:199], v[38:41]
	v_mfma_f32_16x16x32_bf16 v[34:37], v[178:181], v[196:199], v[34:37]
	v_mfma_f32_16x16x32_bf16 v[22:25], v[170:173], v[204:207], v[22:25]
	v_mfma_f32_16x16x32_bf16 v[18:21], v[178:181], v[204:207], v[18:21]
	v_mfma_f32_16x16x32_bf16 v[6:9], v[170:173], v[212:215], v[6:9]
	v_mfma_f32_16x16x32_bf16 v[2:5], v[178:181], v[212:215], v[2:5]
	v_mfma_f32_16x16x32_bf16 v[54:57], v[174:177], v[192:195], v[54:57]
	v_mfma_f32_16x16x32_bf16 v[50:53], v[182:185], v[192:195], v[50:53]
	v_mfma_f32_16x16x32_bf16 v[38:41], v[174:177], v[200:203], v[38:41]
	v_mfma_f32_16x16x32_bf16 v[34:37], v[182:185], v[200:203], v[34:37]
	v_mfma_f32_16x16x32_bf16 v[22:25], v[174:177], v[208:211], v[22:25]
	v_mfma_f32_16x16x32_bf16 v[18:21], v[182:185], v[208:211], v[18:21]
	v_mfma_f32_16x16x32_bf16 v[6:9], v[174:177], v[216:219], v[6:9]
	v_mfma_f32_16x16x32_bf16 v[2:5], v[182:185], v[216:219], v[2:5]
	s_setprio 0
	s_barrier
	s_add_i32 s16, 0, 0x18000
	v_add_u32_e32 v153, s16, v147
	s_add_i32 s17, 0, 0x1c000
	ds_read_b128 v[142:145], v153
	ds_read_b128 v[154:157], v153 offset:1024
	ds_read_b128 v[158:161], v153 offset:2048
	ds_read_b128 v[166:169], v153 offset:3072
	v_add_u32_e32 v153, s17, v147
	ds_read_b128 v[170:173], v153
	ds_read_b128 v[174:177], v153 offset:1024
	ds_read_b128 v[178:181], v153 offset:2048
	ds_read_b128 v[182:185], v153 offset:3072
	s_add_u32 s6, s76, 0x100000
	s_addc_u32 s7, s77, 0
	s_mov_b32 m0, s29
	ds_read_b128 v[188:191], v151 offset:32768
	ds_read_b128 v[192:195], v151 offset:33792
	ds_read_b128 v[196:199], v151 offset:34816
	ds_read_b128 v[200:203], v151 offset:35840
	ds_read_b128 v[204:207], v151 offset:36864
	ds_read_b128 v[208:211], v151 offset:37888
	ds_read_b128 v[212:215], v151 offset:38912
	ds_read_b128 v[216:219], v151 offset:39936
	global_load_lds_dwordx4 v130, s[6:7]
	s_mov_b32 m0, s40
	s_nop 0
	global_load_lds_dwordx4 v134, s[6:7]
	s_waitcnt vmcnt(8)
	s_waitcnt lgkmcnt(0)
	s_barrier
	s_setprio 1
	s_waitcnt lgkmcnt(0)
	v_mfma_f32_16x16x32_bf16 v[126:129], v[142:145], v[188:191], v[126:129]
	v_mfma_f32_16x16x32_bf16 v[122:125], v[158:161], v[188:191], v[122:125]
	v_mfma_f32_16x16x32_bf16 v[110:113], v[142:145], v[196:199], v[110:113]
	v_mfma_f32_16x16x32_bf16 v[106:109], v[158:161], v[196:199], v[106:109]
	v_mfma_f32_16x16x32_bf16 v[94:97], v[142:145], v[204:207], v[94:97]
	v_mfma_f32_16x16x32_bf16 v[90:93], v[158:161], v[204:207], v[90:93]
	v_mfma_f32_16x16x32_bf16 v[78:81], v[142:145], v[212:215], v[78:81]
	v_mfma_f32_16x16x32_bf16 v[74:77], v[158:161], v[212:215], v[74:77]
	v_mfma_f32_16x16x32_bf16 v[126:129], v[154:157], v[192:195], v[126:129]
	v_mfma_f32_16x16x32_bf16 v[122:125], v[166:169], v[192:195], v[122:125]
	v_mfma_f32_16x16x32_bf16 v[110:113], v[154:157], v[200:203], v[110:113]
	v_mfma_f32_16x16x32_bf16 v[106:109], v[166:169], v[200:203], v[106:109]
	v_mfma_f32_16x16x32_bf16 v[94:97], v[154:157], v[208:211], v[94:97]
	v_mfma_f32_16x16x32_bf16 v[90:93], v[166:169], v[208:211], v[90:93]
	v_mfma_f32_16x16x32_bf16 v[78:81], v[154:157], v[216:219], v[78:81]
	v_mfma_f32_16x16x32_bf16 v[74:77], v[166:169], v[216:219], v[74:77]
	s_setprio 0
	s_setprio 1
	v_mfma_f32_16x16x32_bf16 v[118:121], v[170:173], v[188:191], v[118:121]
	v_mfma_f32_16x16x32_bf16 v[114:117], v[178:181], v[188:191], v[114:117]
	v_mfma_f32_16x16x32_bf16 v[102:105], v[170:173], v[196:199], v[102:105]
	v_mfma_f32_16x16x32_bf16 v[98:101], v[178:181], v[196:199], v[98:101]
	v_mfma_f32_16x16x32_bf16 v[86:89], v[170:173], v[204:207], v[86:89]
	v_mfma_f32_16x16x32_bf16 v[82:85], v[178:181], v[204:207], v[82:85]
	v_mfma_f32_16x16x32_bf16 v[70:73], v[170:173], v[212:215], v[70:73]
	v_mfma_f32_16x16x32_bf16 v[66:69], v[178:181], v[212:215], v[66:69]
	v_mfma_f32_16x16x32_bf16 v[118:121], v[174:177], v[192:195], v[118:121]
	v_mfma_f32_16x16x32_bf16 v[114:117], v[182:185], v[192:195], v[114:117]
	v_mfma_f32_16x16x32_bf16 v[102:105], v[174:177], v[200:203], v[102:105]
	v_mfma_f32_16x16x32_bf16 v[98:101], v[182:185], v[200:203], v[98:101]
	v_mfma_f32_16x16x32_bf16 v[86:89], v[174:177], v[208:211], v[86:89]
	v_mfma_f32_16x16x32_bf16 v[82:85], v[182:185], v[208:211], v[82:85]
	v_mfma_f32_16x16x32_bf16 v[70:73], v[174:177], v[216:219], v[70:73]
	v_mfma_f32_16x16x32_bf16 v[66:69], v[182:185], v[216:219], v[66:69]
	s_setprio 0
	s_barrier
	s_add_i32 s6, s16, s26
	v_lshl_add_u64 v[162:163], v[162:163], 0, s[12:13]
	s_mov_b32 m0, s6
	ds_read_b128 v[188:191], v151 offset:49152
	ds_read_b128 v[192:195], v151 offset:50176
	ds_read_b128 v[196:199], v151 offset:51200
	ds_read_b128 v[200:203], v151 offset:52224
	ds_read_b128 v[204:207], v151 offset:53248
	ds_read_b128 v[208:211], v151 offset:54272
	ds_read_b128 v[212:215], v151 offset:55296
	ds_read_b128 v[216:219], v151 offset:56320
	global_load_lds_dwordx4 v[162:163], off
	s_add_i32 m0, s6, 0x2000
	s_add_u32 s6, s74, 0x100080
	v_lshl_add_u64 v[162:163], v[220:221], 0, s[12:13]
	s_addc_u32 s7, s75, 0
	s_add_i32 s16, s17, s26
	global_load_lds_dwordx4 v[162:163], off
	s_mov_b32 m0, s16
	s_nop 0
	global_load_lds_dwordx4 v132, s[6:7]
	s_add_i32 m0, s16, 0x2000
	s_nop 0
	global_load_lds_dwordx4 v136, s[6:7]
	v_lshl_add_u64 v[162:163], v[222:223], 0, s[12:13]
	s_mov_b32 m0, s56
	s_nop 0
	global_load_lds_dwordx4 v[162:163], off
	v_lshl_add_u64 v[162:163], v[224:225], 0, s[12:13]
	s_mov_b32 m0, s57
	s_nop 0
	global_load_lds_dwordx4 v[162:163], off
	s_waitcnt vmcnt(8)
	s_waitcnt lgkmcnt(0)
	s_barrier
	s_setprio 1
	s_waitcnt lgkmcnt(0)
	v_mfma_f32_16x16x32_bf16 v[62:65], v[142:145], v[188:191], v[62:65]
	v_mfma_f32_16x16x32_bf16 v[58:61], v[158:161], v[188:191], v[58:61]
	v_mfma_f32_16x16x32_bf16 v[46:49], v[142:145], v[196:199], v[46:49]
	v_mfma_f32_16x16x32_bf16 v[42:45], v[158:161], v[196:199], v[42:45]
	v_mfma_f32_16x16x32_bf16 v[30:33], v[142:145], v[204:207], v[30:33]
	v_mfma_f32_16x16x32_bf16 v[26:29], v[158:161], v[204:207], v[26:29]
	v_mfma_f32_16x16x32_bf16 v[14:17], v[142:145], v[212:215], v[14:17]
	v_mfma_f32_16x16x32_bf16 v[10:13], v[158:161], v[212:215], v[10:13]
	v_mfma_f32_16x16x32_bf16 v[62:65], v[154:157], v[192:195], v[62:65]
	v_mfma_f32_16x16x32_bf16 v[58:61], v[166:169], v[192:195], v[58:61]
	v_mfma_f32_16x16x32_bf16 v[46:49], v[154:157], v[200:203], v[46:49]
	v_mfma_f32_16x16x32_bf16 v[42:45], v[166:169], v[200:203], v[42:45]
	v_mfma_f32_16x16x32_bf16 v[30:33], v[154:157], v[208:211], v[30:33]
	v_mfma_f32_16x16x32_bf16 v[26:29], v[166:169], v[208:211], v[26:29]
	v_mfma_f32_16x16x32_bf16 v[14:17], v[154:157], v[216:219], v[14:17]
	v_mfma_f32_16x16x32_bf16 v[10:13], v[166:169], v[216:219], v[10:13]
	s_setprio 0
	s_setprio 1
	v_mfma_f32_16x16x32_bf16 v[54:57], v[170:173], v[188:191], v[54:57]
	v_mfma_f32_16x16x32_bf16 v[50:53], v[178:181], v[188:191], v[50:53]
	v_mfma_f32_16x16x32_bf16 v[38:41], v[170:173], v[196:199], v[38:41]
	v_mfma_f32_16x16x32_bf16 v[34:37], v[178:181], v[196:199], v[34:37]
	v_mfma_f32_16x16x32_bf16 v[22:25], v[170:173], v[204:207], v[22:25]
	v_mfma_f32_16x16x32_bf16 v[18:21], v[178:181], v[204:207], v[18:21]
	v_mfma_f32_16x16x32_bf16 v[6:9], v[170:173], v[212:215], v[6:9]
	v_mfma_f32_16x16x32_bf16 v[2:5], v[178:181], v[212:215], v[2:5]
	v_mfma_f32_16x16x32_bf16 v[54:57], v[174:177], v[192:195], v[54:57]
	v_mfma_f32_16x16x32_bf16 v[50:53], v[182:185], v[192:195], v[50:53]
	v_mfma_f32_16x16x32_bf16 v[38:41], v[174:177], v[200:203], v[38:41]
	v_mfma_f32_16x16x32_bf16 v[34:37], v[182:185], v[200:203], v[34:37]
	v_mfma_f32_16x16x32_bf16 v[22:25], v[174:177], v[208:211], v[22:25]
	v_mfma_f32_16x16x32_bf16 v[18:21], v[182:185], v[208:211], v[18:21]
	v_mfma_f32_16x16x32_bf16 v[6:9], v[174:177], v[216:219], v[6:9]
	v_mfma_f32_16x16x32_bf16 v[2:5], v[182:185], v[216:219], v[2:5]
	s_setprio 0
	s_barrier
	s_add_i32 s83, s83, 2
	s_add_u32 s81, s81, 0x100
	s_addc_u32 s82, s82, 0
	s_add_u32 s72, s72, 0x100
	s_addc_u32 s73, s73, 0
	s_cmp_gt_u32 s83, 61
	s_cbranch_scc0 .LBB0_1984
	v_lshl_add_u32 v245, s70, 8, v146
	v_lshl_or_b32 v246, s68, 8, v148
	v_lshlrev_b32_e32 v245, 13, v245
	v_lshl_add_u32 v245, v246, 1, v245
	global_load_dwordx4 v[142:145], v245, s[24:25]
	global_load_dwordx4 v[154:157], v245, s[24:25] offset:256
	s_add_u32 s68, s24, 0x20000
	s_addc_u32 s69, s25, 0
	global_load_dwordx4 v[158:161], v245, s[68:69]
	global_load_dwordx4 v[166:169], v245, s[68:69] offset:256
	s_add_u32 s68, s24, 0x40000
	s_addc_u32 s69, s25, 0
	global_load_dwordx4 v[170:173], v245, s[68:69]
	global_load_dwordx4 v[174:177], v245, s[68:69] offset:256
	s_add_u32 s68, s24, 0x60000
	s_addc_u32 s69, s25, 0
	global_load_dwordx4 v[178:181], v245, s[68:69]
	global_load_dwordx4 v[182:185], v245, s[68:69] offset:256
	s_add_u32 s68, s24, 0x100000
	s_addc_u32 s69, s25, 0
	global_load_dwordx4 v[188:191], v245, s[68:69]
	global_load_dwordx4 v[192:195], v245, s[68:69] offset:256
	s_add_u32 s68, s24, 0x120000
	s_addc_u32 s69, s25, 0
	global_load_dwordx4 v[196:199], v245, s[68:69]
	global_load_dwordx4 v[200:203], v245, s[68:69] offset:256
	s_add_u32 s68, s24, 0x140000
	s_addc_u32 s69, s25, 0
	global_load_dwordx4 v[204:207], v245, s[68:69]
	global_load_dwordx4 v[208:211], v245, s[68:69] offset:256
	s_add_u32 s68, s24, 0x160000
	s_addc_u32 s69, s25, 0
	global_load_dwordx4 v[212:215], v245, s[68:69]
	global_load_dwordx4 v[216:219], v245, s[68:69] offset:256
	s_and_b64 vcc, exec, s[44:45]
	s_cbranch_vccz .LBB0_1987
	s_barrier
.LBB0_1987:
	s_waitcnt vmcnt(15)
	v_lshlrev_b32_e32 v246, 16, v142
	v_and_b32_e32 v247, 0xffff0000, v142
	v_pk_add_f32 v[126:127], v[126:127], v[246:247]
	v_lshlrev_b32_e32 v246, 16, v143
	v_and_b32_e32 v247, 0xffff0000, v143
	v_pk_add_f32 v[128:129], v[128:129], v[246:247]
	v_lshlrev_b32_e32 v246, 16, v144
	v_and_b32_e32 v247, 0xffff0000, v144
	v_pk_add_f32 v[122:123], v[122:123], v[246:247]
	v_lshlrev_b32_e32 v246, 16, v145
	v_and_b32_e32 v247, 0xffff0000, v145
	v_pk_add_f32 v[124:125], v[124:125], v[246:247]
	v_cvt_pk_bf16_f32 v142, v126, v127
	v_cvt_pk_bf16_f32 v143, v128, v129
	v_cvt_pk_bf16_f32 v144, v122, v123
	v_cvt_pk_bf16_f32 v145, v124, v125
	global_store_dwordx4 v245, v[142:145], s[24:25] sc0 sc1
	v_mul_f32_e32 v126, v126, v126
	v_fmac_f32_e32 v126, v127, v127
	v_fmac_f32_e32 v126, v128, v128
	v_fmac_f32_e32 v126, v129, v129
	v_fmac_f32_e32 v126, v122, v122
	v_fmac_f32_e32 v126, v123, v123
	v_fmac_f32_e32 v126, v124, v124
	v_fmac_f32_e32 v126, v125, v125
	s_waitcnt vmcnt(15)
	v_lshlrev_b32_e32 v246, 16, v154
	v_and_b32_e32 v247, 0xffff0000, v154
	v_pk_add_f32 v[118:119], v[118:119], v[246:247]
	v_lshlrev_b32_e32 v246, 16, v155
	v_and_b32_e32 v247, 0xffff0000, v155
	v_pk_add_f32 v[120:121], v[120:121], v[246:247]
	v_lshlrev_b32_e32 v246, 16, v156
	v_and_b32_e32 v247, 0xffff0000, v156
	v_pk_add_f32 v[114:115], v[114:115], v[246:247]
	v_lshlrev_b32_e32 v246, 16, v157
	v_and_b32_e32 v247, 0xffff0000, v157
	v_pk_add_f32 v[116:117], v[116:117], v[246:247]
	v_cvt_pk_bf16_f32 v154, v118, v119
	v_cvt_pk_bf16_f32 v155, v120, v121
	v_cvt_pk_bf16_f32 v156, v114, v115
	v_cvt_pk_bf16_f32 v157, v116, v117
	global_store_dwordx4 v245, v[154:157], s[24:25] offset:256 sc0 sc1
	v_fmac_f32_e32 v126, v118, v118
	v_fmac_f32_e32 v126, v119, v119
	v_fmac_f32_e32 v126, v120, v120
	v_fmac_f32_e32 v126, v121, v121
	v_fmac_f32_e32 v126, v114, v114
	v_fmac_f32_e32 v126, v115, v115
	v_fmac_f32_e32 v126, v116, v116
	v_fmac_f32_e32 v126, v117, v117
	s_add_u32 s68, s24, 0x20000
	s_addc_u32 s69, s25, 0
	s_waitcnt vmcnt(15)
	v_lshlrev_b32_e32 v246, 16, v158
	v_and_b32_e32 v247, 0xffff0000, v158
	v_pk_add_f32 v[110:111], v[110:111], v[246:247]
	v_lshlrev_b32_e32 v246, 16, v159
	v_and_b32_e32 v247, 0xffff0000, v159
	v_pk_add_f32 v[112:113], v[112:113], v[246:247]
	v_lshlrev_b32_e32 v246, 16, v160
	v_and_b32_e32 v247, 0xffff0000, v160
	v_pk_add_f32 v[106:107], v[106:107], v[246:247]
	v_lshlrev_b32_e32 v246, 16, v161
	v_and_b32_e32 v247, 0xffff0000, v161
	v_pk_add_f32 v[108:109], v[108:109], v[246:247]
	v_cvt_pk_bf16_f32 v158, v110, v111
	v_cvt_pk_bf16_f32 v159, v112, v113
	v_cvt_pk_bf16_f32 v160, v106, v107
	v_cvt_pk_bf16_f32 v161, v108, v109
	global_store_dwordx4 v245, v[158:161], s[68:69] sc0 sc1
	v_mul_f32_e32 v110, v110, v110
	v_fmac_f32_e32 v110, v111, v111
	v_fmac_f32_e32 v110, v112, v112
	v_fmac_f32_e32 v110, v113, v113
	v_fmac_f32_e32 v110, v106, v106
	v_fmac_f32_e32 v110, v107, v107
	v_fmac_f32_e32 v110, v108, v108
	v_fmac_f32_e32 v110, v109, v109
	s_waitcnt vmcnt(15)
	v_lshlrev_b32_e32 v246, 16, v166
	v_and_b32_e32 v247, 0xffff0000, v166
	v_pk_add_f32 v[102:103], v[102:103], v[246:247]
	v_lshlrev_b32_e32 v246, 16, v167
	v_and_b32_e32 v247, 0xffff0000, v167
	v_pk_add_f32 v[104:105], v[104:105], v[246:247]
	v_lshlrev_b32_e32 v246, 16, v168
	v_and_b32_e32 v247, 0xffff0000, v168
	v_pk_add_f32 v[98:99], v[98:99], v[246:247]
	v_lshlrev_b32_e32 v246, 16, v169
	v_and_b32_e32 v247, 0xffff0000, v169
	v_pk_add_f32 v[100:101], v[100:101], v[246:247]
	v_cvt_pk_bf16_f32 v166, v102, v103
	v_cvt_pk_bf16_f32 v167, v104, v105
	v_cvt_pk_bf16_f32 v168, v98, v99
	v_cvt_pk_bf16_f32 v169, v100, v101
	global_store_dwordx4 v245, v[166:169], s[68:69] offset:256 sc0 sc1
	v_fmac_f32_e32 v110, v102, v102
	v_fmac_f32_e32 v110, v103, v103
	v_fmac_f32_e32 v110, v104, v104
	v_fmac_f32_e32 v110, v105, v105
	v_fmac_f32_e32 v110, v98, v98
	v_fmac_f32_e32 v110, v99, v99
	v_fmac_f32_e32 v110, v100, v100
	v_fmac_f32_e32 v110, v101, v101
	s_add_u32 s68, s24, 0x40000
	s_addc_u32 s69, s25, 0
	s_waitcnt vmcnt(15)
	v_lshlrev_b32_e32 v246, 16, v170
	v_and_b32_e32 v247, 0xffff0000, v170
	v_pk_add_f32 v[94:95], v[94:95], v[246:247]
	v_lshlrev_b32_e32 v246, 16, v171
	v_and_b32_e32 v247, 0xffff0000, v171
	v_pk_add_f32 v[96:97], v[96:97], v[246:247]
	v_lshlrev_b32_e32 v246, 16, v172
	v_and_b32_e32 v247, 0xffff0000, v172
	v_pk_add_f32 v[90:91], v[90:91], v[246:247]
	v_lshlrev_b32_e32 v246, 16, v173
	v_and_b32_e32 v247, 0xffff0000, v173
	v_pk_add_f32 v[92:93], v[92:93], v[246:247]
	v_cvt_pk_bf16_f32 v170, v94, v95
	v_cvt_pk_bf16_f32 v171, v96, v97
	v_cvt_pk_bf16_f32 v172, v90, v91
	v_cvt_pk_bf16_f32 v173, v92, v93
	global_store_dwordx4 v245, v[170:173], s[68:69] sc0 sc1
	v_mul_f32_e32 v94, v94, v94
	v_fmac_f32_e32 v94, v95, v95
	v_fmac_f32_e32 v94, v96, v96
	v_fmac_f32_e32 v94, v97, v97
	v_fmac_f32_e32 v94, v90, v90
	v_fmac_f32_e32 v94, v91, v91
	v_fmac_f32_e32 v94, v92, v92
	v_fmac_f32_e32 v94, v93, v93
	s_waitcnt vmcnt(15)
	v_lshlrev_b32_e32 v246, 16, v174
	v_and_b32_e32 v247, 0xffff0000, v174
	v_pk_add_f32 v[86:87], v[86:87], v[246:247]
	v_lshlrev_b32_e32 v246, 16, v175
	v_and_b32_e32 v247, 0xffff0000, v175
	v_pk_add_f32 v[88:89], v[88:89], v[246:247]
	v_lshlrev_b32_e32 v246, 16, v176
	v_and_b32_e32 v247, 0xffff0000, v176
	v_pk_add_f32 v[82:83], v[82:83], v[246:247]
	v_lshlrev_b32_e32 v246, 16, v177
	v_and_b32_e32 v247, 0xffff0000, v177
	v_pk_add_f32 v[84:85], v[84:85], v[246:247]
	v_cvt_pk_bf16_f32 v174, v86, v87
	v_cvt_pk_bf16_f32 v175, v88, v89
	v_cvt_pk_bf16_f32 v176, v82, v83
	v_cvt_pk_bf16_f32 v177, v84, v85
	global_store_dwordx4 v245, v[174:177], s[68:69] offset:256 sc0 sc1
	v_fmac_f32_e32 v94, v86, v86
	v_fmac_f32_e32 v94, v87, v87
	v_fmac_f32_e32 v94, v88, v88
	v_fmac_f32_e32 v94, v89, v89
	v_fmac_f32_e32 v94, v82, v82
	v_fmac_f32_e32 v94, v83, v83
	v_fmac_f32_e32 v94, v84, v84
	v_fmac_f32_e32 v94, v85, v85
	s_add_u32 s68, s24, 0x60000
	s_addc_u32 s69, s25, 0
	s_waitcnt vmcnt(15)
	v_lshlrev_b32_e32 v246, 16, v178
	v_and_b32_e32 v247, 0xffff0000, v178
	v_pk_add_f32 v[78:79], v[78:79], v[246:247]
	v_lshlrev_b32_e32 v246, 16, v179
	v_and_b32_e32 v247, 0xffff0000, v179
	v_pk_add_f32 v[80:81], v[80:81], v[246:247]
	v_lshlrev_b32_e32 v246, 16, v180
	v_and_b32_e32 v247, 0xffff0000, v180
	v_pk_add_f32 v[74:75], v[74:75], v[246:247]
	v_lshlrev_b32_e32 v246, 16, v181
	v_and_b32_e32 v247, 0xffff0000, v181
	v_pk_add_f32 v[76:77], v[76:77], v[246:247]
	v_cvt_pk_bf16_f32 v178, v78, v79
	v_cvt_pk_bf16_f32 v179, v80, v81
	v_cvt_pk_bf16_f32 v180, v74, v75
	v_cvt_pk_bf16_f32 v181, v76, v77
	global_store_dwordx4 v245, v[178:181], s[68:69] sc0 sc1
	v_mul_f32_e32 v78, v78, v78
	v_fmac_f32_e32 v78, v79, v79
	v_fmac_f32_e32 v78, v80, v80
	v_fmac_f32_e32 v78, v81, v81
	v_fmac_f32_e32 v78, v74, v74
	v_fmac_f32_e32 v78, v75, v75
	v_fmac_f32_e32 v78, v76, v76
	v_fmac_f32_e32 v78, v77, v77
	s_waitcnt vmcnt(15)
	v_lshlrev_b32_e32 v246, 16, v182
	v_and_b32_e32 v247, 0xffff0000, v182
	v_pk_add_f32 v[70:71], v[70:71], v[246:247]
	v_lshlrev_b32_e32 v246, 16, v183
	v_and_b32_e32 v247, 0xffff0000, v183
	v_pk_add_f32 v[72:73], v[72:73], v[246:247]
	v_lshlrev_b32_e32 v246, 16, v184
	v_and_b32_e32 v247, 0xffff0000, v184
	v_pk_add_f32 v[66:67], v[66:67], v[246:247]
	v_lshlrev_b32_e32 v246, 16, v185
	v_and_b32_e32 v247, 0xffff0000, v185
	v_pk_add_f32 v[68:69], v[68:69], v[246:247]
	v_cvt_pk_bf16_f32 v182, v70, v71
	v_cvt_pk_bf16_f32 v183, v72, v73
	v_cvt_pk_bf16_f32 v184, v66, v67
	v_cvt_pk_bf16_f32 v185, v68, v69
	global_store_dwordx4 v245, v[182:185], s[68:69] offset:256 sc0 sc1
	v_fmac_f32_e32 v78, v70, v70
	v_fmac_f32_e32 v78, v71, v71
	v_fmac_f32_e32 v78, v72, v72
	v_fmac_f32_e32 v78, v73, v73
	v_fmac_f32_e32 v78, v66, v66
	v_fmac_f32_e32 v78, v67, v67
	v_fmac_f32_e32 v78, v68, v68
	v_fmac_f32_e32 v78, v69, v69
	s_add_u32 s68, s24, 0x100000
	s_addc_u32 s69, s25, 0
	s_waitcnt vmcnt(15)
	v_lshlrev_b32_e32 v246, 16, v188
	v_and_b32_e32 v247, 0xffff0000, v188
	v_pk_add_f32 v[62:63], v[62:63], v[246:247]
	v_lshlrev_b32_e32 v246, 16, v189
	v_and_b32_e32 v247, 0xffff0000, v189
	v_pk_add_f32 v[64:65], v[64:65], v[246:247]
	v_lshlrev_b32_e32 v246, 16, v190
	v_and_b32_e32 v247, 0xffff0000, v190
	v_pk_add_f32 v[58:59], v[58:59], v[246:247]
	v_lshlrev_b32_e32 v246, 16, v191
	v_and_b32_e32 v247, 0xffff0000, v191
	v_pk_add_f32 v[60:61], v[60:61], v[246:247]
	v_cvt_pk_bf16_f32 v188, v62, v63
	v_cvt_pk_bf16_f32 v189, v64, v65
	v_cvt_pk_bf16_f32 v190, v58, v59
	v_cvt_pk_bf16_f32 v191, v60, v61
	global_store_dwordx4 v245, v[188:191], s[68:69] sc0 sc1
	v_mul_f32_e32 v62, v62, v62
	v_fmac_f32_e32 v62, v63, v63
	v_fmac_f32_e32 v62, v64, v64
	v_fmac_f32_e32 v62, v65, v65
	v_fmac_f32_e32 v62, v58, v58
	v_fmac_f32_e32 v62, v59, v59
	v_fmac_f32_e32 v62, v60, v60
	v_fmac_f32_e32 v62, v61, v61
	s_waitcnt vmcnt(15)
	v_lshlrev_b32_e32 v246, 16, v192
	v_and_b32_e32 v247, 0xffff0000, v192
	v_pk_add_f32 v[54:55], v[54:55], v[246:247]
	v_lshlrev_b32_e32 v246, 16, v193
	v_and_b32_e32 v247, 0xffff0000, v193
	v_pk_add_f32 v[56:57], v[56:57], v[246:247]
	v_lshlrev_b32_e32 v246, 16, v194
	v_and_b32_e32 v247, 0xffff0000, v194
	v_pk_add_f32 v[50:51], v[50:51], v[246:247]
	v_lshlrev_b32_e32 v246, 16, v195
	v_and_b32_e32 v247, 0xffff0000, v195
	v_pk_add_f32 v[52:53], v[52:53], v[246:247]
	v_cvt_pk_bf16_f32 v192, v54, v55
	v_cvt_pk_bf16_f32 v193, v56, v57
	v_cvt_pk_bf16_f32 v194, v50, v51
	v_cvt_pk_bf16_f32 v195, v52, v53
	global_store_dwordx4 v245, v[192:195], s[68:69] offset:256 sc0 sc1
	v_fmac_f32_e32 v62, v54, v54
	v_fmac_f32_e32 v62, v55, v55
	v_fmac_f32_e32 v62, v56, v56
	v_fmac_f32_e32 v62, v57, v57
	v_fmac_f32_e32 v62, v50, v50
	v_fmac_f32_e32 v62, v51, v51
	v_fmac_f32_e32 v62, v52, v52
	v_fmac_f32_e32 v62, v53, v53
	s_add_u32 s68, s24, 0x120000
	s_addc_u32 s69, s25, 0
	s_waitcnt vmcnt(15)
	v_lshlrev_b32_e32 v246, 16, v196
	v_and_b32_e32 v247, 0xffff0000, v196
	v_pk_add_f32 v[46:47], v[46:47], v[246:247]
	v_lshlrev_b32_e32 v246, 16, v197
	v_and_b32_e32 v247, 0xffff0000, v197
	v_pk_add_f32 v[48:49], v[48:49], v[246:247]
	v_lshlrev_b32_e32 v246, 16, v198
	v_and_b32_e32 v247, 0xffff0000, v198
	v_pk_add_f32 v[42:43], v[42:43], v[246:247]
	v_lshlrev_b32_e32 v246, 16, v199
	v_and_b32_e32 v247, 0xffff0000, v199
	v_pk_add_f32 v[44:45], v[44:45], v[246:247]
	v_cvt_pk_bf16_f32 v196, v46, v47
	v_cvt_pk_bf16_f32 v197, v48, v49
	v_cvt_pk_bf16_f32 v198, v42, v43
	v_cvt_pk_bf16_f32 v199, v44, v45
	global_store_dwordx4 v245, v[196:199], s[68:69] sc0 sc1
	v_mul_f32_e32 v46, v46, v46
	v_fmac_f32_e32 v46, v47, v47
	v_fmac_f32_e32 v46, v48, v48
	v_fmac_f32_e32 v46, v49, v49
	v_fmac_f32_e32 v46, v42, v42
	v_fmac_f32_e32 v46, v43, v43
	v_fmac_f32_e32 v46, v44, v44
	v_fmac_f32_e32 v46, v45, v45
	s_waitcnt vmcnt(15)
	v_lshlrev_b32_e32 v246, 16, v200
	v_and_b32_e32 v247, 0xffff0000, v200
	v_pk_add_f32 v[38:39], v[38:39], v[246:247]
	v_lshlrev_b32_e32 v246, 16, v201
	v_and_b32_e32 v247, 0xffff0000, v201
	v_pk_add_f32 v[40:41], v[40:41], v[246:247]
	v_lshlrev_b32_e32 v246, 16, v202
	v_and_b32_e32 v247, 0xffff0000, v202
	v_pk_add_f32 v[34:35], v[34:35], v[246:247]
	v_lshlrev_b32_e32 v246, 16, v203
	v_and_b32_e32 v247, 0xffff0000, v203
	v_pk_add_f32 v[36:37], v[36:37], v[246:247]
	v_cvt_pk_bf16_f32 v200, v38, v39
	v_cvt_pk_bf16_f32 v201, v40, v41
	v_cvt_pk_bf16_f32 v202, v34, v35
	v_cvt_pk_bf16_f32 v203, v36, v37
	global_store_dwordx4 v245, v[200:203], s[68:69] offset:256 sc0 sc1
	v_fmac_f32_e32 v46, v38, v38
	v_fmac_f32_e32 v46, v39, v39
	v_fmac_f32_e32 v46, v40, v40
	v_fmac_f32_e32 v46, v41, v41
	v_fmac_f32_e32 v46, v34, v34
	v_fmac_f32_e32 v46, v35, v35
	v_fmac_f32_e32 v46, v36, v36
	v_fmac_f32_e32 v46, v37, v37
	s_add_u32 s68, s24, 0x140000
	s_addc_u32 s69, s25, 0
	s_waitcnt vmcnt(15)
	v_lshlrev_b32_e32 v246, 16, v204
	v_and_b32_e32 v247, 0xffff0000, v204
	v_pk_add_f32 v[30:31], v[30:31], v[246:247]
	v_lshlrev_b32_e32 v246, 16, v205
	v_and_b32_e32 v247, 0xffff0000, v205
	v_pk_add_f32 v[32:33], v[32:33], v[246:247]
	v_lshlrev_b32_e32 v246, 16, v206
	v_and_b32_e32 v247, 0xffff0000, v206
	v_pk_add_f32 v[26:27], v[26:27], v[246:247]
	v_lshlrev_b32_e32 v246, 16, v207
	v_and_b32_e32 v247, 0xffff0000, v207
	v_pk_add_f32 v[28:29], v[28:29], v[246:247]
	v_cvt_pk_bf16_f32 v204, v30, v31
	v_cvt_pk_bf16_f32 v205, v32, v33
	v_cvt_pk_bf16_f32 v206, v26, v27
	v_cvt_pk_bf16_f32 v207, v28, v29
	global_store_dwordx4 v245, v[204:207], s[68:69] sc0 sc1
	v_mul_f32_e32 v30, v30, v30
	v_fmac_f32_e32 v30, v31, v31
	v_fmac_f32_e32 v30, v32, v32
	v_fmac_f32_e32 v30, v33, v33
	v_fmac_f32_e32 v30, v26, v26
	v_fmac_f32_e32 v30, v27, v27
	v_fmac_f32_e32 v30, v28, v28
	v_fmac_f32_e32 v30, v29, v29
	s_waitcnt vmcnt(15)
	v_lshlrev_b32_e32 v246, 16, v208
	v_and_b32_e32 v247, 0xffff0000, v208
	v_pk_add_f32 v[22:23], v[22:23], v[246:247]
	v_lshlrev_b32_e32 v246, 16, v209
	v_and_b32_e32 v247, 0xffff0000, v209
	v_pk_add_f32 v[24:25], v[24:25], v[246:247]
	v_lshlrev_b32_e32 v246, 16, v210
	v_and_b32_e32 v247, 0xffff0000, v210
	v_pk_add_f32 v[18:19], v[18:19], v[246:247]
	v_lshlrev_b32_e32 v246, 16, v211
	v_and_b32_e32 v247, 0xffff0000, v211
	v_pk_add_f32 v[20:21], v[20:21], v[246:247]
	v_cvt_pk_bf16_f32 v208, v22, v23
	v_cvt_pk_bf16_f32 v209, v24, v25
	v_cvt_pk_bf16_f32 v210, v18, v19
	v_cvt_pk_bf16_f32 v211, v20, v21
	global_store_dwordx4 v245, v[208:211], s[68:69] offset:256 sc0 sc1
	v_fmac_f32_e32 v30, v22, v22
	v_fmac_f32_e32 v30, v23, v23
	v_fmac_f32_e32 v30, v24, v24
	v_fmac_f32_e32 v30, v25, v25
	v_fmac_f32_e32 v30, v18, v18
	v_fmac_f32_e32 v30, v19, v19
	v_fmac_f32_e32 v30, v20, v20
	v_fmac_f32_e32 v30, v21, v21
	s_add_u32 s68, s24, 0x160000
	s_addc_u32 s69, s25, 0
	s_waitcnt vmcnt(15)
	v_lshlrev_b32_e32 v246, 16, v212
	v_and_b32_e32 v247, 0xffff0000, v212
	v_pk_add_f32 v[14:15], v[14:15], v[246:247]
	v_lshlrev_b32_e32 v246, 16, v213
	v_and_b32_e32 v247, 0xffff0000, v213
	v_pk_add_f32 v[16:17], v[16:17], v[246:247]
	v_lshlrev_b32_e32 v246, 16, v214
	v_and_b32_e32 v247, 0xffff0000, v214
	v_pk_add_f32 v[10:11], v[10:11], v[246:247]
	v_lshlrev_b32_e32 v246, 16, v215
	v_and_b32_e32 v247, 0xffff0000, v215
	v_pk_add_f32 v[12:13], v[12:13], v[246:247]
	v_cvt_pk_bf16_f32 v212, v14, v15
	v_cvt_pk_bf16_f32 v213, v16, v17
	v_cvt_pk_bf16_f32 v214, v10, v11
	v_cvt_pk_bf16_f32 v215, v12, v13
	global_store_dwordx4 v245, v[212:215], s[68:69] sc0 sc1
	v_mul_f32_e32 v14, v14, v14
	v_fmac_f32_e32 v14, v15, v15
	v_fmac_f32_e32 v14, v16, v16
	v_fmac_f32_e32 v14, v17, v17
	v_fmac_f32_e32 v14, v10, v10
	v_fmac_f32_e32 v14, v11, v11
	v_fmac_f32_e32 v14, v12, v12
	v_fmac_f32_e32 v14, v13, v13
	s_waitcnt vmcnt(15)
	v_lshlrev_b32_e32 v246, 16, v216
	v_and_b32_e32 v247, 0xffff0000, v216
	v_pk_add_f32 v[6:7], v[6:7], v[246:247]
	v_lshlrev_b32_e32 v246, 16, v217
	v_and_b32_e32 v247, 0xffff0000, v217
	v_pk_add_f32 v[8:9], v[8:9], v[246:247]
	v_lshlrev_b32_e32 v246, 16, v218
	v_and_b32_e32 v247, 0xffff0000, v218
	v_pk_add_f32 v[2:3], v[2:3], v[246:247]
	v_lshlrev_b32_e32 v246, 16, v219
	v_and_b32_e32 v247, 0xffff0000, v219
	v_pk_add_f32 v[4:5], v[4:5], v[246:247]
	v_cvt_pk_bf16_f32 v216, v6, v7
	v_cvt_pk_bf16_f32 v217, v8, v9
	v_cvt_pk_bf16_f32 v218, v2, v3
	v_cvt_pk_bf16_f32 v219, v4, v5
	global_store_dwordx4 v245, v[216:219], s[68:69] offset:256 sc0 sc1
	v_fmac_f32_e32 v14, v6, v6
	v_fmac_f32_e32 v14, v7, v7
	v_fmac_f32_e32 v14, v8, v8
	v_fmac_f32_e32 v14, v9, v9
	v_fmac_f32_e32 v14, v2, v2
	v_fmac_f32_e32 v14, v3, v3
	v_fmac_f32_e32 v14, v4, v4
	v_fmac_f32_e32 v14, v5, v5
	v_mbcnt_lo_u32_b32 v246, -1, 0
	v_mbcnt_hi_u32_b32 v246, -1, v246
	v_xor_b32_e32 v247, 32, v246
	v_xor_b32_e32 v246, 16, v246
	v_lshlrev_b32_e32 v246, 2, v246
	v_lshlrev_b32_e32 v247, 2, v247
	ds_bpermute_b32 v127, v246, v126
	ds_bpermute_b32 v111, v246, v110
	ds_bpermute_b32 v95, v246, v94
	ds_bpermute_b32 v79, v246, v78
	ds_bpermute_b32 v63, v246, v62
	ds_bpermute_b32 v47, v246, v46
	ds_bpermute_b32 v31, v246, v30
	ds_bpermute_b32 v15, v246, v14
	s_waitcnt lgkmcnt(0)
	v_add_f32_e32 v126, v126, v127
	v_add_f32_e32 v110, v110, v111
	v_add_f32_e32 v94, v94, v95
	v_add_f32_e32 v78, v78, v79
	v_add_f32_e32 v62, v62, v63
	v_add_f32_e32 v46, v46, v47
	v_add_f32_e32 v30, v30, v31
	v_add_f32_e32 v14, v14, v15
	ds_bpermute_b32 v127, v247, v126
	ds_bpermute_b32 v111, v247, v110
	ds_bpermute_b32 v95, v247, v94
	ds_bpermute_b32 v79, v247, v78
	ds_bpermute_b32 v63, v247, v62
	ds_bpermute_b32 v47, v247, v46
	ds_bpermute_b32 v31, v247, v30
	ds_bpermute_b32 v15, v247, v14
	s_waitcnt lgkmcnt(0)
	v_add_f32_e32 v126, v126, v127
	v_add_f32_e32 v110, v110, v111
	v_add_f32_e32 v94, v94, v95
	v_add_f32_e32 v78, v78, v79
	v_add_f32_e32 v62, v62, v63
	v_add_f32_e32 v46, v46, v47
	v_add_f32_e32 v30, v30, v31
	v_add_f32_e32 v14, v14, v15
	v_lshl_add_u32 v246, s70, 8, v146
	v_lshlrev_b32_e32 v246, 2, v246
	s_and_saveexec_b64 s[68:69], s[8:9]
	global_atomic_add_f32 v246, v126, s[42:43]
	global_atomic_add_f32 v246, v110, s[42:43] offset:64
	global_atomic_add_f32 v246, v94, s[42:43] offset:128
	global_atomic_add_f32 v246, v78, s[42:43] offset:192
	global_atomic_add_f32 v246, v62, s[42:43] offset:512
	global_atomic_add_f32 v246, v46, s[42:43] offset:576
	global_atomic_add_f32 v246, v30, s[42:43] offset:640
	global_atomic_add_f32 v246, v14, s[42:43] offset:704
	s_mov_b64 exec, s[68:69]
	s_andn2_b64 vcc, exec, s[46:47]
	s_mov_b64 s[46:47], -1
	s_cbranch_vccnz .LBB0_1976
	s_andn2_b64 vcc, exec, s[10:11]
	s_cbranch_vccnz .LBB0_1975
	s_barrier
	s_branch .LBB0_1975

.LBB0_2029:
	s_waitcnt vmcnt(0) lgkmcnt(0)
	v_lshlrev_b32_e32 v77, 16, v63
	v_and_b32_e32 v63, 0xffff0000, v63
	v_lshlrev_b32_e32 v80, 16, v65
	v_and_b32_e32 v65, 0xffff0000, v65
	v_max_f32_e64 v78, |v63|, |v63|
	v_max_f32_e64 v79, |v77|, |v77|
	v_max_f32_e64 v81, |v65|, |v65|
	v_max_f32_e64 v82, |v80|, |v80|
	v_lshlrev_b32_e32 v76, 16, v62
	v_and_b32_e32 v62, 0xffff0000, v62
	v_max_f32_e32 v78, v79, v78
	v_lshlrev_b32_e32 v79, 16, v64
	v_and_b32_e32 v64, 0xffff0000, v64
	v_max_f32_e32 v81, v82, v81
	v_lshlrev_b32_e32 v82, 16, v59
	v_and_b32_e32 v59, 0xffff0000, v59
	v_lshlrev_b32_e32 v85, 16, v61
	v_and_b32_e32 v61, 0xffff0000, v61
	v_max3_f32 v78, |v76|, |v62|, v78
	v_max3_f32 v81, |v79|, |v64|, v81
	v_max_f32_e64 v83, |v59|, |v59|
	v_max_f32_e64 v84, |v82|, |v82|
	v_max_f32_e64 v86, |v61|, |v61|
	v_max_f32_e64 v87, |v85|, |v85|
	v_max3_f32 v78, v78, 0, v81
	v_lshlrev_b32_e32 v81, 16, v58
	v_and_b32_e32 v58, 0xffff0000, v58
	v_max_f32_e32 v83, v84, v83
	v_lshlrev_b32_e32 v84, 16, v60
	v_and_b32_e32 v60, 0xffff0000, v60
	v_max_f32_e32 v86, v87, v86
	v_max3_f32 v83, |v81|, |v58|, v83
	v_max3_f32 v86, |v84|, |v60|, v86
	v_max3_f32 v78, v78, v83, v86
	v_lshlrev_b32_e32 v86, 16, v55
	v_and_b32_e32 v55, 0xffff0000, v55
	v_lshlrev_b32_e32 v89, 16, v57
	v_and_b32_e32 v57, 0xffff0000, v57
	v_max_f32_e64 v87, |v55|, |v55|
	v_max_f32_e64 v88, |v86|, |v86|
	v_max_f32_e64 v90, |v57|, |v57|
	v_max_f32_e64 v91, |v89|, |v89|
	v_lshlrev_b32_e32 v83, 16, v54
	v_and_b32_e32 v54, 0xffff0000, v54
	v_max_f32_e32 v87, v88, v87
	v_lshlrev_b32_e32 v88, 16, v56
	v_and_b32_e32 v56, 0xffff0000, v56
	v_max_f32_e32 v90, v91, v90
	v_max3_f32 v87, |v83|, |v54|, v87
	v_max3_f32 v90, |v88|, |v56|, v90
	v_max3_f32 v78, v78, v87, v90
	v_lshlrev_b32_e32 v90, 16, v51
	v_and_b32_e32 v51, 0xffff0000, v51
	v_lshlrev_b32_e32 v93, 16, v53
	v_and_b32_e32 v53, 0xffff0000, v53
	v_max_f32_e64 v91, |v51|, |v51|
	v_max_f32_e64 v92, |v90|, |v90|
	v_max_f32_e64 v94, |v53|, |v53|
	v_max_f32_e64 v95, |v93|, |v93|
	v_lshlrev_b32_e32 v87, 16, v50
	v_and_b32_e32 v50, 0xffff0000, v50
	v_max_f32_e32 v91, v92, v91
	v_lshlrev_b32_e32 v92, 16, v52
	v_and_b32_e32 v52, 0xffff0000, v52
	v_max_f32_e32 v94, v95, v94
	v_max3_f32 v91, |v87|, |v50|, v91
	v_max3_f32 v94, |v92|, |v52|, v94
	v_max3_f32 v78, v78, v91, v94
	v_lshlrev_b32_e32 v94, 16, v47
	v_and_b32_e32 v47, 0xffff0000, v47
	v_lshlrev_b32_e32 v97, 16, v49
	v_and_b32_e32 v49, 0xffff0000, v49
	v_max_f32_e64 v95, |v47|, |v47|
	v_max_f32_e64 v96, |v94|, |v94|
	v_max_f32_e64 v98, |v49|, |v49|
	v_max_f32_e64 v99, |v97|, |v97|
	v_lshlrev_b32_e32 v91, 16, v46
	v_and_b32_e32 v46, 0xffff0000, v46
	v_max_f32_e32 v95, v96, v95
	v_lshlrev_b32_e32 v96, 16, v48
	v_and_b32_e32 v48, 0xffff0000, v48
	v_max_f32_e32 v98, v99, v98
	v_max3_f32 v95, |v91|, |v46|, v95
	v_max3_f32 v98, |v96|, |v48|, v98
	v_max3_f32 v78, v78, v95, v98
	v_lshlrev_b32_e32 v98, 16, v43
	v_and_b32_e32 v43, 0xffff0000, v43
	v_lshlrev_b32_e32 v101, 16, v45
	v_and_b32_e32 v45, 0xffff0000, v45
	v_max_f32_e64 v99, |v43|, |v43|
	v_max_f32_e64 v100, |v98|, |v98|
	v_max_f32_e64 v102, |v45|, |v45|
	v_max_f32_e64 v103, |v101|, |v101|
	v_lshlrev_b32_e32 v95, 16, v42
	v_and_b32_e32 v42, 0xffff0000, v42
	v_max_f32_e32 v99, v100, v99
	v_lshlrev_b32_e32 v100, 16, v44
	v_and_b32_e32 v44, 0xffff0000, v44
	v_max_f32_e32 v102, v103, v102
	v_max3_f32 v99, |v95|, |v42|, v99
	v_max3_f32 v102, |v100|, |v44|, v102
	v_lshlrev_b32_e32 v103, 16, v39
	v_and_b32_e32 v104, 0xffff0000, v39
	v_max3_f32 v78, v78, v99, v102
	v_lshlrev_b32_e32 v99, 16, v38
	v_and_b32_e32 v102, 0xffff0000, v38
	v_max_f32_e64 v38, |v104|, |v104|
	v_max_f32_e64 v39, |v103|, |v103|
	v_lshlrev_b32_e32 v106, 16, v41
	v_and_b32_e32 v41, 0xffff0000, v41
	v_max_f32_e32 v38, v39, v38
	v_max_f32_e64 v39, |v41|, |v41|
	v_max_f32_e64 v107, |v106|, |v106|
	v_lshlrev_b32_e32 v105, 16, v40
	v_and_b32_e32 v40, 0xffff0000, v40
	v_max_f32_e32 v39, v107, v39
	v_max3_f32 v38, |v99|, |v102|, v38
	v_max3_f32 v39, |v105|, |v40|, v39
	v_lshlrev_b32_e32 v108, 16, v35
	v_and_b32_e32 v109, 0xffff0000, v35
	v_max3_f32 v38, v78, v38, v39
	v_lshlrev_b32_e32 v78, 16, v34
	v_and_b32_e32 v107, 0xffff0000, v34
	v_max_f32_e64 v34, |v109|, |v109|
	v_max_f32_e64 v35, |v108|, |v108|
	v_lshlrev_b32_e32 v112, 16, v37
	v_and_b32_e32 v37, 0xffff0000, v37
	v_max_f32_e32 v34, v35, v34
	v_lshlrev_b32_e32 v110, 16, v36
	v_and_b32_e32 v111, 0xffff0000, v36
	v_max_f32_e64 v35, |v37|, |v37|
	v_max_f32_e64 v36, |v112|, |v112|
	v_max_f32_e32 v35, v36, v35
	v_max3_f32 v34, |v78|, |v107|, v34
	v_max3_f32 v35, |v110|, |v111|, v35
	v_max3_f32 v34, v38, v34, v35
	ds_bpermute_b32 v35, v70, v34
	s_waitcnt lgkmcnt(0)
	v_max_f32_e32 v35, v35, v35
	v_max_f32_e32 v34, v34, v35
	ds_bpermute_b32 v35, v71, v34
	s_waitcnt lgkmcnt(0)
	v_max_f32_e32 v35, v35, v35
	v_max_f32_e32 v34, v34, v35
	ds_bpermute_b32 v35, v72, v34
	s_waitcnt lgkmcnt(0)
	v_max_f32_e32 v35, v35, v35
	v_max_f32_e32 v34, v34, v35
	ds_bpermute_b32 v35, v73, v34
	s_waitcnt lgkmcnt(0)
	v_max_f32_e32 v35, v35, v35
	v_max_f32_e32 v34, v34, v35
	ds_bpermute_b32 v35, v74, v34
	s_waitcnt lgkmcnt(0)
	v_max_f32_e32 v35, v35, v35
	v_max_f32_e32 v34, v34, v35
	ds_bpermute_b32 v35, v75, v34
	s_waitcnt lgkmcnt(0)
	v_max_f32_e32 v35, v35, v35
	v_max_f32_e32 v36, v34, v35
	v_div_scale_f32 v34, s[6:7], v36, v36, s15
	v_rcp_f32_e32 v35, v34
	s_nop 0
	v_fma_f32 v38, -v34, v35, 1.0
	v_fmac_f32_e32 v35, v38, v35
	v_div_scale_f32 v38, vcc, s15, v36, s15
	v_mul_f32_e32 v39, v38, v35
	v_fma_f32 v113, -v34, v39, v38
	v_fmac_f32_e32 v39, v113, v35
	v_fma_f32 v34, -v34, v39, v38
	v_div_fmas_f32 v34, v34, v35, v39
	v_div_fixup_f32 v34, v34, v36, s15
	v_cmp_lt_f32_e32 vcc, 0, v36
	s_nop 1
	v_cndmask_b32_e32 v113, 0, v34, vcc
	v_mul_f32_e32 v35, v113, v62
	v_mul_f32_e32 v34, v113, v76
	v_rndne_f32_e32 v35, v35
	v_mul_f32_e32 v38, v113, v77
	v_mul_f32_e32 v39, v113, v63
	v_rndne_f32_e32 v34, v34
	v_cvt_i32_f32_e32 v35, v35
	v_rndne_f32_e32 v38, v38
	v_rndne_f32_e32 v39, v39
	v_mul_f32_e32 v63, v113, v64
	v_cvt_i32_f32_e32 v34, v34
	v_cvt_i32_f32_sdwa v38, v38 dst_sel:WORD_1 dst_unused:UNUSED_PAD src0_sel:DWORD
	v_cvt_i32_f32_e32 v39, v39
	v_mul_f32_e32 v62, v113, v79
	v_rndne_f32_e32 v63, v63
	v_mul_f32_e32 v64, v113, v80
	v_mul_f32_e32 v65, v113, v65
	v_rndne_f32_e32 v62, v62
	v_cvt_i32_f32_e32 v63, v63
	v_rndne_f32_e32 v64, v64
	v_rndne_f32_e32 v65, v65
	v_cvt_i32_f32_e32 v62, v62
	v_cvt_i32_f32_sdwa v64, v64 dst_sel:WORD_1 dst_unused:UNUSED_PAD src0_sel:DWORD
	v_cvt_i32_f32_e32 v65, v65
	v_lshlrev_b32_e32 v35, 8, v35
	v_and_b32_e32 v35, 0xff00, v35
	v_and_b32_e32 v38, 0xff0000, v38
	v_perm_b32 v34, v39, v34, s26
	v_or3_b32 v38, v34, v35, v38
	v_lshlrev_b32_e32 v34, 8, v63
	v_and_b32_e32 v34, 0xff00, v34
	v_and_b32_e32 v35, 0xff0000, v64
	v_perm_b32 v39, v65, v62, s26
	v_or3_b32 v39, v39, v34, v35
	v_lshl_add_u64 v[34:35], s[22:23], 0, v[66:67]
	v_add_co_u32_e32 v34, vcc, s27, v34
	v_mul_f32_e32 v59, v113, v59
	s_nop 0
	v_addc_co_u32_e32 v35, vcc, 0, v35, vcc
	flat_store_dwordx2 v[34:35], v[38:39] sc0 sc1
	v_mul_f32_e32 v39, v113, v58
	v_mul_f32_e32 v38, v113, v81
	v_rndne_f32_e32 v39, v39
	v_mul_f32_e32 v58, v113, v82
	v_rndne_f32_e32 v38, v38
	v_cvt_i32_f32_e32 v39, v39
	v_rndne_f32_e32 v58, v58
	v_rndne_f32_e32 v59, v59
	v_mul_f32_e32 v60, v113, v60
	v_cvt_i32_f32_e32 v38, v38
	v_cvt_i32_f32_sdwa v58, v58 dst_sel:WORD_1 dst_unused:UNUSED_PAD src0_sel:DWORD
	v_cvt_i32_f32_e32 v59, v59
	v_mul_f32_e32 v62, v113, v84
	v_rndne_f32_e32 v60, v60
	v_mul_f32_e32 v63, v113, v85
	v_mul_f32_e32 v61, v113, v61
	v_rndne_f32_e32 v62, v62
	v_cvt_i32_f32_e32 v60, v60
	v_rndne_f32_e32 v63, v63
	v_rndne_f32_e32 v61, v61
	v_cvt_i32_f32_e32 v62, v62
	v_cvt_i32_f32_sdwa v63, v63 dst_sel:WORD_1 dst_unused:UNUSED_PAD src0_sel:DWORD
	v_cvt_i32_f32_e32 v61, v61
	v_lshlrev_b32_e32 v39, 8, v39
	v_and_b32_e32 v39, 0xff00, v39
	v_and_b32_e32 v58, 0xff0000, v58
	v_perm_b32 v38, v59, v38, s26
	v_or3_b32 v38, v38, v39, v58
	v_lshlrev_b32_e32 v39, 8, v60
	v_and_b32_e32 v39, 0xff00, v39
	v_and_b32_e32 v58, 0xff0000, v63
	v_perm_b32 v59, v61, v62, s26
	v_or3_b32 v39, v59, v39, v58
	flat_store_dwordx2 v[34:35], v[38:39] offset:512 sc0 sc1
	v_mul_f32_e32 v39, v113, v54
	v_mul_f32_e32 v38, v113, v83
	v_rndne_f32_e32 v39, v39
	v_mul_f32_e32 v54, v113, v86
	v_mul_f32_e32 v55, v113, v55
	v_rndne_f32_e32 v38, v38
	v_cvt_i32_f32_e32 v39, v39
	v_rndne_f32_e32 v54, v54
	v_rndne_f32_e32 v55, v55
	v_mul_f32_e32 v56, v113, v56
	v_cvt_i32_f32_e32 v38, v38
	v_cvt_i32_f32_sdwa v54, v54 dst_sel:WORD_1 dst_unused:UNUSED_PAD src0_sel:DWORD
	v_cvt_i32_f32_e32 v55, v55
	v_mul_f32_e32 v58, v113, v88
	v_rndne_f32_e32 v56, v56
	v_mul_f32_e32 v59, v113, v89
	v_mul_f32_e32 v57, v113, v57
	v_rndne_f32_e32 v58, v58
	v_cvt_i32_f32_e32 v56, v56
	v_rndne_f32_e32 v59, v59
	v_rndne_f32_e32 v57, v57
	v_cvt_i32_f32_e32 v58, v58
	v_cvt_i32_f32_sdwa v59, v59 dst_sel:WORD_1 dst_unused:UNUSED_PAD src0_sel:DWORD
	v_cvt_i32_f32_e32 v57, v57
	v_lshlrev_b32_e32 v39, 8, v39
	v_and_b32_e32 v39, 0xff00, v39
	v_and_b32_e32 v54, 0xff0000, v54
	v_perm_b32 v38, v55, v38, s26
	v_or3_b32 v38, v38, v39, v54
	v_lshlrev_b32_e32 v39, 8, v56
	v_and_b32_e32 v39, 0xff00, v39
	v_and_b32_e32 v54, 0xff0000, v59
	v_perm_b32 v55, v57, v58, s26
	v_or3_b32 v39, v55, v39, v54
	flat_store_dwordx2 v[34:35], v[38:39] offset:1024 sc0 sc1
	v_mul_f32_e32 v39, v113, v50
	v_mul_f32_e32 v38, v113, v87
	v_rndne_f32_e32 v39, v39
	v_mul_f32_e32 v50, v113, v90
	v_mul_f32_e32 v51, v113, v51
	v_rndne_f32_e32 v38, v38
	v_cvt_i32_f32_e32 v39, v39
	v_rndne_f32_e32 v50, v50
	v_rndne_f32_e32 v51, v51
	v_mul_f32_e32 v52, v113, v52
	v_cvt_i32_f32_e32 v38, v38
	v_cvt_i32_f32_sdwa v50, v50 dst_sel:WORD_1 dst_unused:UNUSED_PAD src0_sel:DWORD
	v_cvt_i32_f32_e32 v51, v51
	v_mul_f32_e32 v54, v113, v92
	v_rndne_f32_e32 v52, v52
	v_mul_f32_e32 v55, v113, v93
	v_mul_f32_e32 v53, v113, v53
	v_rndne_f32_e32 v54, v54
	v_cvt_i32_f32_e32 v52, v52
	v_rndne_f32_e32 v55, v55
	v_rndne_f32_e32 v53, v53
	v_cvt_i32_f32_e32 v54, v54
	v_cvt_i32_f32_sdwa v55, v55 dst_sel:WORD_1 dst_unused:UNUSED_PAD src0_sel:DWORD
	v_cvt_i32_f32_e32 v53, v53
	v_lshlrev_b32_e32 v39, 8, v39
	v_and_b32_e32 v39, 0xff00, v39
	v_and_b32_e32 v50, 0xff0000, v50
	v_perm_b32 v38, v51, v38, s26
	v_or3_b32 v38, v38, v39, v50
	v_lshlrev_b32_e32 v39, 8, v52
	v_and_b32_e32 v39, 0xff00, v39
	v_and_b32_e32 v50, 0xff0000, v55
	v_perm_b32 v51, v53, v54, s26
	v_or3_b32 v39, v51, v39, v50
	flat_store_dwordx2 v[34:35], v[38:39] offset:1536 sc0 sc1
	v_mul_f32_e32 v39, v113, v46
	v_mul_f32_e32 v38, v113, v91
	v_rndne_f32_e32 v39, v39
	v_mul_f32_e32 v46, v113, v94
	v_mul_f32_e32 v47, v113, v47
	v_rndne_f32_e32 v38, v38
	v_cvt_i32_f32_e32 v39, v39
	v_rndne_f32_e32 v46, v46
	v_rndne_f32_e32 v47, v47
	v_mul_f32_e32 v48, v113, v48
	v_cvt_i32_f32_e32 v38, v38
	v_cvt_i32_f32_sdwa v46, v46 dst_sel:WORD_1 dst_unused:UNUSED_PAD src0_sel:DWORD
	v_cvt_i32_f32_e32 v47, v47
	v_mul_f32_e32 v50, v113, v96
	v_rndne_f32_e32 v48, v48
	v_mul_f32_e32 v51, v113, v97
	v_mul_f32_e32 v49, v113, v49
	v_rndne_f32_e32 v50, v50
	v_cvt_i32_f32_e32 v48, v48
	v_rndne_f32_e32 v51, v51
	v_rndne_f32_e32 v49, v49
	v_cvt_i32_f32_e32 v50, v50
	v_cvt_i32_f32_sdwa v51, v51 dst_sel:WORD_1 dst_unused:UNUSED_PAD src0_sel:DWORD
	v_cvt_i32_f32_e32 v49, v49
	v_lshlrev_b32_e32 v39, 8, v39
	v_and_b32_e32 v39, 0xff00, v39
	v_and_b32_e32 v46, 0xff0000, v46
	v_perm_b32 v38, v47, v38, s26
	v_or3_b32 v38, v38, v39, v46
	v_lshlrev_b32_e32 v39, 8, v48
	v_and_b32_e32 v39, 0xff00, v39
	v_and_b32_e32 v46, 0xff0000, v51
	v_perm_b32 v47, v49, v50, s26
	v_or3_b32 v39, v47, v39, v46
	flat_store_dwordx2 v[34:35], v[38:39] offset:2048 sc0 sc1
	v_mul_f32_e32 v39, v113, v42
	v_mul_f32_e32 v38, v113, v95
	v_rndne_f32_e32 v39, v39
	v_mul_f32_e32 v42, v113, v98
	v_mul_f32_e32 v43, v113, v43
	v_rndne_f32_e32 v38, v38
	v_cvt_i32_f32_e32 v39, v39
	v_rndne_f32_e32 v42, v42
	v_rndne_f32_e32 v43, v43
	v_mul_f32_e32 v44, v113, v44
	v_cvt_i32_f32_e32 v38, v38
	v_cvt_i32_f32_sdwa v42, v42 dst_sel:WORD_1 dst_unused:UNUSED_PAD src0_sel:DWORD
	v_cvt_i32_f32_e32 v43, v43
	v_mul_f32_e32 v46, v113, v100
	v_rndne_f32_e32 v44, v44
	v_mul_f32_e32 v47, v113, v101
	v_mul_f32_e32 v45, v113, v45
	v_rndne_f32_e32 v46, v46
	v_cvt_i32_f32_e32 v44, v44
	v_rndne_f32_e32 v47, v47
	v_rndne_f32_e32 v45, v45
	v_cvt_i32_f32_e32 v46, v46
	v_cvt_i32_f32_sdwa v47, v47 dst_sel:WORD_1 dst_unused:UNUSED_PAD src0_sel:DWORD
	v_cvt_i32_f32_e32 v45, v45
	v_lshlrev_b32_e32 v39, 8, v39
	v_and_b32_e32 v39, 0xff00, v39
	v_and_b32_e32 v42, 0xff0000, v42
	v_perm_b32 v38, v43, v38, s26
	v_or3_b32 v38, v38, v39, v42
	v_lshlrev_b32_e32 v39, 8, v44
	v_and_b32_e32 v39, 0xff00, v39
	v_and_b32_e32 v42, 0xff0000, v47
	v_perm_b32 v43, v45, v46, s26
	v_or3_b32 v39, v43, v39, v42
	flat_store_dwordx2 v[34:35], v[38:39] offset:2560 sc0 sc1
	v_mul_f32_e32 v39, v113, v102
	v_mul_f32_e32 v38, v113, v99
	v_rndne_f32_e32 v39, v39
	v_mul_f32_e32 v42, v113, v103
	v_mul_f32_e32 v43, v113, v104
	v_rndne_f32_e32 v38, v38
	v_cvt_i32_f32_e32 v39, v39
	v_rndne_f32_e32 v42, v42
	v_rndne_f32_e32 v43, v43
	v_mul_f32_e32 v40, v113, v40
	v_cvt_i32_f32_e32 v38, v38
	v_cvt_i32_f32_sdwa v42, v42 dst_sel:WORD_1 dst_unused:UNUSED_PAD src0_sel:DWORD
	v_cvt_i32_f32_e32 v43, v43
	v_mul_f32_e32 v44, v113, v105
	v_rndne_f32_e32 v40, v40
	v_mul_f32_e32 v45, v113, v106
	v_mul_f32_e32 v41, v113, v41
	v_rndne_f32_e32 v44, v44
	v_cvt_i32_f32_e32 v40, v40
	v_rndne_f32_e32 v45, v45
	v_rndne_f32_e32 v41, v41
	v_cvt_i32_f32_e32 v44, v44
	v_cvt_i32_f32_sdwa v45, v45 dst_sel:WORD_1 dst_unused:UNUSED_PAD src0_sel:DWORD
	v_cvt_i32_f32_e32 v41, v41
	v_lshlrev_b32_e32 v39, 8, v39
	v_and_b32_e32 v39, 0xff00, v39
	v_and_b32_e32 v42, 0xff0000, v42
	v_perm_b32 v38, v43, v38, s26
	v_or3_b32 v38, v38, v39, v42
	v_lshlrev_b32_e32 v39, 8, v40
	v_and_b32_e32 v39, 0xff00, v39
	v_and_b32_e32 v40, 0xff0000, v45
	v_perm_b32 v41, v41, v44, s26
	v_or3_b32 v39, v41, v39, v40
	flat_store_dwordx2 v[34:35], v[38:39] offset:3072 sc0 sc1
	v_mul_f32_e32 v39, v113, v107
	v_mul_f32_e32 v38, v113, v78
	v_rndne_f32_e32 v39, v39
	v_mul_f32_e32 v40, v113, v108
	v_mul_f32_e32 v41, v113, v109
	v_rndne_f32_e32 v38, v38
	v_cvt_i32_f32_e32 v39, v39
	v_rndne_f32_e32 v40, v40
	v_rndne_f32_e32 v41, v41
	v_mul_f32_e32 v43, v113, v111
	v_cvt_i32_f32_e32 v38, v38
	v_cvt_i32_f32_sdwa v40, v40 dst_sel:WORD_1 dst_unused:UNUSED_PAD src0_sel:DWORD
	v_cvt_i32_f32_e32 v41, v41
	v_mul_f32_e32 v42, v113, v110
	v_rndne_f32_e32 v43, v43
	v_mul_f32_e32 v44, v113, v112
	v_mul_f32_e32 v37, v113, v37
	v_rndne_f32_e32 v42, v42
	v_cvt_i32_f32_e32 v43, v43
	v_rndne_f32_e32 v44, v44
	v_rndne_f32_e32 v37, v37
	v_cvt_i32_f32_e32 v42, v42
	v_cvt_i32_f32_sdwa v44, v44 dst_sel:WORD_1 dst_unused:UNUSED_PAD src0_sel:DWORD
	v_cvt_i32_f32_e32 v37, v37
	v_lshlrev_b32_e32 v39, 8, v39
	v_and_b32_e32 v39, 0xff00, v39
	v_and_b32_e32 v40, 0xff0000, v40
	v_perm_b32 v38, v41, v38, s26
	v_or3_b32 v38, v38, v39, v40
	v_lshlrev_b32_e32 v39, 8, v43
	v_and_b32_e32 v39, 0xff00, v39
	v_and_b32_e32 v40, 0xff0000, v44
	v_perm_b32 v37, v37, v42, s26
	v_or3_b32 v39, v37, v39, v40
	flat_store_dwordx2 v[34:35], v[38:39] offset:3584 sc0 sc1
	s_and_saveexec_b64 s[60:61], s[8:9]
	s_cbranch_execz .LBB0_2031
	s_add_u32 s6, s22, s40
	s_addc_u32 s7, s23, s41
	v_mul_f32_e32 v36, 0x3c010204, v36
	v_mov_b64_e32 v[34:35], s[6:7]
	flat_store_dword v[34:35], v36 sc0 sc1

.LBB0_2067:
	ds_read_b128 v[2:5], v185
	ds_read_b128 v[6:9], v185 offset:1024
	ds_read_b128 v[138:141], v185 offset:2048
	ds_read_b128 v[142:145], v185 offset:3072
	ds_read_b128 v[146:149], v186
	ds_read_b128 v[150:153], v186 offset:1024
	ds_read_b128 v[170:173], v186 offset:2048
	ds_read_b128 v[174:177], v186 offset:3072
	s_add_u32 s6, s10, 0xfff80080
	s_addc_u32 s7, s11, -1
	s_cmp_eq_u32 s85, 28
	s_cselect_b32 s15, s28, s7
	s_cselect_b32 s14, s29, s6
	s_cselect_b32 s13, s65, s84
	s_cselect_b32 s12, s67, s83
	s_add_i32 m0, s39, 0xc000
	ds_read_b128 v[178:181], v187
	ds_read_b128 v[190:193], v187 offset:1024
	ds_read_b128 v[194:197], v187 offset:2048
	ds_read_b128 v[198:201], v187 offset:3072
	ds_read_b128 v[202:205], v187 offset:4096
	ds_read_b128 v[206:209], v187 offset:5120
	ds_read_b128 v[210:213], v187 offset:6144
	ds_read_b128 v[214:217], v187 offset:7168
	global_load_lds_dwordx4 v164, s[10:11]
	s_add_i32 m0, s39, 0xe000
	s_nop 0
	global_load_lds_dwordx4 v162, s[10:11]
	s_waitcnt vmcnt(8)
	s_waitcnt lgkmcnt(0)
	s_barrier
	s_setprio 1
	s_waitcnt lgkmcnt(0)
	v_mfma_i32_16x16x64_i8 v[134:137], v[2:5], v[178:181], v[134:137]
	v_mfma_i32_16x16x64_i8 v[126:129], v[138:141], v[178:181], v[126:129]
	v_mfma_i32_16x16x64_i8 v[118:121], v[2:5], v[194:197], v[118:121]
	v_mfma_i32_16x16x64_i8 v[110:113], v[138:141], v[194:197], v[110:113]
	v_mfma_i32_16x16x64_i8 v[102:105], v[2:5], v[202:205], v[102:105]
	v_mfma_i32_16x16x64_i8 v[94:97], v[138:141], v[202:205], v[94:97]
	v_mfma_i32_16x16x64_i8 v[86:89], v[2:5], v[210:213], v[86:89]
	v_mfma_i32_16x16x64_i8 v[78:81], v[138:141], v[210:213], v[78:81]
	v_mfma_i32_16x16x64_i8 v[134:137], v[6:9], v[190:193], v[134:137]
	v_mfma_i32_16x16x64_i8 v[126:129], v[142:145], v[190:193], v[126:129]
	v_mfma_i32_16x16x64_i8 v[118:121], v[6:9], v[198:201], v[118:121]
	v_mfma_i32_16x16x64_i8 v[110:113], v[142:145], v[198:201], v[110:113]
	v_mfma_i32_16x16x64_i8 v[102:105], v[6:9], v[206:209], v[102:105]
	v_mfma_i32_16x16x64_i8 v[94:97], v[142:145], v[206:209], v[94:97]
	v_mfma_i32_16x16x64_i8 v[86:89], v[6:9], v[214:217], v[86:89]
	v_mfma_i32_16x16x64_i8 v[78:81], v[142:145], v[214:217], v[78:81]
	s_setprio 0
	s_setprio 1
	v_mfma_i32_16x16x64_i8 v[130:133], v[146:149], v[178:181], v[130:133]
	v_mfma_i32_16x16x64_i8 v[122:125], v[170:173], v[178:181], v[122:125]
	v_mfma_i32_16x16x64_i8 v[114:117], v[146:149], v[194:197], v[114:117]
	v_mfma_i32_16x16x64_i8 v[106:109], v[170:173], v[194:197], v[106:109]
	v_mfma_i32_16x16x64_i8 v[98:101], v[146:149], v[202:205], v[98:101]
	v_mfma_i32_16x16x64_i8 v[90:93], v[170:173], v[202:205], v[90:93]
	v_mfma_i32_16x16x64_i8 v[82:85], v[146:149], v[210:213], v[82:85]
	v_mfma_i32_16x16x64_i8 v[74:77], v[170:173], v[210:213], v[74:77]
	v_mfma_i32_16x16x64_i8 v[130:133], v[150:153], v[190:193], v[130:133]
	v_mfma_i32_16x16x64_i8 v[122:125], v[174:177], v[190:193], v[122:125]
	v_mfma_i32_16x16x64_i8 v[114:117], v[150:153], v[198:201], v[114:117]
	v_mfma_i32_16x16x64_i8 v[106:109], v[174:177], v[198:201], v[106:109]
	v_mfma_i32_16x16x64_i8 v[98:101], v[150:153], v[206:209], v[98:101]
	v_mfma_i32_16x16x64_i8 v[90:93], v[174:177], v[206:209], v[90:93]
	v_mfma_i32_16x16x64_i8 v[82:85], v[150:153], v[214:217], v[82:85]
	v_mfma_i32_16x16x64_i8 v[74:77], v[174:177], v[214:217], v[74:77]
	s_setprio 0
	s_barrier
	s_add_i32 s6, s79, s63
	v_lshl_add_u64 v[218:219], s[12:13], 0, v[156:157]
	s_mov_b32 m0, s6
	ds_read_b128 v[178:181], v187 offset:16384
	ds_read_b128 v[190:193], v187 offset:17408
	ds_read_b128 v[194:197], v187 offset:18432
	ds_read_b128 v[198:201], v187 offset:19456
	ds_read_b128 v[202:205], v187 offset:20480
	ds_read_b128 v[206:209], v187 offset:21504
	ds_read_b128 v[210:213], v187 offset:22528
	ds_read_b128 v[214:217], v187 offset:23552
	global_load_lds_dwordx4 v[218:219], off
	s_add_i32 m0, s6, 0x2000
	s_add_u32 s6, s12, 0x80000
	v_lshl_add_u64 v[220:221], s[12:13], 0, v[160:161]
	s_addc_u32 s7, s13, 0
	s_add_i32 s16, s80, s63
	global_load_lds_dwordx4 v[220:221], off
	s_mov_b32 m0, s16
	v_lshl_add_u64 v[224:225], s[14:15], 0, v[158:159]
	global_load_lds_dwordx4 v156, s[6:7]
	s_add_i32 m0, s16, 0x2000
	s_nop 0
	global_load_lds_dwordx4 v160, s[6:7]
	v_lshl_add_u64 v[222:223], s[14:15], 0, v[154:155]
	s_mov_b32 m0, s39
	s_nop 0
	global_load_lds_dwordx4 v[222:223], off
	s_mov_b32 m0, s72
	s_nop 0
	global_load_lds_dwordx4 v[224:225], off
	s_waitcnt vmcnt(8)
	s_waitcnt lgkmcnt(0)
	s_barrier
	s_setprio 1
	s_waitcnt lgkmcnt(0)
	v_mfma_i32_16x16x64_i8 v[70:73], v[2:5], v[178:181], v[70:73]
	v_mfma_i32_16x16x64_i8 v[62:65], v[138:141], v[178:181], v[62:65]
	v_mfma_i32_16x16x64_i8 v[54:57], v[2:5], v[194:197], v[54:57]
	v_mfma_i32_16x16x64_i8 v[46:49], v[138:141], v[194:197], v[46:49]
	v_mfma_i32_16x16x64_i8 v[38:41], v[2:5], v[202:205], v[38:41]
	v_mfma_i32_16x16x64_i8 v[30:33], v[138:141], v[202:205], v[30:33]
	v_mfma_i32_16x16x64_i8 v[2:5], v[2:5], v[210:213], v[22:25]
	v_mfma_i32_16x16x64_i8 v[70:73], v[6:9], v[190:193], v[70:73]
	v_mfma_i32_16x16x64_i8 v[62:65], v[142:145], v[190:193], v[62:65]
	v_mfma_i32_16x16x64_i8 v[54:57], v[6:9], v[198:201], v[54:57]
	v_mfma_i32_16x16x64_i8 v[46:49], v[142:145], v[198:201], v[46:49]
	v_mfma_i32_16x16x64_i8 v[38:41], v[6:9], v[206:209], v[38:41]
	v_mfma_i32_16x16x64_i8 v[30:33], v[142:145], v[206:209], v[30:33]
	v_mfma_i32_16x16x64_i8 v[2:5], v[6:9], v[214:217], v[2:5]
	v_mfma_i32_16x16x64_i8 v[6:9], v[138:141], v[210:213], v[14:17]
	v_mfma_i32_16x16x64_i8 v[6:9], v[142:145], v[214:217], v[6:9]
	s_setprio 0
	s_setprio 1
	v_mfma_i32_16x16x64_i8 v[14:17], v[146:149], v[178:181], v[66:69]
	v_mfma_i32_16x16x64_i8 v[66:69], v[150:153], v[190:193], v[14:17]
	v_mfma_i32_16x16x64_i8 v[14:17], v[170:173], v[178:181], v[58:61]
	v_mfma_i32_16x16x64_i8 v[58:61], v[174:177], v[190:193], v[14:17]
	v_mfma_i32_16x16x64_i8 v[14:17], v[146:149], v[194:197], v[50:53]
	v_mfma_i32_16x16x64_i8 v[50:53], v[150:153], v[198:201], v[14:17]
	v_mfma_i32_16x16x64_i8 v[14:17], v[170:173], v[194:197], v[42:45]
	v_mfma_i32_16x16x64_i8 v[42:45], v[174:177], v[198:201], v[14:17]
	v_mfma_i32_16x16x64_i8 v[14:17], v[146:149], v[202:205], v[34:37]
	v_mfma_i32_16x16x64_i8 v[34:37], v[150:153], v[206:209], v[14:17]
	v_mfma_i32_16x16x64_i8 v[14:17], v[170:173], v[202:205], v[26:29]
	v_mfma_i32_16x16x64_i8 v[26:29], v[174:177], v[206:209], v[14:17]
	v_mfma_i32_16x16x64_i8 v[14:17], v[146:149], v[210:213], v[18:21]
	v_mfma_i32_16x16x64_i8 v[10:13], v[170:173], v[210:213], v[10:13]
	v_mfma_i32_16x16x64_i8 v[18:21], v[150:153], v[214:217], v[14:17]
	v_mfma_i32_16x16x64_i8 v[10:13], v[174:177], v[214:217], v[10:13]
	s_setprio 0
	s_barrier
	s_add_i32 s16, 0, 0x18000
	s_add_i32 s17, 0, 0x1c000
	v_add_u32_e32 v142, s16, v183
	v_add_u32_e32 v174, s17, v183
	ds_read_b128 v[14:17], v142
	ds_read_b128 v[22:25], v142 offset:1024
	ds_read_b128 v[138:141], v142 offset:2048
	ds_read_b128 v[142:145], v142 offset:3072
	ds_read_b128 v[146:149], v174
	ds_read_b128 v[150:153], v174 offset:1024
	ds_read_b128 v[170:173], v174 offset:2048
	ds_read_b128 v[174:177], v174 offset:3072
	s_add_u32 s6, s14, 0x80000
	s_addc_u32 s7, s15, 0
	s_mov_b32 m0, s73
	ds_read_b128 v[178:181], v187 offset:32768
	ds_read_b128 v[190:193], v187 offset:33792
	ds_read_b128 v[194:197], v187 offset:34816
	ds_read_b128 v[198:201], v187 offset:35840
	ds_read_b128 v[202:205], v187 offset:36864
	ds_read_b128 v[206:209], v187 offset:37888
	ds_read_b128 v[210:213], v187 offset:38912
	ds_read_b128 v[214:217], v187 offset:39936
	global_load_lds_dwordx4 v154, s[6:7]
	s_mov_b32 m0, s74
	s_nop 0
	global_load_lds_dwordx4 v158, s[6:7]
	s_waitcnt vmcnt(8)
	s_waitcnt lgkmcnt(0)
	s_barrier
	s_setprio 1
	s_waitcnt lgkmcnt(0)
	v_mfma_i32_16x16x64_i8 v[134:137], v[14:17], v[178:181], v[134:137]
	v_mfma_i32_16x16x64_i8 v[126:129], v[138:141], v[178:181], v[126:129]
	v_mfma_i32_16x16x64_i8 v[118:121], v[14:17], v[194:197], v[118:121]
	v_mfma_i32_16x16x64_i8 v[110:113], v[138:141], v[194:197], v[110:113]
	v_mfma_i32_16x16x64_i8 v[102:105], v[14:17], v[202:205], v[102:105]
	v_mfma_i32_16x16x64_i8 v[94:97], v[138:141], v[202:205], v[94:97]
	v_mfma_i32_16x16x64_i8 v[86:89], v[14:17], v[210:213], v[86:89]
	v_mfma_i32_16x16x64_i8 v[78:81], v[138:141], v[210:213], v[78:81]
	v_mfma_i32_16x16x64_i8 v[134:137], v[22:25], v[190:193], v[134:137]
	v_mfma_i32_16x16x64_i8 v[126:129], v[142:145], v[190:193], v[126:129]
	v_mfma_i32_16x16x64_i8 v[118:121], v[22:25], v[198:201], v[118:121]
	v_mfma_i32_16x16x64_i8 v[110:113], v[142:145], v[198:201], v[110:113]
	v_mfma_i32_16x16x64_i8 v[102:105], v[22:25], v[206:209], v[102:105]
	v_mfma_i32_16x16x64_i8 v[94:97], v[142:145], v[206:209], v[94:97]
	v_mfma_i32_16x16x64_i8 v[86:89], v[22:25], v[214:217], v[86:89]
	v_mfma_i32_16x16x64_i8 v[78:81], v[142:145], v[214:217], v[78:81]
	s_setprio 0
	s_setprio 1
	v_mfma_i32_16x16x64_i8 v[130:133], v[146:149], v[178:181], v[130:133]
	v_mfma_i32_16x16x64_i8 v[122:125], v[170:173], v[178:181], v[122:125]
	v_mfma_i32_16x16x64_i8 v[114:117], v[146:149], v[194:197], v[114:117]
	v_mfma_i32_16x16x64_i8 v[106:109], v[170:173], v[194:197], v[106:109]
	v_mfma_i32_16x16x64_i8 v[98:101], v[146:149], v[202:205], v[98:101]
	v_mfma_i32_16x16x64_i8 v[90:93], v[170:173], v[202:205], v[90:93]
	v_mfma_i32_16x16x64_i8 v[82:85], v[146:149], v[210:213], v[82:85]
	v_mfma_i32_16x16x64_i8 v[74:77], v[170:173], v[210:213], v[74:77]
	v_mfma_i32_16x16x64_i8 v[130:133], v[150:153], v[190:193], v[130:133]
	v_mfma_i32_16x16x64_i8 v[122:125], v[174:177], v[190:193], v[122:125]
	v_mfma_i32_16x16x64_i8 v[114:117], v[150:153], v[198:201], v[114:117]
	v_mfma_i32_16x16x64_i8 v[106:109], v[174:177], v[198:201], v[106:109]
	v_mfma_i32_16x16x64_i8 v[98:101], v[150:153], v[206:209], v[98:101]
	v_mfma_i32_16x16x64_i8 v[90:93], v[174:177], v[206:209], v[90:93]
	v_mfma_i32_16x16x64_i8 v[82:85], v[150:153], v[214:217], v[82:85]
	v_mfma_i32_16x16x64_i8 v[74:77], v[174:177], v[214:217], v[74:77]
	s_setprio 0
	s_barrier
	s_add_i32 s6, s16, s63
	v_lshl_add_u64 v[218:219], v[218:219], 0, s[46:47]
	s_mov_b32 m0, s6
	ds_read_b128 v[178:181], v187 offset:49152
	ds_read_b128 v[190:193], v187 offset:50176
	ds_read_b128 v[194:197], v187 offset:51200
	ds_read_b128 v[198:201], v187 offset:52224
	ds_read_b128 v[202:205], v187 offset:53248
	ds_read_b128 v[206:209], v187 offset:54272
	ds_read_b128 v[210:213], v187 offset:55296
	ds_read_b128 v[214:217], v187 offset:56320
	global_load_lds_dwordx4 v[218:219], off
	s_add_i32 m0, s6, 0x2000
	s_add_u32 s6, s12, 0x80080
	v_lshl_add_u64 v[218:219], v[220:221], 0, s[46:47]
	s_addc_u32 s7, s13, 0
	s_add_i32 s12, s17, s63
	global_load_lds_dwordx4 v[218:219], off
	s_mov_b32 m0, s12
	s_nop 0
	global_load_lds_dwordx4 v156, s[6:7]
	s_add_i32 m0, s12, 0x2000
	s_nop 0
	global_load_lds_dwordx4 v160, s[6:7]
	v_lshl_add_u64 v[218:219], v[222:223], 0, s[46:47]
	s_mov_b32 m0, s76
	s_nop 0
	global_load_lds_dwordx4 v[218:219], off
	v_lshl_add_u64 v[218:219], v[224:225], 0, s[46:47]
	s_mov_b32 m0, s77
	s_nop 0
	global_load_lds_dwordx4 v[218:219], off
	s_waitcnt vmcnt(8)
	s_waitcnt lgkmcnt(0)
	s_barrier
	s_setprio 1
	s_waitcnt lgkmcnt(0)
	v_mfma_i32_16x16x64_i8 v[70:73], v[14:17], v[178:181], v[70:73]
	v_mfma_i32_16x16x64_i8 v[54:57], v[14:17], v[194:197], v[54:57]
	v_mfma_i32_16x16x64_i8 v[38:41], v[14:17], v[202:205], v[38:41]
	v_mfma_i32_16x16x64_i8 v[2:5], v[14:17], v[210:213], v[2:5]
	v_mfma_i32_16x16x64_i8 v[70:73], v[22:25], v[190:193], v[70:73]
	v_mfma_i32_16x16x64_i8 v[62:65], v[138:141], v[178:181], v[62:65]
	v_mfma_i32_16x16x64_i8 v[54:57], v[22:25], v[198:201], v[54:57]
	v_mfma_i32_16x16x64_i8 v[46:49], v[138:141], v[194:197], v[46:49]
	v_mfma_i32_16x16x64_i8 v[38:41], v[22:25], v[206:209], v[38:41]
	v_mfma_i32_16x16x64_i8 v[30:33], v[138:141], v[202:205], v[30:33]
	v_mfma_i32_16x16x64_i8 v[22:25], v[22:25], v[214:217], v[2:5]
	v_mfma_i32_16x16x64_i8 v[2:5], v[138:141], v[210:213], v[6:9]
	v_mfma_i32_16x16x64_i8 v[62:65], v[142:145], v[190:193], v[62:65]
	v_mfma_i32_16x16x64_i8 v[46:49], v[142:145], v[198:201], v[46:49]
	v_mfma_i32_16x16x64_i8 v[30:33], v[142:145], v[206:209], v[30:33]
	v_mfma_i32_16x16x64_i8 v[14:17], v[142:145], v[214:217], v[2:5]
	s_setprio 0
	s_setprio 1
	v_mfma_i32_16x16x64_i8 v[2:5], v[146:149], v[178:181], v[66:69]
	v_mfma_i32_16x16x64_i8 v[66:69], v[150:153], v[190:193], v[2:5]
	v_mfma_i32_16x16x64_i8 v[2:5], v[170:173], v[178:181], v[58:61]
	v_mfma_i32_16x16x64_i8 v[58:61], v[174:177], v[190:193], v[2:5]
	v_mfma_i32_16x16x64_i8 v[2:5], v[146:149], v[194:197], v[50:53]
	v_mfma_i32_16x16x64_i8 v[50:53], v[150:153], v[198:201], v[2:5]
	v_mfma_i32_16x16x64_i8 v[2:5], v[170:173], v[194:197], v[42:45]
	v_mfma_i32_16x16x64_i8 v[42:45], v[174:177], v[198:201], v[2:5]
	v_mfma_i32_16x16x64_i8 v[2:5], v[146:149], v[202:205], v[34:37]
	v_mfma_i32_16x16x64_i8 v[34:37], v[150:153], v[206:209], v[2:5]
	v_mfma_i32_16x16x64_i8 v[2:5], v[170:173], v[202:205], v[26:29]
	v_mfma_i32_16x16x64_i8 v[26:29], v[174:177], v[206:209], v[2:5]
	v_mfma_i32_16x16x64_i8 v[2:5], v[146:149], v[210:213], v[18:21]
	v_mfma_i32_16x16x64_i8 v[18:21], v[150:153], v[214:217], v[2:5]
	v_mfma_i32_16x16x64_i8 v[2:5], v[170:173], v[210:213], v[10:13]
	v_mfma_i32_16x16x64_i8 v[10:13], v[174:177], v[214:217], v[2:5]
	s_setprio 0
	s_barrier
	s_add_i32 s85, s85, 2
	s_add_u32 s83, s83, 0x100
	s_addc_u32 s84, s84, 0
	s_add_u32 s10, s10, 0x100
	s_addc_u32 s11, s11, 0
	s_cmp_gt_u32 s85, 29
	s_cbranch_scc0 .LBB0_2067
	s_and_b64 vcc, exec, s[60:61]
	s_cbranch_vccz .LBB0_2070
	s_barrier

.LBB0_2074:
	v_lshl_or_b32 v138, s26, 8, v184
	v_ashrrev_i32_e32 v139, 31, v138
	v_lshl_add_u64 v[138:139], v[138:139], 2, s[44:45]
	flat_load_dwordx4 v[150:153], v[138:139]
	flat_load_dwordx4 v[146:149], v[138:139] offset:512
	flat_load_dwordx4 v[142:145], v[138:139] offset:16
	s_nop 0
	flat_load_dwordx4 v[138:141], v[138:139] offset:528
	v_cvt_f32_i32_e32 v135, v135
	v_cvt_f32_i32_e32 v134, v134
	v_cvt_f32_i32_e32 v131, v131
	v_cvt_f32_i32_e32 v130, v130
	v_cvt_f32_i32_e32 v137, v137
	v_cvt_f32_i32_e32 v136, v136
	v_cvt_f32_i32_e32 v133, v133
	v_cvt_f32_i32_e32 v132, v132
	v_cvt_f32_i32_e32 v127, v127
	v_cvt_f32_i32_e32 v126, v126
	v_cvt_f32_i32_e32 v193, v123
	v_cvt_f32_i32_e32 v192, v122
	v_cvt_f32_i32_e32 v129, v129
	v_cvt_f32_i32_e32 v128, v128
	v_cvt_f32_i32_e32 v195, v115
	v_cvt_f32_i32_e32 v194, v114
	v_lshl_or_b32 v190, s26, 7, v184
	v_ashrrev_i32_e32 v191, 31, v190
	v_lshlrev_b64 v[114:115], 1, v[190:191]
	v_cvt_f32_i32_e32 v125, v125
	v_cvt_f32_i32_e32 v124, v124
	v_mov_b64_e32 v[122:123], s[30:31]
	v_cvt_f32_i32_e32 v121, v121
	v_cvt_f32_i32_e32 v120, v120
	v_cvt_f32_i32_e32 v117, v117
	v_cvt_f32_i32_e32 v116, v116
	v_cvt_f32_i32_e32 v111, v111
	v_cvt_f32_i32_e32 v110, v110
	v_mad_u64_u32 v[196:197], s[6:7], v180, s82, v[122:123]
	v_mov_b32_e32 v180, v197
	v_mad_u64_u32 v[180:181], s[6:7], v181, s82, v[180:181]
	v_mov_b32_e32 v197, v180
	v_cvt_f32_i32_e32 v119, v119
	v_cvt_f32_i32_e32 v118, v118
	v_lshl_add_u64 v[180:181], v[196:197], 0, v[114:115]
	v_cvt_f32_i32_e32 v107, v107
	v_cvt_f32_i32_e32 v106, v106
	v_cvt_f32_i32_e32 v113, v113
	v_cvt_f32_i32_e32 v112, v112
	v_cvt_f32_i32_e32 v103, v103
	v_cvt_f32_i32_e32 v102, v102
	v_cvt_f32_i32_e32 v99, v99
	v_cvt_f32_i32_e32 v98, v98
	v_cvt_f32_i32_e32 v105, v105
	v_cvt_f32_i32_e32 v104, v104
	v_cvt_f32_i32_e32 v101, v101
	v_cvt_f32_i32_e32 v100, v100
	v_cvt_f32_i32_e32 v95, v95
	v_cvt_f32_i32_e32 v94, v94
	v_cvt_f32_i32_e32 v91, v91
	v_cvt_f32_i32_e32 v90, v90
	v_cvt_f32_i32_e32 v97, v97
	v_cvt_f32_i32_e32 v96, v96
	v_cvt_f32_i32_e32 v83, v83
	v_cvt_f32_i32_e32 v82, v82
	v_cvt_f32_i32_e32 v89, v89
	v_cvt_f32_i32_e32 v88, v88
	v_cvt_f32_i32_e32 v85, v85
	v_cvt_f32_i32_e32 v84, v84
	v_cvt_f32_i32_e32 v79, v79
	v_cvt_f32_i32_e32 v78, v78
	v_cvt_f32_i32_e32 v75, v75
	v_cvt_f32_i32_e32 v74, v74
	v_cvt_f32_i32_e32 v81, v81
	v_cvt_f32_i32_e32 v80, v80
	v_cvt_f32_i32_e32 v77, v77
	v_cvt_f32_i32_e32 v76, v76
	v_cvt_f32_i32_e32 v71, v71
	v_cvt_f32_i32_e32 v70, v70
	v_cvt_f32_i32_e32 v67, v67
	v_cvt_f32_i32_e32 v66, v66
	v_cvt_f32_i32_e32 v69, v69
	v_cvt_f32_i32_e32 v68, v68
	v_cvt_f32_i32_e32 v63, v63
	s_waitcnt vmcnt(0) lgkmcnt(0)
	v_pk_mul_f32 v[134:135], v[150:151], v[134:135]
	v_pk_mul_f32 v[130:131], v[146:147], v[130:131]
	v_pk_mul_f32 v[136:137], v[152:153], v[136:137]
	v_pk_mul_f32 v[132:133], v[148:149], v[132:133]
	v_pk_mul_f32 v[126:127], v[142:143], v[126:127]
	v_pk_mul_f32 v[190:191], v[138:139], v[192:193]
	v_pk_mul_f32 v[128:129], v[144:145], v[128:129]
	v_pk_mul_f32 v[134:135], v[2:3], v[134:135] op_sel_hi:[0,1]
	v_pk_mul_f32 v[130:131], v[2:3], v[130:131] op_sel_hi:[0,1]
	v_pk_mul_f32 v[136:137], v[2:3], v[136:137] op_sel_hi:[0,1]
	v_pk_mul_f32 v[132:133], v[2:3], v[132:133] op_sel_hi:[0,1]
	v_pk_mul_f32 v[126:127], v[2:3], v[126:127] op_sel_hi:[0,1]
	v_pk_mul_f32 v[192:193], v[146:147], v[194:195]
	v_pk_mul_f32 v[190:191], v[2:3], v[190:191] op_sel_hi:[0,1]
	v_pk_mul_f32 v[128:129], v[2:3], v[128:129] op_sel_hi:[0,1]
	v_pk_mul_f32 v[194:195], v[134:135], s[62:63] op_sel_hi:[1,0]
	v_pk_mul_f32 v[130:131], v[134:135], v[130:131]
	v_pk_mul_f32 v[134:135], v[136:137], s[62:63] op_sel_hi:[1,0]
	v_pk_mul_f32 v[132:133], v[136:137], v[132:133]
	v_pk_mul_f32 v[136:137], v[126:127], s[62:63] op_sel_hi:[1,0]
	v_pk_mul_f32 v[126:127], v[126:127], v[190:191]
	v_pk_mul_f32 v[190:191], v[128:129], s[62:63] op_sel_hi:[1,0]
	v_exp_f32_e32 v136, v136
	v_exp_f32_e32 v137, v137
	v_exp_f32_e32 v194, v194
	v_exp_f32_e32 v195, v195
	v_exp_f32_e32 v134, v134
	v_exp_f32_e32 v135, v135
	v_exp_f32_e32 v190, v190
	v_exp_f32_e32 v191, v191
	v_pk_add_f32 v[136:137], v[136:137], 1.0 op_sel_hi:[1,0]
	v_pk_add_f32 v[194:195], v[194:195], 1.0 op_sel_hi:[1,0]
	v_pk_add_f32 v[134:135], v[134:135], 1.0 op_sel_hi:[1,0]
	v_pk_add_f32 v[190:191], v[190:191], 1.0 op_sel_hi:[1,0]
	v_rcp_f32_e32 v136, v136
	v_rcp_f32_e32 v137, v137
	v_rcp_f32_e32 v194, v194
	v_rcp_f32_e32 v195, v195
	v_rcp_f32_e32 v134, v134
	v_rcp_f32_e32 v135, v135
	v_rcp_f32_e32 v190, v190
	v_rcp_f32_e32 v191, v191
	v_pk_mul_f32 v[124:125], v[140:141], v[124:125]
	v_pk_mul_f32 v[126:127], v[126:127], v[136:137]
	v_pk_mul_f32 v[124:125], v[2:3], v[124:125] op_sel_hi:[0,1]
	v_pk_mul_f32 v[124:125], v[128:129], v[124:125]
	v_pk_mul_f32 v[120:121], v[152:153], v[120:121]
	v_pk_mul_f32 v[116:117], v[148:149], v[116:117]
	v_pk_mul_f32 v[110:111], v[142:143], v[110:111]
	v_pk_mul_f32 v[130:131], v[130:131], v[194:195]
	v_pk_mul_f32 v[132:133], v[132:133], v[134:135]
	v_pk_mul_f32 v[134:135], v[124:125], v[190:191]
	s_nop 0
	v_cvt_pk_bf16_f32 v124, v130, v131
	s_nop 0
	v_cvt_pk_bf16_f32 v125, v132, v133
	s_nop 0
	v_cvt_pk_bf16_f32 v126, v126, v127
	v_pk_mul_f32 v[120:121], v[2:3], v[120:121] op_sel:[1,0]
	s_nop 0
	v_cvt_pk_bf16_f32 v127, v134, v135
	v_pk_mul_f32 v[116:117], v[2:3], v[116:117] op_sel:[1,0]
	v_pk_mul_f32 v[110:111], v[2:3], v[110:111] op_sel:[1,0]
	flat_store_dwordx4 v[180:181], v[124:127] sc0 sc1
	v_pk_mul_f32 v[116:117], v[120:121], v[116:117]
	v_pk_mul_f32 v[118:119], v[150:151], v[118:119]
	v_pk_mul_f32 v[126:127], v[120:121], s[62:63] op_sel_hi:[1,0]
	v_pk_mul_f32 v[120:121], v[110:111], s[62:63] op_sel_hi:[1,0]
	v_pk_mul_f32 v[106:107], v[138:139], v[106:107]
	v_exp_f32_e32 v120, v120
	v_exp_f32_e32 v121, v121
	v_pk_mul_f32 v[118:119], v[2:3], v[118:119] op_sel:[1,0]
	v_pk_mul_f32 v[106:107], v[2:3], v[106:107] op_sel:[1,0]
	v_pk_mul_f32 v[128:129], v[118:119], s[62:63] op_sel_hi:[1,0]
	v_pk_add_f32 v[120:121], v[120:121], 1.0 op_sel_hi:[1,0]
	v_pk_mul_f32 v[106:107], v[110:111], v[106:107]
	v_pk_mul_f32 v[110:111], v[144:145], v[112:113]
	v_exp_f32_e32 v128, v128
	v_exp_f32_e32 v129, v129
	v_rcp_f32_e32 v120, v120
	v_rcp_f32_e32 v121, v121
	v_pk_mul_f32 v[110:111], v[2:3], v[110:111] op_sel:[1,0]
	v_pk_add_f32 v[124:125], v[128:129], 1.0 op_sel_hi:[1,0]
	v_pk_mul_f32 v[112:113], v[110:111], s[62:63] op_sel_hi:[1,0]
	v_pk_mul_f32 v[120:121], v[106:107], v[120:121]
	v_exp_f32_e32 v112, v112
	v_exp_f32_e32 v113, v113
	v_cvt_f32_i32_e32 v107, v109
	v_cvt_f32_i32_e32 v106, v108
	v_rcp_f32_e32 v124, v124
	v_rcp_f32_e32 v125, v125
	v_exp_f32_e32 v126, v126
	v_exp_f32_e32 v127, v127
	v_pk_add_f32 v[108:109], v[112:113], 1.0 op_sel_hi:[1,0]
	v_pk_mul_f32 v[192:193], v[2:3], v[192:193] op_sel:[1,0]
	v_rcp_f32_e32 v108, v108
	v_rcp_f32_e32 v109, v109
	v_pk_mul_f32 v[118:119], v[118:119], v[192:193]
	v_pk_mul_f32 v[106:107], v[140:141], v[106:107]
	v_pk_mul_f32 v[118:119], v[118:119], v[124:125]
	v_pk_add_f32 v[124:125], v[126:127], 1.0 op_sel_hi:[1,0]
	v_pk_mul_f32 v[2:3], v[2:3], v[106:107] op_sel:[1,0]
	v_rcp_f32_e32 v124, v124
	v_rcp_f32_e32 v125, v125
	v_pk_mul_f32 v[2:3], v[110:111], v[2:3]
	v_mad_u64_u32 v[106:107], s[6:7], v176, s82, v[122:123]
	v_pk_mul_f32 v[2:3], v[2:3], v[108:109]
	v_mov_b32_e32 v108, v107
	v_mad_u64_u32 v[108:109], s[6:7], v177, s82, v[108:109]
	v_mov_b32_e32 v107, v108
	v_pk_mul_f32 v[116:117], v[116:117], v[124:125]
	v_lshl_add_u64 v[110:111], v[106:107], 0, v[114:115]
	s_nop 0
	v_cvt_pk_bf16_f32 v106, v118, v119
	s_nop 0
	v_cvt_pk_bf16_f32 v107, v116, v117
	s_nop 0
	v_cvt_pk_bf16_f32 v108, v120, v121
	s_nop 0
	v_cvt_pk_bf16_f32 v109, v2, v3
	v_pk_mul_f32 v[2:3], v[150:151], v[102:103]
	v_pk_mul_f32 v[98:99], v[146:147], v[98:99]
	v_pk_mul_f32 v[2:3], v[4:5], v[2:3] op_sel_hi:[0,1]
	v_pk_mul_f32 v[98:99], v[4:5], v[98:99] op_sel_hi:[0,1]
	v_pk_mul_f32 v[102:103], v[2:3], s[62:63] op_sel_hi:[1,0]
	v_pk_mul_f32 v[2:3], v[2:3], v[98:99]
	v_pk_mul_f32 v[98:99], v[152:153], v[104:105]
	v_pk_mul_f32 v[100:101], v[148:149], v[100:101]
	v_pk_mul_f32 v[94:95], v[142:143], v[94:95]
	v_pk_mul_f32 v[98:99], v[4:5], v[98:99] op_sel_hi:[0,1]
	v_pk_mul_f32 v[100:101], v[4:5], v[100:101] op_sel_hi:[0,1]
	v_pk_mul_f32 v[94:95], v[4:5], v[94:95] op_sel_hi:[0,1]
	v_pk_mul_f32 v[104:105], v[98:99], s[62:63] op_sel_hi:[1,0]
	v_pk_mul_f32 v[98:99], v[98:99], v[100:101]
	v_pk_mul_f32 v[100:101], v[94:95], s[62:63] op_sel_hi:[1,0]
	v_pk_mul_f32 v[90:91], v[138:139], v[90:91]
	v_exp_f32_e32 v100, v100
	v_exp_f32_e32 v101, v101
	v_pk_mul_f32 v[90:91], v[4:5], v[90:91] op_sel_hi:[0,1]
	v_pk_mul_f32 v[90:91], v[94:95], v[90:91]
	v_pk_mul_f32 v[94:95], v[144:145], v[96:97]
	v_pk_add_f32 v[100:101], v[100:101], 1.0 op_sel_hi:[1,0]
	v_pk_mul_f32 v[94:95], v[4:5], v[94:95] op_sel_hi:[0,1]
	v_rcp_f32_e32 v100, v100
	v_rcp_f32_e32 v101, v101
	v_pk_mul_f32 v[96:97], v[94:95], s[62:63] op_sel_hi:[1,0]
	v_exp_f32_e32 v102, v102
	v_exp_f32_e32 v96, v96
	v_exp_f32_e32 v97, v97
	v_pk_mul_f32 v[100:101], v[90:91], v[100:101]
	v_cvt_f32_i32_e32 v91, v93
	v_cvt_f32_i32_e32 v90, v92
	v_exp_f32_e32 v103, v103
	v_pk_add_f32 v[92:93], v[96:97], 1.0 op_sel_hi:[1,0]
	flat_store_dwordx4 v[110:111], v[106:109] sc0 sc1
	v_rcp_f32_e32 v92, v92
	v_rcp_f32_e32 v93, v93
	v_pk_mul_f32 v[90:91], v[140:141], v[90:91]
	v_pk_add_f32 v[102:103], v[102:103], 1.0 op_sel_hi:[1,0]
	v_pk_mul_f32 v[90:91], v[4:5], v[90:91] op_sel_hi:[0,1]
	v_rcp_f32_e32 v102, v102
	v_rcp_f32_e32 v103, v103
	v_pk_mul_f32 v[90:91], v[94:95], v[90:91]
	v_pk_mul_f32 v[82:83], v[146:147], v[82:83]
	v_pk_mul_f32 v[94:95], v[90:91], v[92:93]
	v_mad_u64_u32 v[90:91], s[6:7], v174, s82, v[122:123]
	v_mov_b32_e32 v4, v91
	v_mad_u64_u32 v[92:93], s[6:7], v175, s82, v[4:5]
	v_pk_mul_f32 v[2:3], v[2:3], v[102:103]
	v_mov_b32_e32 v91, v92
	v_lshl_add_u64 v[96:97], v[90:91], 0, v[114:115]
	s_nop 0
	v_cvt_pk_bf16_f32 v90, v2, v3
	v_cvt_f32_i32_e32 v3, v87
	v_cvt_f32_i32_e32 v2, v86
	v_mov_b32_e32 v4, v5
	v_pk_mul_f32 v[82:83], v[4:5], v[82:83] op_sel_hi:[0,1]
	v_pk_mul_f32 v[84:85], v[148:149], v[84:85]
	v_pk_mul_f32 v[2:3], v[150:151], v[2:3]
	v_pk_mul_f32 v[78:79], v[142:143], v[78:79]
	v_pk_mul_f32 v[2:3], v[4:5], v[2:3] op_sel_hi:[0,1]
	v_pk_mul_f32 v[86:87], v[2:3], s[62:63] op_sel_hi:[1,0]
	v_pk_mul_f32 v[2:3], v[2:3], v[82:83]
	v_pk_mul_f32 v[82:83], v[152:153], v[88:89]
	v_pk_mul_f32 v[74:75], v[138:139], v[74:75]
	v_pk_mul_f32 v[82:83], v[4:5], v[82:83] op_sel_hi:[0,1]
	v_pk_mul_f32 v[84:85], v[4:5], v[84:85] op_sel_hi:[0,1]
	v_pk_mul_f32 v[78:79], v[4:5], v[78:79] op_sel_hi:[0,1]
	v_pk_mul_f32 v[74:75], v[4:5], v[74:75] op_sel_hi:[0,1]
	v_pk_mul_f32 v[88:89], v[82:83], s[62:63] op_sel_hi:[1,0]
	v_pk_mul_f32 v[82:83], v[82:83], v[84:85]
	v_pk_mul_f32 v[84:85], v[78:79], s[62:63] op_sel_hi:[1,0]
	v_pk_mul_f32 v[74:75], v[78:79], v[74:75]
	v_pk_mul_f32 v[78:79], v[144:145], v[80:81]
	v_exp_f32_e32 v86, v86
	v_pk_mul_f32 v[78:79], v[4:5], v[78:79] op_sel_hi:[0,1]
	v_exp_f32_e32 v87, v87
	v_pk_mul_f32 v[80:81], v[78:79], s[62:63] op_sel_hi:[1,0]
	v_exp_f32_e32 v84, v84
	v_exp_f32_e32 v80, v80
	v_exp_f32_e32 v81, v81
	v_pk_add_f32 v[86:87], v[86:87], 1.0 op_sel_hi:[1,0]
	v_exp_f32_e32 v85, v85
	v_exp_f32_e32 v104, v104
	v_exp_f32_e32 v105, v105
	v_rcp_f32_e32 v86, v86
	v_rcp_f32_e32 v87, v87
	v_exp_f32_e32 v88, v88
	v_exp_f32_e32 v89, v89
	v_pk_add_f32 v[80:81], v[80:81], 1.0 op_sel_hi:[1,0]
	v_pk_mul_f32 v[76:77], v[140:141], v[76:77]
	v_rcp_f32_e32 v80, v80
	v_rcp_f32_e32 v81, v81
	v_pk_add_f32 v[84:85], v[84:85], 1.0 op_sel_hi:[1,0]
	v_pk_mul_f32 v[4:5], v[4:5], v[76:77] op_sel_hi:[0,1]
	v_pk_add_f32 v[102:103], v[104:105], 1.0 op_sel_hi:[1,0]
	v_pk_mul_f32 v[2:3], v[2:3], v[86:87]
	v_pk_add_f32 v[86:87], v[88:89], 1.0 op_sel_hi:[1,0]
	v_rcp_f32_e32 v84, v84
	v_rcp_f32_e32 v85, v85
	v_pk_mul_f32 v[4:5], v[78:79], v[4:5]
	v_rcp_f32_e32 v102, v102
	v_rcp_f32_e32 v103, v103
	v_rcp_f32_e32 v86, v86
	v_rcp_f32_e32 v87, v87
	v_pk_mul_f32 v[76:77], v[4:5], v[80:81]
	v_mad_u64_u32 v[4:5], s[6:7], v172, s82, v[122:123]
	v_mov_b32_e32 v78, v5
	v_mad_u64_u32 v[78:79], s[6:7], v173, s82, v[78:79]
	v_pk_mul_f32 v[70:71], v[150:151], v[70:71]
	v_pk_mul_f32 v[74:75], v[74:75], v[84:85]
	v_mov_b32_e32 v5, v78
	v_pk_mul_f32 v[70:71], v[6:7], v[70:71] op_sel_hi:[0,1]
	v_pk_mul_f32 v[98:99], v[98:99], v[102:103]
	v_pk_mul_f32 v[82:83], v[82:83], v[86:87]
	s_nop 0
	v_cvt_pk_bf16_f32 v91, v98, v99
	s_nop 0
	v_cvt_pk_bf16_f32 v92, v100, v101
	s_nop 0
	v_cvt_pk_bf16_f32 v93, v94, v95
	flat_store_dwordx4 v[96:97], v[90:93] sc0 sc1
	v_lshl_add_u64 v[78:79], v[4:5], 0, v[114:115]
	s_nop 0
	v_cvt_pk_bf16_f32 v2, v2, v3
	s_nop 0
	v_cvt_pk_bf16_f32 v3, v82, v83
	s_nop 0
	v_cvt_pk_bf16_f32 v4, v74, v75
	v_pk_mul_f32 v[74:75], v[70:71], s[62:63] op_sel_hi:[1,0]
	s_nop 0
	v_cvt_pk_bf16_f32 v5, v76, v77
	flat_store_dwordx4 v[78:79], v[2:5] sc0 sc1
	v_exp_f32_e32 v74, v74
	v_exp_f32_e32 v75, v75
	v_pk_mul_f32 v[2:3], v[146:147], v[66:67]
	v_cvt_f32_i32_e32 v67, v73
	v_cvt_f32_i32_e32 v66, v72
	v_pk_add_f32 v[4:5], v[74:75], 1.0 op_sel_hi:[1,0]
	v_cvt_f32_i32_e32 v62, v62
	v_rcp_f32_e32 v4, v4
	v_rcp_f32_e32 v5, v5
	v_cvt_f32_i32_e32 v59, v59
	v_cvt_f32_i32_e32 v58, v58
	v_pk_mul_f32 v[2:3], v[6:7], v[2:3] op_sel_hi:[0,1]
	v_cvt_f32_i32_e32 v65, v65
	v_cvt_f32_i32_e32 v64, v64
	v_pk_mul_f32 v[2:3], v[70:71], v[2:3]
	v_pk_mul_f32 v[66:67], v[152:153], v[66:67]
	v_pk_mul_f32 v[2:3], v[2:3], v[4:5]
	v_pk_mul_f32 v[4:5], v[148:149], v[68:69]
	v_pk_mul_f32 v[62:63], v[142:143], v[62:63]
	v_pk_mul_f32 v[58:59], v[138:139], v[58:59]
	v_pk_mul_f32 v[66:67], v[6:7], v[66:67] op_sel_hi:[0,1]
	v_pk_mul_f32 v[4:5], v[6:7], v[4:5] op_sel_hi:[0,1]
	v_pk_mul_f32 v[62:63], v[6:7], v[62:63] op_sel_hi:[0,1]
	v_pk_mul_f32 v[58:59], v[6:7], v[58:59] op_sel_hi:[0,1]
	v_pk_mul_f32 v[70:71], v[66:67], s[62:63] op_sel_hi:[1,0]
	v_pk_mul_f32 v[4:5], v[66:67], v[4:5]
	v_pk_mul_f32 v[66:67], v[62:63], s[62:63] op_sel_hi:[1,0]
	v_pk_mul_f32 v[58:59], v[62:63], v[58:59]
	v_pk_mul_f32 v[62:63], v[144:145], v[64:65]
	v_exp_f32_e32 v70, v70
	v_pk_mul_f32 v[62:63], v[6:7], v[62:63] op_sel_hi:[0,1]
	v_pk_mul_f32 v[64:65], v[62:63], s[62:63] op_sel_hi:[1,0]
	v_exp_f32_e32 v71, v71
	v_exp_f32_e32 v64, v64
	v_exp_f32_e32 v65, v65
	v_exp_f32_e32 v66, v66
	v_exp_f32_e32 v67, v67
	v_cvt_f32_i32_e32 v61, v61
	v_cvt_f32_i32_e32 v60, v60
	v_pk_add_f32 v[64:65], v[64:65], 1.0 op_sel_hi:[1,0]
	v_pk_add_f32 v[68:69], v[70:71], 1.0 op_sel_hi:[1,0]
	v_pk_add_f32 v[66:67], v[66:67], 1.0 op_sel_hi:[1,0]
	v_rcp_f32_e32 v64, v64
	v_rcp_f32_e32 v65, v65
	v_pk_mul_f32 v[60:61], v[140:141], v[60:61]
	v_cvt_f32_i32_e32 v55, v55
	v_cvt_f32_i32_e32 v54, v54
	v_rcp_f32_e32 v68, v68
	v_rcp_f32_e32 v69, v69
	v_rcp_f32_e32 v66, v66
	v_rcp_f32_e32 v67, v67
	v_pk_mul_f32 v[60:61], v[6:7], v[60:61] op_sel_hi:[0,1]
	v_pk_mul_f32 v[60:61], v[62:63], v[60:61]
	v_mad_u64_u32 v[62:63], s[6:7], v178, s82, v[122:123]
	v_mov_b32_e32 v6, v63
	v_pk_mul_f32 v[60:61], v[60:61], v[64:65]
	v_mad_u64_u32 v[64:65], s[6:7], v179, s82, v[6:7]
	v_mov_b32_e32 v6, v7
	v_pk_mul_f32 v[54:55], v[150:151], v[54:55]
	v_pk_mul_f32 v[4:5], v[4:5], v[68:69]
	v_pk_mul_f32 v[58:59], v[58:59], v[66:67]
	v_pk_mul_f32 v[54:55], v[6:7], v[54:55] op_sel_hi:[0,1]
	s_nop 0
	v_cvt_pk_bf16_f32 v2, v2, v3
	s_nop 0
	v_cvt_pk_bf16_f32 v3, v4, v5
	s_nop 0
	v_cvt_pk_bf16_f32 v4, v58, v59
	v_pk_mul_f32 v[58:59], v[54:55], s[62:63] op_sel_hi:[1,0]
	v_cvt_f32_i32_e32 v51, v51
	v_exp_f32_e32 v58, v58
	v_exp_f32_e32 v59, v59
	v_cvt_f32_i32_e32 v50, v50
	v_mov_b32_e32 v63, v64
	v_lshl_add_u64 v[62:63], v[62:63], 0, v[114:115]
	s_nop 0
	v_cvt_pk_bf16_f32 v5, v60, v61
	flat_store_dwordx4 v[62:63], v[2:5] sc0 sc1
	v_cvt_f32_i32_e32 v53, v53
	v_cvt_f32_i32_e32 v52, v52
	v_pk_add_f32 v[4:5], v[58:59], 1.0 op_sel_hi:[1,0]
	v_pk_mul_f32 v[2:3], v[146:147], v[50:51]
	v_cvt_f32_i32_e32 v51, v57
	v_cvt_f32_i32_e32 v50, v56
	v_rcp_f32_e32 v4, v4
	v_rcp_f32_e32 v5, v5
	v_cvt_f32_i32_e32 v47, v47
	v_cvt_f32_i32_e32 v46, v46
	v_cvt_f32_i32_e32 v43, v43
	v_cvt_f32_i32_e32 v42, v42
	v_pk_mul_f32 v[2:3], v[6:7], v[2:3] op_sel_hi:[0,1]
	v_cvt_f32_i32_e32 v49, v49
	v_cvt_f32_i32_e32 v48, v48
	v_pk_mul_f32 v[2:3], v[54:55], v[2:3]
	v_pk_mul_f32 v[50:51], v[152:153], v[50:51]
	v_pk_mul_f32 v[2:3], v[2:3], v[4:5]
	v_pk_mul_f32 v[4:5], v[148:149], v[52:53]
	v_pk_mul_f32 v[46:47], v[142:143], v[46:47]
	v_pk_mul_f32 v[42:43], v[138:139], v[42:43]
	v_pk_mul_f32 v[50:51], v[6:7], v[50:51] op_sel_hi:[0,1]
	v_pk_mul_f32 v[4:5], v[6:7], v[4:5] op_sel_hi:[0,1]
	v_pk_mul_f32 v[46:47], v[6:7], v[46:47] op_sel_hi:[0,1]
	v_pk_mul_f32 v[42:43], v[6:7], v[42:43] op_sel_hi:[0,1]
	v_pk_mul_f32 v[54:55], v[50:51], s[62:63] op_sel_hi:[1,0]
	v_pk_mul_f32 v[4:5], v[50:51], v[4:5]
	v_pk_mul_f32 v[50:51], v[46:47], s[62:63] op_sel_hi:[1,0]
	v_pk_mul_f32 v[42:43], v[46:47], v[42:43]
	v_pk_mul_f32 v[46:47], v[144:145], v[48:49]
	v_exp_f32_e32 v54, v54
	v_pk_mul_f32 v[46:47], v[6:7], v[46:47] op_sel_hi:[0,1]
	v_pk_mul_f32 v[48:49], v[46:47], s[62:63] op_sel_hi:[1,0]
	v_exp_f32_e32 v55, v55
	v_exp_f32_e32 v48, v48
	v_exp_f32_e32 v49, v49
	v_exp_f32_e32 v50, v50
	v_exp_f32_e32 v51, v51
	v_cvt_f32_i32_e32 v45, v45
	v_cvt_f32_i32_e32 v44, v44
	v_pk_add_f32 v[52:53], v[54:55], 1.0 op_sel_hi:[1,0]
	v_pk_add_f32 v[48:49], v[48:49], 1.0 op_sel_hi:[1,0]
	v_rcp_f32_e32 v52, v52
	v_rcp_f32_e32 v53, v53
	v_pk_add_f32 v[50:51], v[50:51], 1.0 op_sel_hi:[1,0]
	v_rcp_f32_e32 v48, v48
	v_rcp_f32_e32 v49, v49
	v_rcp_f32_e32 v50, v50
	v_rcp_f32_e32 v51, v51
	v_pk_mul_f32 v[44:45], v[140:141], v[44:45]
	v_cvt_f32_i32_e32 v39, v39
	v_cvt_f32_i32_e32 v38, v38
	v_pk_mul_f32 v[6:7], v[6:7], v[44:45] op_sel_hi:[0,1]
	v_pk_mul_f32 v[6:7], v[46:47], v[6:7]
	v_pk_mul_f32 v[4:5], v[4:5], v[52:53]
	v_pk_mul_f32 v[6:7], v[6:7], v[48:49]
	v_pk_mul_f32 v[42:43], v[42:43], v[50:51]
	s_nop 0
	v_cvt_pk_bf16_f32 v2, v2, v3
	s_nop 0
	v_cvt_pk_bf16_f32 v3, v4, v5
	v_cvt_f32_i32_e32 v35, v35
	s_nop 0
	v_cvt_pk_bf16_f32 v4, v42, v43
	s_nop 0
	v_cvt_pk_bf16_f32 v5, v6, v7
	v_pk_mul_f32 v[6:7], v[150:151], v[38:39]
	v_cvt_f32_i32_e32 v34, v34
	v_add_u32_e32 v44, 16, v170
	v_pk_mul_f32 v[6:7], v[8:9], v[6:7] op_sel_hi:[0,1]
	v_mad_i64_i32 v[44:45], s[6:7], v44, s82, v[122:123]
	v_pk_mul_f32 v[38:39], v[6:7], s[62:63] op_sel_hi:[1,0]
	v_lshl_add_u64 v[44:45], v[44:45], 0, v[114:115]
	v_exp_f32_e32 v38, v38
	v_exp_f32_e32 v39, v39
	flat_store_dwordx4 v[44:45], v[2:5] sc0 sc1
	v_cvt_f32_i32_e32 v31, v31
	v_cvt_f32_i32_e32 v30, v30
	v_pk_mul_f32 v[2:3], v[146:147], v[34:35]
	v_cvt_f32_i32_e32 v35, v41
	v_cvt_f32_i32_e32 v34, v40
	v_pk_mul_f32 v[2:3], v[8:9], v[2:3] op_sel_hi:[0,1]
	v_pk_add_f32 v[4:5], v[38:39], 1.0 op_sel_hi:[1,0]
	v_pk_mul_f32 v[2:3], v[6:7], v[2:3]
	v_rcp_f32_e32 v4, v4
	v_rcp_f32_e32 v5, v5
	v_pk_mul_f32 v[6:7], v[152:153], v[34:35]
	v_cvt_f32_i32_e32 v35, v37
	v_cvt_f32_i32_e32 v34, v36
	v_pk_mul_f32 v[2:3], v[2:3], v[4:5]
	v_pk_mul_f32 v[6:7], v[8:9], v[6:7] op_sel_hi:[0,1]
	v_cvt_f32_i32_e32 v27, v27
	v_pk_mul_f32 v[4:5], v[148:149], v[34:35]
	v_cvt_f32_i32_e32 v26, v26
	v_pk_mul_f32 v[4:5], v[8:9], v[4:5] op_sel_hi:[0,1]
	v_pk_mul_f32 v[36:37], v[6:7], s[62:63] op_sel_hi:[1,0]
	v_pk_mul_f32 v[4:5], v[6:7], v[4:5]
	v_pk_mul_f32 v[6:7], v[142:143], v[30:31]
	v_cvt_f32_i32_e32 v33, v33
	v_pk_mul_f32 v[6:7], v[8:9], v[6:7] op_sel_hi:[0,1]
	v_cvt_f32_i32_e32 v32, v32
	v_pk_mul_f32 v[30:31], v[6:7], s[62:63] op_sel_hi:[1,0]
	v_exp_f32_e32 v36, v36
	v_exp_f32_e32 v37, v37
	v_exp_f32_e32 v30, v30
	v_exp_f32_e32 v31, v31
	v_pk_mul_f32 v[26:27], v[138:139], v[26:27]
	v_pk_add_f32 v[34:35], v[36:37], 1.0 op_sel_hi:[1,0]
	v_pk_mul_f32 v[26:27], v[8:9], v[26:27] op_sel_hi:[0,1]
	v_pk_mul_f32 v[6:7], v[6:7], v[26:27]
	v_pk_mul_f32 v[26:27], v[144:145], v[32:33]
	v_pk_add_f32 v[30:31], v[30:31], 1.0 op_sel_hi:[1,0]
	v_pk_mul_f32 v[26:27], v[8:9], v[26:27] op_sel_hi:[0,1]
	v_pk_mul_f32 v[32:33], v[26:27], s[62:63] op_sel_hi:[1,0]
	v_cvt_f32_i32_e32 v29, v29
	v_cvt_f32_i32_e32 v28, v28
	v_rcp_f32_e32 v34, v34
	v_rcp_f32_e32 v35, v35
	v_rcp_f32_e32 v30, v30
	v_rcp_f32_e32 v31, v31
	v_exp_f32_e32 v32, v32
	v_exp_f32_e32 v33, v33
	v_cvt_f32_i32_e32 v23, v23
	v_cvt_f32_i32_e32 v22, v22
	v_pk_mul_f32 v[28:29], v[140:141], v[28:29]
	v_pk_mul_f32 v[4:5], v[4:5], v[34:35]
	v_pk_mul_f32 v[6:7], v[6:7], v[30:31]
	v_pk_add_f32 v[30:31], v[32:33], 1.0 op_sel_hi:[1,0]
	v_pk_mul_f32 v[28:29], v[8:9], v[28:29] op_sel_hi:[0,1]
	v_add_u32_e32 v8, 32, v170
	v_rcp_f32_e32 v30, v30
	v_rcp_f32_e32 v31, v31
	v_pk_mul_f32 v[26:27], v[26:27], v[28:29]
	v_mad_i64_i32 v[28:29], s[6:7], v8, s82, v[122:123]
	s_nop 0
	v_cvt_pk_bf16_f32 v2, v2, v3
	s_nop 0
	v_cvt_pk_bf16_f32 v3, v4, v5
	s_nop 0
	v_cvt_pk_bf16_f32 v4, v6, v7
	v_mov_b32_e32 v6, v9
	v_pk_mul_f32 v[8:9], v[150:151], v[22:23]
	v_cvt_f32_i32_e32 v19, v19
	v_cvt_f32_i32_e32 v18, v18
	v_pk_mul_f32 v[8:9], v[6:7], v[8:9] op_sel_hi:[0,1]
	v_pk_mul_f32 v[22:23], v[8:9], s[62:63] op_sel_hi:[1,0]
	v_lshl_add_u64 v[28:29], v[28:29], 0, v[114:115]
	v_exp_f32_e32 v22, v22
	v_exp_f32_e32 v23, v23
	v_pk_mul_f32 v[26:27], v[26:27], v[30:31]
	v_cvt_f32_i32_e32 v15, v15
	s_nop 0
	v_cvt_pk_bf16_f32 v5, v26, v27
	flat_store_dwordx4 v[28:29], v[2:5] sc0 sc1
	v_cvt_f32_i32_e32 v14, v14
	v_cvt_f32_i32_e32 v11, v11
	v_pk_mul_f32 v[2:3], v[146:147], v[18:19]
	v_cvt_f32_i32_e32 v19, v25
	v_cvt_f32_i32_e32 v18, v24
	v_pk_mul_f32 v[2:3], v[6:7], v[2:3] op_sel_hi:[0,1]
	v_pk_add_f32 v[4:5], v[22:23], 1.0 op_sel_hi:[1,0]
	v_pk_mul_f32 v[2:3], v[8:9], v[2:3]
	v_rcp_f32_e32 v4, v4
	v_rcp_f32_e32 v5, v5
	v_pk_mul_f32 v[8:9], v[152:153], v[18:19]
	v_cvt_f32_i32_e32 v19, v21
	v_cvt_f32_i32_e32 v18, v20
	v_pk_mul_f32 v[2:3], v[2:3], v[4:5]
	v_pk_mul_f32 v[8:9], v[6:7], v[8:9] op_sel_hi:[0,1]
	v_cvt_f32_i32_e32 v10, v10
	v_pk_mul_f32 v[4:5], v[148:149], v[18:19]
	v_pk_mul_f32 v[20:21], v[8:9], s[62:63] op_sel_hi:[1,0]
	v_pk_mul_f32 v[4:5], v[6:7], v[4:5] op_sel_hi:[0,1]
	v_pk_mul_f32 v[4:5], v[8:9], v[4:5]
	v_pk_mul_f32 v[8:9], v[142:143], v[14:15]
	v_cvt_f32_i32_e32 v17, v17
	v_pk_mul_f32 v[8:9], v[6:7], v[8:9] op_sel_hi:[0,1]
	v_cvt_f32_i32_e32 v16, v16
	v_pk_mul_f32 v[14:15], v[8:9], s[62:63] op_sel_hi:[1,0]
	v_pk_mul_f32 v[10:11], v[138:139], v[10:11]
	v_exp_f32_e32 v14, v14
	v_exp_f32_e32 v15, v15
	v_pk_mul_f32 v[10:11], v[6:7], v[10:11] op_sel_hi:[0,1]
	v_pk_mul_f32 v[8:9], v[8:9], v[10:11]
	v_pk_mul_f32 v[10:11], v[144:145], v[16:17]
	v_exp_f32_e32 v20, v20
	v_pk_mul_f32 v[10:11], v[6:7], v[10:11] op_sel_hi:[0,1]
	v_exp_f32_e32 v21, v21
	v_pk_add_f32 v[14:15], v[14:15], 1.0 op_sel_hi:[1,0]
	v_pk_mul_f32 v[16:17], v[10:11], s[62:63] op_sel_hi:[1,0]
	v_rcp_f32_e32 v14, v14
	v_rcp_f32_e32 v15, v15
	v_exp_f32_e32 v16, v16
	v_exp_f32_e32 v17, v17
	v_cvt_f32_i32_e32 v13, v13
	v_cvt_f32_i32_e32 v12, v12
	v_pk_add_f32 v[18:19], v[20:21], 1.0 op_sel_hi:[1,0]
	v_pk_mul_f32 v[8:9], v[8:9], v[14:15]
	v_rcp_f32_e32 v18, v18
	v_rcp_f32_e32 v19, v19
	v_pk_add_f32 v[14:15], v[16:17], 1.0 op_sel_hi:[1,0]
	v_pk_mul_f32 v[12:13], v[140:141], v[12:13]
	v_rcp_f32_e32 v14, v14
	v_rcp_f32_e32 v15, v15
	v_pk_mul_f32 v[6:7], v[6:7], v[12:13] op_sel_hi:[0,1]
	v_pk_mul_f32 v[6:7], v[10:11], v[6:7]
	v_add_u32_e32 v10, 48, v170
	v_mad_i64_i32 v[10:11], s[6:7], v10, s82, v[122:123]
	v_pk_mul_f32 v[4:5], v[4:5], v[18:19]
	v_lshl_add_u64 v[10:11], v[10:11], 0, v[114:115]
	s_andn2_b64 vcc, exec, s[8:9]
	s_mov_b64 s[8:9], -1
	v_pk_mul_f32 v[6:7], v[6:7], v[14:15]
	s_nop 0
	v_cvt_pk_bf16_f32 v2, v2, v3
	s_nop 0
	v_cvt_pk_bf16_f32 v3, v4, v5
	s_nop 0
	v_cvt_pk_bf16_f32 v4, v8, v9
	s_nop 0
	s_nop 0
	v_cvt_pk_bf16_f32 v5, v6, v7
	flat_store_dwordx4 v[10:11], v[2:5] sc0 sc1
	s_cbranch_vccnz .LBB0_2059
	s_andn2_b64 vcc, exec, s[40:41]
	s_cbranch_vccnz .LBB0_2058
	s_barrier
	s_branch .LBB0_2058

.LBB0_2118:
	ds_read_b128 v[142:145], v149
	ds_read_b128 v[154:157], v149 offset:1024
	ds_read_b128 v[158:161], v149 offset:2048
	ds_read_b128 v[162:165], v149 offset:3072
	ds_read_b128 v[166:169], v150
	ds_read_b128 v[170:173], v150 offset:1024
	ds_read_b128 v[174:177], v150 offset:2048
	ds_read_b128 v[178:181], v150 offset:3072
	s_add_u32 s16, s40, 0xffd50080
	s_addc_u32 s17, s41, -1
	s_cmpk_eq_i32 s71, 0xa8
	s_cselect_b32 s45, s37, s17
	s_cselect_b32 s44, s36, s16
	s_cselect_b32 s43, s39, s70
	s_cselect_b32 s42, s38, s69
	s_add_i32 m0, s27, 0xc000
	ds_read_b128 v[182:185], v151
	ds_read_b128 v[186:189], v151 offset:1024
	ds_read_b128 v[190:193], v151 offset:2048
	ds_read_b128 v[194:197], v151 offset:3072
	ds_read_b128 v[198:201], v151 offset:4096
	ds_read_b128 v[202:205], v151 offset:5120
	ds_read_b128 v[206:209], v151 offset:6144
	ds_read_b128 v[210:213], v151 offset:7168
	global_load_lds_dwordx4 v140, s[40:41]
	s_add_i32 m0, s27, 0xe000
	s_nop 0
	global_load_lds_dwordx4 v138, s[40:41]
	s_waitcnt vmcnt(8)
	s_waitcnt lgkmcnt(0)
	s_barrier
	s_setprio 1
	s_waitcnt lgkmcnt(0)
	v_mfma_f32_16x16x32_bf16 v[126:129], v[142:145], v[182:185], v[126:129]
	v_mfma_f32_16x16x32_bf16 v[122:125], v[158:161], v[182:185], v[122:125]
	v_mfma_f32_16x16x32_bf16 v[110:113], v[142:145], v[190:193], v[110:113]
	v_mfma_f32_16x16x32_bf16 v[106:109], v[158:161], v[190:193], v[106:109]
	v_mfma_f32_16x16x32_bf16 v[94:97], v[142:145], v[198:201], v[94:97]
	v_mfma_f32_16x16x32_bf16 v[90:93], v[158:161], v[198:201], v[90:93]
	v_mfma_f32_16x16x32_bf16 v[78:81], v[142:145], v[206:209], v[78:81]
	v_mfma_f32_16x16x32_bf16 v[74:77], v[158:161], v[206:209], v[74:77]
	v_mfma_f32_16x16x32_bf16 v[126:129], v[154:157], v[186:189], v[126:129]
	v_mfma_f32_16x16x32_bf16 v[122:125], v[162:165], v[186:189], v[122:125]
	v_mfma_f32_16x16x32_bf16 v[110:113], v[154:157], v[194:197], v[110:113]
	v_mfma_f32_16x16x32_bf16 v[106:109], v[162:165], v[194:197], v[106:109]
	v_mfma_f32_16x16x32_bf16 v[94:97], v[154:157], v[202:205], v[94:97]
	v_mfma_f32_16x16x32_bf16 v[90:93], v[162:165], v[202:205], v[90:93]
	v_mfma_f32_16x16x32_bf16 v[78:81], v[154:157], v[210:213], v[78:81]
	v_mfma_f32_16x16x32_bf16 v[74:77], v[162:165], v[210:213], v[74:77]
	s_setprio 0
	s_setprio 1
	v_mfma_f32_16x16x32_bf16 v[118:121], v[166:169], v[182:185], v[118:121]
	v_mfma_f32_16x16x32_bf16 v[114:117], v[174:177], v[182:185], v[114:117]
	v_mfma_f32_16x16x32_bf16 v[102:105], v[166:169], v[190:193], v[102:105]
	v_mfma_f32_16x16x32_bf16 v[98:101], v[174:177], v[190:193], v[98:101]
	v_mfma_f32_16x16x32_bf16 v[86:89], v[166:169], v[198:201], v[86:89]
	v_mfma_f32_16x16x32_bf16 v[82:85], v[174:177], v[198:201], v[82:85]
	v_mfma_f32_16x16x32_bf16 v[70:73], v[166:169], v[206:209], v[70:73]
	v_mfma_f32_16x16x32_bf16 v[66:69], v[174:177], v[206:209], v[66:69]
	v_mfma_f32_16x16x32_bf16 v[118:121], v[170:173], v[186:189], v[118:121]
	v_mfma_f32_16x16x32_bf16 v[114:117], v[178:181], v[186:189], v[114:117]
	v_mfma_f32_16x16x32_bf16 v[102:105], v[170:173], v[194:197], v[102:105]
	v_mfma_f32_16x16x32_bf16 v[98:101], v[178:181], v[194:197], v[98:101]
	v_mfma_f32_16x16x32_bf16 v[86:89], v[170:173], v[202:205], v[86:89]
	v_mfma_f32_16x16x32_bf16 v[82:85], v[178:181], v[202:205], v[82:85]
	v_mfma_f32_16x16x32_bf16 v[70:73], v[170:173], v[210:213], v[70:73]
	v_mfma_f32_16x16x32_bf16 v[66:69], v[178:181], v[210:213], v[66:69]
	s_setprio 0
	s_barrier
	s_add_i32 s16, s63, s26
	v_lshl_add_u64 v[214:215], s[42:43], 0, v[132:133]
	s_mov_b32 m0, s16
	ds_read_b128 v[182:185], v151 offset:16384
	ds_read_b128 v[186:189], v151 offset:17408
	ds_read_b128 v[190:193], v151 offset:18432
	ds_read_b128 v[194:197], v151 offset:19456
	ds_read_b128 v[198:201], v151 offset:20480
	ds_read_b128 v[202:205], v151 offset:21504
	ds_read_b128 v[206:209], v151 offset:22528
	ds_read_b128 v[210:213], v151 offset:23552
	global_load_lds_dwordx4 v[214:215], off
	s_add_i32 m0, s16, 0x2000
	s_add_u32 s16, s42, 0x2b0000
	v_lshl_add_u64 v[216:217], s[42:43], 0, v[136:137]
	s_addc_u32 s17, s43, 0
	s_add_i32 s72, s64, s26
	global_load_lds_dwordx4 v[216:217], off
	s_mov_b32 m0, s72
	v_lshl_add_u64 v[220:221], s[44:45], 0, v[134:135]
	global_load_lds_dwordx4 v132, s[16:17]
	s_add_i32 m0, s72, 0x2000
	s_nop 0
	global_load_lds_dwordx4 v136, s[16:17]
	v_lshl_add_u64 v[218:219], s[44:45], 0, v[130:131]
	s_mov_b32 m0, s27
	s_nop 0
	global_load_lds_dwordx4 v[218:219], off
	s_mov_b32 m0, s28
	s_nop 0
	global_load_lds_dwordx4 v[220:221], off
	s_waitcnt vmcnt(8)
	s_waitcnt lgkmcnt(0)
	s_barrier
	s_setprio 1
	s_waitcnt lgkmcnt(0)
	v_mfma_f32_16x16x32_bf16 v[62:65], v[142:145], v[182:185], v[62:65]
	v_mfma_f32_16x16x32_bf16 v[58:61], v[158:161], v[182:185], v[58:61]
	v_mfma_f32_16x16x32_bf16 v[46:49], v[142:145], v[190:193], v[46:49]
	v_mfma_f32_16x16x32_bf16 v[42:45], v[158:161], v[190:193], v[42:45]
	v_mfma_f32_16x16x32_bf16 v[30:33], v[142:145], v[198:201], v[30:33]
	v_mfma_f32_16x16x32_bf16 v[26:29], v[158:161], v[198:201], v[26:29]
	v_mfma_f32_16x16x32_bf16 v[14:17], v[142:145], v[206:209], v[14:17]
	v_mfma_f32_16x16x32_bf16 v[10:13], v[158:161], v[206:209], v[10:13]
	v_mfma_f32_16x16x32_bf16 v[62:65], v[154:157], v[186:189], v[62:65]
	v_mfma_f32_16x16x32_bf16 v[58:61], v[162:165], v[186:189], v[58:61]
	v_mfma_f32_16x16x32_bf16 v[46:49], v[154:157], v[194:197], v[46:49]
	v_mfma_f32_16x16x32_bf16 v[42:45], v[162:165], v[194:197], v[42:45]
	v_mfma_f32_16x16x32_bf16 v[30:33], v[154:157], v[202:205], v[30:33]
	v_mfma_f32_16x16x32_bf16 v[26:29], v[162:165], v[202:205], v[26:29]
	v_mfma_f32_16x16x32_bf16 v[14:17], v[154:157], v[210:213], v[14:17]
	v_mfma_f32_16x16x32_bf16 v[10:13], v[162:165], v[210:213], v[10:13]
	s_setprio 0
	s_setprio 1
	v_mfma_f32_16x16x32_bf16 v[54:57], v[166:169], v[182:185], v[54:57]
	v_mfma_f32_16x16x32_bf16 v[50:53], v[174:177], v[182:185], v[50:53]
	v_mfma_f32_16x16x32_bf16 v[38:41], v[166:169], v[190:193], v[38:41]
	v_mfma_f32_16x16x32_bf16 v[34:37], v[174:177], v[190:193], v[34:37]
	v_mfma_f32_16x16x32_bf16 v[22:25], v[166:169], v[198:201], v[22:25]
	v_mfma_f32_16x16x32_bf16 v[18:21], v[174:177], v[198:201], v[18:21]
	v_mfma_f32_16x16x32_bf16 v[6:9], v[166:169], v[206:209], v[6:9]
	v_mfma_f32_16x16x32_bf16 v[2:5], v[174:177], v[206:209], v[2:5]
	v_mfma_f32_16x16x32_bf16 v[54:57], v[170:173], v[186:189], v[54:57]
	v_mfma_f32_16x16x32_bf16 v[50:53], v[178:181], v[186:189], v[50:53]
	v_mfma_f32_16x16x32_bf16 v[38:41], v[170:173], v[194:197], v[38:41]
	v_mfma_f32_16x16x32_bf16 v[34:37], v[178:181], v[194:197], v[34:37]
	v_mfma_f32_16x16x32_bf16 v[22:25], v[170:173], v[202:205], v[22:25]
	v_mfma_f32_16x16x32_bf16 v[18:21], v[178:181], v[202:205], v[18:21]
	v_mfma_f32_16x16x32_bf16 v[6:9], v[170:173], v[210:213], v[6:9]
	v_mfma_f32_16x16x32_bf16 v[2:5], v[178:181], v[210:213], v[2:5]
	s_setprio 0
	s_barrier
	s_add_i32 s72, 0, 0x18000
	v_add_u32_e32 v153, s72, v147
	s_add_i32 s73, 0, 0x1c000
	ds_read_b128 v[142:145], v153
	ds_read_b128 v[154:157], v153 offset:1024
	ds_read_b128 v[158:161], v153 offset:2048
	ds_read_b128 v[162:165], v153 offset:3072
	v_add_u32_e32 v153, s73, v147
	ds_read_b128 v[166:169], v153
	ds_read_b128 v[170:173], v153 offset:1024
	ds_read_b128 v[174:177], v153 offset:2048
	ds_read_b128 v[178:181], v153 offset:3072
	s_add_u32 s16, s44, 0x2b0000
	s_addc_u32 s17, s45, 0
	s_mov_b32 m0, s29
	ds_read_b128 v[182:185], v151 offset:32768
	ds_read_b128 v[186:189], v151 offset:33792
	ds_read_b128 v[190:193], v151 offset:34816
	ds_read_b128 v[194:197], v151 offset:35840
	ds_read_b128 v[198:201], v151 offset:36864
	ds_read_b128 v[202:205], v151 offset:37888
	ds_read_b128 v[206:209], v151 offset:38912
	ds_read_b128 v[210:213], v151 offset:39936
	global_load_lds_dwordx4 v130, s[16:17]
	s_mov_b32 m0, s56
	s_nop 0
	global_load_lds_dwordx4 v134, s[16:17]
	s_waitcnt vmcnt(8)
	s_waitcnt lgkmcnt(0)
	s_barrier
	s_setprio 1
	s_waitcnt lgkmcnt(0)
	v_mfma_f32_16x16x32_bf16 v[126:129], v[142:145], v[182:185], v[126:129]
	v_mfma_f32_16x16x32_bf16 v[122:125], v[158:161], v[182:185], v[122:125]
	v_mfma_f32_16x16x32_bf16 v[110:113], v[142:145], v[190:193], v[110:113]
	v_mfma_f32_16x16x32_bf16 v[106:109], v[158:161], v[190:193], v[106:109]
	v_mfma_f32_16x16x32_bf16 v[94:97], v[142:145], v[198:201], v[94:97]
	v_mfma_f32_16x16x32_bf16 v[90:93], v[158:161], v[198:201], v[90:93]
	v_mfma_f32_16x16x32_bf16 v[78:81], v[142:145], v[206:209], v[78:81]
	v_mfma_f32_16x16x32_bf16 v[74:77], v[158:161], v[206:209], v[74:77]
	v_mfma_f32_16x16x32_bf16 v[126:129], v[154:157], v[186:189], v[126:129]
	v_mfma_f32_16x16x32_bf16 v[122:125], v[162:165], v[186:189], v[122:125]
	v_mfma_f32_16x16x32_bf16 v[110:113], v[154:157], v[194:197], v[110:113]
	v_mfma_f32_16x16x32_bf16 v[106:109], v[162:165], v[194:197], v[106:109]
	v_mfma_f32_16x16x32_bf16 v[94:97], v[154:157], v[202:205], v[94:97]
	v_mfma_f32_16x16x32_bf16 v[90:93], v[162:165], v[202:205], v[90:93]
	v_mfma_f32_16x16x32_bf16 v[78:81], v[154:157], v[210:213], v[78:81]
	v_mfma_f32_16x16x32_bf16 v[74:77], v[162:165], v[210:213], v[74:77]
	s_setprio 0
	s_setprio 1
	v_mfma_f32_16x16x32_bf16 v[118:121], v[166:169], v[182:185], v[118:121]
	v_mfma_f32_16x16x32_bf16 v[114:117], v[174:177], v[182:185], v[114:117]
	v_mfma_f32_16x16x32_bf16 v[102:105], v[166:169], v[190:193], v[102:105]
	v_mfma_f32_16x16x32_bf16 v[98:101], v[174:177], v[190:193], v[98:101]
	v_mfma_f32_16x16x32_bf16 v[86:89], v[166:169], v[198:201], v[86:89]
	v_mfma_f32_16x16x32_bf16 v[82:85], v[174:177], v[198:201], v[82:85]
	v_mfma_f32_16x16x32_bf16 v[70:73], v[166:169], v[206:209], v[70:73]
	v_mfma_f32_16x16x32_bf16 v[66:69], v[174:177], v[206:209], v[66:69]
	v_mfma_f32_16x16x32_bf16 v[118:121], v[170:173], v[186:189], v[118:121]
	v_mfma_f32_16x16x32_bf16 v[114:117], v[178:181], v[186:189], v[114:117]
	v_mfma_f32_16x16x32_bf16 v[102:105], v[170:173], v[194:197], v[102:105]
	v_mfma_f32_16x16x32_bf16 v[98:101], v[178:181], v[194:197], v[98:101]
	v_mfma_f32_16x16x32_bf16 v[86:89], v[170:173], v[202:205], v[86:89]
	v_mfma_f32_16x16x32_bf16 v[82:85], v[178:181], v[202:205], v[82:85]
	v_mfma_f32_16x16x32_bf16 v[70:73], v[170:173], v[210:213], v[70:73]
	v_mfma_f32_16x16x32_bf16 v[66:69], v[178:181], v[210:213], v[66:69]
	s_setprio 0
	s_barrier
	s_add_i32 s16, s72, s26
	v_lshl_add_u64 v[214:215], v[214:215], 0, s[14:15]
	s_mov_b32 m0, s16
	ds_read_b128 v[182:185], v151 offset:49152
	ds_read_b128 v[186:189], v151 offset:50176
	ds_read_b128 v[190:193], v151 offset:51200
	ds_read_b128 v[194:197], v151 offset:52224
	ds_read_b128 v[198:201], v151 offset:53248
	ds_read_b128 v[202:205], v151 offset:54272
	ds_read_b128 v[206:209], v151 offset:55296
	ds_read_b128 v[210:213], v151 offset:56320
	global_load_lds_dwordx4 v[214:215], off
	s_add_i32 m0, s16, 0x2000
	s_add_u32 s16, s42, 0x2b0080
	v_lshl_add_u64 v[214:215], v[216:217], 0, s[14:15]
	s_addc_u32 s17, s43, 0
	s_add_i32 s42, s73, s26
	global_load_lds_dwordx4 v[214:215], off
	s_mov_b32 m0, s42
	s_nop 0
	global_load_lds_dwordx4 v132, s[16:17]
	s_add_i32 m0, s42, 0x2000
	s_nop 0
	global_load_lds_dwordx4 v136, s[16:17]
	v_lshl_add_u64 v[214:215], v[218:219], 0, s[14:15]
	s_mov_b32 m0, s60
	s_nop 0
	global_load_lds_dwordx4 v[214:215], off
	v_lshl_add_u64 v[214:215], v[220:221], 0, s[14:15]
	s_mov_b32 m0, s61
	s_nop 0
	global_load_lds_dwordx4 v[214:215], off
	s_waitcnt vmcnt(8)
	s_waitcnt lgkmcnt(0)
	s_barrier
	s_setprio 1
	s_waitcnt lgkmcnt(0)
	v_mfma_f32_16x16x32_bf16 v[62:65], v[142:145], v[182:185], v[62:65]
	v_mfma_f32_16x16x32_bf16 v[58:61], v[158:161], v[182:185], v[58:61]
	v_mfma_f32_16x16x32_bf16 v[46:49], v[142:145], v[190:193], v[46:49]
	v_mfma_f32_16x16x32_bf16 v[42:45], v[158:161], v[190:193], v[42:45]
	v_mfma_f32_16x16x32_bf16 v[30:33], v[142:145], v[198:201], v[30:33]
	v_mfma_f32_16x16x32_bf16 v[26:29], v[158:161], v[198:201], v[26:29]
	v_mfma_f32_16x16x32_bf16 v[14:17], v[142:145], v[206:209], v[14:17]
	v_mfma_f32_16x16x32_bf16 v[10:13], v[158:161], v[206:209], v[10:13]
	v_mfma_f32_16x16x32_bf16 v[62:65], v[154:157], v[186:189], v[62:65]
	v_mfma_f32_16x16x32_bf16 v[58:61], v[162:165], v[186:189], v[58:61]
	v_mfma_f32_16x16x32_bf16 v[46:49], v[154:157], v[194:197], v[46:49]
	v_mfma_f32_16x16x32_bf16 v[42:45], v[162:165], v[194:197], v[42:45]
	v_mfma_f32_16x16x32_bf16 v[30:33], v[154:157], v[202:205], v[30:33]
	v_mfma_f32_16x16x32_bf16 v[26:29], v[162:165], v[202:205], v[26:29]
	v_mfma_f32_16x16x32_bf16 v[14:17], v[154:157], v[210:213], v[14:17]
	v_mfma_f32_16x16x32_bf16 v[10:13], v[162:165], v[210:213], v[10:13]
	s_setprio 0
	s_setprio 1
	v_mfma_f32_16x16x32_bf16 v[54:57], v[166:169], v[182:185], v[54:57]
	v_mfma_f32_16x16x32_bf16 v[50:53], v[174:177], v[182:185], v[50:53]
	v_mfma_f32_16x16x32_bf16 v[38:41], v[166:169], v[190:193], v[38:41]
	v_mfma_f32_16x16x32_bf16 v[34:37], v[174:177], v[190:193], v[34:37]
	v_mfma_f32_16x16x32_bf16 v[22:25], v[166:169], v[198:201], v[22:25]
	v_mfma_f32_16x16x32_bf16 v[18:21], v[174:177], v[198:201], v[18:21]
	v_mfma_f32_16x16x32_bf16 v[6:9], v[166:169], v[206:209], v[6:9]
	v_mfma_f32_16x16x32_bf16 v[2:5], v[174:177], v[206:209], v[2:5]
	v_mfma_f32_16x16x32_bf16 v[54:57], v[170:173], v[186:189], v[54:57]
	v_mfma_f32_16x16x32_bf16 v[50:53], v[178:181], v[186:189], v[50:53]
	v_mfma_f32_16x16x32_bf16 v[38:41], v[170:173], v[194:197], v[38:41]
	v_mfma_f32_16x16x32_bf16 v[34:37], v[178:181], v[194:197], v[34:37]
	v_mfma_f32_16x16x32_bf16 v[22:25], v[170:173], v[202:205], v[22:25]
	v_mfma_f32_16x16x32_bf16 v[18:21], v[178:181], v[202:205], v[18:21]
	v_mfma_f32_16x16x32_bf16 v[6:9], v[170:173], v[210:213], v[6:9]
	v_mfma_f32_16x16x32_bf16 v[2:5], v[178:181], v[210:213], v[2:5]
	s_setprio 0
	s_barrier
	s_add_i32 s71, s71, 2
	s_add_u32 s69, s69, 0x100
	s_addc_u32 s70, s70, 0
	s_add_u32 s40, s40, 0x100
	s_addc_u32 s41, s41, 0
	s_cmpk_gt_u32 s71, 0xa9
	s_cbranch_scc0 .LBB0_2118
	v_lshl_add_u32 v245, s68, 8, v146
	v_lshl_or_b32 v246, s67, 8, v148
	v_lshlrev_b32_e32 v245, 13, v245
	v_lshl_add_u32 v245, v246, 1, v245
	global_load_dwordx4 v[142:145], v245, s[24:25]
	global_load_dwordx4 v[154:157], v245, s[24:25] offset:256
	s_add_u32 s40, s24, 0x20000
	s_addc_u32 s41, s25, 0
	global_load_dwordx4 v[158:161], v245, s[40:41]
	global_load_dwordx4 v[162:165], v245, s[40:41] offset:256
	s_add_u32 s40, s24, 0x40000
	s_addc_u32 s41, s25, 0
	global_load_dwordx4 v[166:169], v245, s[40:41]
	global_load_dwordx4 v[170:173], v245, s[40:41] offset:256
	s_add_u32 s40, s24, 0x60000
	s_addc_u32 s41, s25, 0
	global_load_dwordx4 v[174:177], v245, s[40:41]
	global_load_dwordx4 v[178:181], v245, s[40:41] offset:256
	s_add_u32 s40, s24, 0x100000
	s_addc_u32 s41, s25, 0
	global_load_dwordx4 v[182:185], v245, s[40:41]
	global_load_dwordx4 v[186:189], v245, s[40:41] offset:256
	s_add_u32 s40, s24, 0x120000
	s_addc_u32 s41, s25, 0
	global_load_dwordx4 v[190:193], v245, s[40:41]
	global_load_dwordx4 v[194:197], v245, s[40:41] offset:256
	s_add_u32 s40, s24, 0x140000
	s_addc_u32 s41, s25, 0
	global_load_dwordx4 v[198:201], v245, s[40:41]
	global_load_dwordx4 v[202:205], v245, s[40:41] offset:256
	s_add_u32 s40, s24, 0x160000
	s_addc_u32 s41, s25, 0
	global_load_dwordx4 v[206:209], v245, s[40:41]
	global_load_dwordx4 v[210:213], v245, s[40:41] offset:256
	s_and_b64 vcc, exec, s[34:35]
	s_cbranch_vccz .LBB0_2121
	s_barrier
.LBB0_2121:
	s_waitcnt vmcnt(15)
	v_lshlrev_b32_e32 v246, 16, v142
	v_and_b32_e32 v247, 0xffff0000, v142
	v_pk_add_f32 v[126:127], v[126:127], v[246:247]
	v_lshlrev_b32_e32 v246, 16, v143
	v_and_b32_e32 v247, 0xffff0000, v143
	v_pk_add_f32 v[128:129], v[128:129], v[246:247]
	v_lshlrev_b32_e32 v246, 16, v144
	v_and_b32_e32 v247, 0xffff0000, v144
	v_pk_add_f32 v[122:123], v[122:123], v[246:247]
	v_lshlrev_b32_e32 v246, 16, v145
	v_and_b32_e32 v247, 0xffff0000, v145
	v_pk_add_f32 v[124:125], v[124:125], v[246:247]
	v_cvt_pk_bf16_f32 v142, v126, v127
	v_cvt_pk_bf16_f32 v143, v128, v129
	v_cvt_pk_bf16_f32 v144, v122, v123
	v_cvt_pk_bf16_f32 v145, v124, v125
	global_store_dwordx4 v245, v[142:145], s[24:25] sc0 sc1
	v_mul_f32_e32 v126, v126, v126
	v_fmac_f32_e32 v126, v127, v127
	v_fmac_f32_e32 v126, v128, v128
	v_fmac_f32_e32 v126, v129, v129
	v_fmac_f32_e32 v126, v122, v122
	v_fmac_f32_e32 v126, v123, v123
	v_fmac_f32_e32 v126, v124, v124
	v_fmac_f32_e32 v126, v125, v125
	s_waitcnt vmcnt(15)
	v_lshlrev_b32_e32 v246, 16, v154
	v_and_b32_e32 v247, 0xffff0000, v154
	v_pk_add_f32 v[118:119], v[118:119], v[246:247]
	v_lshlrev_b32_e32 v246, 16, v155
	v_and_b32_e32 v247, 0xffff0000, v155
	v_pk_add_f32 v[120:121], v[120:121], v[246:247]
	v_lshlrev_b32_e32 v246, 16, v156
	v_and_b32_e32 v247, 0xffff0000, v156
	v_pk_add_f32 v[114:115], v[114:115], v[246:247]
	v_lshlrev_b32_e32 v246, 16, v157
	v_and_b32_e32 v247, 0xffff0000, v157
	v_pk_add_f32 v[116:117], v[116:117], v[246:247]
	v_cvt_pk_bf16_f32 v154, v118, v119
	v_cvt_pk_bf16_f32 v155, v120, v121
	v_cvt_pk_bf16_f32 v156, v114, v115
	v_cvt_pk_bf16_f32 v157, v116, v117
	global_store_dwordx4 v245, v[154:157], s[24:25] offset:256 sc0 sc1
	v_fmac_f32_e32 v126, v118, v118
	v_fmac_f32_e32 v126, v119, v119
	v_fmac_f32_e32 v126, v120, v120
	v_fmac_f32_e32 v126, v121, v121
	v_fmac_f32_e32 v126, v114, v114
	v_fmac_f32_e32 v126, v115, v115
	v_fmac_f32_e32 v126, v116, v116
	v_fmac_f32_e32 v126, v117, v117
	s_add_u32 s40, s24, 0x20000
	s_addc_u32 s41, s25, 0
	s_waitcnt vmcnt(15)
	v_lshlrev_b32_e32 v246, 16, v158
	v_and_b32_e32 v247, 0xffff0000, v158
	v_pk_add_f32 v[110:111], v[110:111], v[246:247]
	v_lshlrev_b32_e32 v246, 16, v159
	v_and_b32_e32 v247, 0xffff0000, v159
	v_pk_add_f32 v[112:113], v[112:113], v[246:247]
	v_lshlrev_b32_e32 v246, 16, v160
	v_and_b32_e32 v247, 0xffff0000, v160
	v_pk_add_f32 v[106:107], v[106:107], v[246:247]
	v_lshlrev_b32_e32 v246, 16, v161
	v_and_b32_e32 v247, 0xffff0000, v161
	v_pk_add_f32 v[108:109], v[108:109], v[246:247]
	v_cvt_pk_bf16_f32 v158, v110, v111
	v_cvt_pk_bf16_f32 v159, v112, v113
	v_cvt_pk_bf16_f32 v160, v106, v107
	v_cvt_pk_bf16_f32 v161, v108, v109
	global_store_dwordx4 v245, v[158:161], s[40:41] sc0 sc1
	v_mul_f32_e32 v110, v110, v110
	v_fmac_f32_e32 v110, v111, v111
	v_fmac_f32_e32 v110, v112, v112
	v_fmac_f32_e32 v110, v113, v113
	v_fmac_f32_e32 v110, v106, v106
	v_fmac_f32_e32 v110, v107, v107
	v_fmac_f32_e32 v110, v108, v108
	v_fmac_f32_e32 v110, v109, v109
	s_waitcnt vmcnt(15)
	v_lshlrev_b32_e32 v246, 16, v162
	v_and_b32_e32 v247, 0xffff0000, v162
	v_pk_add_f32 v[102:103], v[102:103], v[246:247]
	v_lshlrev_b32_e32 v246, 16, v163
	v_and_b32_e32 v247, 0xffff0000, v163
	v_pk_add_f32 v[104:105], v[104:105], v[246:247]
	v_lshlrev_b32_e32 v246, 16, v164
	v_and_b32_e32 v247, 0xffff0000, v164
	v_pk_add_f32 v[98:99], v[98:99], v[246:247]
	v_lshlrev_b32_e32 v246, 16, v165
	v_and_b32_e32 v247, 0xffff0000, v165
	v_pk_add_f32 v[100:101], v[100:101], v[246:247]
	v_cvt_pk_bf16_f32 v162, v102, v103
	v_cvt_pk_bf16_f32 v163, v104, v105
	v_cvt_pk_bf16_f32 v164, v98, v99
	v_cvt_pk_bf16_f32 v165, v100, v101
	global_store_dwordx4 v245, v[162:165], s[40:41] offset:256 sc0 sc1
	v_fmac_f32_e32 v110, v102, v102
	v_fmac_f32_e32 v110, v103, v103
	v_fmac_f32_e32 v110, v104, v104
	v_fmac_f32_e32 v110, v105, v105
	v_fmac_f32_e32 v110, v98, v98
	v_fmac_f32_e32 v110, v99, v99
	v_fmac_f32_e32 v110, v100, v100
	v_fmac_f32_e32 v110, v101, v101
	s_add_u32 s40, s24, 0x40000
	s_addc_u32 s41, s25, 0
	s_waitcnt vmcnt(15)
	v_lshlrev_b32_e32 v246, 16, v166
	v_and_b32_e32 v247, 0xffff0000, v166
	v_pk_add_f32 v[94:95], v[94:95], v[246:247]
	v_lshlrev_b32_e32 v246, 16, v167
	v_and_b32_e32 v247, 0xffff0000, v167
	v_pk_add_f32 v[96:97], v[96:97], v[246:247]
	v_lshlrev_b32_e32 v246, 16, v168
	v_and_b32_e32 v247, 0xffff0000, v168
	v_pk_add_f32 v[90:91], v[90:91], v[246:247]
	v_lshlrev_b32_e32 v246, 16, v169
	v_and_b32_e32 v247, 0xffff0000, v169
	v_pk_add_f32 v[92:93], v[92:93], v[246:247]
	v_cvt_pk_bf16_f32 v166, v94, v95
	v_cvt_pk_bf16_f32 v167, v96, v97
	v_cvt_pk_bf16_f32 v168, v90, v91
	v_cvt_pk_bf16_f32 v169, v92, v93
	global_store_dwordx4 v245, v[166:169], s[40:41] sc0 sc1
	v_mul_f32_e32 v94, v94, v94
	v_fmac_f32_e32 v94, v95, v95
	v_fmac_f32_e32 v94, v96, v96
	v_fmac_f32_e32 v94, v97, v97
	v_fmac_f32_e32 v94, v90, v90
	v_fmac_f32_e32 v94, v91, v91
	v_fmac_f32_e32 v94, v92, v92
	v_fmac_f32_e32 v94, v93, v93
	s_waitcnt vmcnt(15)
	v_lshlrev_b32_e32 v246, 16, v170
	v_and_b32_e32 v247, 0xffff0000, v170
	v_pk_add_f32 v[86:87], v[86:87], v[246:247]
	v_lshlrev_b32_e32 v246, 16, v171
	v_and_b32_e32 v247, 0xffff0000, v171
	v_pk_add_f32 v[88:89], v[88:89], v[246:247]
	v_lshlrev_b32_e32 v246, 16, v172
	v_and_b32_e32 v247, 0xffff0000, v172
	v_pk_add_f32 v[82:83], v[82:83], v[246:247]
	v_lshlrev_b32_e32 v246, 16, v173
	v_and_b32_e32 v247, 0xffff0000, v173
	v_pk_add_f32 v[84:85], v[84:85], v[246:247]
	v_cvt_pk_bf16_f32 v170, v86, v87
	v_cvt_pk_bf16_f32 v171, v88, v89
	v_cvt_pk_bf16_f32 v172, v82, v83
	v_cvt_pk_bf16_f32 v173, v84, v85
	global_store_dwordx4 v245, v[170:173], s[40:41] offset:256 sc0 sc1
	v_fmac_f32_e32 v94, v86, v86
	v_fmac_f32_e32 v94, v87, v87
	v_fmac_f32_e32 v94, v88, v88
	v_fmac_f32_e32 v94, v89, v89
	v_fmac_f32_e32 v94, v82, v82
	v_fmac_f32_e32 v94, v83, v83
	v_fmac_f32_e32 v94, v84, v84
	v_fmac_f32_e32 v94, v85, v85
	s_add_u32 s40, s24, 0x60000
	s_addc_u32 s41, s25, 0
	s_waitcnt vmcnt(15)
	v_lshlrev_b32_e32 v246, 16, v174
	v_and_b32_e32 v247, 0xffff0000, v174
	v_pk_add_f32 v[78:79], v[78:79], v[246:247]
	v_lshlrev_b32_e32 v246, 16, v175
	v_and_b32_e32 v247, 0xffff0000, v175
	v_pk_add_f32 v[80:81], v[80:81], v[246:247]
	v_lshlrev_b32_e32 v246, 16, v176
	v_and_b32_e32 v247, 0xffff0000, v176
	v_pk_add_f32 v[74:75], v[74:75], v[246:247]
	v_lshlrev_b32_e32 v246, 16, v177
	v_and_b32_e32 v247, 0xffff0000, v177
	v_pk_add_f32 v[76:77], v[76:77], v[246:247]
	v_cvt_pk_bf16_f32 v174, v78, v79
	v_cvt_pk_bf16_f32 v175, v80, v81
	v_cvt_pk_bf16_f32 v176, v74, v75
	v_cvt_pk_bf16_f32 v177, v76, v77
	global_store_dwordx4 v245, v[174:177], s[40:41] sc0 sc1
	v_mul_f32_e32 v78, v78, v78
	v_fmac_f32_e32 v78, v79, v79
	v_fmac_f32_e32 v78, v80, v80
	v_fmac_f32_e32 v78, v81, v81
	v_fmac_f32_e32 v78, v74, v74
	v_fmac_f32_e32 v78, v75, v75
	v_fmac_f32_e32 v78, v76, v76
	v_fmac_f32_e32 v78, v77, v77
	s_waitcnt vmcnt(15)
	v_lshlrev_b32_e32 v246, 16, v178
	v_and_b32_e32 v247, 0xffff0000, v178
	v_pk_add_f32 v[70:71], v[70:71], v[246:247]
	v_lshlrev_b32_e32 v246, 16, v179
	v_and_b32_e32 v247, 0xffff0000, v179
	v_pk_add_f32 v[72:73], v[72:73], v[246:247]
	v_lshlrev_b32_e32 v246, 16, v180
	v_and_b32_e32 v247, 0xffff0000, v180
	v_pk_add_f32 v[66:67], v[66:67], v[246:247]
	v_lshlrev_b32_e32 v246, 16, v181
	v_and_b32_e32 v247, 0xffff0000, v181
	v_pk_add_f32 v[68:69], v[68:69], v[246:247]
	v_cvt_pk_bf16_f32 v178, v70, v71
	v_cvt_pk_bf16_f32 v179, v72, v73
	v_cvt_pk_bf16_f32 v180, v66, v67
	v_cvt_pk_bf16_f32 v181, v68, v69
	global_store_dwordx4 v245, v[178:181], s[40:41] offset:256 sc0 sc1
	v_fmac_f32_e32 v78, v70, v70
	v_fmac_f32_e32 v78, v71, v71
	v_fmac_f32_e32 v78, v72, v72
	v_fmac_f32_e32 v78, v73, v73
	v_fmac_f32_e32 v78, v66, v66
	v_fmac_f32_e32 v78, v67, v67
	v_fmac_f32_e32 v78, v68, v68
	v_fmac_f32_e32 v78, v69, v69
	s_add_u32 s40, s24, 0x100000
	s_addc_u32 s41, s25, 0
	s_waitcnt vmcnt(15)
	v_lshlrev_b32_e32 v246, 16, v182
	v_and_b32_e32 v247, 0xffff0000, v182
	v_pk_add_f32 v[62:63], v[62:63], v[246:247]
	v_lshlrev_b32_e32 v246, 16, v183
	v_and_b32_e32 v247, 0xffff0000, v183
	v_pk_add_f32 v[64:65], v[64:65], v[246:247]
	v_lshlrev_b32_e32 v246, 16, v184
	v_and_b32_e32 v247, 0xffff0000, v184
	v_pk_add_f32 v[58:59], v[58:59], v[246:247]
	v_lshlrev_b32_e32 v246, 16, v185
	v_and_b32_e32 v247, 0xffff0000, v185
	v_pk_add_f32 v[60:61], v[60:61], v[246:247]
	v_cvt_pk_bf16_f32 v182, v62, v63
	v_cvt_pk_bf16_f32 v183, v64, v65
	v_cvt_pk_bf16_f32 v184, v58, v59
	v_cvt_pk_bf16_f32 v185, v60, v61
	global_store_dwordx4 v245, v[182:185], s[40:41] sc0 sc1
	v_mul_f32_e32 v62, v62, v62
	v_fmac_f32_e32 v62, v63, v63
	v_fmac_f32_e32 v62, v64, v64
	v_fmac_f32_e32 v62, v65, v65
	v_fmac_f32_e32 v62, v58, v58
	v_fmac_f32_e32 v62, v59, v59
	v_fmac_f32_e32 v62, v60, v60
	v_fmac_f32_e32 v62, v61, v61
	s_waitcnt vmcnt(15)
	v_lshlrev_b32_e32 v246, 16, v186
	v_and_b32_e32 v247, 0xffff0000, v186
	v_pk_add_f32 v[54:55], v[54:55], v[246:247]
	v_lshlrev_b32_e32 v246, 16, v187
	v_and_b32_e32 v247, 0xffff0000, v187
	v_pk_add_f32 v[56:57], v[56:57], v[246:247]
	v_lshlrev_b32_e32 v246, 16, v188
	v_and_b32_e32 v247, 0xffff0000, v188
	v_pk_add_f32 v[50:51], v[50:51], v[246:247]
	v_lshlrev_b32_e32 v246, 16, v189
	v_and_b32_e32 v247, 0xffff0000, v189
	v_pk_add_f32 v[52:53], v[52:53], v[246:247]
	v_cvt_pk_bf16_f32 v186, v54, v55
	v_cvt_pk_bf16_f32 v187, v56, v57
	v_cvt_pk_bf16_f32 v188, v50, v51
	v_cvt_pk_bf16_f32 v189, v52, v53
	global_store_dwordx4 v245, v[186:189], s[40:41] offset:256 sc0 sc1
	v_fmac_f32_e32 v62, v54, v54
	v_fmac_f32_e32 v62, v55, v55
	v_fmac_f32_e32 v62, v56, v56
	v_fmac_f32_e32 v62, v57, v57
	v_fmac_f32_e32 v62, v50, v50
	v_fmac_f32_e32 v62, v51, v51
	v_fmac_f32_e32 v62, v52, v52
	v_fmac_f32_e32 v62, v53, v53
	s_add_u32 s40, s24, 0x120000
	s_addc_u32 s41, s25, 0
	s_waitcnt vmcnt(15)
	v_lshlrev_b32_e32 v246, 16, v190
	v_and_b32_e32 v247, 0xffff0000, v190
	v_pk_add_f32 v[46:47], v[46:47], v[246:247]
	v_lshlrev_b32_e32 v246, 16, v191
	v_and_b32_e32 v247, 0xffff0000, v191
	v_pk_add_f32 v[48:49], v[48:49], v[246:247]
	v_lshlrev_b32_e32 v246, 16, v192
	v_and_b32_e32 v247, 0xffff0000, v192
	v_pk_add_f32 v[42:43], v[42:43], v[246:247]
	v_lshlrev_b32_e32 v246, 16, v193
	v_and_b32_e32 v247, 0xffff0000, v193
	v_pk_add_f32 v[44:45], v[44:45], v[246:247]
	v_cvt_pk_bf16_f32 v190, v46, v47
	v_cvt_pk_bf16_f32 v191, v48, v49
	v_cvt_pk_bf16_f32 v192, v42, v43
	v_cvt_pk_bf16_f32 v193, v44, v45
	global_store_dwordx4 v245, v[190:193], s[40:41] sc0 sc1
	v_mul_f32_e32 v46, v46, v46
	v_fmac_f32_e32 v46, v47, v47
	v_fmac_f32_e32 v46, v48, v48
	v_fmac_f32_e32 v46, v49, v49
	v_fmac_f32_e32 v46, v42, v42
	v_fmac_f32_e32 v46, v43, v43
	v_fmac_f32_e32 v46, v44, v44
	v_fmac_f32_e32 v46, v45, v45
	s_waitcnt vmcnt(15)
	v_lshlrev_b32_e32 v246, 16, v194
	v_and_b32_e32 v247, 0xffff0000, v194
	v_pk_add_f32 v[38:39], v[38:39], v[246:247]
	v_lshlrev_b32_e32 v246, 16, v195
	v_and_b32_e32 v247, 0xffff0000, v195
	v_pk_add_f32 v[40:41], v[40:41], v[246:247]
	v_lshlrev_b32_e32 v246, 16, v196
	v_and_b32_e32 v247, 0xffff0000, v196
	v_pk_add_f32 v[34:35], v[34:35], v[246:247]
	v_lshlrev_b32_e32 v246, 16, v197
	v_and_b32_e32 v247, 0xffff0000, v197
	v_pk_add_f32 v[36:37], v[36:37], v[246:247]
	v_cvt_pk_bf16_f32 v194, v38, v39
	v_cvt_pk_bf16_f32 v195, v40, v41
	v_cvt_pk_bf16_f32 v196, v34, v35
	v_cvt_pk_bf16_f32 v197, v36, v37
	global_store_dwordx4 v245, v[194:197], s[40:41] offset:256 sc0 sc1
	v_fmac_f32_e32 v46, v38, v38
	v_fmac_f32_e32 v46, v39, v39
	v_fmac_f32_e32 v46, v40, v40
	v_fmac_f32_e32 v46, v41, v41
	v_fmac_f32_e32 v46, v34, v34
	v_fmac_f32_e32 v46, v35, v35
	v_fmac_f32_e32 v46, v36, v36
	v_fmac_f32_e32 v46, v37, v37
	s_add_u32 s40, s24, 0x140000
	s_addc_u32 s41, s25, 0
	s_waitcnt vmcnt(15)
	v_lshlrev_b32_e32 v246, 16, v198
	v_and_b32_e32 v247, 0xffff0000, v198
	v_pk_add_f32 v[30:31], v[30:31], v[246:247]
	v_lshlrev_b32_e32 v246, 16, v199
	v_and_b32_e32 v247, 0xffff0000, v199
	v_pk_add_f32 v[32:33], v[32:33], v[246:247]
	v_lshlrev_b32_e32 v246, 16, v200
	v_and_b32_e32 v247, 0xffff0000, v200
	v_pk_add_f32 v[26:27], v[26:27], v[246:247]
	v_lshlrev_b32_e32 v246, 16, v201
	v_and_b32_e32 v247, 0xffff0000, v201
	v_pk_add_f32 v[28:29], v[28:29], v[246:247]
	v_cvt_pk_bf16_f32 v198, v30, v31
	v_cvt_pk_bf16_f32 v199, v32, v33
	v_cvt_pk_bf16_f32 v200, v26, v27
	v_cvt_pk_bf16_f32 v201, v28, v29
	global_store_dwordx4 v245, v[198:201], s[40:41] sc0 sc1
	v_mul_f32_e32 v30, v30, v30
	v_fmac_f32_e32 v30, v31, v31
	v_fmac_f32_e32 v30, v32, v32
	v_fmac_f32_e32 v30, v33, v33
	v_fmac_f32_e32 v30, v26, v26
	v_fmac_f32_e32 v30, v27, v27
	v_fmac_f32_e32 v30, v28, v28
	v_fmac_f32_e32 v30, v29, v29
	s_waitcnt vmcnt(15)
	v_lshlrev_b32_e32 v246, 16, v202
	v_and_b32_e32 v247, 0xffff0000, v202
	v_pk_add_f32 v[22:23], v[22:23], v[246:247]
	v_lshlrev_b32_e32 v246, 16, v203
	v_and_b32_e32 v247, 0xffff0000, v203
	v_pk_add_f32 v[24:25], v[24:25], v[246:247]
	v_lshlrev_b32_e32 v246, 16, v204
	v_and_b32_e32 v247, 0xffff0000, v204
	v_pk_add_f32 v[18:19], v[18:19], v[246:247]
	v_lshlrev_b32_e32 v246, 16, v205
	v_and_b32_e32 v247, 0xffff0000, v205
	v_pk_add_f32 v[20:21], v[20:21], v[246:247]
	v_cvt_pk_bf16_f32 v202, v22, v23
	v_cvt_pk_bf16_f32 v203, v24, v25
	v_cvt_pk_bf16_f32 v204, v18, v19
	v_cvt_pk_bf16_f32 v205, v20, v21
	global_store_dwordx4 v245, v[202:205], s[40:41] offset:256 sc0 sc1
	v_fmac_f32_e32 v30, v22, v22
	v_fmac_f32_e32 v30, v23, v23
	v_fmac_f32_e32 v30, v24, v24
	v_fmac_f32_e32 v30, v25, v25
	v_fmac_f32_e32 v30, v18, v18
	v_fmac_f32_e32 v30, v19, v19
	v_fmac_f32_e32 v30, v20, v20
	v_fmac_f32_e32 v30, v21, v21
	s_add_u32 s40, s24, 0x160000
	s_addc_u32 s41, s25, 0
	s_waitcnt vmcnt(15)
	v_lshlrev_b32_e32 v246, 16, v206
	v_and_b32_e32 v247, 0xffff0000, v206
	v_pk_add_f32 v[14:15], v[14:15], v[246:247]
	v_lshlrev_b32_e32 v246, 16, v207
	v_and_b32_e32 v247, 0xffff0000, v207
	v_pk_add_f32 v[16:17], v[16:17], v[246:247]
	v_lshlrev_b32_e32 v246, 16, v208
	v_and_b32_e32 v247, 0xffff0000, v208
	v_pk_add_f32 v[10:11], v[10:11], v[246:247]
	v_lshlrev_b32_e32 v246, 16, v209
	v_and_b32_e32 v247, 0xffff0000, v209
	v_pk_add_f32 v[12:13], v[12:13], v[246:247]
	v_cvt_pk_bf16_f32 v206, v14, v15
	v_cvt_pk_bf16_f32 v207, v16, v17
	v_cvt_pk_bf16_f32 v208, v10, v11
	v_cvt_pk_bf16_f32 v209, v12, v13
	global_store_dwordx4 v245, v[206:209], s[40:41] sc0 sc1
	v_mul_f32_e32 v14, v14, v14
	v_fmac_f32_e32 v14, v15, v15
	v_fmac_f32_e32 v14, v16, v16
	v_fmac_f32_e32 v14, v17, v17
	v_fmac_f32_e32 v14, v10, v10
	v_fmac_f32_e32 v14, v11, v11
	v_fmac_f32_e32 v14, v12, v12
	v_fmac_f32_e32 v14, v13, v13
	s_waitcnt vmcnt(15)
	v_lshlrev_b32_e32 v246, 16, v210
	v_and_b32_e32 v247, 0xffff0000, v210
	v_pk_add_f32 v[6:7], v[6:7], v[246:247]
	v_lshlrev_b32_e32 v246, 16, v211
	v_and_b32_e32 v247, 0xffff0000, v211
	v_pk_add_f32 v[8:9], v[8:9], v[246:247]
	v_lshlrev_b32_e32 v246, 16, v212
	v_and_b32_e32 v247, 0xffff0000, v212
	v_pk_add_f32 v[2:3], v[2:3], v[246:247]
	v_lshlrev_b32_e32 v246, 16, v213
	v_and_b32_e32 v247, 0xffff0000, v213
	v_pk_add_f32 v[4:5], v[4:5], v[246:247]
	v_cvt_pk_bf16_f32 v210, v6, v7
	v_cvt_pk_bf16_f32 v211, v8, v9
	v_cvt_pk_bf16_f32 v212, v2, v3
	v_cvt_pk_bf16_f32 v213, v4, v5
	global_store_dwordx4 v245, v[210:213], s[40:41] offset:256 sc0 sc1
	v_fmac_f32_e32 v14, v6, v6
	v_fmac_f32_e32 v14, v7, v7
	v_fmac_f32_e32 v14, v8, v8
	v_fmac_f32_e32 v14, v9, v9
	v_fmac_f32_e32 v14, v2, v2
	v_fmac_f32_e32 v14, v3, v3
	v_fmac_f32_e32 v14, v4, v4
	v_fmac_f32_e32 v14, v5, v5
	v_mbcnt_lo_u32_b32 v246, -1, 0
	v_mbcnt_hi_u32_b32 v246, -1, v246
	v_xor_b32_e32 v247, 32, v246
	v_xor_b32_e32 v246, 16, v246
	v_lshlrev_b32_e32 v246, 2, v246
	v_lshlrev_b32_e32 v247, 2, v247
	ds_bpermute_b32 v127, v246, v126
	ds_bpermute_b32 v111, v246, v110
	ds_bpermute_b32 v95, v246, v94
	ds_bpermute_b32 v79, v246, v78
	ds_bpermute_b32 v63, v246, v62
	ds_bpermute_b32 v47, v246, v46
	ds_bpermute_b32 v31, v246, v30
	ds_bpermute_b32 v15, v246, v14
	s_waitcnt lgkmcnt(0)
	v_add_f32_e32 v126, v126, v127
	v_add_f32_e32 v110, v110, v111
	v_add_f32_e32 v94, v94, v95
	v_add_f32_e32 v78, v78, v79
	v_add_f32_e32 v62, v62, v63
	v_add_f32_e32 v46, v46, v47
	v_add_f32_e32 v30, v30, v31
	v_add_f32_e32 v14, v14, v15
	ds_bpermute_b32 v127, v247, v126
	ds_bpermute_b32 v111, v247, v110
	ds_bpermute_b32 v95, v247, v94
	ds_bpermute_b32 v79, v247, v78
	ds_bpermute_b32 v63, v247, v62
	ds_bpermute_b32 v47, v247, v46
	ds_bpermute_b32 v31, v247, v30
	ds_bpermute_b32 v15, v247, v14
	s_waitcnt lgkmcnt(0)
	v_add_f32_e32 v126, v126, v127
	v_add_f32_e32 v110, v110, v111
	v_add_f32_e32 v94, v94, v95
	v_add_f32_e32 v78, v78, v79
	v_add_f32_e32 v62, v62, v63
	v_add_f32_e32 v46, v46, v47
	v_add_f32_e32 v30, v30, v31
	v_add_f32_e32 v14, v14, v15
	v_lshl_add_u32 v246, s68, 8, v146
	v_lshlrev_b32_e32 v246, 2, v246
	s_and_saveexec_b64 s[40:41], s[6:7]
	global_atomic_add_f32 v246, v126, s[12:13]
	global_atomic_add_f32 v246, v110, s[12:13] offset:64
	global_atomic_add_f32 v246, v94, s[12:13] offset:128
	global_atomic_add_f32 v246, v78, s[12:13] offset:192
	global_atomic_add_f32 v246, v62, s[12:13] offset:512
	global_atomic_add_f32 v246, v46, s[12:13] offset:576
	global_atomic_add_f32 v246, v30, s[12:13] offset:640
	global_atomic_add_f32 v246, v14, s[12:13] offset:704
	s_mov_b64 exec, s[40:41]
	s_and_b64 vcc, exec, s[8:9]
	s_mov_b64 s[8:9], -1
	s_cbranch_vccnz .LBB0_2106
	s_andn2_b64 vcc, exec, s[10:11]
	s_cbranch_vccnz .LBB0_2105
	s_barrier
	s_branch .LBB0_2105

.LBB0_2159:
	ds_read_b128 v[2:5], v183
	ds_read_b128 v[6:9], v183 offset:1024
	ds_read_b128 v[138:141], v183 offset:2048
	ds_read_b128 v[142:145], v183 offset:3072
	ds_read_b128 v[146:149], v184
	ds_read_b128 v[150:153], v184 offset:1024
	ds_read_b128 v[168:171], v184 offset:2048
	ds_read_b128 v[172:175], v184 offset:3072
	s_add_u32 s10, s8, 0xfff80080
	s_addc_u32 s11, s9, -1
	s_cmp_eq_u32 s79, 28
	s_cselect_b32 s13, s41, s11
	s_cselect_b32 s12, s75, s10
	s_cselect_b32 s11, s39, s78
	s_cselect_b32 s10, s76, s77
	s_add_i32 m0, s15, 0xc000
	ds_read_b128 v[176:179], v185
	ds_read_b128 v[188:191], v185 offset:1024
	ds_read_b128 v[192:195], v185 offset:2048
	ds_read_b128 v[196:199], v185 offset:3072
	ds_read_b128 v[200:203], v185 offset:4096
	ds_read_b128 v[204:207], v185 offset:5120
	ds_read_b128 v[208:211], v185 offset:6144
	ds_read_b128 v[212:215], v185 offset:7168
	global_load_lds_dwordx4 v164, s[8:9]
	s_add_i32 m0, s15, 0xe000
	s_nop 0
	global_load_lds_dwordx4 v162, s[8:9]
	s_waitcnt vmcnt(8)
	s_waitcnt lgkmcnt(0)
	s_barrier
	s_setprio 1
	s_waitcnt lgkmcnt(0)
	v_mfma_i32_16x16x64_i8 v[134:137], v[2:5], v[176:179], v[134:137]
	v_mfma_i32_16x16x64_i8 v[126:129], v[138:141], v[176:179], v[126:129]
	v_mfma_i32_16x16x64_i8 v[118:121], v[2:5], v[192:195], v[118:121]
	v_mfma_i32_16x16x64_i8 v[110:113], v[138:141], v[192:195], v[110:113]
	v_mfma_i32_16x16x64_i8 v[102:105], v[2:5], v[200:203], v[102:105]
	v_mfma_i32_16x16x64_i8 v[94:97], v[138:141], v[200:203], v[94:97]
	v_mfma_i32_16x16x64_i8 v[86:89], v[2:5], v[208:211], v[86:89]
	v_mfma_i32_16x16x64_i8 v[78:81], v[138:141], v[208:211], v[78:81]
	v_mfma_i32_16x16x64_i8 v[134:137], v[6:9], v[188:191], v[134:137]
	v_mfma_i32_16x16x64_i8 v[126:129], v[142:145], v[188:191], v[126:129]
	v_mfma_i32_16x16x64_i8 v[118:121], v[6:9], v[196:199], v[118:121]
	v_mfma_i32_16x16x64_i8 v[110:113], v[142:145], v[196:199], v[110:113]
	v_mfma_i32_16x16x64_i8 v[102:105], v[6:9], v[204:207], v[102:105]
	v_mfma_i32_16x16x64_i8 v[94:97], v[142:145], v[204:207], v[94:97]
	v_mfma_i32_16x16x64_i8 v[86:89], v[6:9], v[212:215], v[86:89]
	v_mfma_i32_16x16x64_i8 v[78:81], v[142:145], v[212:215], v[78:81]
	s_setprio 0
	s_setprio 1
	v_mfma_i32_16x16x64_i8 v[130:133], v[146:149], v[176:179], v[130:133]
	v_mfma_i32_16x16x64_i8 v[122:125], v[168:171], v[176:179], v[122:125]
	v_mfma_i32_16x16x64_i8 v[114:117], v[146:149], v[192:195], v[114:117]
	v_mfma_i32_16x16x64_i8 v[106:109], v[168:171], v[192:195], v[106:109]
	v_mfma_i32_16x16x64_i8 v[98:101], v[146:149], v[200:203], v[98:101]
	v_mfma_i32_16x16x64_i8 v[90:93], v[168:171], v[200:203], v[90:93]
	v_mfma_i32_16x16x64_i8 v[82:85], v[146:149], v[208:211], v[82:85]
	v_mfma_i32_16x16x64_i8 v[74:77], v[168:171], v[208:211], v[74:77]
	v_mfma_i32_16x16x64_i8 v[130:133], v[150:153], v[188:191], v[130:133]
	v_mfma_i32_16x16x64_i8 v[122:125], v[172:175], v[188:191], v[122:125]
	v_mfma_i32_16x16x64_i8 v[114:117], v[150:153], v[196:199], v[114:117]
	v_mfma_i32_16x16x64_i8 v[106:109], v[172:175], v[196:199], v[106:109]
	v_mfma_i32_16x16x64_i8 v[98:101], v[150:153], v[204:207], v[98:101]
	v_mfma_i32_16x16x64_i8 v[90:93], v[172:175], v[204:207], v[90:93]
	v_mfma_i32_16x16x64_i8 v[82:85], v[150:153], v[212:215], v[82:85]
	v_mfma_i32_16x16x64_i8 v[74:77], v[172:175], v[212:215], v[74:77]
	s_setprio 0
	s_barrier
	s_add_i32 s16, s69, s56
	v_lshl_add_u64 v[216:217], s[10:11], 0, v[156:157]
	s_mov_b32 m0, s16
	ds_read_b128 v[176:179], v185 offset:16384
	ds_read_b128 v[188:191], v185 offset:17408
	ds_read_b128 v[192:195], v185 offset:18432
	ds_read_b128 v[196:199], v185 offset:19456
	ds_read_b128 v[200:203], v185 offset:20480
	ds_read_b128 v[204:207], v185 offset:21504
	ds_read_b128 v[208:211], v185 offset:22528
	ds_read_b128 v[212:215], v185 offset:23552
	global_load_lds_dwordx4 v[216:217], off
	s_add_i32 m0, s16, 0x2000
	s_add_u32 s16, s10, 0x80000
	v_lshl_add_u64 v[218:219], s[10:11], 0, v[160:161]
	s_addc_u32 s17, s11, 0
	s_add_i32 s80, s70, s56
	global_load_lds_dwordx4 v[218:219], off
	s_mov_b32 m0, s80
	v_lshl_add_u64 v[222:223], s[12:13], 0, v[158:159]
	global_load_lds_dwordx4 v156, s[16:17]
	s_add_i32 m0, s80, 0x2000
	s_nop 0
	global_load_lds_dwordx4 v160, s[16:17]
	v_lshl_add_u64 v[220:221], s[12:13], 0, v[154:155]
	s_mov_b32 m0, s15
	s_nop 0
	global_load_lds_dwordx4 v[220:221], off
	s_mov_b32 m0, s60
	s_nop 0
	global_load_lds_dwordx4 v[222:223], off
	s_waitcnt vmcnt(8)
	s_waitcnt lgkmcnt(0)
	s_barrier
	s_setprio 1
	s_waitcnt lgkmcnt(0)
	v_mfma_i32_16x16x64_i8 v[70:73], v[2:5], v[176:179], v[70:73]
	v_mfma_i32_16x16x64_i8 v[62:65], v[138:141], v[176:179], v[62:65]
	v_mfma_i32_16x16x64_i8 v[54:57], v[2:5], v[192:195], v[54:57]
	v_mfma_i32_16x16x64_i8 v[46:49], v[138:141], v[192:195], v[46:49]
	v_mfma_i32_16x16x64_i8 v[38:41], v[2:5], v[200:203], v[38:41]
	v_mfma_i32_16x16x64_i8 v[30:33], v[138:141], v[200:203], v[30:33]
	v_mfma_i32_16x16x64_i8 v[2:5], v[2:5], v[208:211], v[22:25]
	v_mfma_i32_16x16x64_i8 v[70:73], v[6:9], v[188:191], v[70:73]
	v_mfma_i32_16x16x64_i8 v[62:65], v[142:145], v[188:191], v[62:65]
	v_mfma_i32_16x16x64_i8 v[54:57], v[6:9], v[196:199], v[54:57]
	v_mfma_i32_16x16x64_i8 v[46:49], v[142:145], v[196:199], v[46:49]
	v_mfma_i32_16x16x64_i8 v[38:41], v[6:9], v[204:207], v[38:41]
	v_mfma_i32_16x16x64_i8 v[30:33], v[142:145], v[204:207], v[30:33]
	v_mfma_i32_16x16x64_i8 v[2:5], v[6:9], v[212:215], v[2:5]
	v_mfma_i32_16x16x64_i8 v[6:9], v[138:141], v[208:211], v[14:17]
	v_mfma_i32_16x16x64_i8 v[6:9], v[142:145], v[212:215], v[6:9]
	s_setprio 0
	s_setprio 1
	v_mfma_i32_16x16x64_i8 v[14:17], v[146:149], v[176:179], v[66:69]
	v_mfma_i32_16x16x64_i8 v[66:69], v[150:153], v[188:191], v[14:17]
	v_mfma_i32_16x16x64_i8 v[14:17], v[168:171], v[176:179], v[58:61]
	v_mfma_i32_16x16x64_i8 v[58:61], v[172:175], v[188:191], v[14:17]
	v_mfma_i32_16x16x64_i8 v[14:17], v[146:149], v[192:195], v[50:53]
	v_mfma_i32_16x16x64_i8 v[50:53], v[150:153], v[196:199], v[14:17]
	v_mfma_i32_16x16x64_i8 v[14:17], v[168:171], v[192:195], v[42:45]
	v_mfma_i32_16x16x64_i8 v[42:45], v[172:175], v[196:199], v[14:17]
	v_mfma_i32_16x16x64_i8 v[14:17], v[146:149], v[200:203], v[34:37]
	v_mfma_i32_16x16x64_i8 v[34:37], v[150:153], v[204:207], v[14:17]
	v_mfma_i32_16x16x64_i8 v[14:17], v[168:171], v[200:203], v[26:29]
	v_mfma_i32_16x16x64_i8 v[26:29], v[172:175], v[204:207], v[14:17]
	v_mfma_i32_16x16x64_i8 v[14:17], v[146:149], v[208:211], v[18:21]
	v_mfma_i32_16x16x64_i8 v[10:13], v[168:171], v[208:211], v[10:13]
	v_mfma_i32_16x16x64_i8 v[18:21], v[150:153], v[212:215], v[14:17]
	v_mfma_i32_16x16x64_i8 v[10:13], v[172:175], v[212:215], v[10:13]
	s_setprio 0
	s_barrier
	s_add_i32 s16, 0, 0x18000
	s_add_i32 s17, 0, 0x1c000
	v_add_u32_e32 v142, s16, v181
	v_add_u32_e32 v172, s17, v181
	ds_read_b128 v[14:17], v142
	ds_read_b128 v[22:25], v142 offset:1024
	ds_read_b128 v[138:141], v142 offset:2048
	ds_read_b128 v[142:145], v142 offset:3072
	ds_read_b128 v[146:149], v172
	ds_read_b128 v[150:153], v172 offset:1024
	ds_read_b128 v[168:171], v172 offset:2048
	ds_read_b128 v[172:175], v172 offset:3072
	s_add_u32 s12, s12, 0x80000
	s_addc_u32 s13, s13, 0
	s_mov_b32 m0, s61
	ds_read_b128 v[176:179], v185 offset:32768
	ds_read_b128 v[188:191], v185 offset:33792
	ds_read_b128 v[192:195], v185 offset:34816
	ds_read_b128 v[196:199], v185 offset:35840
	ds_read_b128 v[200:203], v185 offset:36864
	ds_read_b128 v[204:207], v185 offset:37888
	ds_read_b128 v[208:211], v185 offset:38912
	ds_read_b128 v[212:215], v185 offset:39936
	global_load_lds_dwordx4 v154, s[12:13]
	s_mov_b32 m0, s62
	s_nop 0
	global_load_lds_dwordx4 v158, s[12:13]
	s_waitcnt vmcnt(8)
	s_waitcnt lgkmcnt(0)
	s_barrier
	s_setprio 1
	s_waitcnt lgkmcnt(0)
	v_mfma_i32_16x16x64_i8 v[134:137], v[14:17], v[176:179], v[134:137]
	v_mfma_i32_16x16x64_i8 v[126:129], v[138:141], v[176:179], v[126:129]
	v_mfma_i32_16x16x64_i8 v[118:121], v[14:17], v[192:195], v[118:121]
	v_mfma_i32_16x16x64_i8 v[110:113], v[138:141], v[192:195], v[110:113]
	v_mfma_i32_16x16x64_i8 v[102:105], v[14:17], v[200:203], v[102:105]
	v_mfma_i32_16x16x64_i8 v[94:97], v[138:141], v[200:203], v[94:97]
	v_mfma_i32_16x16x64_i8 v[86:89], v[14:17], v[208:211], v[86:89]
	v_mfma_i32_16x16x64_i8 v[78:81], v[138:141], v[208:211], v[78:81]
	v_mfma_i32_16x16x64_i8 v[134:137], v[22:25], v[188:191], v[134:137]
	v_mfma_i32_16x16x64_i8 v[126:129], v[142:145], v[188:191], v[126:129]
	v_mfma_i32_16x16x64_i8 v[118:121], v[22:25], v[196:199], v[118:121]
	v_mfma_i32_16x16x64_i8 v[110:113], v[142:145], v[196:199], v[110:113]
	v_mfma_i32_16x16x64_i8 v[102:105], v[22:25], v[204:207], v[102:105]
	v_mfma_i32_16x16x64_i8 v[94:97], v[142:145], v[204:207], v[94:97]
	v_mfma_i32_16x16x64_i8 v[86:89], v[22:25], v[212:215], v[86:89]
	v_mfma_i32_16x16x64_i8 v[78:81], v[142:145], v[212:215], v[78:81]
	s_setprio 0
	s_setprio 1
	v_mfma_i32_16x16x64_i8 v[130:133], v[146:149], v[176:179], v[130:133]
	v_mfma_i32_16x16x64_i8 v[122:125], v[168:171], v[176:179], v[122:125]
	v_mfma_i32_16x16x64_i8 v[114:117], v[146:149], v[192:195], v[114:117]
	v_mfma_i32_16x16x64_i8 v[106:109], v[168:171], v[192:195], v[106:109]
	v_mfma_i32_16x16x64_i8 v[98:101], v[146:149], v[200:203], v[98:101]
	v_mfma_i32_16x16x64_i8 v[90:93], v[168:171], v[200:203], v[90:93]
	v_mfma_i32_16x16x64_i8 v[82:85], v[146:149], v[208:211], v[82:85]
	v_mfma_i32_16x16x64_i8 v[74:77], v[168:171], v[208:211], v[74:77]
	v_mfma_i32_16x16x64_i8 v[130:133], v[150:153], v[188:191], v[130:133]
	v_mfma_i32_16x16x64_i8 v[122:125], v[172:175], v[188:191], v[122:125]
	v_mfma_i32_16x16x64_i8 v[114:117], v[150:153], v[196:199], v[114:117]
	v_mfma_i32_16x16x64_i8 v[106:109], v[172:175], v[196:199], v[106:109]
	v_mfma_i32_16x16x64_i8 v[98:101], v[150:153], v[204:207], v[98:101]
	v_mfma_i32_16x16x64_i8 v[90:93], v[172:175], v[204:207], v[90:93]
	v_mfma_i32_16x16x64_i8 v[82:85], v[150:153], v[212:215], v[82:85]
	v_mfma_i32_16x16x64_i8 v[74:77], v[172:175], v[212:215], v[74:77]
	s_setprio 0
	s_barrier
	s_add_i32 s12, s16, s56
	v_lshl_add_u64 v[216:217], v[216:217], 0, s[34:35]
	s_mov_b32 m0, s12
	ds_read_b128 v[176:179], v185 offset:49152
	ds_read_b128 v[188:191], v185 offset:50176
	ds_read_b128 v[192:195], v185 offset:51200
	ds_read_b128 v[196:199], v185 offset:52224
	ds_read_b128 v[200:203], v185 offset:53248
	ds_read_b128 v[204:207], v185 offset:54272
	ds_read_b128 v[208:211], v185 offset:55296
	ds_read_b128 v[212:215], v185 offset:56320
	global_load_lds_dwordx4 v[216:217], off
	s_add_i32 m0, s12, 0x2000
	s_add_u32 s10, s10, 0x80080
	v_lshl_add_u64 v[216:217], v[218:219], 0, s[34:35]
	s_addc_u32 s11, s11, 0
	s_add_i32 s12, s17, s56
	global_load_lds_dwordx4 v[216:217], off
	s_mov_b32 m0, s12
	s_nop 0
	global_load_lds_dwordx4 v156, s[10:11]
	s_add_i32 m0, s12, 0x2000
	s_nop 0
	global_load_lds_dwordx4 v160, s[10:11]
	v_lshl_add_u64 v[216:217], v[220:221], 0, s[34:35]
	s_mov_b32 m0, s64
	s_nop 0
	global_load_lds_dwordx4 v[216:217], off
	v_lshl_add_u64 v[216:217], v[222:223], 0, s[34:35]
	s_mov_b32 m0, s65
	s_nop 0
	global_load_lds_dwordx4 v[216:217], off
	s_waitcnt vmcnt(8)
	s_waitcnt lgkmcnt(0)
	s_barrier
	s_setprio 1
	s_waitcnt lgkmcnt(0)
	v_mfma_i32_16x16x64_i8 v[70:73], v[14:17], v[176:179], v[70:73]
	v_mfma_i32_16x16x64_i8 v[54:57], v[14:17], v[192:195], v[54:57]
	v_mfma_i32_16x16x64_i8 v[38:41], v[14:17], v[200:203], v[38:41]
	v_mfma_i32_16x16x64_i8 v[2:5], v[14:17], v[208:211], v[2:5]
	v_mfma_i32_16x16x64_i8 v[70:73], v[22:25], v[188:191], v[70:73]
	v_mfma_i32_16x16x64_i8 v[62:65], v[138:141], v[176:179], v[62:65]
	v_mfma_i32_16x16x64_i8 v[54:57], v[22:25], v[196:199], v[54:57]
	v_mfma_i32_16x16x64_i8 v[46:49], v[138:141], v[192:195], v[46:49]
	v_mfma_i32_16x16x64_i8 v[38:41], v[22:25], v[204:207], v[38:41]
	v_mfma_i32_16x16x64_i8 v[30:33], v[138:141], v[200:203], v[30:33]
	v_mfma_i32_16x16x64_i8 v[22:25], v[22:25], v[212:215], v[2:5]
	v_mfma_i32_16x16x64_i8 v[2:5], v[138:141], v[208:211], v[6:9]
	v_mfma_i32_16x16x64_i8 v[62:65], v[142:145], v[188:191], v[62:65]
	v_mfma_i32_16x16x64_i8 v[46:49], v[142:145], v[196:199], v[46:49]
	v_mfma_i32_16x16x64_i8 v[30:33], v[142:145], v[204:207], v[30:33]
	v_mfma_i32_16x16x64_i8 v[14:17], v[142:145], v[212:215], v[2:5]
	s_setprio 0
	s_setprio 1
	v_mfma_i32_16x16x64_i8 v[2:5], v[146:149], v[176:179], v[66:69]
	v_mfma_i32_16x16x64_i8 v[66:69], v[150:153], v[188:191], v[2:5]
	v_mfma_i32_16x16x64_i8 v[2:5], v[168:171], v[176:179], v[58:61]
	v_mfma_i32_16x16x64_i8 v[58:61], v[172:175], v[188:191], v[2:5]
	v_mfma_i32_16x16x64_i8 v[2:5], v[146:149], v[192:195], v[50:53]
	v_mfma_i32_16x16x64_i8 v[50:53], v[150:153], v[196:199], v[2:5]
	v_mfma_i32_16x16x64_i8 v[2:5], v[168:171], v[192:195], v[42:45]
	v_mfma_i32_16x16x64_i8 v[42:45], v[172:175], v[196:199], v[2:5]
	v_mfma_i32_16x16x64_i8 v[2:5], v[146:149], v[200:203], v[34:37]
	v_mfma_i32_16x16x64_i8 v[34:37], v[150:153], v[204:207], v[2:5]
	v_mfma_i32_16x16x64_i8 v[2:5], v[168:171], v[200:203], v[26:29]
	v_mfma_i32_16x16x64_i8 v[26:29], v[172:175], v[204:207], v[2:5]
	v_mfma_i32_16x16x64_i8 v[2:5], v[146:149], v[208:211], v[18:21]
	v_mfma_i32_16x16x64_i8 v[18:21], v[150:153], v[212:215], v[2:5]
	v_mfma_i32_16x16x64_i8 v[2:5], v[168:171], v[208:211], v[10:13]
	v_mfma_i32_16x16x64_i8 v[10:13], v[172:175], v[212:215], v[2:5]
	s_setprio 0
	s_barrier
	s_add_i32 s79, s79, 2
	s_add_u32 s77, s77, 0x100
	s_addc_u32 s78, s78, 0
	s_add_u32 s8, s8, 0x100
	s_addc_u32 s9, s9, 0
	s_cmp_gt_u32 s79, 29
	s_cbranch_scc0 .LBB0_2159
	s_and_b64 vcc, exec, s[36:37]
	s_cbranch_vccz .LBB0_2162
	s_barrier

.LBB0_2248:
	ds_read_b128 v[146:149], v152
	ds_read_b128 v[156:159], v152 offset:1024
	ds_read_b128 v[160:163], v152 offset:2048
	ds_read_b128 v[164:167], v152 offset:3072
	ds_read_b128 v[168:171], v153
	ds_read_b128 v[172:175], v153 offset:1024
	ds_read_b128 v[176:179], v153 offset:2048
	ds_read_b128 v[180:183], v153 offset:3072
	s_add_u32 s28, s26, 0xffd50080
	s_addc_u32 s29, s27, -1
	s_cmpk_eq_i32 s64, 0xa8
	s_cselect_b32 s31, s11, s29
	s_cselect_b32 s30, s10, s28
	s_cselect_b32 s29, s25, s63
	s_cselect_b32 s28, s24, s62
	s_add_i32 m0, s38, 0xc000
	ds_read_b128 v[184:187], v154
	ds_read_b128 v[188:191], v154 offset:1024
	ds_read_b128 v[192:195], v154 offset:2048
	ds_read_b128 v[196:199], v154 offset:3072
	ds_read_b128 v[200:203], v154 offset:4096
	ds_read_b128 v[204:207], v154 offset:5120
	ds_read_b128 v[208:211], v154 offset:6144
	ds_read_b128 v[212:215], v154 offset:7168
	global_load_lds_dwordx4 v140, s[26:27]
	s_add_i32 m0, s38, 0xe000
	s_nop 0
	global_load_lds_dwordx4 v138, s[26:27]
	s_waitcnt vmcnt(8)
	s_waitcnt lgkmcnt(0)
	s_barrier
	s_setprio 1
	s_waitcnt lgkmcnt(0)
	v_mfma_f32_16x16x32_bf16 v[126:129], v[146:149], v[184:187], v[126:129]
	v_mfma_f32_16x16x32_bf16 v[122:125], v[160:163], v[184:187], v[122:125]
	v_mfma_f32_16x16x32_bf16 v[110:113], v[146:149], v[192:195], v[110:113]
	v_mfma_f32_16x16x32_bf16 v[106:109], v[160:163], v[192:195], v[106:109]
	v_mfma_f32_16x16x32_bf16 v[94:97], v[146:149], v[200:203], v[94:97]
	v_mfma_f32_16x16x32_bf16 v[90:93], v[160:163], v[200:203], v[90:93]
	v_mfma_f32_16x16x32_bf16 v[78:81], v[146:149], v[208:211], v[78:81]
	v_mfma_f32_16x16x32_bf16 v[74:77], v[160:163], v[208:211], v[74:77]
	v_mfma_f32_16x16x32_bf16 v[126:129], v[156:159], v[188:191], v[126:129]
	v_mfma_f32_16x16x32_bf16 v[122:125], v[164:167], v[188:191], v[122:125]
	v_mfma_f32_16x16x32_bf16 v[110:113], v[156:159], v[196:199], v[110:113]
	v_mfma_f32_16x16x32_bf16 v[106:109], v[164:167], v[196:199], v[106:109]
	v_mfma_f32_16x16x32_bf16 v[94:97], v[156:159], v[204:207], v[94:97]
	v_mfma_f32_16x16x32_bf16 v[90:93], v[164:167], v[204:207], v[90:93]
	v_mfma_f32_16x16x32_bf16 v[78:81], v[156:159], v[212:215], v[78:81]
	v_mfma_f32_16x16x32_bf16 v[74:77], v[164:167], v[212:215], v[74:77]
	s_setprio 0
	s_setprio 1
	v_mfma_f32_16x16x32_bf16 v[118:121], v[168:171], v[184:187], v[118:121]
	v_mfma_f32_16x16x32_bf16 v[114:117], v[176:179], v[184:187], v[114:117]
	v_mfma_f32_16x16x32_bf16 v[102:105], v[168:171], v[192:195], v[102:105]
	v_mfma_f32_16x16x32_bf16 v[98:101], v[176:179], v[192:195], v[98:101]
	v_mfma_f32_16x16x32_bf16 v[86:89], v[168:171], v[200:203], v[86:89]
	v_mfma_f32_16x16x32_bf16 v[82:85], v[176:179], v[200:203], v[82:85]
	v_mfma_f32_16x16x32_bf16 v[70:73], v[168:171], v[208:211], v[70:73]
	v_mfma_f32_16x16x32_bf16 v[66:69], v[176:179], v[208:211], v[66:69]
	v_mfma_f32_16x16x32_bf16 v[118:121], v[172:175], v[188:191], v[118:121]
	v_mfma_f32_16x16x32_bf16 v[114:117], v[180:183], v[188:191], v[114:117]
	v_mfma_f32_16x16x32_bf16 v[102:105], v[172:175], v[196:199], v[102:105]
	v_mfma_f32_16x16x32_bf16 v[98:101], v[180:183], v[196:199], v[98:101]
	v_mfma_f32_16x16x32_bf16 v[86:89], v[172:175], v[204:207], v[86:89]
	v_mfma_f32_16x16x32_bf16 v[82:85], v[180:183], v[204:207], v[82:85]
	v_mfma_f32_16x16x32_bf16 v[70:73], v[172:175], v[212:215], v[70:73]
	v_mfma_f32_16x16x32_bf16 v[66:69], v[180:183], v[212:215], v[66:69]
	s_setprio 0
	s_barrier
	s_add_i32 s65, s47, s37
	v_lshl_add_u64 v[216:217], s[28:29], 0, v[132:133]
	s_mov_b32 m0, s65
	ds_read_b128 v[184:187], v154 offset:16384
	ds_read_b128 v[188:191], v154 offset:17408
	ds_read_b128 v[192:195], v154 offset:18432
	ds_read_b128 v[196:199], v154 offset:19456
	ds_read_b128 v[200:203], v154 offset:20480
	ds_read_b128 v[204:207], v154 offset:21504
	ds_read_b128 v[208:211], v154 offset:22528
	ds_read_b128 v[212:215], v154 offset:23552
	global_load_lds_dwordx4 v[216:217], off
	s_add_i32 m0, s65, 0x2000
	s_add_u32 s66, s28, 0x2b0000
	v_lshl_add_u64 v[218:219], s[28:29], 0, v[136:137]
	s_addc_u32 s67, s29, 0
	s_add_i32 s65, s49, s37
	global_load_lds_dwordx4 v[218:219], off
	s_mov_b32 m0, s65
	v_lshl_add_u64 v[222:223], s[30:31], 0, v[134:135]
	global_load_lds_dwordx4 v132, s[66:67]
	s_add_i32 m0, s65, 0x2000
	s_nop 0
	global_load_lds_dwordx4 v136, s[66:67]
	v_lshl_add_u64 v[220:221], s[30:31], 0, v[130:131]
	s_mov_b32 m0, s38
	s_nop 0
	global_load_lds_dwordx4 v[220:221], off
	s_mov_b32 m0, s39
	s_nop 0
	global_load_lds_dwordx4 v[222:223], off
	s_waitcnt vmcnt(8)
	s_waitcnt lgkmcnt(0)
	s_barrier
	s_setprio 1
	s_waitcnt lgkmcnt(0)
	v_mfma_f32_16x16x32_bf16 v[62:65], v[146:149], v[184:187], v[62:65]
	v_mfma_f32_16x16x32_bf16 v[58:61], v[160:163], v[184:187], v[58:61]
	v_mfma_f32_16x16x32_bf16 v[46:49], v[146:149], v[192:195], v[46:49]
	v_mfma_f32_16x16x32_bf16 v[42:45], v[160:163], v[192:195], v[42:45]
	v_mfma_f32_16x16x32_bf16 v[30:33], v[146:149], v[200:203], v[30:33]
	v_mfma_f32_16x16x32_bf16 v[26:29], v[160:163], v[200:203], v[26:29]
	v_mfma_f32_16x16x32_bf16 v[14:17], v[146:149], v[208:211], v[14:17]
	v_mfma_f32_16x16x32_bf16 v[10:13], v[160:163], v[208:211], v[10:13]
	v_mfma_f32_16x16x32_bf16 v[62:65], v[156:159], v[188:191], v[62:65]
	v_mfma_f32_16x16x32_bf16 v[58:61], v[164:167], v[188:191], v[58:61]
	v_mfma_f32_16x16x32_bf16 v[46:49], v[156:159], v[196:199], v[46:49]
	v_mfma_f32_16x16x32_bf16 v[42:45], v[164:167], v[196:199], v[42:45]
	v_mfma_f32_16x16x32_bf16 v[30:33], v[156:159], v[204:207], v[30:33]
	v_mfma_f32_16x16x32_bf16 v[26:29], v[164:167], v[204:207], v[26:29]
	v_mfma_f32_16x16x32_bf16 v[14:17], v[156:159], v[212:215], v[14:17]
	v_mfma_f32_16x16x32_bf16 v[10:13], v[164:167], v[212:215], v[10:13]
	s_setprio 0
	s_setprio 1
	v_mfma_f32_16x16x32_bf16 v[54:57], v[168:171], v[184:187], v[54:57]
	v_mfma_f32_16x16x32_bf16 v[50:53], v[176:179], v[184:187], v[50:53]
	v_mfma_f32_16x16x32_bf16 v[38:41], v[168:171], v[192:195], v[38:41]
	v_mfma_f32_16x16x32_bf16 v[34:37], v[176:179], v[192:195], v[34:37]
	v_mfma_f32_16x16x32_bf16 v[22:25], v[168:171], v[200:203], v[22:25]
	v_mfma_f32_16x16x32_bf16 v[18:21], v[176:179], v[200:203], v[18:21]
	v_mfma_f32_16x16x32_bf16 v[6:9], v[168:171], v[208:211], v[6:9]
	v_mfma_f32_16x16x32_bf16 v[2:5], v[176:179], v[208:211], v[2:5]
	v_mfma_f32_16x16x32_bf16 v[54:57], v[172:175], v[188:191], v[54:57]
	v_mfma_f32_16x16x32_bf16 v[50:53], v[180:183], v[188:191], v[50:53]
	v_mfma_f32_16x16x32_bf16 v[38:41], v[172:175], v[196:199], v[38:41]
	v_mfma_f32_16x16x32_bf16 v[34:37], v[180:183], v[196:199], v[34:37]
	v_mfma_f32_16x16x32_bf16 v[22:25], v[172:175], v[204:207], v[22:25]
	v_mfma_f32_16x16x32_bf16 v[18:21], v[180:183], v[204:207], v[18:21]
	v_mfma_f32_16x16x32_bf16 v[6:9], v[172:175], v[212:215], v[6:9]
	v_mfma_f32_16x16x32_bf16 v[2:5], v[180:183], v[212:215], v[2:5]
	s_setprio 0
	s_barrier
	s_add_i32 s65, 0, 0x18000
	s_add_i32 s66, 0, 0x1c000
	v_add_u32_e32 v164, s65, v150
	v_add_u32_e32 v180, s66, v150
	ds_read_b128 v[146:149], v164
	ds_read_b128 v[156:159], v164 offset:1024
	ds_read_b128 v[160:163], v164 offset:2048
	ds_read_b128 v[164:167], v164 offset:3072
	ds_read_b128 v[168:171], v180
	ds_read_b128 v[172:175], v180 offset:1024
	ds_read_b128 v[176:179], v180 offset:2048
	ds_read_b128 v[180:183], v180 offset:3072
	s_add_u32 s30, s30, 0x2b0000
	s_addc_u32 s31, s31, 0
	s_mov_b32 m0, s40
	ds_read_b128 v[184:187], v154 offset:32768
	ds_read_b128 v[188:191], v154 offset:33792
	ds_read_b128 v[192:195], v154 offset:34816
	ds_read_b128 v[196:199], v154 offset:35840
	ds_read_b128 v[200:203], v154 offset:36864
	ds_read_b128 v[204:207], v154 offset:37888
	ds_read_b128 v[208:211], v154 offset:38912
	ds_read_b128 v[212:215], v154 offset:39936
	global_load_lds_dwordx4 v130, s[30:31]
	s_mov_b32 m0, s41
	s_nop 0
	global_load_lds_dwordx4 v134, s[30:31]
	s_waitcnt vmcnt(8)
	s_waitcnt lgkmcnt(0)
	s_barrier
	s_setprio 1
	s_waitcnt lgkmcnt(0)
	v_mfma_f32_16x16x32_bf16 v[126:129], v[146:149], v[184:187], v[126:129]
	v_mfma_f32_16x16x32_bf16 v[122:125], v[160:163], v[184:187], v[122:125]
	v_mfma_f32_16x16x32_bf16 v[110:113], v[146:149], v[192:195], v[110:113]
	v_mfma_f32_16x16x32_bf16 v[106:109], v[160:163], v[192:195], v[106:109]
	v_mfma_f32_16x16x32_bf16 v[94:97], v[146:149], v[200:203], v[94:97]
	v_mfma_f32_16x16x32_bf16 v[90:93], v[160:163], v[200:203], v[90:93]
	v_mfma_f32_16x16x32_bf16 v[78:81], v[146:149], v[208:211], v[78:81]
	v_mfma_f32_16x16x32_bf16 v[74:77], v[160:163], v[208:211], v[74:77]
	v_mfma_f32_16x16x32_bf16 v[126:129], v[156:159], v[188:191], v[126:129]
	v_mfma_f32_16x16x32_bf16 v[122:125], v[164:167], v[188:191], v[122:125]
	v_mfma_f32_16x16x32_bf16 v[110:113], v[156:159], v[196:199], v[110:113]
	v_mfma_f32_16x16x32_bf16 v[106:109], v[164:167], v[196:199], v[106:109]
	v_mfma_f32_16x16x32_bf16 v[94:97], v[156:159], v[204:207], v[94:97]
	v_mfma_f32_16x16x32_bf16 v[90:93], v[164:167], v[204:207], v[90:93]
	v_mfma_f32_16x16x32_bf16 v[78:81], v[156:159], v[212:215], v[78:81]
	v_mfma_f32_16x16x32_bf16 v[74:77], v[164:167], v[212:215], v[74:77]
	s_setprio 0
	s_setprio 1
	v_mfma_f32_16x16x32_bf16 v[118:121], v[168:171], v[184:187], v[118:121]
	v_mfma_f32_16x16x32_bf16 v[114:117], v[176:179], v[184:187], v[114:117]
	v_mfma_f32_16x16x32_bf16 v[102:105], v[168:171], v[192:195], v[102:105]
	v_mfma_f32_16x16x32_bf16 v[98:101], v[176:179], v[192:195], v[98:101]
	v_mfma_f32_16x16x32_bf16 v[86:89], v[168:171], v[200:203], v[86:89]
	v_mfma_f32_16x16x32_bf16 v[82:85], v[176:179], v[200:203], v[82:85]
	v_mfma_f32_16x16x32_bf16 v[70:73], v[168:171], v[208:211], v[70:73]
	v_mfma_f32_16x16x32_bf16 v[66:69], v[176:179], v[208:211], v[66:69]
	v_mfma_f32_16x16x32_bf16 v[118:121], v[172:175], v[188:191], v[118:121]
	v_mfma_f32_16x16x32_bf16 v[114:117], v[180:183], v[188:191], v[114:117]
	v_mfma_f32_16x16x32_bf16 v[102:105], v[172:175], v[196:199], v[102:105]
	v_mfma_f32_16x16x32_bf16 v[98:101], v[180:183], v[196:199], v[98:101]
	v_mfma_f32_16x16x32_bf16 v[86:89], v[172:175], v[204:207], v[86:89]
	v_mfma_f32_16x16x32_bf16 v[82:85], v[180:183], v[204:207], v[82:85]
	v_mfma_f32_16x16x32_bf16 v[70:73], v[172:175], v[212:215], v[70:73]
	v_mfma_f32_16x16x32_bf16 v[66:69], v[180:183], v[212:215], v[66:69]
	s_setprio 0
	s_barrier
	s_add_i32 s30, s65, s37
	v_lshl_add_u64 v[216:217], v[216:217], 0, s[20:21]
	s_mov_b32 m0, s30
	ds_read_b128 v[184:187], v154 offset:49152
	ds_read_b128 v[188:191], v154 offset:50176
	ds_read_b128 v[192:195], v154 offset:51200
	ds_read_b128 v[196:199], v154 offset:52224
	ds_read_b128 v[200:203], v154 offset:53248
	ds_read_b128 v[204:207], v154 offset:54272
	ds_read_b128 v[208:211], v154 offset:55296
	ds_read_b128 v[212:215], v154 offset:56320
	global_load_lds_dwordx4 v[216:217], off
	s_add_i32 m0, s30, 0x2000
	s_add_u32 s28, s28, 0x2b0080
	v_lshl_add_u64 v[216:217], v[218:219], 0, s[20:21]
	s_addc_u32 s29, s29, 0
	s_add_i32 s30, s66, s37
	global_load_lds_dwordx4 v[216:217], off
	s_mov_b32 m0, s30
	s_nop 0
	global_load_lds_dwordx4 v132, s[28:29]
	s_add_i32 m0, s30, 0x2000
	s_nop 0
	global_load_lds_dwordx4 v136, s[28:29]
	v_lshl_add_u64 v[216:217], v[220:221], 0, s[20:21]
	s_mov_b32 m0, s44
	s_nop 0
	global_load_lds_dwordx4 v[216:217], off
	v_lshl_add_u64 v[216:217], v[222:223], 0, s[20:21]
	s_mov_b32 m0, s45
	s_nop 0
	global_load_lds_dwordx4 v[216:217], off
	s_waitcnt vmcnt(8)
	s_waitcnt lgkmcnt(0)
	s_barrier
	s_setprio 1
	s_waitcnt lgkmcnt(0)
	v_mfma_f32_16x16x32_bf16 v[62:65], v[146:149], v[184:187], v[62:65]
	v_mfma_f32_16x16x32_bf16 v[58:61], v[160:163], v[184:187], v[58:61]
	v_mfma_f32_16x16x32_bf16 v[46:49], v[146:149], v[192:195], v[46:49]
	v_mfma_f32_16x16x32_bf16 v[42:45], v[160:163], v[192:195], v[42:45]
	v_mfma_f32_16x16x32_bf16 v[30:33], v[146:149], v[200:203], v[30:33]
	v_mfma_f32_16x16x32_bf16 v[26:29], v[160:163], v[200:203], v[26:29]
	v_mfma_f32_16x16x32_bf16 v[14:17], v[146:149], v[208:211], v[14:17]
	v_mfma_f32_16x16x32_bf16 v[10:13], v[160:163], v[208:211], v[10:13]
	v_mfma_f32_16x16x32_bf16 v[62:65], v[156:159], v[188:191], v[62:65]
	v_mfma_f32_16x16x32_bf16 v[58:61], v[164:167], v[188:191], v[58:61]
	v_mfma_f32_16x16x32_bf16 v[46:49], v[156:159], v[196:199], v[46:49]
	v_mfma_f32_16x16x32_bf16 v[42:45], v[164:167], v[196:199], v[42:45]
	v_mfma_f32_16x16x32_bf16 v[30:33], v[156:159], v[204:207], v[30:33]
	v_mfma_f32_16x16x32_bf16 v[26:29], v[164:167], v[204:207], v[26:29]
	v_mfma_f32_16x16x32_bf16 v[14:17], v[156:159], v[212:215], v[14:17]
	v_mfma_f32_16x16x32_bf16 v[10:13], v[164:167], v[212:215], v[10:13]
	s_setprio 0
	s_setprio 1
	v_mfma_f32_16x16x32_bf16 v[54:57], v[168:171], v[184:187], v[54:57]
	v_mfma_f32_16x16x32_bf16 v[50:53], v[176:179], v[184:187], v[50:53]
	v_mfma_f32_16x16x32_bf16 v[38:41], v[168:171], v[192:195], v[38:41]
	v_mfma_f32_16x16x32_bf16 v[34:37], v[176:179], v[192:195], v[34:37]
	v_mfma_f32_16x16x32_bf16 v[22:25], v[168:171], v[200:203], v[22:25]
	v_mfma_f32_16x16x32_bf16 v[18:21], v[176:179], v[200:203], v[18:21]
	v_mfma_f32_16x16x32_bf16 v[6:9], v[168:171], v[208:211], v[6:9]
	v_mfma_f32_16x16x32_bf16 v[2:5], v[176:179], v[208:211], v[2:5]
	v_mfma_f32_16x16x32_bf16 v[54:57], v[172:175], v[188:191], v[54:57]
	v_mfma_f32_16x16x32_bf16 v[50:53], v[180:183], v[188:191], v[50:53]
	v_mfma_f32_16x16x32_bf16 v[38:41], v[172:175], v[196:199], v[38:41]
	v_mfma_f32_16x16x32_bf16 v[34:37], v[180:183], v[196:199], v[34:37]
	v_mfma_f32_16x16x32_bf16 v[22:25], v[172:175], v[204:207], v[22:25]
	v_mfma_f32_16x16x32_bf16 v[18:21], v[180:183], v[204:207], v[18:21]
	v_mfma_f32_16x16x32_bf16 v[6:9], v[172:175], v[212:215], v[6:9]
	v_mfma_f32_16x16x32_bf16 v[2:5], v[180:183], v[212:215], v[2:5]
	s_setprio 0
	s_barrier
	s_add_i32 s64, s64, 2
	s_add_u32 s62, s62, 0x100
	s_addc_u32 s63, s63, 0
	s_add_u32 s26, s26, 0x100
	s_addc_u32 s27, s27, 0
	s_cmpk_gt_u32 s64, 0xa9
	s_cbranch_scc0 .LBB0_2248
	v_lshl_add_u32 v245, s60, 8, v1
	v_lshl_or_b32 v246, s61, 8, v151
	v_lshlrev_b32_e32 v245, 13, v245
	v_lshl_add_u32 v245, v246, 1, v245
	global_load_dwordx4 v[146:149], v245, s[16:17]
	global_load_dwordx4 v[156:159], v245, s[16:17] offset:256
	s_add_u32 s26, s16, 0x20000
	s_addc_u32 s27, s17, 0
	global_load_dwordx4 v[160:163], v245, s[26:27]
	global_load_dwordx4 v[164:167], v245, s[26:27] offset:256
	s_add_u32 s26, s16, 0x40000
	s_addc_u32 s27, s17, 0
	global_load_dwordx4 v[168:171], v245, s[26:27]
	global_load_dwordx4 v[172:175], v245, s[26:27] offset:256
	s_add_u32 s26, s16, 0x60000
	s_addc_u32 s27, s17, 0
	global_load_dwordx4 v[176:179], v245, s[26:27]
	global_load_dwordx4 v[180:183], v245, s[26:27] offset:256
	s_add_u32 s26, s16, 0x100000
	s_addc_u32 s27, s17, 0
	global_load_dwordx4 v[184:187], v245, s[26:27]
	global_load_dwordx4 v[188:191], v245, s[26:27] offset:256
	s_add_u32 s26, s16, 0x120000
	s_addc_u32 s27, s17, 0
	global_load_dwordx4 v[192:195], v245, s[26:27]
	global_load_dwordx4 v[196:199], v245, s[26:27] offset:256
	s_add_u32 s26, s16, 0x140000
	s_addc_u32 s27, s17, 0
	global_load_dwordx4 v[200:203], v245, s[26:27]
	global_load_dwordx4 v[204:207], v245, s[26:27] offset:256
	s_add_u32 s26, s16, 0x160000
	s_addc_u32 s27, s17, 0
	global_load_dwordx4 v[208:211], v245, s[26:27]
	global_load_dwordx4 v[212:215], v245, s[26:27] offset:256
	s_and_b64 vcc, exec, s[22:23]
	s_cbranch_vccz .LBB0_2251
	s_barrier
